# XCD-local row-block dependency counters: norm rows of a row-block handled on the XCD that produced it (plain stores, shared L2), grid barrier ahead of norm2 / next-layer norm1 skipped; runtime XCC-con
# speedup vs baseline: 1.0020x; 1.0020x over previous
; #define LAS __attribute__((address_space(3)))
; DI unsigned xb_add(unsigned* p, unsigned v) { return __hip_atomic_fetch_add(p, v, __ATOMIC_RELAXED, __HIP_MEMORY_SCOPE_AGENT); }
; DI unsigned xb_xcc_id() { return (unsigned)__builtin_amdgcn_s_getreg((3 << 11) | 20) & 0xFu; }
; DI XcdBarrier xcd_barrier_post(unsigned* bar, volatile LAS unsigned* st) {
;   XcdBarrier b; b.bar = bar; b.x = xb_xcc_id(); b.st = st;
;   if (threadIdx.x == 0) (void)xb_add(&bar[XB_XCNT(b.x)], 1u);
;   return b;
; }
; __global__ void __launch_bounds__(256, 2) mega(Params p, int ph_lo, int ph_hi) {
;   __shared__ __attribute__((aligned(16))) char lds[65536 + 16];
;   cg::grid_group grid = cg::this_grid();
;   volatile LAS unsigned* st = (volatile LAS unsigned*)(lds + 65536);
;   if (threadIdx.x == 0) { st[0] = 0u; st[1] = 0u; }
;   __syncthreads();
;   XcdBarrier xb = xcd_barrier_post(p.BAR, st);
.LBB0_2:
	s_or_b64 exec, exec, s[6:7]
	s_waitcnt lgkmcnt(0)
	s_barrier
	s_getreg_b32 s3, hwreg(HW_REG_XCC_ID, 0, 4)
	s_and_b32 s6, s3, 15
	v_writelane_b32 v250, 0, 43
	s_mov_b64 s[10:11], exec
	v_readlane_b32 s4, v251, 2
	v_readlane_b32 s5, v251, 3
	s_and_b64 s[4:5], s[10:11], s[4:5]
	s_mov_b64 exec, s[4:5]
	s_cbranch_execz .LBB0_5
	s_mov_b64 s[4:5], exec
	v_mbcnt_lo_u32_b32 v1, s4, 0
	v_mbcnt_hi_u32_b32 v1, s5, v1
	v_cmp_eq_u32_e32 vcc, 0, v1
	s_and_b64 s[8:9], exec, vcc
	s_mov_b64 exec, s[8:9]
	s_cbranch_execz .LBB0_5
	s_lshl_b32 s7, s6, 8
	s_bcnt1_i32_b64 s4, s[4:5]
	v_mov_b32_e32 v1, s7
	v_mov_b32_e32 v2, s4
	global_atomic_add v1, v2, s[70:71] offset:1024
	s_and_b32 s7, s2, 7
	s_lshl_b32 s7, s7, 2
	s_add_i32 s7, s7, 0x100
	v_mov_b32_e32 v16, s7
	s_add_i32 s7, s6, 1
	v_mov_b32_e32 v17, s7
	global_atomic_umax v16, v17, s[70:71]
	s_sub_i32 s7, 16, s6
	v_mov_b32_e32 v18, s7
	global_atomic_umax v16, v18, s[70:71] offset:64

; DI unsigned xb_add(unsigned* p, unsigned v) { return __hip_atomic_fetch_add(p, v, __ATOMIC_RELAXED, __HIP_MEMORY_SCOPE_AGENT); }
; DI void xcd_barrier(const XcdBarrier& b) {
;   asm volatile("s_waitcnt vmcnt(0)" ::: "memory");
;   __syncthreads();
;   if (threadIdx.x == 0) {
;     unsigned* bar = b.bar;
;     __builtin_amdgcn_s_waitcnt(0);
;     unsigned nloc = b.st[0], nx = b.st[1];
;     if (nloc == 0u) { xcd_barrier_complete(bar, b.x, nloc, nx); b.st[0] = nloc; b.st[1] = nx; }
;     const unsigned old = xb_add(&bar[XB_XSUB(b.x)], 1u);
; __global__ void __launch_bounds__(256, 2) mega(Params p, int ph_lo, int ph_hi) {
;     ...
;   for (int ph = ph_lo; ph < ph_hi; ++ph) {
;     if (ph > ph_lo) xcd_barrier(xb);
;     run_phase<-1>(p, ph, lds);
.LBB0_8:
	s_cmp_le_i32 s77, s80
	s_cbranch_scc1 .LBB0_62
	s_cmp_eq_u32 s77, 7
	s_cbranch_scc1 .Ldep_dec
	s_cmp_eq_u32 s77, 10
	s_cbranch_scc0 .Ldep_bar
.Ldep_dec:
	global_load_dwordx4 v[2:5], v111, s[70:71] offset:256 sc1
	global_load_dwordx4 v[6:9], v111, s[70:71] offset:272 sc1
	global_load_dwordx4 v[10:13], v111, s[70:71] offset:320 sc1
	global_load_dwordx4 v[14:17], v111, s[70:71] offset:336 sc1
	s_waitcnt vmcnt(0)
	v_add3_u32 v2, v2, v3, v4
	v_add3_u32 v5, v5, v6, v7
	v_add3_u32 v8, v8, v9, v10
	v_add3_u32 v11, v11, v12, v13
	v_add3_u32 v14, v14, v15, v16
	v_add3_u32 v2, v2, v5, v8
	v_add3_u32 v2, v2, v11, v14
	v_add_u32_e32 v2, v2, v17
	s_nop 1
	v_readfirstlane_b32 s0, v2
	s_cmpk_eq_u32 s0, 0x88
	s_cselect_b32 s1, 1, 0
	v_writelane_b32 v250, s1, 43
	s_cbranch_scc1 .LBB0_62
.Ldep_bar:
	s_waitcnt vmcnt(0)
	s_barrier
	s_mov_b64 s[0:1], exec
	v_readlane_b32 s2, v251, 2
	v_readlane_b32 s3, v251, 3
	s_and_b64 s[2:3], s[0:1], s[2:3]
	s_mov_b64 exec, s[2:3]
	s_cbranch_execz .LBB0_61
	s_waitcnt vmcnt(0) expcnt(0) lgkmcnt(0)
	ds_read_b32 v3, v140
	ds_read_b32 v2, v141
	s_waitcnt lgkmcnt(1)
	v_cmp_ne_u32_e32 vcc, 0, v3
	s_cbranch_vccnz .LBB0_25
	s_mov_b32 s21, 1
	s_branch .LBB0_13

; template <class Epi>
; DI void gemm_tile(const bf16_t* __restrict__ A, int lda, const bf16_t* __restrict__ Bt, int ldb, int K, int row0, int col0, char* lds, const Epi& epi) {
;     ...
;   for (int kt = 0; kt < KT; ++kt) {
;     asm volatile("s_waitcnt vmcnt(0)" ::: "memory");
;     __syncthreads();
;     const char* sa = lds + (kt & 1) * 32768 + (wr * 64 + fr) * 128;
;     const char* sb = lds + (kt & 1) * 32768 + 16384 + (wc * 64 + fr) * 128;
; #pragma unroll
;     for (int kk = 0; kk < 2; ++kk) {
;       if (kt + 1 < KT) { if (kk == 0) stage_a(kt + 1, (kt + 1) & 1); else stage_b(kt + 1, (kt + 1) & 1); }
;       bf16x8 a[4], b[4];
;       const int co = ((kk * 4 + fq) ^ swz) * 16;
; #pragma unroll
;       for (int m = 0; m < 4; ++m) a[m] = *(const bf16x8*)(sa + m * 2048 + co);
; #pragma unroll
;       for (int n = 0; n < 4; ++n) b[n] = *(const bf16x8*)(sb + n * 2048 + co);
; #pragma unroll
;       for (int m = 0; m < 4; ++m)
; #pragma unroll
;         for (int n = 0; n < 4; ++n) acc[m][n] = __builtin_amdgcn_mfma_f32_16x16x32_bf16(b[n], a[m], acc[m][n], 0, 0, 0);
;     }
;   }
.LBB0_84:
	s_add_i32 s20, s28, 0xffff8000
	s_and_b32 s29, s28, 0x8000
	s_and_b32 s20, s20, 0x8000
	v_add_u32_e32 v102, s29, v90
	v_add_u32_e32 v110, s20, v91
	v_or_b32_e32 v136, s20, v93
	v_add_u32_e32 v103, 0x1000, v102
	v_readfirstlane_b32 s20, v102
	v_lshl_add_u64 v[94:95], v[74:75], 0, s[0:1]
	v_add_u32_e32 v104, 0x2000, v102
	s_mov_b32 m0, s20
	v_readfirstlane_b32 s20, v103
	s_waitcnt vmcnt(0)
	s_waitcnt vmcnt(0) lgkmcnt(0)
	s_barrier
	v_lshl_add_u64 v[96:97], v[76:77], 0, s[0:1]
	v_add_u32_e32 v105, 0x3000, v102
	global_load_lds_dwordx4 v[94:95], off
	s_mov_b32 m0, s20
	v_readfirstlane_b32 s20, v104
	v_add_u32_e32 v137, 0x4000, v102
	v_lshl_add_u64 v[98:99], v[78:79], 0, s[0:1]
	global_load_lds_dwordx4 v[96:97], off
	s_mov_b32 m0, s20
	v_readfirstlane_b32 s20, v105
	v_add_u32_e32 v159, 0x5000, v102
	v_lshl_add_u64 v[100:101], v[80:81], 0, s[0:1]
	global_load_lds_dwordx4 v[98:99], off
	s_mov_b32 m0, s20
	v_readfirstlane_b32 s20, v137
	v_lshl_add_u64 v[132:133], v[66:67], 0, s[0:1]
	v_add_u32_e32 v160, 0x6000, v102
	global_load_lds_dwordx4 v[100:101], off
	v_add_u32_e32 v106, v110, v92
	v_add_u32_e32 v128, v136, v92
	s_mov_b32 m0, s20
	v_readfirstlane_b32 s20, v159
	v_lshl_add_u64 v[134:135], v[68:69], 0, s[0:1]
	v_add_u32_e32 v161, 0x7000, v102
	ds_read_b128 v[94:97], v106
	ds_read_b128 v[98:101], v106 offset:2048
	ds_read_b128 v[102:105], v106 offset:4096
	ds_read_b128 v[106:109], v106 offset:6144
	ds_read_b128 v[116:119], v128 offset:16384
	ds_read_b128 v[120:123], v128 offset:18432
	ds_read_b128 v[124:127], v128 offset:20480
	ds_read_b128 v[128:131], v128 offset:22528
	global_load_lds_dwordx4 v[132:133], off
	s_mov_b32 m0, s20
	v_readfirstlane_b32 s20, v160
	v_lshl_add_u64 v[84:85], v[70:71], 0, s[0:1]
	global_load_lds_dwordx4 v[134:135], off
	s_mov_b32 m0, s20
	v_readfirstlane_b32 s20, v161
	v_lshl_add_u64 v[82:83], v[72:73], 0, s[0:1]
	global_load_lds_dwordx4 v[84:85], off
	s_mov_b32 m0, s20
	s_waitcnt lgkmcnt(0)
	v_mfma_f32_16x16x32_bf16 v[30:33], v[116:119], v[102:105], v[30:33]
	global_load_lds_dwordx4 v[82:83], off
	s_add_u32 s0, s0, 0x80
	v_mfma_f32_16x16x32_bf16 v[26:29], v[120:123], v[102:105], v[26:29]
	s_addc_u32 s1, s1, 0
	s_add_i32 s28, s28, 0x8000
	s_cmpk_eq_i32 s0, 0x1580
	v_mfma_f32_16x16x32_bf16 v[22:25], v[124:127], v[102:105], v[22:25]
	v_mfma_f32_16x16x32_bf16 v[18:21], v[128:131], v[102:105], v[18:21]
	v_add_u32_e32 v102, v110, v89
	v_add_u32_e32 v110, v136, v89
	v_mfma_f32_16x16x32_bf16 v[62:65], v[116:119], v[94:97], v[62:65]
	v_mfma_f32_16x16x32_bf16 v[58:61], v[120:123], v[94:97], v[58:61]
	v_mfma_f32_16x16x32_bf16 v[54:57], v[124:127], v[94:97], v[54:57]
	v_mfma_f32_16x16x32_bf16 v[50:53], v[128:131], v[94:97], v[50:53]
	v_mfma_f32_16x16x32_bf16 v[46:49], v[116:119], v[98:101], v[46:49]
	v_mfma_f32_16x16x32_bf16 v[42:45], v[120:123], v[98:101], v[42:45]
	v_mfma_f32_16x16x32_bf16 v[38:41], v[124:127], v[98:101], v[38:41]
	v_mfma_f32_16x16x32_bf16 v[34:37], v[128:131], v[98:101], v[34:37]
	ds_read_b128 v[82:85], v102
	ds_read_b128 v[94:97], v102 offset:2048
	ds_read_b128 v[98:101], v102 offset:4096
	ds_read_b128 v[102:105], v102 offset:6144
	v_mfma_f32_16x16x32_bf16 v[14:17], v[116:119], v[106:109], v[14:17]
	v_mfma_f32_16x16x32_bf16 v[10:13], v[120:123], v[106:109], v[10:13]
	v_mfma_f32_16x16x32_bf16 v[6:9], v[124:127], v[106:109], v[6:9]
	v_mfma_f32_16x16x32_bf16 v[2:5], v[128:131], v[106:109], v[2:5]
	ds_read_b128 v[106:109], v110 offset:16384
	ds_read_b128 v[116:119], v110 offset:18432
	ds_read_b128 v[120:123], v110 offset:20480
	ds_read_b128 v[124:127], v110 offset:22528
	s_waitcnt lgkmcnt(0)
	v_mfma_f32_16x16x32_bf16 v[62:65], v[106:109], v[82:85], v[62:65]
	v_mfma_f32_16x16x32_bf16 v[58:61], v[116:119], v[82:85], v[58:61]
	v_mfma_f32_16x16x32_bf16 v[54:57], v[120:123], v[82:85], v[54:57]
	v_mfma_f32_16x16x32_bf16 v[50:53], v[124:127], v[82:85], v[50:53]
	v_mfma_f32_16x16x32_bf16 v[46:49], v[106:109], v[94:97], v[46:49]
	v_mfma_f32_16x16x32_bf16 v[42:45], v[116:119], v[94:97], v[42:45]
	v_mfma_f32_16x16x32_bf16 v[38:41], v[120:123], v[94:97], v[38:41]
	v_mfma_f32_16x16x32_bf16 v[34:37], v[124:127], v[94:97], v[34:37]
	v_mfma_f32_16x16x32_bf16 v[30:33], v[106:109], v[98:101], v[30:33]
	v_mfma_f32_16x16x32_bf16 v[26:29], v[116:119], v[98:101], v[26:29]
	v_mfma_f32_16x16x32_bf16 v[22:25], v[120:123], v[98:101], v[22:25]
	v_mfma_f32_16x16x32_bf16 v[18:21], v[124:127], v[98:101], v[18:21]
	v_mfma_f32_16x16x32_bf16 v[14:17], v[106:109], v[102:105], v[14:17]
	v_mfma_f32_16x16x32_bf16 v[10:13], v[116:119], v[102:105], v[10:13]
	v_mfma_f32_16x16x32_bf16 v[6:9], v[120:123], v[102:105], v[6:9]
	v_mfma_f32_16x16x32_bf16 v[2:5], v[124:127], v[102:105], v[2:5]
	s_cbranch_scc0 .LBB0_84
	v_add_u32_e32 v90, s29, v93
	v_add_u32_e32 v91, s29, v91
	v_add_u32_e32 v82, v90, v92
	v_add_u32_e32 v92, v91, v92
	s_waitcnt vmcnt(0)
	s_waitcnt vmcnt(0)
	s_barrier
; template <class Epi>
; DI void gemm_tile(const bf16_t* __restrict__ A, int lda, const bf16_t* __restrict__ Bt, int ldb, int K, int row0, int col0, char* lds, const Epi& epi) {
;     ...
;       for (int m = 0; m < 4; ++m) a[m] = *(const bf16x8*)(sa + m * 2048 + co);
; #pragma unroll
;       for (int n = 0; n < 4; ++n) b[n] = *(const bf16x8*)(sb + n * 2048 + co);
; #pragma unroll
;       for (int m = 0; m < 4; ++m)
; #pragma unroll
;         for (int n = 0; n < 4; ++n) acc[m][n] = __builtin_amdgcn_mfma_f32_16x16x32_bf16(b[n], a[m], acc[m][n], 0, 0, 0);
;   DI void operator()(const f32x4 (&acc)[4][4], int r0, int c0, int fr, int fq) const {
; #pragma unroll
;     for (int m = 0; m < 4; ++m) {
;       const int row = r0 + m * 16 + fr; const int b = row / TB, s = row % TB;
;       const float* src = xsrc_row(*p, from_inputs, b, s);
;       float* dst = xdst_row(*p, b, s);
;       const float* gate = p->MOD + (size_t)(l * 9 + (s < NCTX ? 8 : b)) * 6144 + gate_off;
; #pragma unroll
;       for (int n = 0; n < 4; ++n) {
;         const int col = c0 + n * 16 + fq * 4;
;         f32x4 g = *(const f32x4*)(gate + col), xv = *(const f32x4*)(src + col);
	ds_read_b128 v[66:69], v82 offset:16384
	ds_read_b128 v[74:77], v82 offset:18432
	ds_read_b128 v[70:73], v92
	ds_read_b128 v[78:81], v82 offset:20480
	ds_read_b128 v[82:85], v82 offset:22528
	s_waitcnt lgkmcnt(2)
	v_mfma_f32_16x16x32_bf16 v[62:65], v[66:69], v[70:73], v[62:65]
	v_mfma_f32_16x16x32_bf16 v[58:61], v[74:77], v[70:73], v[58:61]
	s_waitcnt lgkmcnt(1)
	v_mfma_f32_16x16x32_bf16 v[54:57], v[78:81], v[70:73], v[54:57]
	s_waitcnt lgkmcnt(0)
	v_mfma_f32_16x16x32_bf16 v[50:53], v[82:85], v[70:73], v[50:53]
	ds_read_b128 v[70:73], v92 offset:2048
	s_waitcnt lgkmcnt(0)
	v_mfma_f32_16x16x32_bf16 v[46:49], v[66:69], v[70:73], v[46:49]
	v_mfma_f32_16x16x32_bf16 v[42:45], v[74:77], v[70:73], v[42:45]
	v_mfma_f32_16x16x32_bf16 v[38:41], v[78:81], v[70:73], v[38:41]
	v_mfma_f32_16x16x32_bf16 v[34:37], v[82:85], v[70:73], v[34:37]
	ds_read_b128 v[70:73], v92 offset:4096
	s_waitcnt lgkmcnt(0)
	v_mfma_f32_16x16x32_bf16 v[30:33], v[66:69], v[70:73], v[30:33]
	v_mfma_f32_16x16x32_bf16 v[26:29], v[74:77], v[70:73], v[26:29]
	v_mfma_f32_16x16x32_bf16 v[22:25], v[78:81], v[70:73], v[22:25]
	v_mfma_f32_16x16x32_bf16 v[18:21], v[82:85], v[70:73], v[18:21]
	ds_read_b128 v[70:73], v92 offset:6144
	s_waitcnt lgkmcnt(0)
	v_mfma_f32_16x16x32_bf16 v[10:13], v[74:77], v[70:73], v[10:13]
	v_add_u32_e32 v74, v90, v89
	v_add_u32_e32 v75, v91, v89
	ds_read_b128 v[90:93], v74 offset:22528
	v_mfma_f32_16x16x32_bf16 v[14:17], v[66:69], v[70:73], v[14:17]
	ds_read_b128 v[66:69], v74 offset:16384
	ds_read_b128 v[94:97], v75 offset:6144
	v_mfma_f32_16x16x32_bf16 v[6:9], v[78:81], v[70:73], v[6:9]
	ds_read_b128 v[76:79], v74 offset:18432
	v_mfma_f32_16x16x32_bf16 v[2:5], v[82:85], v[70:73], v[2:5]
	ds_read_b128 v[80:83], v74 offset:20480
	ds_read_b128 v[70:73], v75
	s_waitcnt lgkmcnt(0)
	v_mfma_f32_16x16x32_bf16 v[62:65], v[66:69], v[70:73], v[62:65]
	v_mfma_f32_16x16x32_bf16 v[58:61], v[76:79], v[70:73], v[58:61]
	v_mfma_f32_16x16x32_bf16 v[54:57], v[80:83], v[70:73], v[54:57]
	v_mfma_f32_16x16x32_bf16 v[50:53], v[90:93], v[70:73], v[50:53]
	ds_read_b128 v[70:73], v75 offset:2048
	s_waitcnt lgkmcnt(0)
	v_mfma_f32_16x16x32_bf16 v[46:49], v[66:69], v[70:73], v[46:49]
	v_mfma_f32_16x16x32_bf16 v[42:45], v[76:79], v[70:73], v[42:45]
	v_mfma_f32_16x16x32_bf16 v[38:41], v[80:83], v[70:73], v[38:41]
	v_mfma_f32_16x16x32_bf16 v[34:37], v[90:93], v[70:73], v[34:37]
	ds_read_b128 v[70:73], v75 offset:4096
	s_waitcnt lgkmcnt(0)
	v_mfma_f32_16x16x32_bf16 v[30:33], v[66:69], v[70:73], v[30:33]
	v_mfma_f32_16x16x32_bf16 v[26:29], v[76:79], v[70:73], v[26:29]
	v_mfma_f32_16x16x32_bf16 v[22:25], v[80:83], v[70:73], v[22:25]
	v_mfma_f32_16x16x32_bf16 v[18:21], v[90:93], v[70:73], v[18:21]
	v_or_b32_e32 v70, s3, v87
	v_lshl_add_u32 v74, v88, 6, v70
	v_mfma_f32_16x16x32_bf16 v[14:17], v[66:69], v[94:97], v[14:17]
	v_mul_hi_i32 v66, v74, s47
	v_lshrrev_b32_e32 v67, 31, v66
	v_ashrrev_i32_e32 v66, 9, v66
	v_mfma_f32_16x16x32_bf16 v[10:13], v[76:79], v[94:97], v[10:13]
	v_add_u32_e32 v75, v66, v67
	v_mul_i32_i24_e32 v66, 0x900, v75
	v_sub_u32_e32 v71, v74, v66
	v_mfma_f32_16x16x32_bf16 v[6:9], v[80:83], v[94:97], v[6:9]
	v_lshlrev_b32_e32 v67, 11, v75
	v_cmp_lt_i32_e32 vcc, s33, v71
	v_mov_b64_e32 v[68:69], s[64:65]
	v_mfma_f32_16x16x32_bf16 v[2:5], v[90:93], v[94:97], v[2:5]
	v_lshlrev_b32_e32 v1, 6, v1
	v_lshlrev_b32_e32 v67, 2, v86
	v_or3_b32 v80, v1, v67, s2
	v_lshlrev_b32_e32 v66, 2, v80
	v_mov_b32_e32 v67, 0
	v_mov_b32_e32 v100, s64
	v_mov_b32_e32 v101, s65
	v_mov_b32_e32 v102, s56
	v_mov_b32_e32 v103, s57
	s_add_u32 s0, s58, 0x5000
	s_addc_u32 s1, s59, 0
	v_mov_b32_e32 v108, s0
	v_mov_b32_e32 v109, s1
	v_mov_b32_e32 v110, 8
	v_mov_b32_e32 v88, v74
	v_mul_hi_i32 v89, v88, s47
	v_lshrrev_b32_e32 v90, 31, v89
	v_ashrrev_i32_e32 v89, 9, v89
	v_add_u32_e32 v91, v89, v90
	v_mul_i32_i24_e32 v89, 0x900, v91
	v_sub_u32_e32 v92, v88, v89
	v_cmp_lt_i32_e32 vcc, s33, v92
	v_lshlrev_b32_e32 v89, 11, v91
	v_add3_u32 v89, v92, v89, s75
	v_lshl_add_u32 v90, v91, 8, v92
	v_cndmask_b32_e32 v94, v90, v89, vcc
	v_ashrrev_i32_e32 v95, 31, v94
	v_lshlrev_b64 v[96:97], 12, v[94:95]
	v_lshl_add_u64 v[96:97], v[96:97], 0, v[66:67]
	v_cndmask_b32_e32 v98, v100, v102, vcc
	v_cndmask_b32_e32 v99, v101, v103, vcc
	v_lshl_add_u64 v[224:225], v[98:99], 0, v[96:97]
	v_cndmask_b32_e32 v93, v110, v91, vcc
	v_add_u32_e32 v93, s82, v93
	v_mad_i64_i32 v[240:241], s[0:1], v93, s24, v[108:109]
	s_nop 0
	v_lshl_add_u64 v[240:241], v[240:241], 0, v[66:67]
	global_load_dwordx4 v[116:119], v[240:241], off
	global_load_dwordx4 v[120:123], v[240:241], off offset:64
	global_load_dwordx4 v[124:127], v[240:241], off offset:128
	global_load_dwordx4 v[128:131], v[240:241], off offset:192
	global_load_dwordx4 v[160:163], v[224:225], off
	global_load_dwordx4 v[164:167], v[224:225], off offset:64
	global_load_dwordx4 v[168:171], v[224:225], off offset:128
	global_load_dwordx4 v[172:175], v[224:225], off offset:192
	v_or_b32_e32 v88, 16, v74
	v_mul_hi_i32 v89, v88, s47
	v_lshrrev_b32_e32 v90, 31, v89
	v_ashrrev_i32_e32 v89, 9, v89
	v_add_u32_e32 v91, v89, v90
	v_mul_i32_i24_e32 v89, 0x900, v91
	v_sub_u32_e32 v92, v88, v89
	v_cmp_lt_i32_e32 vcc, s33, v92
	v_lshlrev_b32_e32 v89, 11, v91
	v_add3_u32 v89, v92, v89, s75
	v_lshl_add_u32 v90, v91, 8, v92
	v_cndmask_b32_e32 v94, v90, v89, vcc
	v_ashrrev_i32_e32 v95, 31, v94
	v_lshlrev_b64 v[96:97], 12, v[94:95]
	v_lshl_add_u64 v[96:97], v[96:97], 0, v[66:67]
	v_cndmask_b32_e32 v98, v100, v102, vcc
;   DI void operator()(const f32x4 (&acc)[4][4], int r0, int c0, int fr, int fq) const {
; #pragma unroll
;     for (int m = 0; m < 4; ++m) {
;       const int row = r0 + m * 16 + fr; const int b = row / TB, s = row % TB;
;       const float* src = xsrc_row(*p, from_inputs, b, s);
;       float* dst = xdst_row(*p, b, s);
;       const float* gate = p->MOD + (size_t)(l * 9 + (s < NCTX ? 8 : b)) * 6144 + gate_off;
; #pragma unroll
;       for (int n = 0; n < 4; ++n) {
;         const int col = c0 + n * 16 + fq * 4;
;         f32x4 g = *(const f32x4*)(gate + col), xv = *(const f32x4*)(src + col);
;         *(f32x4*)(dst + col) = xv + g * acc[m][n];
;       }
;     }
	v_cndmask_b32_e32 v99, v101, v103, vcc
	v_lshl_add_u64 v[226:227], v[98:99], 0, v[96:97]
	global_load_dwordx4 v[176:179], v[226:227], off
	global_load_dwordx4 v[180:183], v[226:227], off offset:64
	global_load_dwordx4 v[184:187], v[226:227], off offset:128
	global_load_dwordx4 v[188:191], v[226:227], off offset:192
	v_or_b32_e32 v88, 32, v74
	v_mul_hi_i32 v89, v88, s47
	v_lshrrev_b32_e32 v90, 31, v89
	v_ashrrev_i32_e32 v89, 9, v89
	v_add_u32_e32 v91, v89, v90
	v_mul_i32_i24_e32 v89, 0x900, v91
	v_sub_u32_e32 v92, v88, v89
	v_cmp_lt_i32_e32 vcc, s33, v92
	v_lshlrev_b32_e32 v89, 11, v91
	v_add3_u32 v89, v92, v89, s75
	v_lshl_add_u32 v90, v91, 8, v92
	v_cndmask_b32_e32 v94, v90, v89, vcc
	v_ashrrev_i32_e32 v95, 31, v94
	v_lshlrev_b64 v[96:97], 12, v[94:95]
	v_lshl_add_u64 v[96:97], v[96:97], 0, v[66:67]
	v_cndmask_b32_e32 v98, v100, v102, vcc
	v_cndmask_b32_e32 v99, v101, v103, vcc
	v_lshl_add_u64 v[228:229], v[98:99], 0, v[96:97]
	global_load_dwordx4 v[192:195], v[228:229], off
	global_load_dwordx4 v[196:199], v[228:229], off offset:64
	global_load_dwordx4 v[200:203], v[228:229], off offset:128
	global_load_dwordx4 v[204:207], v[228:229], off offset:192
	v_or_b32_e32 v88, 48, v74
	v_mul_hi_i32 v89, v88, s47
	v_lshrrev_b32_e32 v90, 31, v89
	v_ashrrev_i32_e32 v89, 9, v89
	v_add_u32_e32 v91, v89, v90
	v_mul_i32_i24_e32 v89, 0x900, v91
	v_sub_u32_e32 v92, v88, v89
	v_cmp_lt_i32_e32 vcc, s33, v92
	v_lshlrev_b32_e32 v89, 11, v91
	v_add3_u32 v89, v92, v89, s75
	v_lshl_add_u32 v90, v91, 8, v92
	v_cndmask_b32_e32 v94, v90, v89, vcc
	v_ashrrev_i32_e32 v95, 31, v94
	v_lshlrev_b64 v[96:97], 12, v[94:95]
	v_lshl_add_u64 v[96:97], v[96:97], 0, v[66:67]
	v_cndmask_b32_e32 v98, v100, v102, vcc
	v_cndmask_b32_e32 v99, v101, v103, vcc
	v_lshl_add_u64 v[230:231], v[98:99], 0, v[96:97]
	global_load_dwordx4 v[208:211], v[230:231], off
	global_load_dwordx4 v[212:215], v[230:231], off offset:64
	global_load_dwordx4 v[216:219], v[230:231], off offset:128
	global_load_dwordx4 v[220:223], v[230:231], off offset:192
	s_waitcnt vmcnt(15)
	v_pk_fma_f32 v[64:65], v[64:65], v[118:119], v[162:163]
	v_pk_fma_f32 v[62:63], v[62:63], v[116:117], v[160:161]
	global_store_dwordx4 v[224:225], v[62:65], off
	s_waitcnt vmcnt(15)
	v_pk_fma_f32 v[60:61], v[60:61], v[122:123], v[166:167]
	v_pk_fma_f32 v[58:59], v[58:59], v[120:121], v[164:165]
	global_store_dwordx4 v[224:225], v[58:61], off offset:64
	s_waitcnt vmcnt(15)
	v_pk_fma_f32 v[56:57], v[56:57], v[126:127], v[170:171]
	v_pk_fma_f32 v[54:55], v[54:55], v[124:125], v[168:169]
	global_store_dwordx4 v[224:225], v[54:57], off offset:128
	s_waitcnt vmcnt(15)
	v_pk_fma_f32 v[52:53], v[52:53], v[130:131], v[174:175]
	v_pk_fma_f32 v[50:51], v[50:51], v[128:129], v[172:173]
	global_store_dwordx4 v[224:225], v[50:53], off offset:192
	s_waitcnt vmcnt(15)
	v_pk_fma_f32 v[48:49], v[48:49], v[118:119], v[178:179]
	v_pk_fma_f32 v[46:47], v[46:47], v[116:117], v[176:177]
	global_store_dwordx4 v[226:227], v[46:49], off
	s_waitcnt vmcnt(15)
	v_pk_fma_f32 v[44:45], v[44:45], v[122:123], v[182:183]
	v_pk_fma_f32 v[42:43], v[42:43], v[120:121], v[180:181]
	global_store_dwordx4 v[226:227], v[42:45], off offset:64
	s_waitcnt vmcnt(15)
	v_pk_fma_f32 v[40:41], v[40:41], v[126:127], v[186:187]
	v_pk_fma_f32 v[38:39], v[38:39], v[124:125], v[184:185]
	global_store_dwordx4 v[226:227], v[38:41], off offset:128
	s_waitcnt vmcnt(15)
	v_pk_fma_f32 v[36:37], v[36:37], v[130:131], v[190:191]
	v_pk_fma_f32 v[34:35], v[34:35], v[128:129], v[188:189]
	global_store_dwordx4 v[226:227], v[34:37], off offset:192
	s_waitcnt vmcnt(15)
	v_pk_fma_f32 v[32:33], v[32:33], v[118:119], v[194:195]
	v_pk_fma_f32 v[30:31], v[30:31], v[116:117], v[192:193]
	global_store_dwordx4 v[228:229], v[30:33], off
	s_waitcnt vmcnt(15)
	v_pk_fma_f32 v[28:29], v[28:29], v[122:123], v[198:199]
	v_pk_fma_f32 v[26:27], v[26:27], v[120:121], v[196:197]
	global_store_dwordx4 v[228:229], v[26:29], off offset:64
	s_waitcnt vmcnt(15)
	v_pk_fma_f32 v[24:25], v[24:25], v[126:127], v[202:203]
	v_pk_fma_f32 v[22:23], v[22:23], v[124:125], v[200:201]
	global_store_dwordx4 v[228:229], v[22:25], off offset:128
	s_waitcnt vmcnt(15)
	v_pk_fma_f32 v[20:21], v[20:21], v[130:131], v[206:207]
	v_pk_fma_f32 v[18:19], v[18:19], v[128:129], v[204:205]
	global_store_dwordx4 v[228:229], v[18:21], off offset:192
	s_waitcnt vmcnt(15)
	v_pk_fma_f32 v[16:17], v[16:17], v[118:119], v[210:211]
	v_pk_fma_f32 v[14:15], v[14:15], v[116:117], v[208:209]
	global_store_dwordx4 v[230:231], v[14:17], off
	s_waitcnt vmcnt(15)
	v_pk_fma_f32 v[12:13], v[12:13], v[122:123], v[214:215]
	v_pk_fma_f32 v[10:11], v[10:11], v[120:121], v[212:213]
	global_store_dwordx4 v[230:231], v[10:13], off offset:64
	s_waitcnt vmcnt(15)
	v_pk_fma_f32 v[8:9], v[8:9], v[126:127], v[218:219]
	v_pk_fma_f32 v[6:7], v[6:7], v[124:125], v[216:217]
	global_store_dwordx4 v[230:231], v[6:9], off offset:128
	s_waitcnt vmcnt(15)
	v_pk_fma_f32 v[4:5], v[4:5], v[130:131], v[222:223]
	v_pk_fma_f32 v[2:3], v[2:3], v[128:129], v[220:221]
	global_store_dwordx4 v[230:231], v[2:5], off offset:192
	s_cmp_lg_u32 s77, 9
	s_cbranch_scc1 .Ldep_nosig_k9
	s_waitcnt vmcnt(0)
	s_barrier
	v_readfirstlane_b32 s0, v74
	s_lshr_b32 s0, s0, 7
	s_lshl_b32 s0, s0, 2
	s_add_i32 s0, s0, 0x1e40
	v_mov_b32_e32 v88, s0
	v_mov_b32_e32 v89, 1
	v_cmp_eq_u32_e32 vcc, 0, v138
	s_and_saveexec_b64 s[0:1], vcc
	global_atomic_add v88, v89, s[70:71]
	s_or_b64 exec, exec, s[0:1]

; DI void modnorm_rows(const Params& p, int l, int which  , bool from_inputs, bool skip_ctx, int w0, int wstride, int lane) {
;   const float* g = (which ? p.norm2_g : p.norm1_g) + l * DM;
;   f32x4 gg[4];
; #pragma unroll
;   for (int i = 0; i < 4; ++i) gg[i] = *(const f32x4*)(g + i * 256 + lane * 4);
;   const int nrows = skip_ctx ? 8 * NLAT : T_TOK;
;   auto rowof = [&](int i) -> int { return skip_ctx ? (i / NLAT) * TB + NCTX + (i % NLAT) : i; };
;   int i = w0;
;   if (i >= nrows) return;
;   f32x4 vn[4];
;   {
;     const int row = rowof(i); const float* src = xsrc_row(p, from_inputs, row / TB, row % TB);
; #pragma unroll
;     for (int q = 0; q < 4; ++q) vn[q] = *(const f32x4*)(src + q * 256 + lane * 4);
;   }
;   for (; i < nrows; i += wstride) {
;     const int row = rowof(i); const int b = row / TB, s = row % TB;
;     f32x4 v[4];
; #pragma unroll
;     for (int q = 0; q < 4; ++q) v[q] = vn[q];
;     if (i + wstride < nrows) {
;       const int rn = rowof(i + wstride); const float* src = xsrc_row(p, from_inputs, rn / TB, rn % TB);
; #pragma unroll
;       for (int q = 0; q < 4; ++q) vn[q] = *(const f32x4*)(src + q * 256 + lane * 4);
;     }
;     const float* mod = p.MOD + (size_t)(l * 9 + (s < NCTX ? 8 : b)) * 6144 + (which ? 3 * 1024 : 0);
;     f32x4 sh[4], sc[4];
; #pragma unroll
;     for (int q = 0; q < 4; ++q) { sh[q] = *(const f32x4*)(mod + q * 256 + lane * 4); sc[q] = *(const f32x4*)(mod + 1024 + q * 256 + lane * 4); }
.LBB0_228:
	s_andn2_b64 vcc, exec, s[0:1]
	s_cbranch_vccnz .LBB0_249
	v_readlane_b32 s0, v252, 9
	s_nop 1
	v_add_u32_e32 v1, s0, v158
	v_readlane_b32 s0, v250, 4
	v_readlane_b32 s1, v250, 5
	s_and_b64 s[0:1], s[0:1], exec
	s_movk_i32 s0, 0x4800
	s_cselect_b32 s26, 0x4000, s0
	v_cmp_gt_i32_e32 vcc, s26, v1
	s_and_saveexec_b64 s[2:3], vcc
	s_cbranch_execz .LBB0_248
	v_readlane_b32 s0, v252, 9
	v_lshlrev_b32_e32 v244, 4, v115
	v_lshlrev_b32_e32 v245, 3, v115
	v_add_u32_e32 v1, s0, v158
	s_nop 1
	v_readfirstlane_b32 s20, v1
	v_readlane_b32 s4, v254, 42
	v_readlane_b32 s5, v254, 43
	v_readlane_b32 s12, v254, 28
	v_readlane_b32 s13, v254, 29
	v_readlane_b32 s14, v254, 32
	v_readlane_b32 s15, v254, 33
	v_readlane_b32 s16, v253, 40
	v_readlane_b32 s17, v253, 41
	v_readlane_b32 s18, v250, 4
	v_readlane_b32 s19, v250, 5
	s_nop 3
	s_lshl_b32 s0, s49, 12
	s_add_u32 s4, s4, s0
	s_addc_u32 s5, s5, 0
	global_load_dwordx4 v[2:5], v244, s[4:5]
	global_load_dwordx4 v[6:9], v244, s[4:5] offset:1024
	global_load_dwordx4 v[10:13], v244, s[4:5] offset:2048
	global_load_dwordx4 v[14:17], v244, s[4:5] offset:3072
	s_mov_b32 s12, s56
	s_mov_b32 s13, s57
	s_mov_b32 s14, s64
	s_mov_b32 s15, s65
	s_cmp_lg_u64 s[18:19], 0
	s_cbranch_scc1 .Lnorm2_last
	v_readlane_b32 s6, v250, 43
	s_nop 1
	s_cmp_eq_u32 s6, 1
	s_cbranch_scc1 .Lnorm2_dep
	s_add_i32 s21, s20, 0
	s_mul_hi_u32 s7, s21, 0x38e38e39
	s_lshr_b32 s7, s7, 9
	s_mul_i32 s8, s7, 0x900
	s_sub_i32 s8, s21, s8
	s_lshl_b32 s9, s7, 11
	s_add_i32 s9, s9, s8
	s_add_i32 s9, s9, 0xffffff00
	s_lshl_b32 s10, s7, 8
	s_add_i32 s10, s10, s8
	s_cmpk_gt_i32 s8, 0xff
	s_cselect_b32 s9, s9, s10
	s_cselect_b32 s26, s12, s14
	s_cselect_b32 s27, s13, s15
	s_cselect_b32 s10, s7, 8
	s_lshl_b32 s9, s9, 12
	s_add_u32 s26, s26, s9
	s_addc_u32 s27, s27, 0
	s_add_i32 s10, s10, s82
	s_mul_i32 s10, s10, s24
	s_add_u32 s28, s58, s10
	s_addc_u32 s29, s59, 0
	s_add_u32 s28, s28, 0x3000
	s_addc_u32 s29, s29, 0
	s_add_u32 s0, s28, 0x1000
	s_addc_u32 s1, s29, 0
	global_load_dwordx4 v[18:21], v244, s[26:27]
	global_load_dwordx4 v[22:25], v244, s[26:27] offset:1024
	global_load_dwordx4 v[26:29], v244, s[26:27] offset:2048
	global_load_dwordx4 v[30:33], v244, s[26:27] offset:3072
	global_load_dwordx4 v[34:37], v244, s[28:29]
	global_load_dwordx4 v[38:41], v244, s[28:29] offset:1024
	global_load_dwordx4 v[42:45], v244, s[28:29] offset:2048
	global_load_dwordx4 v[46:49], v244, s[28:29] offset:3072
	global_load_dwordx4 v[50:53], v244, s[0:1]
	global_load_dwordx4 v[54:57], v244, s[0:1] offset:1024
	global_load_dwordx4 v[58:61], v244, s[0:1] offset:2048
	global_load_dwordx4 v[62:65], v244, s[0:1] offset:3072
	s_add_i32 s21, s20, 2048
	s_mul_hi_u32 s7, s21, 0x38e38e39
	s_lshr_b32 s7, s7, 9
	s_mul_i32 s8, s7, 0x900
	s_sub_i32 s8, s21, s8
	s_lshl_b32 s9, s7, 11
	s_add_i32 s9, s9, s8
	s_add_i32 s9, s9, 0xffffff00
	s_lshl_b32 s10, s7, 8
	s_add_i32 s10, s10, s8
	s_cmpk_gt_i32 s8, 0xff
	s_cselect_b32 s9, s9, s10
	s_cselect_b32 s26, s12, s14
	s_cselect_b32 s27, s13, s15
	s_cselect_b32 s10, s7, 8
	s_lshl_b32 s9, s9, 12
	s_add_u32 s26, s26, s9
	s_addc_u32 s27, s27, 0
	s_add_i32 s10, s10, s82
	s_mul_i32 s10, s10, s24
	s_add_u32 s28, s58, s10
	s_addc_u32 s29, s59, 0
	s_add_u32 s28, s28, 0x3000
	s_addc_u32 s29, s29, 0
	s_add_u32 s0, s28, 0x1000
	s_addc_u32 s1, s29, 0
	global_load_dwordx4 v[66:69], v244, s[26:27]
	global_load_dwordx4 v[70:73], v244, s[26:27] offset:1024
	global_load_dwordx4 v[74:77], v244, s[26:27] offset:2048
	global_load_dwordx4 v[78:81], v244, s[26:27] offset:3072
	global_load_dwordx4 v[82:85], v244, s[28:29]
	global_load_dwordx4 v[86:89], v244, s[28:29] offset:1024
	global_load_dwordx4 v[90:93], v244, s[28:29] offset:2048
	global_load_dwordx4 v[94:97], v244, s[28:29] offset:3072
	global_load_dwordx4 v[98:101], v244, s[0:1]
	global_load_dwordx4 v[102:105], v244, s[0:1] offset:1024
	global_load_dwordx4 v[106:109], v244, s[0:1] offset:2048
	global_load_dwordx4 v[118:121], v244, s[0:1] offset:3072
	s_add_i32 s21, s20, 4096
	s_mul_hi_u32 s7, s21, 0x38e38e39
	s_lshr_b32 s7, s7, 9
	s_mul_i32 s8, s7, 0x900
	s_sub_i32 s8, s21, s8
	s_lshl_b32 s9, s7, 11
	s_add_i32 s9, s9, s8
	s_add_i32 s9, s9, 0xffffff00
	s_lshl_b32 s10, s7, 8
	s_add_i32 s10, s10, s8
	s_cmpk_gt_i32 s8, 0xff
	s_cselect_b32 s9, s9, s10
	s_cselect_b32 s26, s12, s14
	s_cselect_b32 s27, s13, s15
	s_cselect_b32 s10, s7, 8
	s_lshl_b32 s9, s9, 12
	s_add_u32 s26, s26, s9
	s_addc_u32 s27, s27, 0
	s_add_i32 s10, s10, s82
	s_mul_i32 s10, s10, s24
	s_add_u32 s28, s58, s10
	s_addc_u32 s29, s59, 0
	s_add_u32 s28, s28, 0x3000
	s_addc_u32 s29, s29, 0
	s_add_u32 s0, s28, 0x1000
	s_addc_u32 s1, s29, 0
	global_load_dwordx4 v[122:125], v244, s[26:27]
	global_load_dwordx4 v[126:129], v244, s[26:27] offset:1024
	global_load_dwordx4 v[130:133], v244, s[26:27] offset:2048
	global_load_dwordx4 v[134:137], v244, s[26:27] offset:3072
	global_load_dwordx4 v[160:163], v244, s[28:29]
	global_load_dwordx4 v[164:167], v244, s[28:29] offset:1024
	global_load_dwordx4 v[168:171], v244, s[28:29] offset:2048
	global_load_dwordx4 v[172:175], v244, s[28:29] offset:3072
	global_load_dwordx4 v[176:179], v244, s[0:1]
	global_load_dwordx4 v[180:183], v244, s[0:1] offset:1024
	global_load_dwordx4 v[184:187], v244, s[0:1] offset:2048
	global_load_dwordx4 v[188:191], v244, s[0:1] offset:3072
	s_waitcnt vmcnt(24)
; DI unsigned pk_bf16(float lo, float hi) { f32x2 v = {lo, hi}; bf16v2 b = __builtin_convertvector(v, bf16v2); return __builtin_bit_cast(unsigned, b); }
; DI float red64(float x) { for (int o = 32; o > 0; o >>= 1) x += __shfl_xor(x, o); return x; }
; DI void modnorm_rows(const Params& p, int l, int which  , bool from_inputs, bool skip_ctx, int w0, int wstride, int lane) {
;     ...
;   for (; i < nrows; i += wstride) {
;     const int row = rowof(i); const int b = row / TB, s = row % TB;
;     f32x4 v[4];
; #pragma unroll
;     for (int q = 0; q < 4; ++q) v[q] = vn[q];
;     if (i + wstride < nrows) {
;       const int rn = rowof(i + wstride); const float* src = xsrc_row(p, from_inputs, rn / TB, rn % TB);
; #pragma unroll
;       for (int q = 0; q < 4; ++q) vn[q] = *(const f32x4*)(src + q * 256 + lane * 4);
;     }
;     const float* mod = p.MOD + (size_t)(l * 9 + (s < NCTX ? 8 : b)) * 6144 + (which ? 3 * 1024 : 0);
;     f32x4 sh[4], sc[4];
; #pragma unroll
;     for (int q = 0; q < 4; ++q) { sh[q] = *(const f32x4*)(mod + q * 256 + lane * 4); sc[q] = *(const f32x4*)(mod + 1024 + q * 256 + lane * 4); }
;     float ss = 0.f;
; #pragma unroll
;     for (int q = 0; q < 4; ++q) ss += v[q][0] * v[q][0] + v[q][1] * v[q][1] + v[q][2] * v[q][2] + v[q][3] * v[q][3];
;     ss = red64(ss);
;     const float rs = rsqrtf(ss * (1.f / 1024.f) + EPSF);
;     bf16_t* dst = p.HY + (size_t)row * DM;
; #pragma unroll
;     for (int q = 0; q < 4; ++q) {
;       float o[4];
; #pragma unroll
;       for (int j = 0; j < 4; ++j) o[j] = (v[q][j] * rs * gg[q][j]) * (1.f + sc[q][j]) + sh[q][j];
;       u32x2 w = {pk_bf16(o[0], o[1]), pk_bf16(o[2], o[3])};
;       *(u32x2*)(dst + q * 256 + lane * 4) = w;
;     }
	v_pk_mul_f32 v[246:247], v[18:19], v[18:19]
	v_pk_fma_f32 v[246:247], v[20:21], v[20:21], v[246:247]
	v_pk_fma_f32 v[246:247], v[22:23], v[22:23], v[246:247]
	v_pk_fma_f32 v[246:247], v[24:25], v[24:25], v[246:247]
	v_pk_fma_f32 v[246:247], v[26:27], v[26:27], v[246:247]
	v_pk_fma_f32 v[246:247], v[28:29], v[28:29], v[246:247]
	v_pk_fma_f32 v[246:247], v[30:31], v[30:31], v[246:247]
	v_pk_fma_f32 v[246:247], v[32:33], v[32:33], v[246:247]
	s_nop 0
	v_add_f32_e32 v246, v246, v247
	s_nop 1
	v_add_f32_dpp v246, v246, v246 quad_perm:[1,0,3,2] row_mask:0xf bank_mask:0xf
	s_nop 1
	v_add_f32_dpp v246, v246, v246 quad_perm:[2,3,0,1] row_mask:0xf bank_mask:0xf
	s_nop 1
	v_add_f32_dpp v246, v246, v246 row_half_mirror row_mask:0xf bank_mask:0xf
	s_nop 1
	v_add_f32_dpp v246, v246, v246 row_mirror row_mask:0xf bank_mask:0xf
	s_nop 1
	v_add_f32_dpp v246, v246, v246 row_bcast:15 row_mask:0xa bank_mask:0xf
	s_nop 1
	v_add_f32_dpp v246, v246, v246 row_bcast:31 row_mask:0xc bank_mask:0xf
	s_nop 1
	v_readlane_b32 s0, v246, 63
	s_add_i32 s21, s20, 0
	s_lshl_b32 s21, s21, 11
	s_add_u32 s10, s16, s21
	s_addc_u32 s11, s17, 0
	v_mov_b32_e32 v248, s0
	v_fmamk_f32 v248, v248, 0x3a800000, v143
	v_rsq_f32_e32 v248, v248
	s_nop 0
	v_pk_mul_f32 v[18:19], v[18:19], v[248:249] op_sel_hi:[1,0]
	v_pk_add_f32 v[50:51], v[50:51], 1.0 op_sel_hi:[1,0]
	v_pk_mul_f32 v[18:19], v[2:3], v[18:19]
	v_pk_fma_f32 v[18:19], v[50:51], v[18:19], v[34:35]
	v_pk_mul_f32 v[20:21], v[20:21], v[248:249] op_sel_hi:[1,0]
	v_pk_add_f32 v[52:53], v[52:53], 1.0 op_sel_hi:[1,0]
	v_pk_mul_f32 v[20:21], v[4:5], v[20:21]
	v_pk_fma_f32 v[20:21], v[52:53], v[20:21], v[36:37]
	v_cvt_pk_bf16_f32 v34, v18, v19
	v_cvt_pk_bf16_f32 v35, v20, v21
	global_store_dwordx2 v245, v[34:35], s[10:11]
	v_pk_mul_f32 v[22:23], v[22:23], v[248:249] op_sel_hi:[1,0]
	v_pk_add_f32 v[54:55], v[54:55], 1.0 op_sel_hi:[1,0]
	v_pk_mul_f32 v[22:23], v[6:7], v[22:23]
	v_pk_fma_f32 v[22:23], v[54:55], v[22:23], v[38:39]
	v_pk_mul_f32 v[24:25], v[24:25], v[248:249] op_sel_hi:[1,0]
	v_pk_add_f32 v[56:57], v[56:57], 1.0 op_sel_hi:[1,0]
	v_pk_mul_f32 v[24:25], v[8:9], v[24:25]
	v_pk_fma_f32 v[24:25], v[56:57], v[24:25], v[40:41]
	v_cvt_pk_bf16_f32 v38, v22, v23
	v_cvt_pk_bf16_f32 v39, v24, v25
	global_store_dwordx2 v245, v[38:39], s[10:11] offset:512
	v_pk_mul_f32 v[26:27], v[26:27], v[248:249] op_sel_hi:[1,0]
	v_pk_add_f32 v[58:59], v[58:59], 1.0 op_sel_hi:[1,0]
	v_pk_mul_f32 v[26:27], v[10:11], v[26:27]
	v_pk_fma_f32 v[26:27], v[58:59], v[26:27], v[42:43]
	v_pk_mul_f32 v[28:29], v[28:29], v[248:249] op_sel_hi:[1,0]
	v_pk_add_f32 v[60:61], v[60:61], 1.0 op_sel_hi:[1,0]
	v_pk_mul_f32 v[28:29], v[12:13], v[28:29]
	v_pk_fma_f32 v[28:29], v[60:61], v[28:29], v[44:45]
	v_cvt_pk_bf16_f32 v42, v26, v27
	v_cvt_pk_bf16_f32 v43, v28, v29
	global_store_dwordx2 v245, v[42:43], s[10:11] offset:1024
	v_pk_mul_f32 v[30:31], v[30:31], v[248:249] op_sel_hi:[1,0]
	v_pk_add_f32 v[62:63], v[62:63], 1.0 op_sel_hi:[1,0]
	v_pk_mul_f32 v[30:31], v[14:15], v[30:31]
	v_pk_fma_f32 v[30:31], v[62:63], v[30:31], v[46:47]
	v_pk_mul_f32 v[32:33], v[32:33], v[248:249] op_sel_hi:[1,0]
	v_pk_add_f32 v[64:65], v[64:65], 1.0 op_sel_hi:[1,0]
	v_pk_mul_f32 v[32:33], v[16:17], v[32:33]
	v_pk_fma_f32 v[32:33], v[64:65], v[32:33], v[48:49]
	v_cvt_pk_bf16_f32 v46, v30, v31
	v_cvt_pk_bf16_f32 v47, v32, v33
	global_store_dwordx2 v245, v[46:47], s[10:11] offset:1536
	s_add_i32 s21, s20, 6144
	s_mul_hi_u32 s7, s21, 0x38e38e39
	s_lshr_b32 s7, s7, 9
	s_mul_i32 s8, s7, 0x900
	s_sub_i32 s8, s21, s8
	s_lshl_b32 s9, s7, 11
	s_add_i32 s9, s9, s8
	s_add_i32 s9, s9, 0xffffff00
	s_lshl_b32 s10, s7, 8
	s_add_i32 s10, s10, s8
	s_cmpk_gt_i32 s8, 0xff
	s_cselect_b32 s9, s9, s10
	s_cselect_b32 s26, s12, s14
	s_cselect_b32 s27, s13, s15
	s_cselect_b32 s10, s7, 8
	s_lshl_b32 s9, s9, 12
	s_add_u32 s26, s26, s9
	s_addc_u32 s27, s27, 0
	s_add_i32 s10, s10, s82
	s_mul_i32 s10, s10, s24
	s_add_u32 s28, s58, s10
	s_addc_u32 s29, s59, 0
	s_add_u32 s28, s28, 0x3000
	s_addc_u32 s29, s29, 0
	s_add_u32 s0, s28, 0x1000
	s_addc_u32 s1, s29, 0
	global_load_dwordx4 v[18:21], v244, s[26:27]
	global_load_dwordx4 v[22:25], v244, s[26:27] offset:1024
	global_load_dwordx4 v[26:29], v244, s[26:27] offset:2048
	global_load_dwordx4 v[30:33], v244, s[26:27] offset:3072
	global_load_dwordx4 v[34:37], v244, s[28:29]
	global_load_dwordx4 v[38:41], v244, s[28:29] offset:1024
	global_load_dwordx4 v[42:45], v244, s[28:29] offset:2048
	global_load_dwordx4 v[46:49], v244, s[28:29] offset:3072
	global_load_dwordx4 v[50:53], v244, s[0:1]
	global_load_dwordx4 v[54:57], v244, s[0:1] offset:1024
	global_load_dwordx4 v[58:61], v244, s[0:1] offset:2048
	global_load_dwordx4 v[62:65], v244, s[0:1] offset:3072
	s_waitcnt vmcnt(28)
; DI unsigned pk_bf16(float lo, float hi) { f32x2 v = {lo, hi}; bf16v2 b = __builtin_convertvector(v, bf16v2); return __builtin_bit_cast(unsigned, b); }
; DI float red64(float x) { for (int o = 32; o > 0; o >>= 1) x += __shfl_xor(x, o); return x; }
; DI void modnorm_rows(const Params& p, int l, int which  , bool from_inputs, bool skip_ctx, int w0, int wstride, int lane) {
;     ...
;   for (; i < nrows; i += wstride) {
;     const int row = rowof(i); const int b = row / TB, s = row % TB;
;     f32x4 v[4];
; #pragma unroll
;     for (int q = 0; q < 4; ++q) v[q] = vn[q];
;     if (i + wstride < nrows) {
;       const int rn = rowof(i + wstride); const float* src = xsrc_row(p, from_inputs, rn / TB, rn % TB);
; #pragma unroll
;       for (int q = 0; q < 4; ++q) vn[q] = *(const f32x4*)(src + q * 256 + lane * 4);
;     }
;     const float* mod = p.MOD + (size_t)(l * 9 + (s < NCTX ? 8 : b)) * 6144 + (which ? 3 * 1024 : 0);
;     f32x4 sh[4], sc[4];
; #pragma unroll
;     for (int q = 0; q < 4; ++q) { sh[q] = *(const f32x4*)(mod + q * 256 + lane * 4); sc[q] = *(const f32x4*)(mod + 1024 + q * 256 + lane * 4); }
;     float ss = 0.f;
; #pragma unroll
;     for (int q = 0; q < 4; ++q) ss += v[q][0] * v[q][0] + v[q][1] * v[q][1] + v[q][2] * v[q][2] + v[q][3] * v[q][3];
;     ss = red64(ss);
;     const float rs = rsqrtf(ss * (1.f / 1024.f) + EPSF);
;     bf16_t* dst = p.HY + (size_t)row * DM;
; #pragma unroll
;     for (int q = 0; q < 4; ++q) {
;       float o[4];
; #pragma unroll
;       for (int j = 0; j < 4; ++j) o[j] = (v[q][j] * rs * gg[q][j]) * (1.f + sc[q][j]) + sh[q][j];
;       u32x2 w = {pk_bf16(o[0], o[1]), pk_bf16(o[2], o[3])};
;       *(u32x2*)(dst + q * 256 + lane * 4) = w;
;     }
	v_pk_mul_f32 v[246:247], v[66:67], v[66:67]
	v_pk_fma_f32 v[246:247], v[68:69], v[68:69], v[246:247]
	v_pk_fma_f32 v[246:247], v[70:71], v[70:71], v[246:247]
	v_pk_fma_f32 v[246:247], v[72:73], v[72:73], v[246:247]
	v_pk_fma_f32 v[246:247], v[74:75], v[74:75], v[246:247]
	v_pk_fma_f32 v[246:247], v[76:77], v[76:77], v[246:247]
	v_pk_fma_f32 v[246:247], v[78:79], v[78:79], v[246:247]
	v_pk_fma_f32 v[246:247], v[80:81], v[80:81], v[246:247]
	s_nop 0
	v_add_f32_e32 v246, v246, v247
	s_nop 1
	v_add_f32_dpp v246, v246, v246 quad_perm:[1,0,3,2] row_mask:0xf bank_mask:0xf
	s_nop 1
	v_add_f32_dpp v246, v246, v246 quad_perm:[2,3,0,1] row_mask:0xf bank_mask:0xf
	s_nop 1
	v_add_f32_dpp v246, v246, v246 row_half_mirror row_mask:0xf bank_mask:0xf
	s_nop 1
	v_add_f32_dpp v246, v246, v246 row_mirror row_mask:0xf bank_mask:0xf
	s_nop 1
	v_add_f32_dpp v246, v246, v246 row_bcast:15 row_mask:0xa bank_mask:0xf
	s_nop 1
	v_add_f32_dpp v246, v246, v246 row_bcast:31 row_mask:0xc bank_mask:0xf
	s_nop 1
	v_readlane_b32 s0, v246, 63
	s_add_i32 s21, s20, 2048
	s_lshl_b32 s21, s21, 11
	s_add_u32 s10, s16, s21
	s_addc_u32 s11, s17, 0
	v_mov_b32_e32 v248, s0
	v_fmamk_f32 v248, v248, 0x3a800000, v143
	v_rsq_f32_e32 v248, v248
	s_nop 0
	v_pk_mul_f32 v[66:67], v[66:67], v[248:249] op_sel_hi:[1,0]
	v_pk_add_f32 v[98:99], v[98:99], 1.0 op_sel_hi:[1,0]
	v_pk_mul_f32 v[66:67], v[2:3], v[66:67]
	v_pk_fma_f32 v[66:67], v[98:99], v[66:67], v[82:83]
	v_pk_mul_f32 v[68:69], v[68:69], v[248:249] op_sel_hi:[1,0]
	v_pk_add_f32 v[100:101], v[100:101], 1.0 op_sel_hi:[1,0]
	v_pk_mul_f32 v[68:69], v[4:5], v[68:69]
	v_pk_fma_f32 v[68:69], v[100:101], v[68:69], v[84:85]
	v_cvt_pk_bf16_f32 v82, v66, v67
	v_cvt_pk_bf16_f32 v83, v68, v69
	global_store_dwordx2 v245, v[82:83], s[10:11]
	v_pk_mul_f32 v[70:71], v[70:71], v[248:249] op_sel_hi:[1,0]
	v_pk_add_f32 v[102:103], v[102:103], 1.0 op_sel_hi:[1,0]
	v_pk_mul_f32 v[70:71], v[6:7], v[70:71]
	v_pk_fma_f32 v[70:71], v[102:103], v[70:71], v[86:87]
	v_pk_mul_f32 v[72:73], v[72:73], v[248:249] op_sel_hi:[1,0]
	v_pk_add_f32 v[104:105], v[104:105], 1.0 op_sel_hi:[1,0]
	v_pk_mul_f32 v[72:73], v[8:9], v[72:73]
	v_pk_fma_f32 v[72:73], v[104:105], v[72:73], v[88:89]
	v_cvt_pk_bf16_f32 v86, v70, v71
	v_cvt_pk_bf16_f32 v87, v72, v73
	global_store_dwordx2 v245, v[86:87], s[10:11] offset:512
	v_pk_mul_f32 v[74:75], v[74:75], v[248:249] op_sel_hi:[1,0]
	v_pk_add_f32 v[106:107], v[106:107], 1.0 op_sel_hi:[1,0]
	v_pk_mul_f32 v[74:75], v[10:11], v[74:75]
	v_pk_fma_f32 v[74:75], v[106:107], v[74:75], v[90:91]
	v_pk_mul_f32 v[76:77], v[76:77], v[248:249] op_sel_hi:[1,0]
	v_pk_add_f32 v[108:109], v[108:109], 1.0 op_sel_hi:[1,0]
	v_pk_mul_f32 v[76:77], v[12:13], v[76:77]
	v_pk_fma_f32 v[76:77], v[108:109], v[76:77], v[92:93]
	v_cvt_pk_bf16_f32 v90, v74, v75
	v_cvt_pk_bf16_f32 v91, v76, v77
	global_store_dwordx2 v245, v[90:91], s[10:11] offset:1024
	v_pk_mul_f32 v[78:79], v[78:79], v[248:249] op_sel_hi:[1,0]
	v_pk_add_f32 v[118:119], v[118:119], 1.0 op_sel_hi:[1,0]
	v_pk_mul_f32 v[78:79], v[14:15], v[78:79]
	v_pk_fma_f32 v[78:79], v[118:119], v[78:79], v[94:95]
	v_pk_mul_f32 v[80:81], v[80:81], v[248:249] op_sel_hi:[1,0]
	v_pk_add_f32 v[120:121], v[120:121], 1.0 op_sel_hi:[1,0]
	v_pk_mul_f32 v[80:81], v[16:17], v[80:81]
	v_pk_fma_f32 v[80:81], v[120:121], v[80:81], v[96:97]
	v_cvt_pk_bf16_f32 v94, v78, v79
	v_cvt_pk_bf16_f32 v95, v80, v81
	global_store_dwordx2 v245, v[94:95], s[10:11] offset:1536
	s_add_i32 s21, s20, 8192
	s_mul_hi_u32 s7, s21, 0x38e38e39
	s_lshr_b32 s7, s7, 9
	s_mul_i32 s8, s7, 0x900
	s_sub_i32 s8, s21, s8
	s_lshl_b32 s9, s7, 11
	s_add_i32 s9, s9, s8
	s_add_i32 s9, s9, 0xffffff00
	s_lshl_b32 s10, s7, 8
	s_add_i32 s10, s10, s8
	s_cmpk_gt_i32 s8, 0xff
	s_cselect_b32 s9, s9, s10
	s_cselect_b32 s26, s12, s14
	s_cselect_b32 s27, s13, s15
	s_cselect_b32 s10, s7, 8
	s_lshl_b32 s9, s9, 12
	s_add_u32 s26, s26, s9
	s_addc_u32 s27, s27, 0
	s_add_i32 s10, s10, s82
	s_mul_i32 s10, s10, s24
	s_add_u32 s28, s58, s10
	s_addc_u32 s29, s59, 0
	s_add_u32 s28, s28, 0x3000
	s_addc_u32 s29, s29, 0
	s_add_u32 s0, s28, 0x1000
	s_addc_u32 s1, s29, 0
	global_load_dwordx4 v[66:69], v244, s[26:27]
	global_load_dwordx4 v[70:73], v244, s[26:27] offset:1024
	global_load_dwordx4 v[74:77], v244, s[26:27] offset:2048
	global_load_dwordx4 v[78:81], v244, s[26:27] offset:3072
	global_load_dwordx4 v[82:85], v244, s[28:29]
	global_load_dwordx4 v[86:89], v244, s[28:29] offset:1024
	global_load_dwordx4 v[90:93], v244, s[28:29] offset:2048
	global_load_dwordx4 v[94:97], v244, s[28:29] offset:3072
	global_load_dwordx4 v[98:101], v244, s[0:1]
	global_load_dwordx4 v[102:105], v244, s[0:1] offset:1024
	global_load_dwordx4 v[106:109], v244, s[0:1] offset:2048
	global_load_dwordx4 v[118:121], v244, s[0:1] offset:3072
	s_waitcnt vmcnt(32)
; DI unsigned pk_bf16(float lo, float hi) { f32x2 v = {lo, hi}; bf16v2 b = __builtin_convertvector(v, bf16v2); return __builtin_bit_cast(unsigned, b); }
; DI float red64(float x) { for (int o = 32; o > 0; o >>= 1) x += __shfl_xor(x, o); return x; }
; DI void modnorm_rows(const Params& p, int l, int which  , bool from_inputs, bool skip_ctx, int w0, int wstride, int lane) {
;     ...
;   for (; i < nrows; i += wstride) {
;     const int row = rowof(i); const int b = row / TB, s = row % TB;
;     f32x4 v[4];
; #pragma unroll
;     for (int q = 0; q < 4; ++q) v[q] = vn[q];
;     if (i + wstride < nrows) {
;       const int rn = rowof(i + wstride); const float* src = xsrc_row(p, from_inputs, rn / TB, rn % TB);
; #pragma unroll
;       for (int q = 0; q < 4; ++q) vn[q] = *(const f32x4*)(src + q * 256 + lane * 4);
;     }
;     const float* mod = p.MOD + (size_t)(l * 9 + (s < NCTX ? 8 : b)) * 6144 + (which ? 3 * 1024 : 0);
;     f32x4 sh[4], sc[4];
; #pragma unroll
;     for (int q = 0; q < 4; ++q) { sh[q] = *(const f32x4*)(mod + q * 256 + lane * 4); sc[q] = *(const f32x4*)(mod + 1024 + q * 256 + lane * 4); }
;     float ss = 0.f;
; #pragma unroll
;     for (int q = 0; q < 4; ++q) ss += v[q][0] * v[q][0] + v[q][1] * v[q][1] + v[q][2] * v[q][2] + v[q][3] * v[q][3];
;     ss = red64(ss);
;     const float rs = rsqrtf(ss * (1.f / 1024.f) + EPSF);
;     bf16_t* dst = p.HY + (size_t)row * DM;
; #pragma unroll
;     for (int q = 0; q < 4; ++q) {
;       float o[4];
; #pragma unroll
;       for (int j = 0; j < 4; ++j) o[j] = (v[q][j] * rs * gg[q][j]) * (1.f + sc[q][j]) + sh[q][j];
;       u32x2 w = {pk_bf16(o[0], o[1]), pk_bf16(o[2], o[3])};
;       *(u32x2*)(dst + q * 256 + lane * 4) = w;
;     }
	v_pk_mul_f32 v[246:247], v[122:123], v[122:123]
	v_pk_fma_f32 v[246:247], v[124:125], v[124:125], v[246:247]
	v_pk_fma_f32 v[246:247], v[126:127], v[126:127], v[246:247]
	v_pk_fma_f32 v[246:247], v[128:129], v[128:129], v[246:247]
	v_pk_fma_f32 v[246:247], v[130:131], v[130:131], v[246:247]
	v_pk_fma_f32 v[246:247], v[132:133], v[132:133], v[246:247]
	v_pk_fma_f32 v[246:247], v[134:135], v[134:135], v[246:247]
	v_pk_fma_f32 v[246:247], v[136:137], v[136:137], v[246:247]
	s_nop 0
	v_add_f32_e32 v246, v246, v247
	s_nop 1
	v_add_f32_dpp v246, v246, v246 quad_perm:[1,0,3,2] row_mask:0xf bank_mask:0xf
	s_nop 1
	v_add_f32_dpp v246, v246, v246 quad_perm:[2,3,0,1] row_mask:0xf bank_mask:0xf
	s_nop 1
	v_add_f32_dpp v246, v246, v246 row_half_mirror row_mask:0xf bank_mask:0xf
	s_nop 1
	v_add_f32_dpp v246, v246, v246 row_mirror row_mask:0xf bank_mask:0xf
	s_nop 1
	v_add_f32_dpp v246, v246, v246 row_bcast:15 row_mask:0xa bank_mask:0xf
	s_nop 1
	v_add_f32_dpp v246, v246, v246 row_bcast:31 row_mask:0xc bank_mask:0xf
	s_nop 1
	v_readlane_b32 s0, v246, 63
	s_add_i32 s21, s20, 4096
	s_lshl_b32 s21, s21, 11
	s_add_u32 s10, s16, s21
	s_addc_u32 s11, s17, 0
	v_mov_b32_e32 v248, s0
	v_fmamk_f32 v248, v248, 0x3a800000, v143
	v_rsq_f32_e32 v248, v248
	s_nop 0
	v_pk_mul_f32 v[122:123], v[122:123], v[248:249] op_sel_hi:[1,0]
	v_pk_add_f32 v[176:177], v[176:177], 1.0 op_sel_hi:[1,0]
	v_pk_mul_f32 v[122:123], v[2:3], v[122:123]
	v_pk_fma_f32 v[122:123], v[176:177], v[122:123], v[160:161]
	v_pk_mul_f32 v[124:125], v[124:125], v[248:249] op_sel_hi:[1,0]
	v_pk_add_f32 v[178:179], v[178:179], 1.0 op_sel_hi:[1,0]
	v_pk_mul_f32 v[124:125], v[4:5], v[124:125]
	v_pk_fma_f32 v[124:125], v[178:179], v[124:125], v[162:163]
	v_cvt_pk_bf16_f32 v160, v122, v123
	v_cvt_pk_bf16_f32 v161, v124, v125
	global_store_dwordx2 v245, v[160:161], s[10:11]
	v_pk_mul_f32 v[126:127], v[126:127], v[248:249] op_sel_hi:[1,0]
	v_pk_add_f32 v[180:181], v[180:181], 1.0 op_sel_hi:[1,0]
	v_pk_mul_f32 v[126:127], v[6:7], v[126:127]
	v_pk_fma_f32 v[126:127], v[180:181], v[126:127], v[164:165]
	v_pk_mul_f32 v[128:129], v[128:129], v[248:249] op_sel_hi:[1,0]
	v_pk_add_f32 v[182:183], v[182:183], 1.0 op_sel_hi:[1,0]
	v_pk_mul_f32 v[128:129], v[8:9], v[128:129]
	v_pk_fma_f32 v[128:129], v[182:183], v[128:129], v[166:167]
	v_cvt_pk_bf16_f32 v164, v126, v127
	v_cvt_pk_bf16_f32 v165, v128, v129
	global_store_dwordx2 v245, v[164:165], s[10:11] offset:512
	v_pk_mul_f32 v[130:131], v[130:131], v[248:249] op_sel_hi:[1,0]
	v_pk_add_f32 v[184:185], v[184:185], 1.0 op_sel_hi:[1,0]
	v_pk_mul_f32 v[130:131], v[10:11], v[130:131]
	v_pk_fma_f32 v[130:131], v[184:185], v[130:131], v[168:169]
	v_pk_mul_f32 v[132:133], v[132:133], v[248:249] op_sel_hi:[1,0]
	v_pk_add_f32 v[186:187], v[186:187], 1.0 op_sel_hi:[1,0]
	v_pk_mul_f32 v[132:133], v[12:13], v[132:133]
	v_pk_fma_f32 v[132:133], v[186:187], v[132:133], v[170:171]
	v_cvt_pk_bf16_f32 v168, v130, v131
	v_cvt_pk_bf16_f32 v169, v132, v133
	global_store_dwordx2 v245, v[168:169], s[10:11] offset:1024
	v_pk_mul_f32 v[134:135], v[134:135], v[248:249] op_sel_hi:[1,0]
	v_pk_add_f32 v[188:189], v[188:189], 1.0 op_sel_hi:[1,0]
	v_pk_mul_f32 v[134:135], v[14:15], v[134:135]
	v_pk_fma_f32 v[134:135], v[188:189], v[134:135], v[172:173]
	v_pk_mul_f32 v[136:137], v[136:137], v[248:249] op_sel_hi:[1,0]
	v_pk_add_f32 v[190:191], v[190:191], 1.0 op_sel_hi:[1,0]
	v_pk_mul_f32 v[136:137], v[16:17], v[136:137]
	v_pk_fma_f32 v[136:137], v[190:191], v[136:137], v[174:175]
	v_cvt_pk_bf16_f32 v172, v134, v135
	v_cvt_pk_bf16_f32 v173, v136, v137
	global_store_dwordx2 v245, v[172:173], s[10:11] offset:1536
	s_add_i32 s21, s20, 10240
	s_mul_hi_u32 s7, s21, 0x38e38e39
	s_lshr_b32 s7, s7, 9
	s_mul_i32 s8, s7, 0x900
	s_sub_i32 s8, s21, s8
	s_lshl_b32 s9, s7, 11
	s_add_i32 s9, s9, s8
	s_add_i32 s9, s9, 0xffffff00
	s_lshl_b32 s10, s7, 8
	s_add_i32 s10, s10, s8
	s_cmpk_gt_i32 s8, 0xff
	s_cselect_b32 s9, s9, s10
	s_cselect_b32 s26, s12, s14
	s_cselect_b32 s27, s13, s15
	s_cselect_b32 s10, s7, 8
	s_lshl_b32 s9, s9, 12
	s_add_u32 s26, s26, s9
	s_addc_u32 s27, s27, 0
	s_add_i32 s10, s10, s82
	s_mul_i32 s10, s10, s24
	s_add_u32 s28, s58, s10
	s_addc_u32 s29, s59, 0
	s_add_u32 s28, s28, 0x3000
	s_addc_u32 s29, s29, 0
	s_add_u32 s0, s28, 0x1000
	s_addc_u32 s1, s29, 0
	global_load_dwordx4 v[122:125], v244, s[26:27]
	global_load_dwordx4 v[126:129], v244, s[26:27] offset:1024
	global_load_dwordx4 v[130:133], v244, s[26:27] offset:2048
	global_load_dwordx4 v[134:137], v244, s[26:27] offset:3072
	global_load_dwordx4 v[160:163], v244, s[28:29]
	global_load_dwordx4 v[164:167], v244, s[28:29] offset:1024
	global_load_dwordx4 v[168:171], v244, s[28:29] offset:2048
	global_load_dwordx4 v[172:175], v244, s[28:29] offset:3072
	global_load_dwordx4 v[176:179], v244, s[0:1]
	global_load_dwordx4 v[180:183], v244, s[0:1] offset:1024
	global_load_dwordx4 v[184:187], v244, s[0:1] offset:2048
	global_load_dwordx4 v[188:191], v244, s[0:1] offset:3072
	s_waitcnt vmcnt(32)
; DI unsigned pk_bf16(float lo, float hi) { f32x2 v = {lo, hi}; bf16v2 b = __builtin_convertvector(v, bf16v2); return __builtin_bit_cast(unsigned, b); }
; DI float red64(float x) { for (int o = 32; o > 0; o >>= 1) x += __shfl_xor(x, o); return x; }
; DI void modnorm_rows(const Params& p, int l, int which  , bool from_inputs, bool skip_ctx, int w0, int wstride, int lane) {
;     ...
;   for (; i < nrows; i += wstride) {
;     const int row = rowof(i); const int b = row / TB, s = row % TB;
;     f32x4 v[4];
; #pragma unroll
;     for (int q = 0; q < 4; ++q) v[q] = vn[q];
;     if (i + wstride < nrows) {
;       const int rn = rowof(i + wstride); const float* src = xsrc_row(p, from_inputs, rn / TB, rn % TB);
; #pragma unroll
;       for (int q = 0; q < 4; ++q) vn[q] = *(const f32x4*)(src + q * 256 + lane * 4);
;     }
;     const float* mod = p.MOD + (size_t)(l * 9 + (s < NCTX ? 8 : b)) * 6144 + (which ? 3 * 1024 : 0);
;     f32x4 sh[4], sc[4];
; #pragma unroll
;     for (int q = 0; q < 4; ++q) { sh[q] = *(const f32x4*)(mod + q * 256 + lane * 4); sc[q] = *(const f32x4*)(mod + 1024 + q * 256 + lane * 4); }
;     float ss = 0.f;
; #pragma unroll
;     for (int q = 0; q < 4; ++q) ss += v[q][0] * v[q][0] + v[q][1] * v[q][1] + v[q][2] * v[q][2] + v[q][3] * v[q][3];
;     ss = red64(ss);
;     const float rs = rsqrtf(ss * (1.f / 1024.f) + EPSF);
;     bf16_t* dst = p.HY + (size_t)row * DM;
; #pragma unroll
;     for (int q = 0; q < 4; ++q) {
;       float o[4];
; #pragma unroll
;       for (int j = 0; j < 4; ++j) o[j] = (v[q][j] * rs * gg[q][j]) * (1.f + sc[q][j]) + sh[q][j];
;       u32x2 w = {pk_bf16(o[0], o[1]), pk_bf16(o[2], o[3])};
;       *(u32x2*)(dst + q * 256 + lane * 4) = w;
;     }
	v_pk_mul_f32 v[246:247], v[18:19], v[18:19]
	v_pk_fma_f32 v[246:247], v[20:21], v[20:21], v[246:247]
	v_pk_fma_f32 v[246:247], v[22:23], v[22:23], v[246:247]
	v_pk_fma_f32 v[246:247], v[24:25], v[24:25], v[246:247]
	v_pk_fma_f32 v[246:247], v[26:27], v[26:27], v[246:247]
	v_pk_fma_f32 v[246:247], v[28:29], v[28:29], v[246:247]
	v_pk_fma_f32 v[246:247], v[30:31], v[30:31], v[246:247]
	v_pk_fma_f32 v[246:247], v[32:33], v[32:33], v[246:247]
	s_nop 0
	v_add_f32_e32 v246, v246, v247
	s_nop 1
	v_add_f32_dpp v246, v246, v246 quad_perm:[1,0,3,2] row_mask:0xf bank_mask:0xf
	s_nop 1
	v_add_f32_dpp v246, v246, v246 quad_perm:[2,3,0,1] row_mask:0xf bank_mask:0xf
	s_nop 1
	v_add_f32_dpp v246, v246, v246 row_half_mirror row_mask:0xf bank_mask:0xf
	s_nop 1
	v_add_f32_dpp v246, v246, v246 row_mirror row_mask:0xf bank_mask:0xf
	s_nop 1
	v_add_f32_dpp v246, v246, v246 row_bcast:15 row_mask:0xa bank_mask:0xf
	s_nop 1
	v_add_f32_dpp v246, v246, v246 row_bcast:31 row_mask:0xc bank_mask:0xf
	s_nop 1
	v_readlane_b32 s0, v246, 63
	s_add_i32 s21, s20, 6144
	s_lshl_b32 s21, s21, 11
	s_add_u32 s10, s16, s21
	s_addc_u32 s11, s17, 0
	v_mov_b32_e32 v248, s0
	v_fmamk_f32 v248, v248, 0x3a800000, v143
	v_rsq_f32_e32 v248, v248
	s_nop 0
	v_pk_mul_f32 v[18:19], v[18:19], v[248:249] op_sel_hi:[1,0]
	v_pk_add_f32 v[50:51], v[50:51], 1.0 op_sel_hi:[1,0]
	v_pk_mul_f32 v[18:19], v[2:3], v[18:19]
	v_pk_fma_f32 v[18:19], v[50:51], v[18:19], v[34:35]
	v_pk_mul_f32 v[20:21], v[20:21], v[248:249] op_sel_hi:[1,0]
	v_pk_add_f32 v[52:53], v[52:53], 1.0 op_sel_hi:[1,0]
	v_pk_mul_f32 v[20:21], v[4:5], v[20:21]
	v_pk_fma_f32 v[20:21], v[52:53], v[20:21], v[36:37]
	v_cvt_pk_bf16_f32 v34, v18, v19
	v_cvt_pk_bf16_f32 v35, v20, v21
	global_store_dwordx2 v245, v[34:35], s[10:11]
	v_pk_mul_f32 v[22:23], v[22:23], v[248:249] op_sel_hi:[1,0]
	v_pk_add_f32 v[54:55], v[54:55], 1.0 op_sel_hi:[1,0]
	v_pk_mul_f32 v[22:23], v[6:7], v[22:23]
	v_pk_fma_f32 v[22:23], v[54:55], v[22:23], v[38:39]
	v_pk_mul_f32 v[24:25], v[24:25], v[248:249] op_sel_hi:[1,0]
	v_pk_add_f32 v[56:57], v[56:57], 1.0 op_sel_hi:[1,0]
	v_pk_mul_f32 v[24:25], v[8:9], v[24:25]
	v_pk_fma_f32 v[24:25], v[56:57], v[24:25], v[40:41]
	v_cvt_pk_bf16_f32 v38, v22, v23
	v_cvt_pk_bf16_f32 v39, v24, v25
	global_store_dwordx2 v245, v[38:39], s[10:11] offset:512
	v_pk_mul_f32 v[26:27], v[26:27], v[248:249] op_sel_hi:[1,0]
	v_pk_add_f32 v[58:59], v[58:59], 1.0 op_sel_hi:[1,0]
	v_pk_mul_f32 v[26:27], v[10:11], v[26:27]
	v_pk_fma_f32 v[26:27], v[58:59], v[26:27], v[42:43]
	v_pk_mul_f32 v[28:29], v[28:29], v[248:249] op_sel_hi:[1,0]
	v_pk_add_f32 v[60:61], v[60:61], 1.0 op_sel_hi:[1,0]
	v_pk_mul_f32 v[28:29], v[12:13], v[28:29]
	v_pk_fma_f32 v[28:29], v[60:61], v[28:29], v[44:45]
	v_cvt_pk_bf16_f32 v42, v26, v27
	v_cvt_pk_bf16_f32 v43, v28, v29
	global_store_dwordx2 v245, v[42:43], s[10:11] offset:1024
	v_pk_mul_f32 v[30:31], v[30:31], v[248:249] op_sel_hi:[1,0]
	v_pk_add_f32 v[62:63], v[62:63], 1.0 op_sel_hi:[1,0]
	v_pk_mul_f32 v[30:31], v[14:15], v[30:31]
	v_pk_fma_f32 v[30:31], v[62:63], v[30:31], v[46:47]
	v_pk_mul_f32 v[32:33], v[32:33], v[248:249] op_sel_hi:[1,0]
	v_pk_add_f32 v[64:65], v[64:65], 1.0 op_sel_hi:[1,0]
	v_pk_mul_f32 v[32:33], v[16:17], v[32:33]
	v_pk_fma_f32 v[32:33], v[64:65], v[32:33], v[48:49]
	v_cvt_pk_bf16_f32 v46, v30, v31
	v_cvt_pk_bf16_f32 v47, v32, v33
	global_store_dwordx2 v245, v[46:47], s[10:11] offset:1536
	s_add_i32 s21, s20, 12288
	s_mul_hi_u32 s7, s21, 0x38e38e39
	s_lshr_b32 s7, s7, 9
	s_mul_i32 s8, s7, 0x900
	s_sub_i32 s8, s21, s8
	s_lshl_b32 s9, s7, 11
	s_add_i32 s9, s9, s8
	s_add_i32 s9, s9, 0xffffff00
	s_lshl_b32 s10, s7, 8
	s_add_i32 s10, s10, s8
	s_cmpk_gt_i32 s8, 0xff
	s_cselect_b32 s9, s9, s10
	s_cselect_b32 s26, s12, s14
	s_cselect_b32 s27, s13, s15
	s_cselect_b32 s10, s7, 8
	s_lshl_b32 s9, s9, 12
	s_add_u32 s26, s26, s9
	s_addc_u32 s27, s27, 0
	s_add_i32 s10, s10, s82
	s_mul_i32 s10, s10, s24
	s_add_u32 s28, s58, s10
	s_addc_u32 s29, s59, 0
	s_add_u32 s28, s28, 0x3000
	s_addc_u32 s29, s29, 0
	s_add_u32 s0, s28, 0x1000
	s_addc_u32 s1, s29, 0
	global_load_dwordx4 v[18:21], v244, s[26:27]
	global_load_dwordx4 v[22:25], v244, s[26:27] offset:1024
	global_load_dwordx4 v[26:29], v244, s[26:27] offset:2048
	global_load_dwordx4 v[30:33], v244, s[26:27] offset:3072
	global_load_dwordx4 v[34:37], v244, s[28:29]
	global_load_dwordx4 v[38:41], v244, s[28:29] offset:1024
	global_load_dwordx4 v[42:45], v244, s[28:29] offset:2048
	global_load_dwordx4 v[46:49], v244, s[28:29] offset:3072
	global_load_dwordx4 v[50:53], v244, s[0:1]
	global_load_dwordx4 v[54:57], v244, s[0:1] offset:1024
	global_load_dwordx4 v[58:61], v244, s[0:1] offset:2048
	global_load_dwordx4 v[62:65], v244, s[0:1] offset:3072
	s_waitcnt vmcnt(32)
; DI unsigned pk_bf16(float lo, float hi) { f32x2 v = {lo, hi}; bf16v2 b = __builtin_convertvector(v, bf16v2); return __builtin_bit_cast(unsigned, b); }
; DI float red64(float x) { for (int o = 32; o > 0; o >>= 1) x += __shfl_xor(x, o); return x; }
; DI void modnorm_rows(const Params& p, int l, int which  , bool from_inputs, bool skip_ctx, int w0, int wstride, int lane) {
;     ...
;   for (; i < nrows; i += wstride) {
;     const int row = rowof(i); const int b = row / TB, s = row % TB;
;     f32x4 v[4];
; #pragma unroll
;     for (int q = 0; q < 4; ++q) v[q] = vn[q];
;     if (i + wstride < nrows) {
;       const int rn = rowof(i + wstride); const float* src = xsrc_row(p, from_inputs, rn / TB, rn % TB);
; #pragma unroll
;       for (int q = 0; q < 4; ++q) vn[q] = *(const f32x4*)(src + q * 256 + lane * 4);
;     }
;     const float* mod = p.MOD + (size_t)(l * 9 + (s < NCTX ? 8 : b)) * 6144 + (which ? 3 * 1024 : 0);
;     f32x4 sh[4], sc[4];
; #pragma unroll
;     for (int q = 0; q < 4; ++q) { sh[q] = *(const f32x4*)(mod + q * 256 + lane * 4); sc[q] = *(const f32x4*)(mod + 1024 + q * 256 + lane * 4); }
;     float ss = 0.f;
; #pragma unroll
;     for (int q = 0; q < 4; ++q) ss += v[q][0] * v[q][0] + v[q][1] * v[q][1] + v[q][2] * v[q][2] + v[q][3] * v[q][3];
;     ss = red64(ss);
;     const float rs = rsqrtf(ss * (1.f / 1024.f) + EPSF);
;     bf16_t* dst = p.HY + (size_t)row * DM;
; #pragma unroll
;     for (int q = 0; q < 4; ++q) {
;       float o[4];
; #pragma unroll
;       for (int j = 0; j < 4; ++j) o[j] = (v[q][j] * rs * gg[q][j]) * (1.f + sc[q][j]) + sh[q][j];
;       u32x2 w = {pk_bf16(o[0], o[1]), pk_bf16(o[2], o[3])};
;       *(u32x2*)(dst + q * 256 + lane * 4) = w;
;     }
	v_pk_mul_f32 v[246:247], v[66:67], v[66:67]
	v_pk_fma_f32 v[246:247], v[68:69], v[68:69], v[246:247]
	v_pk_fma_f32 v[246:247], v[70:71], v[70:71], v[246:247]
	v_pk_fma_f32 v[246:247], v[72:73], v[72:73], v[246:247]
	v_pk_fma_f32 v[246:247], v[74:75], v[74:75], v[246:247]
	v_pk_fma_f32 v[246:247], v[76:77], v[76:77], v[246:247]
	v_pk_fma_f32 v[246:247], v[78:79], v[78:79], v[246:247]
	v_pk_fma_f32 v[246:247], v[80:81], v[80:81], v[246:247]
	s_nop 0
	v_add_f32_e32 v246, v246, v247
	s_nop 1
	v_add_f32_dpp v246, v246, v246 quad_perm:[1,0,3,2] row_mask:0xf bank_mask:0xf
	s_nop 1
	v_add_f32_dpp v246, v246, v246 quad_perm:[2,3,0,1] row_mask:0xf bank_mask:0xf
	s_nop 1
	v_add_f32_dpp v246, v246, v246 row_half_mirror row_mask:0xf bank_mask:0xf
	s_nop 1
	v_add_f32_dpp v246, v246, v246 row_mirror row_mask:0xf bank_mask:0xf
	s_nop 1
	v_add_f32_dpp v246, v246, v246 row_bcast:15 row_mask:0xa bank_mask:0xf
	s_nop 1
	v_add_f32_dpp v246, v246, v246 row_bcast:31 row_mask:0xc bank_mask:0xf
	s_nop 1
	v_readlane_b32 s0, v246, 63
	s_add_i32 s21, s20, 8192
	s_lshl_b32 s21, s21, 11
	s_add_u32 s10, s16, s21
	s_addc_u32 s11, s17, 0
	v_mov_b32_e32 v248, s0
	v_fmamk_f32 v248, v248, 0x3a800000, v143
	v_rsq_f32_e32 v248, v248
	s_nop 0
	v_pk_mul_f32 v[66:67], v[66:67], v[248:249] op_sel_hi:[1,0]
	v_pk_add_f32 v[98:99], v[98:99], 1.0 op_sel_hi:[1,0]
	v_pk_mul_f32 v[66:67], v[2:3], v[66:67]
	v_pk_fma_f32 v[66:67], v[98:99], v[66:67], v[82:83]
	v_pk_mul_f32 v[68:69], v[68:69], v[248:249] op_sel_hi:[1,0]
	v_pk_add_f32 v[100:101], v[100:101], 1.0 op_sel_hi:[1,0]
	v_pk_mul_f32 v[68:69], v[4:5], v[68:69]
	v_pk_fma_f32 v[68:69], v[100:101], v[68:69], v[84:85]
	v_cvt_pk_bf16_f32 v82, v66, v67
	v_cvt_pk_bf16_f32 v83, v68, v69
	global_store_dwordx2 v245, v[82:83], s[10:11]
	v_pk_mul_f32 v[70:71], v[70:71], v[248:249] op_sel_hi:[1,0]
	v_pk_add_f32 v[102:103], v[102:103], 1.0 op_sel_hi:[1,0]
	v_pk_mul_f32 v[70:71], v[6:7], v[70:71]
	v_pk_fma_f32 v[70:71], v[102:103], v[70:71], v[86:87]
	v_pk_mul_f32 v[72:73], v[72:73], v[248:249] op_sel_hi:[1,0]
	v_pk_add_f32 v[104:105], v[104:105], 1.0 op_sel_hi:[1,0]
	v_pk_mul_f32 v[72:73], v[8:9], v[72:73]
	v_pk_fma_f32 v[72:73], v[104:105], v[72:73], v[88:89]
	v_cvt_pk_bf16_f32 v86, v70, v71
	v_cvt_pk_bf16_f32 v87, v72, v73
	global_store_dwordx2 v245, v[86:87], s[10:11] offset:512
	v_pk_mul_f32 v[74:75], v[74:75], v[248:249] op_sel_hi:[1,0]
	v_pk_add_f32 v[106:107], v[106:107], 1.0 op_sel_hi:[1,0]
	v_pk_mul_f32 v[74:75], v[10:11], v[74:75]
	v_pk_fma_f32 v[74:75], v[106:107], v[74:75], v[90:91]
	v_pk_mul_f32 v[76:77], v[76:77], v[248:249] op_sel_hi:[1,0]
	v_pk_add_f32 v[108:109], v[108:109], 1.0 op_sel_hi:[1,0]
	v_pk_mul_f32 v[76:77], v[12:13], v[76:77]
	v_pk_fma_f32 v[76:77], v[108:109], v[76:77], v[92:93]
	v_cvt_pk_bf16_f32 v90, v74, v75
	v_cvt_pk_bf16_f32 v91, v76, v77
	global_store_dwordx2 v245, v[90:91], s[10:11] offset:1024
	v_pk_mul_f32 v[78:79], v[78:79], v[248:249] op_sel_hi:[1,0]
	v_pk_add_f32 v[118:119], v[118:119], 1.0 op_sel_hi:[1,0]
	v_pk_mul_f32 v[78:79], v[14:15], v[78:79]
	v_pk_fma_f32 v[78:79], v[118:119], v[78:79], v[94:95]
	v_pk_mul_f32 v[80:81], v[80:81], v[248:249] op_sel_hi:[1,0]
	v_pk_add_f32 v[120:121], v[120:121], 1.0 op_sel_hi:[1,0]
	v_pk_mul_f32 v[80:81], v[16:17], v[80:81]
	v_pk_fma_f32 v[80:81], v[120:121], v[80:81], v[96:97]
	v_cvt_pk_bf16_f32 v94, v78, v79
	v_cvt_pk_bf16_f32 v95, v80, v81
	global_store_dwordx2 v245, v[94:95], s[10:11] offset:1536
	s_add_i32 s21, s20, 14336
	s_mul_hi_u32 s7, s21, 0x38e38e39
	s_lshr_b32 s7, s7, 9
	s_mul_i32 s8, s7, 0x900
	s_sub_i32 s8, s21, s8
	s_lshl_b32 s9, s7, 11
	s_add_i32 s9, s9, s8
	s_add_i32 s9, s9, 0xffffff00
	s_lshl_b32 s10, s7, 8
	s_add_i32 s10, s10, s8
	s_cmpk_gt_i32 s8, 0xff
	s_cselect_b32 s9, s9, s10
	s_cselect_b32 s26, s12, s14
	s_cselect_b32 s27, s13, s15
	s_cselect_b32 s10, s7, 8
	s_lshl_b32 s9, s9, 12
	s_add_u32 s26, s26, s9
	s_addc_u32 s27, s27, 0
	s_add_i32 s10, s10, s82
	s_mul_i32 s10, s10, s24
	s_add_u32 s28, s58, s10
	s_addc_u32 s29, s59, 0
	s_add_u32 s28, s28, 0x3000
	s_addc_u32 s29, s29, 0
	s_add_u32 s0, s28, 0x1000
	s_addc_u32 s1, s29, 0
	global_load_dwordx4 v[66:69], v244, s[26:27]
	global_load_dwordx4 v[70:73], v244, s[26:27] offset:1024
	global_load_dwordx4 v[74:77], v244, s[26:27] offset:2048
	global_load_dwordx4 v[78:81], v244, s[26:27] offset:3072
	global_load_dwordx4 v[82:85], v244, s[28:29]
	global_load_dwordx4 v[86:89], v244, s[28:29] offset:1024
	global_load_dwordx4 v[90:93], v244, s[28:29] offset:2048
	global_load_dwordx4 v[94:97], v244, s[28:29] offset:3072
	global_load_dwordx4 v[98:101], v244, s[0:1]
	global_load_dwordx4 v[102:105], v244, s[0:1] offset:1024
	global_load_dwordx4 v[106:109], v244, s[0:1] offset:2048
	global_load_dwordx4 v[118:121], v244, s[0:1] offset:3072
	s_waitcnt vmcnt(32)
; DI unsigned pk_bf16(float lo, float hi) { f32x2 v = {lo, hi}; bf16v2 b = __builtin_convertvector(v, bf16v2); return __builtin_bit_cast(unsigned, b); }
; DI float red64(float x) { for (int o = 32; o > 0; o >>= 1) x += __shfl_xor(x, o); return x; }
; DI void modnorm_rows(const Params& p, int l, int which  , bool from_inputs, bool skip_ctx, int w0, int wstride, int lane) {
;     ...
;   for (; i < nrows; i += wstride) {
;     const int row = rowof(i); const int b = row / TB, s = row % TB;
;     f32x4 v[4];
; #pragma unroll
;     for (int q = 0; q < 4; ++q) v[q] = vn[q];
;     if (i + wstride < nrows) {
;       const int rn = rowof(i + wstride); const float* src = xsrc_row(p, from_inputs, rn / TB, rn % TB);
; #pragma unroll
;       for (int q = 0; q < 4; ++q) vn[q] = *(const f32x4*)(src + q * 256 + lane * 4);
;     }
;     const float* mod = p.MOD + (size_t)(l * 9 + (s < NCTX ? 8 : b)) * 6144 + (which ? 3 * 1024 : 0);
;     f32x4 sh[4], sc[4];
; #pragma unroll
;     for (int q = 0; q < 4; ++q) { sh[q] = *(const f32x4*)(mod + q * 256 + lane * 4); sc[q] = *(const f32x4*)(mod + 1024 + q * 256 + lane * 4); }
;     float ss = 0.f;
; #pragma unroll
;     for (int q = 0; q < 4; ++q) ss += v[q][0] * v[q][0] + v[q][1] * v[q][1] + v[q][2] * v[q][2] + v[q][3] * v[q][3];
;     ss = red64(ss);
;     const float rs = rsqrtf(ss * (1.f / 1024.f) + EPSF);
;     bf16_t* dst = p.HY + (size_t)row * DM;
; #pragma unroll
;     for (int q = 0; q < 4; ++q) {
;       float o[4];
; #pragma unroll
;       for (int j = 0; j < 4; ++j) o[j] = (v[q][j] * rs * gg[q][j]) * (1.f + sc[q][j]) + sh[q][j];
;       u32x2 w = {pk_bf16(o[0], o[1]), pk_bf16(o[2], o[3])};
;       *(u32x2*)(dst + q * 256 + lane * 4) = w;
;     }
	v_pk_mul_f32 v[246:247], v[122:123], v[122:123]
	v_pk_fma_f32 v[246:247], v[124:125], v[124:125], v[246:247]
	v_pk_fma_f32 v[246:247], v[126:127], v[126:127], v[246:247]
	v_pk_fma_f32 v[246:247], v[128:129], v[128:129], v[246:247]
	v_pk_fma_f32 v[246:247], v[130:131], v[130:131], v[246:247]
	v_pk_fma_f32 v[246:247], v[132:133], v[132:133], v[246:247]
	v_pk_fma_f32 v[246:247], v[134:135], v[134:135], v[246:247]
	v_pk_fma_f32 v[246:247], v[136:137], v[136:137], v[246:247]
	s_nop 0
	v_add_f32_e32 v246, v246, v247
	s_nop 1
	v_add_f32_dpp v246, v246, v246 quad_perm:[1,0,3,2] row_mask:0xf bank_mask:0xf
	s_nop 1
	v_add_f32_dpp v246, v246, v246 quad_perm:[2,3,0,1] row_mask:0xf bank_mask:0xf
	s_nop 1
	v_add_f32_dpp v246, v246, v246 row_half_mirror row_mask:0xf bank_mask:0xf
	s_nop 1
	v_add_f32_dpp v246, v246, v246 row_mirror row_mask:0xf bank_mask:0xf
	s_nop 1
	v_add_f32_dpp v246, v246, v246 row_bcast:15 row_mask:0xa bank_mask:0xf
	s_nop 1
	v_add_f32_dpp v246, v246, v246 row_bcast:31 row_mask:0xc bank_mask:0xf
	s_nop 1
	v_readlane_b32 s0, v246, 63
	s_add_i32 s21, s20, 10240
	s_lshl_b32 s21, s21, 11
	s_add_u32 s10, s16, s21
	s_addc_u32 s11, s17, 0
	v_mov_b32_e32 v248, s0
	v_fmamk_f32 v248, v248, 0x3a800000, v143
	v_rsq_f32_e32 v248, v248
	s_nop 0
	v_pk_mul_f32 v[122:123], v[122:123], v[248:249] op_sel_hi:[1,0]
	v_pk_add_f32 v[176:177], v[176:177], 1.0 op_sel_hi:[1,0]
	v_pk_mul_f32 v[122:123], v[2:3], v[122:123]
	v_pk_fma_f32 v[122:123], v[176:177], v[122:123], v[160:161]
	v_pk_mul_f32 v[124:125], v[124:125], v[248:249] op_sel_hi:[1,0]
	v_pk_add_f32 v[178:179], v[178:179], 1.0 op_sel_hi:[1,0]
	v_pk_mul_f32 v[124:125], v[4:5], v[124:125]
	v_pk_fma_f32 v[124:125], v[178:179], v[124:125], v[162:163]
	v_cvt_pk_bf16_f32 v160, v122, v123
	v_cvt_pk_bf16_f32 v161, v124, v125
	global_store_dwordx2 v245, v[160:161], s[10:11]
	v_pk_mul_f32 v[126:127], v[126:127], v[248:249] op_sel_hi:[1,0]
	v_pk_add_f32 v[180:181], v[180:181], 1.0 op_sel_hi:[1,0]
	v_pk_mul_f32 v[126:127], v[6:7], v[126:127]
	v_pk_fma_f32 v[126:127], v[180:181], v[126:127], v[164:165]
	v_pk_mul_f32 v[128:129], v[128:129], v[248:249] op_sel_hi:[1,0]
	v_pk_add_f32 v[182:183], v[182:183], 1.0 op_sel_hi:[1,0]
	v_pk_mul_f32 v[128:129], v[8:9], v[128:129]
	v_pk_fma_f32 v[128:129], v[182:183], v[128:129], v[166:167]
	v_cvt_pk_bf16_f32 v164, v126, v127
	v_cvt_pk_bf16_f32 v165, v128, v129
	global_store_dwordx2 v245, v[164:165], s[10:11] offset:512
	v_pk_mul_f32 v[130:131], v[130:131], v[248:249] op_sel_hi:[1,0]
	v_pk_add_f32 v[184:185], v[184:185], 1.0 op_sel_hi:[1,0]
	v_pk_mul_f32 v[130:131], v[10:11], v[130:131]
	v_pk_fma_f32 v[130:131], v[184:185], v[130:131], v[168:169]
	v_pk_mul_f32 v[132:133], v[132:133], v[248:249] op_sel_hi:[1,0]
	v_pk_add_f32 v[186:187], v[186:187], 1.0 op_sel_hi:[1,0]
	v_pk_mul_f32 v[132:133], v[12:13], v[132:133]
	v_pk_fma_f32 v[132:133], v[186:187], v[132:133], v[170:171]
	v_cvt_pk_bf16_f32 v168, v130, v131
	v_cvt_pk_bf16_f32 v169, v132, v133
	global_store_dwordx2 v245, v[168:169], s[10:11] offset:1024
	v_pk_mul_f32 v[134:135], v[134:135], v[248:249] op_sel_hi:[1,0]
	v_pk_add_f32 v[188:189], v[188:189], 1.0 op_sel_hi:[1,0]
	v_pk_mul_f32 v[134:135], v[14:15], v[134:135]
	v_pk_fma_f32 v[134:135], v[188:189], v[134:135], v[172:173]
	v_pk_mul_f32 v[136:137], v[136:137], v[248:249] op_sel_hi:[1,0]
	v_pk_add_f32 v[190:191], v[190:191], 1.0 op_sel_hi:[1,0]
	v_pk_mul_f32 v[136:137], v[16:17], v[136:137]
	v_pk_fma_f32 v[136:137], v[190:191], v[136:137], v[174:175]
	v_cvt_pk_bf16_f32 v172, v134, v135
	v_cvt_pk_bf16_f32 v173, v136, v137
	global_store_dwordx2 v245, v[172:173], s[10:11] offset:1536
	s_add_i32 s21, s20, 16384
	s_mul_hi_u32 s7, s21, 0x38e38e39
	s_lshr_b32 s7, s7, 9
	s_mul_i32 s8, s7, 0x900
	s_sub_i32 s8, s21, s8
	s_lshl_b32 s9, s7, 11
	s_add_i32 s9, s9, s8
	s_add_i32 s9, s9, 0xffffff00
	s_lshl_b32 s10, s7, 8
	s_add_i32 s10, s10, s8
	s_cmpk_gt_i32 s8, 0xff
	s_cselect_b32 s9, s9, s10
	s_cselect_b32 s26, s12, s14
	s_cselect_b32 s27, s13, s15
	s_cselect_b32 s10, s7, 8
	s_lshl_b32 s9, s9, 12
	s_add_u32 s26, s26, s9
	s_addc_u32 s27, s27, 0
	s_add_i32 s10, s10, s82
	s_mul_i32 s10, s10, s24
	s_add_u32 s28, s58, s10
	s_addc_u32 s29, s59, 0
	s_add_u32 s28, s28, 0x3000
	s_addc_u32 s29, s29, 0
	s_add_u32 s0, s28, 0x1000
	s_addc_u32 s1, s29, 0
	global_load_dwordx4 v[122:125], v244, s[26:27]
	global_load_dwordx4 v[126:129], v244, s[26:27] offset:1024
	global_load_dwordx4 v[130:133], v244, s[26:27] offset:2048
	global_load_dwordx4 v[134:137], v244, s[26:27] offset:3072
	global_load_dwordx4 v[160:163], v244, s[28:29]
	global_load_dwordx4 v[164:167], v244, s[28:29] offset:1024
	global_load_dwordx4 v[168:171], v244, s[28:29] offset:2048
	global_load_dwordx4 v[172:175], v244, s[28:29] offset:3072
	global_load_dwordx4 v[176:179], v244, s[0:1]
	global_load_dwordx4 v[180:183], v244, s[0:1] offset:1024
	global_load_dwordx4 v[184:187], v244, s[0:1] offset:2048
	global_load_dwordx4 v[188:191], v244, s[0:1] offset:3072
	s_waitcnt vmcnt(32)
; DI unsigned pk_bf16(float lo, float hi) { f32x2 v = {lo, hi}; bf16v2 b = __builtin_convertvector(v, bf16v2); return __builtin_bit_cast(unsigned, b); }
; DI float red64(float x) { for (int o = 32; o > 0; o >>= 1) x += __shfl_xor(x, o); return x; }
; DI void modnorm_rows(const Params& p, int l, int which  , bool from_inputs, bool skip_ctx, int w0, int wstride, int lane) {
;     ...
;   for (; i < nrows; i += wstride) {
;     const int row = rowof(i); const int b = row / TB, s = row % TB;
;     f32x4 v[4];
; #pragma unroll
;     for (int q = 0; q < 4; ++q) v[q] = vn[q];
;     if (i + wstride < nrows) {
;       const int rn = rowof(i + wstride); const float* src = xsrc_row(p, from_inputs, rn / TB, rn % TB);
; #pragma unroll
;       for (int q = 0; q < 4; ++q) vn[q] = *(const f32x4*)(src + q * 256 + lane * 4);
;     }
;     const float* mod = p.MOD + (size_t)(l * 9 + (s < NCTX ? 8 : b)) * 6144 + (which ? 3 * 1024 : 0);
;     f32x4 sh[4], sc[4];
; #pragma unroll
;     for (int q = 0; q < 4; ++q) { sh[q] = *(const f32x4*)(mod + q * 256 + lane * 4); sc[q] = *(const f32x4*)(mod + 1024 + q * 256 + lane * 4); }
;     float ss = 0.f;
; #pragma unroll
;     for (int q = 0; q < 4; ++q) ss += v[q][0] * v[q][0] + v[q][1] * v[q][1] + v[q][2] * v[q][2] + v[q][3] * v[q][3];
;     ss = red64(ss);
;     const float rs = rsqrtf(ss * (1.f / 1024.f) + EPSF);
;     bf16_t* dst = p.HY + (size_t)row * DM;
; #pragma unroll
;     for (int q = 0; q < 4; ++q) {
;       float o[4];
; #pragma unroll
;       for (int j = 0; j < 4; ++j) o[j] = (v[q][j] * rs * gg[q][j]) * (1.f + sc[q][j]) + sh[q][j];
;       u32x2 w = {pk_bf16(o[0], o[1]), pk_bf16(o[2], o[3])};
;       *(u32x2*)(dst + q * 256 + lane * 4) = w;
;     }
	v_pk_mul_f32 v[246:247], v[18:19], v[18:19]
	v_pk_fma_f32 v[246:247], v[20:21], v[20:21], v[246:247]
	v_pk_fma_f32 v[246:247], v[22:23], v[22:23], v[246:247]
	v_pk_fma_f32 v[246:247], v[24:25], v[24:25], v[246:247]
	v_pk_fma_f32 v[246:247], v[26:27], v[26:27], v[246:247]
	v_pk_fma_f32 v[246:247], v[28:29], v[28:29], v[246:247]
	v_pk_fma_f32 v[246:247], v[30:31], v[30:31], v[246:247]
	v_pk_fma_f32 v[246:247], v[32:33], v[32:33], v[246:247]
	s_nop 0
	v_add_f32_e32 v246, v246, v247
	s_nop 1
	v_add_f32_dpp v246, v246, v246 quad_perm:[1,0,3,2] row_mask:0xf bank_mask:0xf
	s_nop 1
	v_add_f32_dpp v246, v246, v246 quad_perm:[2,3,0,1] row_mask:0xf bank_mask:0xf
	s_nop 1
	v_add_f32_dpp v246, v246, v246 row_half_mirror row_mask:0xf bank_mask:0xf
	s_nop 1
	v_add_f32_dpp v246, v246, v246 row_mirror row_mask:0xf bank_mask:0xf
	s_nop 1
	v_add_f32_dpp v246, v246, v246 row_bcast:15 row_mask:0xa bank_mask:0xf
	s_nop 1
	v_add_f32_dpp v246, v246, v246 row_bcast:31 row_mask:0xc bank_mask:0xf
	s_nop 1
	v_readlane_b32 s0, v246, 63
	s_add_i32 s21, s20, 12288
	s_lshl_b32 s21, s21, 11
	s_add_u32 s10, s16, s21
	s_addc_u32 s11, s17, 0
	v_mov_b32_e32 v248, s0
	v_fmamk_f32 v248, v248, 0x3a800000, v143
	v_rsq_f32_e32 v248, v248
	s_nop 0
	v_pk_mul_f32 v[18:19], v[18:19], v[248:249] op_sel_hi:[1,0]
	v_pk_add_f32 v[50:51], v[50:51], 1.0 op_sel_hi:[1,0]
	v_pk_mul_f32 v[18:19], v[2:3], v[18:19]
	v_pk_fma_f32 v[18:19], v[50:51], v[18:19], v[34:35]
	v_pk_mul_f32 v[20:21], v[20:21], v[248:249] op_sel_hi:[1,0]
	v_pk_add_f32 v[52:53], v[52:53], 1.0 op_sel_hi:[1,0]
	v_pk_mul_f32 v[20:21], v[4:5], v[20:21]
	v_pk_fma_f32 v[20:21], v[52:53], v[20:21], v[36:37]
	v_cvt_pk_bf16_f32 v34, v18, v19
	v_cvt_pk_bf16_f32 v35, v20, v21
	global_store_dwordx2 v245, v[34:35], s[10:11]
	v_pk_mul_f32 v[22:23], v[22:23], v[248:249] op_sel_hi:[1,0]
	v_pk_add_f32 v[54:55], v[54:55], 1.0 op_sel_hi:[1,0]
	v_pk_mul_f32 v[22:23], v[6:7], v[22:23]
	v_pk_fma_f32 v[22:23], v[54:55], v[22:23], v[38:39]
	v_pk_mul_f32 v[24:25], v[24:25], v[248:249] op_sel_hi:[1,0]
	v_pk_add_f32 v[56:57], v[56:57], 1.0 op_sel_hi:[1,0]
	v_pk_mul_f32 v[24:25], v[8:9], v[24:25]
	v_pk_fma_f32 v[24:25], v[56:57], v[24:25], v[40:41]
	v_cvt_pk_bf16_f32 v38, v22, v23
	v_cvt_pk_bf16_f32 v39, v24, v25
	global_store_dwordx2 v245, v[38:39], s[10:11] offset:512
	v_pk_mul_f32 v[26:27], v[26:27], v[248:249] op_sel_hi:[1,0]
	v_pk_add_f32 v[58:59], v[58:59], 1.0 op_sel_hi:[1,0]
	v_pk_mul_f32 v[26:27], v[10:11], v[26:27]
	v_pk_fma_f32 v[26:27], v[58:59], v[26:27], v[42:43]
	v_pk_mul_f32 v[28:29], v[28:29], v[248:249] op_sel_hi:[1,0]
	v_pk_add_f32 v[60:61], v[60:61], 1.0 op_sel_hi:[1,0]
	v_pk_mul_f32 v[28:29], v[12:13], v[28:29]
	v_pk_fma_f32 v[28:29], v[60:61], v[28:29], v[44:45]
	v_cvt_pk_bf16_f32 v42, v26, v27
	v_cvt_pk_bf16_f32 v43, v28, v29
	global_store_dwordx2 v245, v[42:43], s[10:11] offset:1024
	v_pk_mul_f32 v[30:31], v[30:31], v[248:249] op_sel_hi:[1,0]
	v_pk_add_f32 v[62:63], v[62:63], 1.0 op_sel_hi:[1,0]
	v_pk_mul_f32 v[30:31], v[14:15], v[30:31]
	v_pk_fma_f32 v[30:31], v[62:63], v[30:31], v[46:47]
	v_pk_mul_f32 v[32:33], v[32:33], v[248:249] op_sel_hi:[1,0]
	v_pk_add_f32 v[64:65], v[64:65], 1.0 op_sel_hi:[1,0]
	v_pk_mul_f32 v[32:33], v[16:17], v[32:33]
	v_pk_fma_f32 v[32:33], v[64:65], v[32:33], v[48:49]
	v_cvt_pk_bf16_f32 v46, v30, v31
	v_cvt_pk_bf16_f32 v47, v32, v33
	global_store_dwordx2 v245, v[46:47], s[10:11] offset:1536
	s_waitcnt vmcnt(20)
	v_pk_mul_f32 v[246:247], v[66:67], v[66:67]
	v_pk_fma_f32 v[246:247], v[68:69], v[68:69], v[246:247]
	v_pk_fma_f32 v[246:247], v[70:71], v[70:71], v[246:247]
	v_pk_fma_f32 v[246:247], v[72:73], v[72:73], v[246:247]
	v_pk_fma_f32 v[246:247], v[74:75], v[74:75], v[246:247]
	v_pk_fma_f32 v[246:247], v[76:77], v[76:77], v[246:247]
	v_pk_fma_f32 v[246:247], v[78:79], v[78:79], v[246:247]
	v_pk_fma_f32 v[246:247], v[80:81], v[80:81], v[246:247]
	s_nop 0
	v_add_f32_e32 v246, v246, v247
	s_nop 1
	v_add_f32_dpp v246, v246, v246 quad_perm:[1,0,3,2] row_mask:0xf bank_mask:0xf
	s_nop 1
	v_add_f32_dpp v246, v246, v246 quad_perm:[2,3,0,1] row_mask:0xf bank_mask:0xf
	s_nop 1
	v_add_f32_dpp v246, v246, v246 row_half_mirror row_mask:0xf bank_mask:0xf
	s_nop 1
	v_add_f32_dpp v246, v246, v246 row_mirror row_mask:0xf bank_mask:0xf
	s_nop 1
	v_add_f32_dpp v246, v246, v246 row_bcast:15 row_mask:0xa bank_mask:0xf
	s_nop 1
	v_add_f32_dpp v246, v246, v246 row_bcast:31 row_mask:0xc bank_mask:0xf
	s_nop 1
	v_readlane_b32 s0, v246, 63
	s_add_i32 s21, s20, 14336
	s_lshl_b32 s21, s21, 11
	s_add_u32 s10, s16, s21
	s_addc_u32 s11, s17, 0
	v_mov_b32_e32 v248, s0
	v_fmamk_f32 v248, v248, 0x3a800000, v143
	v_rsq_f32_e32 v248, v248
	s_nop 0
	v_pk_mul_f32 v[66:67], v[66:67], v[248:249] op_sel_hi:[1,0]
	v_pk_add_f32 v[98:99], v[98:99], 1.0 op_sel_hi:[1,0]
	v_pk_mul_f32 v[66:67], v[2:3], v[66:67]
	v_pk_fma_f32 v[66:67], v[98:99], v[66:67], v[82:83]
	v_pk_mul_f32 v[68:69], v[68:69], v[248:249] op_sel_hi:[1,0]
	v_pk_add_f32 v[100:101], v[100:101], 1.0 op_sel_hi:[1,0]
	v_pk_mul_f32 v[68:69], v[4:5], v[68:69]
	v_pk_fma_f32 v[68:69], v[100:101], v[68:69], v[84:85]
	v_cvt_pk_bf16_f32 v82, v66, v67
	v_cvt_pk_bf16_f32 v83, v68, v69
	global_store_dwordx2 v245, v[82:83], s[10:11]
	v_pk_mul_f32 v[70:71], v[70:71], v[248:249] op_sel_hi:[1,0]
	v_pk_add_f32 v[102:103], v[102:103], 1.0 op_sel_hi:[1,0]
	v_pk_mul_f32 v[70:71], v[6:7], v[70:71]
	v_pk_fma_f32 v[70:71], v[102:103], v[70:71], v[86:87]
	v_pk_mul_f32 v[72:73], v[72:73], v[248:249] op_sel_hi:[1,0]
	v_pk_add_f32 v[104:105], v[104:105], 1.0 op_sel_hi:[1,0]
	v_pk_mul_f32 v[72:73], v[8:9], v[72:73]
	v_pk_fma_f32 v[72:73], v[104:105], v[72:73], v[88:89]
	v_cvt_pk_bf16_f32 v86, v70, v71
	v_cvt_pk_bf16_f32 v87, v72, v73
	global_store_dwordx2 v245, v[86:87], s[10:11] offset:512
	v_pk_mul_f32 v[74:75], v[74:75], v[248:249] op_sel_hi:[1,0]
	v_pk_add_f32 v[106:107], v[106:107], 1.0 op_sel_hi:[1,0]
	v_pk_mul_f32 v[74:75], v[10:11], v[74:75]
	v_pk_fma_f32 v[74:75], v[106:107], v[74:75], v[90:91]
	v_pk_mul_f32 v[76:77], v[76:77], v[248:249] op_sel_hi:[1,0]
	v_pk_add_f32 v[108:109], v[108:109], 1.0 op_sel_hi:[1,0]
	v_pk_mul_f32 v[76:77], v[12:13], v[76:77]
	v_pk_fma_f32 v[76:77], v[108:109], v[76:77], v[92:93]
	v_cvt_pk_bf16_f32 v90, v74, v75
	v_cvt_pk_bf16_f32 v91, v76, v77
	global_store_dwordx2 v245, v[90:91], s[10:11] offset:1024
	v_pk_mul_f32 v[78:79], v[78:79], v[248:249] op_sel_hi:[1,0]
	v_pk_add_f32 v[118:119], v[118:119], 1.0 op_sel_hi:[1,0]
	v_pk_mul_f32 v[78:79], v[14:15], v[78:79]
	v_pk_fma_f32 v[78:79], v[118:119], v[78:79], v[94:95]
	v_pk_mul_f32 v[80:81], v[80:81], v[248:249] op_sel_hi:[1,0]
	v_pk_add_f32 v[120:121], v[120:121], 1.0 op_sel_hi:[1,0]
	v_pk_mul_f32 v[80:81], v[16:17], v[80:81]
	v_pk_fma_f32 v[80:81], v[120:121], v[80:81], v[96:97]
	v_cvt_pk_bf16_f32 v94, v78, v79
	v_cvt_pk_bf16_f32 v95, v80, v81
	global_store_dwordx2 v245, v[94:95], s[10:11] offset:1536
	s_waitcnt vmcnt(8)
; DI unsigned pk_bf16(float lo, float hi) { f32x2 v = {lo, hi}; bf16v2 b = __builtin_convertvector(v, bf16v2); return __builtin_bit_cast(unsigned, b); }
; DI float red64(float x) { for (int o = 32; o > 0; o >>= 1) x += __shfl_xor(x, o); return x; }
; DI void modnorm_rows(const Params& p, int l, int which  , bool from_inputs, bool skip_ctx, int w0, int wstride, int lane) {
;     ...
;   for (; i < nrows; i += wstride) {
;     const int row = rowof(i); const int b = row / TB, s = row % TB;
;     f32x4 v[4];
; #pragma unroll
;     for (int q = 0; q < 4; ++q) v[q] = vn[q];
;     if (i + wstride < nrows) {
;       const int rn = rowof(i + wstride); const float* src = xsrc_row(p, from_inputs, rn / TB, rn % TB);
; #pragma unroll
;       for (int q = 0; q < 4; ++q) vn[q] = *(const f32x4*)(src + q * 256 + lane * 4);
;     }
;     const float* mod = p.MOD + (size_t)(l * 9 + (s < NCTX ? 8 : b)) * 6144 + (which ? 3 * 1024 : 0);
;     ...
;     for (int q = 0; q < 4; ++q) ss += v[q][0] * v[q][0] + v[q][1] * v[q][1] + v[q][2] * v[q][2] + v[q][3] * v[q][3];
;     ss = red64(ss);
;     const float rs = rsqrtf(ss * (1.f / 1024.f) + EPSF);
;     bf16_t* dst = p.HY + (size_t)row * DM;
; #pragma unroll
;     for (int q = 0; q < 4; ++q) {
;       float o[4];
; #pragma unroll
;       for (int j = 0; j < 4; ++j) o[j] = (v[q][j] * rs * gg[q][j]) * (1.f + sc[q][j]) + sh[q][j];
;       u32x2 w = {pk_bf16(o[0], o[1]), pk_bf16(o[2], o[3])};
;       *(u32x2*)(dst + q * 256 + lane * 4) = w;
	v_pk_mul_f32 v[246:247], v[122:123], v[122:123]
	v_pk_fma_f32 v[246:247], v[124:125], v[124:125], v[246:247]
	v_pk_fma_f32 v[246:247], v[126:127], v[126:127], v[246:247]
	v_pk_fma_f32 v[246:247], v[128:129], v[128:129], v[246:247]
	v_pk_fma_f32 v[246:247], v[130:131], v[130:131], v[246:247]
	v_pk_fma_f32 v[246:247], v[132:133], v[132:133], v[246:247]
	v_pk_fma_f32 v[246:247], v[134:135], v[134:135], v[246:247]
	v_pk_fma_f32 v[246:247], v[136:137], v[136:137], v[246:247]
	s_nop 0
	v_add_f32_e32 v246, v246, v247
	s_nop 1
	v_add_f32_dpp v246, v246, v246 quad_perm:[1,0,3,2] row_mask:0xf bank_mask:0xf
	s_nop 1
	v_add_f32_dpp v246, v246, v246 quad_perm:[2,3,0,1] row_mask:0xf bank_mask:0xf
	s_nop 1
	v_add_f32_dpp v246, v246, v246 row_half_mirror row_mask:0xf bank_mask:0xf
	s_nop 1
	v_add_f32_dpp v246, v246, v246 row_mirror row_mask:0xf bank_mask:0xf
	s_nop 1
	v_add_f32_dpp v246, v246, v246 row_bcast:15 row_mask:0xa bank_mask:0xf
	s_nop 1
	v_add_f32_dpp v246, v246, v246 row_bcast:31 row_mask:0xc bank_mask:0xf
	s_nop 1
	v_readlane_b32 s0, v246, 63
	s_add_i32 s21, s20, 16384
	s_lshl_b32 s21, s21, 11
	s_add_u32 s10, s16, s21
	s_addc_u32 s11, s17, 0
	v_mov_b32_e32 v248, s0
	v_fmamk_f32 v248, v248, 0x3a800000, v143
	v_rsq_f32_e32 v248, v248
	s_nop 0
	v_pk_mul_f32 v[122:123], v[122:123], v[248:249] op_sel_hi:[1,0]
	v_pk_add_f32 v[176:177], v[176:177], 1.0 op_sel_hi:[1,0]
	v_pk_mul_f32 v[122:123], v[2:3], v[122:123]
	v_pk_fma_f32 v[122:123], v[176:177], v[122:123], v[160:161]
	v_pk_mul_f32 v[124:125], v[124:125], v[248:249] op_sel_hi:[1,0]
	v_pk_add_f32 v[178:179], v[178:179], 1.0 op_sel_hi:[1,0]
	v_pk_mul_f32 v[124:125], v[4:5], v[124:125]
	v_pk_fma_f32 v[124:125], v[178:179], v[124:125], v[162:163]
	v_cvt_pk_bf16_f32 v160, v122, v123
	v_cvt_pk_bf16_f32 v161, v124, v125
	global_store_dwordx2 v245, v[160:161], s[10:11]
	v_pk_mul_f32 v[126:127], v[126:127], v[248:249] op_sel_hi:[1,0]
	v_pk_add_f32 v[180:181], v[180:181], 1.0 op_sel_hi:[1,0]
	v_pk_mul_f32 v[126:127], v[6:7], v[126:127]
	v_pk_fma_f32 v[126:127], v[180:181], v[126:127], v[164:165]
	v_pk_mul_f32 v[128:129], v[128:129], v[248:249] op_sel_hi:[1,0]
	v_pk_add_f32 v[182:183], v[182:183], 1.0 op_sel_hi:[1,0]
	v_pk_mul_f32 v[128:129], v[8:9], v[128:129]
	v_pk_fma_f32 v[128:129], v[182:183], v[128:129], v[166:167]
	v_cvt_pk_bf16_f32 v164, v126, v127
	v_cvt_pk_bf16_f32 v165, v128, v129
	global_store_dwordx2 v245, v[164:165], s[10:11] offset:512
	v_pk_mul_f32 v[130:131], v[130:131], v[248:249] op_sel_hi:[1,0]
	v_pk_add_f32 v[184:185], v[184:185], 1.0 op_sel_hi:[1,0]
	v_pk_mul_f32 v[130:131], v[10:11], v[130:131]
	v_pk_fma_f32 v[130:131], v[184:185], v[130:131], v[168:169]
	v_pk_mul_f32 v[132:133], v[132:133], v[248:249] op_sel_hi:[1,0]
	v_pk_add_f32 v[186:187], v[186:187], 1.0 op_sel_hi:[1,0]
	v_pk_mul_f32 v[132:133], v[12:13], v[132:133]
	v_pk_fma_f32 v[132:133], v[186:187], v[132:133], v[170:171]
	v_cvt_pk_bf16_f32 v168, v130, v131
	v_cvt_pk_bf16_f32 v169, v132, v133
	global_store_dwordx2 v245, v[168:169], s[10:11] offset:1024
	v_pk_mul_f32 v[134:135], v[134:135], v[248:249] op_sel_hi:[1,0]
	v_pk_add_f32 v[188:189], v[188:189], 1.0 op_sel_hi:[1,0]
	v_pk_mul_f32 v[134:135], v[14:15], v[134:135]
	v_pk_fma_f32 v[134:135], v[188:189], v[134:135], v[172:173]
	v_pk_mul_f32 v[136:137], v[136:137], v[248:249] op_sel_hi:[1,0]
	v_pk_add_f32 v[190:191], v[190:191], 1.0 op_sel_hi:[1,0]
	v_pk_mul_f32 v[136:137], v[16:17], v[136:137]
	v_pk_fma_f32 v[136:137], v[190:191], v[136:137], v[174:175]
	v_cvt_pk_bf16_f32 v172, v134, v135
	v_cvt_pk_bf16_f32 v173, v136, v137
	global_store_dwordx2 v245, v[172:173], s[10:11] offset:1536
	s_branch .Lnorm2_done
.Lnorm2_dep:
	buffer_inv sc1
	s_mov_b32 s36, 0
	s_lshr_b32 s37, s20, 5
	s_lshl_b32 s37, s37, 2
	s_and_b32 s38, s20, 3
	s_or_b32 s37, s37, s38
	s_lshr_b32 s38, s20, 2
	s_and_b32 s38, s38, 7
	s_mulk_i32 s38, 0x900
	s_add_i32 s37, s37, s38
	s_add_i32 s6, s37, 0
	s_lshr_b32 s6, s6, 7
	s_lshl_b32 s6, s6, 2
	s_add_i32 s6, s6, 0x1c00
	v_mov_b32_e32 v110, s6
	global_load_dword v114, v110, s[70:71] sc1
	s_add_i32 s6, s37, 256
	s_lshr_b32 s6, s6, 7
	s_lshl_b32 s6, s6, 2
	s_add_i32 s6, s6, 0x1c00
	v_mov_b32_e32 v110, s6
	global_load_dword v116, v110, s[70:71] sc1
	s_add_i32 s6, s37, 512
	s_lshr_b32 s6, s6, 7
	s_lshl_b32 s6, s6, 2
	s_add_i32 s6, s6, 0x1c00
	v_mov_b32_e32 v110, s6
	global_load_dword v117, v110, s[70:71] sc1
	s_waitcnt vmcnt(2)
	v_readfirstlane_b32 s6, v114
	s_cmp_ge_u32 s6, 8
	s_cbranch_scc1 .Ldep_norm2d_ok0
	s_add_i32 s6, s37, 0
	s_lshr_b32 s6, s6, 7
	s_lshl_b32 s6, s6, 2
	s_add_i32 s6, s6, 0x1c00
	v_mov_b32_e32 v110, s6

; DI void modnorm_rows(const Params& p, int l, int which  , bool from_inputs, bool skip_ctx, int w0, int wstride, int lane) {
;     ...
;     if (i + wstride < nrows) {
;       const int rn = rowof(i + wstride); const float* src = xsrc_row(p, from_inputs, rn / TB, rn % TB);
; #pragma unroll
;       for (int q = 0; q < 4; ++q) vn[q] = *(const f32x4*)(src + q * 256 + lane * 4);
.Ldep_norm2d_ok0:
	s_waitcnt vmcnt(1)
	v_readfirstlane_b32 s6, v116
	s_cmp_ge_u32 s6, 8
	s_cbranch_scc1 .Ldep_norm2d_ok1
	s_add_i32 s6, s37, 256
	s_lshr_b32 s6, s6, 7
	s_lshl_b32 s6, s6, 2
	s_add_i32 s6, s6, 0x1c00
	v_mov_b32_e32 v110, s6

; DI void modnorm_rows(const Params& p, int l, int which  , bool from_inputs, bool skip_ctx, int w0, int wstride, int lane) {
;     ...
;     if (i + wstride < nrows) {
;       const int rn = rowof(i + wstride); const float* src = xsrc_row(p, from_inputs, rn / TB, rn % TB);
; #pragma unroll
;       for (int q = 0; q < 4; ++q) vn[q] = *(const f32x4*)(src + q * 256 + lane * 4);
.Ldep_norm2d_ok1:
	s_waitcnt vmcnt(0)
	v_readfirstlane_b32 s6, v117
	s_cmp_ge_u32 s6, 8
	s_cbranch_scc1 .Ldep_norm2d_ok2
	s_add_i32 s6, s37, 512
	s_lshr_b32 s6, s6, 7
	s_lshl_b32 s6, s6, 2
	s_add_i32 s6, s6, 0x1c00
	v_mov_b32_e32 v110, s6

; DI void modnorm_rows(const Params& p, int l, int which  , bool from_inputs, bool skip_ctx, int w0, int wstride, int lane) {
;     ...
;     if (i + wstride < nrows) {
;       const int rn = rowof(i + wstride); const float* src = xsrc_row(p, from_inputs, rn / TB, rn % TB);
; #pragma unroll
;       for (int q = 0; q < 4; ++q) vn[q] = *(const f32x4*)(src + q * 256 + lane * 4);
.Ldep_norm2d_ok2:
	s_add_i32 s21, s37, 0
	s_mul_hi_u32 s7, s21, 0x38e38e39
	s_lshr_b32 s7, s7, 9
	s_mul_i32 s8, s7, 0x900
	s_sub_i32 s8, s21, s8
	s_lshl_b32 s9, s7, 11
	s_add_i32 s9, s9, s8
	s_add_i32 s9, s9, 0xffffff00
	s_lshl_b32 s10, s7, 8
	s_add_i32 s10, s10, s8
	s_cmpk_gt_i32 s8, 0xff
	s_cselect_b32 s9, s9, s10
	s_cselect_b32 s26, s12, s14
	s_cselect_b32 s27, s13, s15
	s_cselect_b32 s10, s7, 8
	s_lshl_b32 s9, s9, 12
	s_add_u32 s26, s26, s9
	s_addc_u32 s27, s27, 0
	s_add_i32 s10, s10, s82
	s_mul_i32 s10, s10, s24
	s_add_u32 s28, s58, s10
	s_addc_u32 s29, s59, 0
	s_add_u32 s28, s28, 0x3000
	s_addc_u32 s29, s29, 0
	s_add_u32 s0, s28, 0x1000
	s_addc_u32 s1, s29, 0
	global_load_dwordx4 v[18:21], v244, s[26:27]
	global_load_dwordx4 v[22:25], v244, s[26:27] offset:1024
	global_load_dwordx4 v[26:29], v244, s[26:27] offset:2048
	global_load_dwordx4 v[30:33], v244, s[26:27] offset:3072
	global_load_dwordx4 v[34:37], v244, s[28:29]
	global_load_dwordx4 v[38:41], v244, s[28:29] offset:1024
	global_load_dwordx4 v[42:45], v244, s[28:29] offset:2048
	global_load_dwordx4 v[46:49], v244, s[28:29] offset:3072
	global_load_dwordx4 v[50:53], v244, s[0:1]
	global_load_dwordx4 v[54:57], v244, s[0:1] offset:1024
	global_load_dwordx4 v[58:61], v244, s[0:1] offset:2048
	global_load_dwordx4 v[62:65], v244, s[0:1] offset:3072
	s_add_i32 s21, s37, 256
	s_mul_hi_u32 s7, s21, 0x38e38e39
	s_lshr_b32 s7, s7, 9
	s_mul_i32 s8, s7, 0x900
	s_sub_i32 s8, s21, s8
	s_lshl_b32 s9, s7, 11
	s_add_i32 s9, s9, s8
	s_add_i32 s9, s9, 0xffffff00
	s_lshl_b32 s10, s7, 8
	s_add_i32 s10, s10, s8
	s_cmpk_gt_i32 s8, 0xff
	s_cselect_b32 s9, s9, s10
	s_cselect_b32 s26, s12, s14
	s_cselect_b32 s27, s13, s15
	s_cselect_b32 s10, s7, 8
	s_lshl_b32 s9, s9, 12
	s_add_u32 s26, s26, s9
	s_addc_u32 s27, s27, 0
	s_add_i32 s10, s10, s82
	s_mul_i32 s10, s10, s24
	s_add_u32 s28, s58, s10
	s_addc_u32 s29, s59, 0
	s_add_u32 s28, s28, 0x3000
	s_addc_u32 s29, s29, 0
	s_add_u32 s0, s28, 0x1000
	s_addc_u32 s1, s29, 0
	global_load_dwordx4 v[66:69], v244, s[26:27]
	global_load_dwordx4 v[70:73], v244, s[26:27] offset:1024
	global_load_dwordx4 v[74:77], v244, s[26:27] offset:2048
	global_load_dwordx4 v[78:81], v244, s[26:27] offset:3072
	global_load_dwordx4 v[82:85], v244, s[28:29]
	global_load_dwordx4 v[86:89], v244, s[28:29] offset:1024
	global_load_dwordx4 v[90:93], v244, s[28:29] offset:2048
	global_load_dwordx4 v[94:97], v244, s[28:29] offset:3072
	global_load_dwordx4 v[98:101], v244, s[0:1]
	global_load_dwordx4 v[102:105], v244, s[0:1] offset:1024
	global_load_dwordx4 v[106:109], v244, s[0:1] offset:2048
	global_load_dwordx4 v[118:121], v244, s[0:1] offset:3072
	s_add_i32 s21, s37, 512
	s_mul_hi_u32 s7, s21, 0x38e38e39
	s_lshr_b32 s7, s7, 9
	s_mul_i32 s8, s7, 0x900
	s_sub_i32 s8, s21, s8
	s_lshl_b32 s9, s7, 11
	s_add_i32 s9, s9, s8
	s_add_i32 s9, s9, 0xffffff00
	s_lshl_b32 s10, s7, 8
	s_add_i32 s10, s10, s8
	s_cmpk_gt_i32 s8, 0xff
	s_cselect_b32 s9, s9, s10
	s_cselect_b32 s26, s12, s14
	s_cselect_b32 s27, s13, s15
	s_cselect_b32 s10, s7, 8
	s_lshl_b32 s9, s9, 12
	s_add_u32 s26, s26, s9
	s_addc_u32 s27, s27, 0
	s_add_i32 s10, s10, s82
	s_mul_i32 s10, s10, s24
	s_add_u32 s28, s58, s10
	s_addc_u32 s29, s59, 0
	s_add_u32 s28, s28, 0x3000
	s_addc_u32 s29, s29, 0
	s_add_u32 s0, s28, 0x1000
	s_addc_u32 s1, s29, 0
	global_load_dwordx4 v[122:125], v244, s[26:27]
	global_load_dwordx4 v[126:129], v244, s[26:27] offset:1024
	global_load_dwordx4 v[130:133], v244, s[26:27] offset:2048
	global_load_dwordx4 v[134:137], v244, s[26:27] offset:3072
	global_load_dwordx4 v[160:163], v244, s[28:29]
	global_load_dwordx4 v[164:167], v244, s[28:29] offset:1024
	global_load_dwordx4 v[168:171], v244, s[28:29] offset:2048
	global_load_dwordx4 v[172:175], v244, s[28:29] offset:3072
	global_load_dwordx4 v[176:179], v244, s[0:1]
	global_load_dwordx4 v[180:183], v244, s[0:1] offset:1024
	global_load_dwordx4 v[184:187], v244, s[0:1] offset:2048
	global_load_dwordx4 v[188:191], v244, s[0:1] offset:3072
	s_add_i32 s6, s37, 768
	s_lshr_b32 s6, s6, 7
	s_lshl_b32 s6, s6, 2
	s_add_i32 s6, s6, 0x1c00
	v_mov_b32_e32 v110, s6
	global_load_dword v114, v110, s[70:71] sc1
	s_waitcnt vmcnt(25)
; DI unsigned pk_bf16(float lo, float hi) { f32x2 v = {lo, hi}; bf16v2 b = __builtin_convertvector(v, bf16v2); return __builtin_bit_cast(unsigned, b); }
; DI float red64(float x) { for (int o = 32; o > 0; o >>= 1) x += __shfl_xor(x, o); return x; }
; DI void modnorm_rows(const Params& p, int l, int which  , bool from_inputs, bool skip_ctx, int w0, int wstride, int lane) {
;     ...
;     if (i + wstride < nrows) {
;       const int rn = rowof(i + wstride); const float* src = xsrc_row(p, from_inputs, rn / TB, rn % TB);
; #pragma unroll
;       for (int q = 0; q < 4; ++q) vn[q] = *(const f32x4*)(src + q * 256 + lane * 4);
;     ...
;     float ss = 0.f;
; #pragma unroll
;     for (int q = 0; q < 4; ++q) ss += v[q][0] * v[q][0] + v[q][1] * v[q][1] + v[q][2] * v[q][2] + v[q][3] * v[q][3];
;     ss = red64(ss);
;     const float rs = rsqrtf(ss * (1.f / 1024.f) + EPSF);
;     bf16_t* dst = p.HY + (size_t)row * DM;
; #pragma unroll
;     for (int q = 0; q < 4; ++q) {
;       float o[4];
; #pragma unroll
;       for (int j = 0; j < 4; ++j) o[j] = (v[q][j] * rs * gg[q][j]) * (1.f + sc[q][j]) + sh[q][j];
;       u32x2 w = {pk_bf16(o[0], o[1]), pk_bf16(o[2], o[3])};
;       *(u32x2*)(dst + q * 256 + lane * 4) = w;
	v_pk_mul_f32 v[246:247], v[18:19], v[18:19]
	v_pk_fma_f32 v[246:247], v[20:21], v[20:21], v[246:247]
	v_pk_fma_f32 v[246:247], v[22:23], v[22:23], v[246:247]
	v_pk_fma_f32 v[246:247], v[24:25], v[24:25], v[246:247]
	v_pk_fma_f32 v[246:247], v[26:27], v[26:27], v[246:247]
	v_pk_fma_f32 v[246:247], v[28:29], v[28:29], v[246:247]
	v_pk_fma_f32 v[246:247], v[30:31], v[30:31], v[246:247]
	v_pk_fma_f32 v[246:247], v[32:33], v[32:33], v[246:247]
	s_nop 0
	v_add_f32_e32 v246, v246, v247
	s_nop 1
	v_add_f32_dpp v246, v246, v246 quad_perm:[1,0,3,2] row_mask:0xf bank_mask:0xf
	s_nop 1
	v_add_f32_dpp v246, v246, v246 quad_perm:[2,3,0,1] row_mask:0xf bank_mask:0xf
	s_nop 1
	v_add_f32_dpp v246, v246, v246 row_half_mirror row_mask:0xf bank_mask:0xf
	s_nop 1
	v_add_f32_dpp v246, v246, v246 row_mirror row_mask:0xf bank_mask:0xf
	s_nop 1
	v_add_f32_dpp v246, v246, v246 row_bcast:15 row_mask:0xa bank_mask:0xf
	s_nop 1
	v_add_f32_dpp v246, v246, v246 row_bcast:31 row_mask:0xc bank_mask:0xf
	s_nop 1
	v_readlane_b32 s0, v246, 63
	s_add_i32 s21, s37, 0
	s_lshl_b32 s21, s21, 11
	s_add_u32 s10, s16, s21
	s_addc_u32 s11, s17, 0
	v_mov_b32_e32 v248, s0
	v_fmamk_f32 v248, v248, 0x3a800000, v143
	v_rsq_f32_e32 v248, v248
	s_nop 0
	v_pk_mul_f32 v[18:19], v[18:19], v[248:249] op_sel_hi:[1,0]
	v_pk_add_f32 v[50:51], v[50:51], 1.0 op_sel_hi:[1,0]
	v_pk_mul_f32 v[18:19], v[2:3], v[18:19]
	v_pk_fma_f32 v[18:19], v[50:51], v[18:19], v[34:35]
	v_pk_mul_f32 v[20:21], v[20:21], v[248:249] op_sel_hi:[1,0]
	v_pk_add_f32 v[52:53], v[52:53], 1.0 op_sel_hi:[1,0]
	v_pk_mul_f32 v[20:21], v[4:5], v[20:21]
	v_pk_fma_f32 v[20:21], v[52:53], v[20:21], v[36:37]
	v_cvt_pk_bf16_f32 v34, v18, v19
	v_cvt_pk_bf16_f32 v35, v20, v21
	global_store_dwordx2 v245, v[34:35], s[10:11]
	v_pk_mul_f32 v[22:23], v[22:23], v[248:249] op_sel_hi:[1,0]
	v_pk_add_f32 v[54:55], v[54:55], 1.0 op_sel_hi:[1,0]
	v_pk_mul_f32 v[22:23], v[6:7], v[22:23]
	v_pk_fma_f32 v[22:23], v[54:55], v[22:23], v[38:39]
	v_pk_mul_f32 v[24:25], v[24:25], v[248:249] op_sel_hi:[1,0]
	v_pk_add_f32 v[56:57], v[56:57], 1.0 op_sel_hi:[1,0]
	v_pk_mul_f32 v[24:25], v[8:9], v[24:25]
	v_pk_fma_f32 v[24:25], v[56:57], v[24:25], v[40:41]
	v_cvt_pk_bf16_f32 v38, v22, v23
	v_cvt_pk_bf16_f32 v39, v24, v25
	global_store_dwordx2 v245, v[38:39], s[10:11] offset:512
	v_pk_mul_f32 v[26:27], v[26:27], v[248:249] op_sel_hi:[1,0]
	v_pk_add_f32 v[58:59], v[58:59], 1.0 op_sel_hi:[1,0]
	v_pk_mul_f32 v[26:27], v[10:11], v[26:27]
	v_pk_fma_f32 v[26:27], v[58:59], v[26:27], v[42:43]
	v_pk_mul_f32 v[28:29], v[28:29], v[248:249] op_sel_hi:[1,0]
	v_pk_add_f32 v[60:61], v[60:61], 1.0 op_sel_hi:[1,0]
	v_pk_mul_f32 v[28:29], v[12:13], v[28:29]
	v_pk_fma_f32 v[28:29], v[60:61], v[28:29], v[44:45]
	v_cvt_pk_bf16_f32 v42, v26, v27
	v_cvt_pk_bf16_f32 v43, v28, v29
	global_store_dwordx2 v245, v[42:43], s[10:11] offset:1024
	v_pk_mul_f32 v[30:31], v[30:31], v[248:249] op_sel_hi:[1,0]
	v_pk_add_f32 v[62:63], v[62:63], 1.0 op_sel_hi:[1,0]
	v_pk_mul_f32 v[30:31], v[14:15], v[30:31]
	v_pk_fma_f32 v[30:31], v[62:63], v[30:31], v[46:47]
	v_pk_mul_f32 v[32:33], v[32:33], v[248:249] op_sel_hi:[1,0]
	v_pk_add_f32 v[64:65], v[64:65], 1.0 op_sel_hi:[1,0]
	v_pk_mul_f32 v[32:33], v[16:17], v[32:33]
	v_pk_fma_f32 v[32:33], v[64:65], v[32:33], v[48:49]
	v_cvt_pk_bf16_f32 v46, v30, v31
	v_cvt_pk_bf16_f32 v47, v32, v33
	global_store_dwordx2 v245, v[46:47], s[10:11] offset:1536
	s_waitcnt vmcnt(4)
	v_readfirstlane_b32 s6, v114
	s_cmp_ge_u32 s6, 8
	s_cbranch_scc1 .Ldep_norm2d_ok3
	s_add_i32 s6, s37, 768
	s_lshr_b32 s6, s6, 7
	s_lshl_b32 s6, s6, 2
	s_add_i32 s6, s6, 0x1c00
	v_mov_b32_e32 v110, s6

; DI unsigned pk_bf16(float lo, float hi) { f32x2 v = {lo, hi}; bf16v2 b = __builtin_convertvector(v, bf16v2); return __builtin_bit_cast(unsigned, b); }
; DI float red64(float x) { for (int o = 32; o > 0; o >>= 1) x += __shfl_xor(x, o); return x; }
; DI void modnorm_rows(const Params& p, int l, int which  , bool from_inputs, bool skip_ctx, int w0, int wstride, int lane) {
;     ...
;     if (i + wstride < nrows) {
;       const int rn = rowof(i + wstride); const float* src = xsrc_row(p, from_inputs, rn / TB, rn % TB);
; #pragma unroll
;       for (int q = 0; q < 4; ++q) vn[q] = *(const f32x4*)(src + q * 256 + lane * 4);
;     ...
;     float ss = 0.f;
; #pragma unroll
;     for (int q = 0; q < 4; ++q) ss += v[q][0] * v[q][0] + v[q][1] * v[q][1] + v[q][2] * v[q][2] + v[q][3] * v[q][3];
;     ss = red64(ss);
;     const float rs = rsqrtf(ss * (1.f / 1024.f) + EPSF);
;     bf16_t* dst = p.HY + (size_t)row * DM;
; #pragma unroll
;     for (int q = 0; q < 4; ++q) {
;       float o[4];
; #pragma unroll
;       for (int j = 0; j < 4; ++j) o[j] = (v[q][j] * rs * gg[q][j]) * (1.f + sc[q][j]) + sh[q][j];
;       u32x2 w = {pk_bf16(o[0], o[1]), pk_bf16(o[2], o[3])};
;       *(u32x2*)(dst + q * 256 + lane * 4) = w;
.Ldep_norm2d_ok3:
	s_add_i32 s21, s37, 768
	s_mul_hi_u32 s7, s21, 0x38e38e39
	s_lshr_b32 s7, s7, 9
	s_mul_i32 s8, s7, 0x900
	s_sub_i32 s8, s21, s8
	s_lshl_b32 s9, s7, 11
	s_add_i32 s9, s9, s8
	s_add_i32 s9, s9, 0xffffff00
	s_lshl_b32 s10, s7, 8
	s_add_i32 s10, s10, s8
	s_cmpk_gt_i32 s8, 0xff
	s_cselect_b32 s9, s9, s10
	s_cselect_b32 s26, s12, s14
	s_cselect_b32 s27, s13, s15
	s_cselect_b32 s10, s7, 8
	s_lshl_b32 s9, s9, 12
	s_add_u32 s26, s26, s9
	s_addc_u32 s27, s27, 0
	s_add_i32 s10, s10, s82
	s_mul_i32 s10, s10, s24
	s_add_u32 s28, s58, s10
	s_addc_u32 s29, s59, 0
	s_add_u32 s28, s28, 0x3000
	s_addc_u32 s29, s29, 0
	s_add_u32 s0, s28, 0x1000
	s_addc_u32 s1, s29, 0
	global_load_dwordx4 v[18:21], v244, s[26:27]
	global_load_dwordx4 v[22:25], v244, s[26:27] offset:1024
	global_load_dwordx4 v[26:29], v244, s[26:27] offset:2048
	global_load_dwordx4 v[30:33], v244, s[26:27] offset:3072
	global_load_dwordx4 v[34:37], v244, s[28:29]
	global_load_dwordx4 v[38:41], v244, s[28:29] offset:1024
	global_load_dwordx4 v[42:45], v244, s[28:29] offset:2048
	global_load_dwordx4 v[46:49], v244, s[28:29] offset:3072
	global_load_dwordx4 v[50:53], v244, s[0:1]
	global_load_dwordx4 v[54:57], v244, s[0:1] offset:1024
	global_load_dwordx4 v[58:61], v244, s[0:1] offset:2048
	global_load_dwordx4 v[62:65], v244, s[0:1] offset:3072
	s_add_i32 s6, s37, 1024
	s_lshr_b32 s6, s6, 7
	s_lshl_b32 s6, s6, 2
	s_add_i32 s6, s6, 0x1c00
	v_mov_b32_e32 v110, s6
	global_load_dword v114, v110, s[70:71] sc1
	s_waitcnt vmcnt(30)
	v_pk_mul_f32 v[246:247], v[66:67], v[66:67]
	v_pk_fma_f32 v[246:247], v[68:69], v[68:69], v[246:247]
	v_pk_fma_f32 v[246:247], v[70:71], v[70:71], v[246:247]
	v_pk_fma_f32 v[246:247], v[72:73], v[72:73], v[246:247]
	v_pk_fma_f32 v[246:247], v[74:75], v[74:75], v[246:247]
	v_pk_fma_f32 v[246:247], v[76:77], v[76:77], v[246:247]
	v_pk_fma_f32 v[246:247], v[78:79], v[78:79], v[246:247]
	v_pk_fma_f32 v[246:247], v[80:81], v[80:81], v[246:247]
	s_nop 0
	v_add_f32_e32 v246, v246, v247
	s_nop 1
	v_add_f32_dpp v246, v246, v246 quad_perm:[1,0,3,2] row_mask:0xf bank_mask:0xf
	s_nop 1
	v_add_f32_dpp v246, v246, v246 quad_perm:[2,3,0,1] row_mask:0xf bank_mask:0xf
	s_nop 1
	v_add_f32_dpp v246, v246, v246 row_half_mirror row_mask:0xf bank_mask:0xf
	s_nop 1
	v_add_f32_dpp v246, v246, v246 row_mirror row_mask:0xf bank_mask:0xf
	s_nop 1
	v_add_f32_dpp v246, v246, v246 row_bcast:15 row_mask:0xa bank_mask:0xf
	s_nop 1
	v_add_f32_dpp v246, v246, v246 row_bcast:31 row_mask:0xc bank_mask:0xf
	s_nop 1
	v_readlane_b32 s0, v246, 63
	s_add_i32 s21, s37, 256
	s_lshl_b32 s21, s21, 11
	s_add_u32 s10, s16, s21
	s_addc_u32 s11, s17, 0
	v_mov_b32_e32 v248, s0
	v_fmamk_f32 v248, v248, 0x3a800000, v143
	v_rsq_f32_e32 v248, v248
	s_nop 0
	v_pk_mul_f32 v[66:67], v[66:67], v[248:249] op_sel_hi:[1,0]
	v_pk_add_f32 v[98:99], v[98:99], 1.0 op_sel_hi:[1,0]
	v_pk_mul_f32 v[66:67], v[2:3], v[66:67]
	v_pk_fma_f32 v[66:67], v[98:99], v[66:67], v[82:83]
	v_pk_mul_f32 v[68:69], v[68:69], v[248:249] op_sel_hi:[1,0]
	v_pk_add_f32 v[100:101], v[100:101], 1.0 op_sel_hi:[1,0]
	v_pk_mul_f32 v[68:69], v[4:5], v[68:69]
	v_pk_fma_f32 v[68:69], v[100:101], v[68:69], v[84:85]
	v_cvt_pk_bf16_f32 v82, v66, v67
	v_cvt_pk_bf16_f32 v83, v68, v69
	global_store_dwordx2 v245, v[82:83], s[10:11]
	v_pk_mul_f32 v[70:71], v[70:71], v[248:249] op_sel_hi:[1,0]
	v_pk_add_f32 v[102:103], v[102:103], 1.0 op_sel_hi:[1,0]
	v_pk_mul_f32 v[70:71], v[6:7], v[70:71]
	v_pk_fma_f32 v[70:71], v[102:103], v[70:71], v[86:87]
	v_pk_mul_f32 v[72:73], v[72:73], v[248:249] op_sel_hi:[1,0]
	v_pk_add_f32 v[104:105], v[104:105], 1.0 op_sel_hi:[1,0]
	v_pk_mul_f32 v[72:73], v[8:9], v[72:73]
	v_pk_fma_f32 v[72:73], v[104:105], v[72:73], v[88:89]
	v_cvt_pk_bf16_f32 v86, v70, v71
	v_cvt_pk_bf16_f32 v87, v72, v73
	global_store_dwordx2 v245, v[86:87], s[10:11] offset:512
	v_pk_mul_f32 v[74:75], v[74:75], v[248:249] op_sel_hi:[1,0]
	v_pk_add_f32 v[106:107], v[106:107], 1.0 op_sel_hi:[1,0]
	v_pk_mul_f32 v[74:75], v[10:11], v[74:75]
	v_pk_fma_f32 v[74:75], v[106:107], v[74:75], v[90:91]
	v_pk_mul_f32 v[76:77], v[76:77], v[248:249] op_sel_hi:[1,0]
	v_pk_add_f32 v[108:109], v[108:109], 1.0 op_sel_hi:[1,0]
	v_pk_mul_f32 v[76:77], v[12:13], v[76:77]
	v_pk_fma_f32 v[76:77], v[108:109], v[76:77], v[92:93]
	v_cvt_pk_bf16_f32 v90, v74, v75
	v_cvt_pk_bf16_f32 v91, v76, v77
	global_store_dwordx2 v245, v[90:91], s[10:11] offset:1024
	v_pk_mul_f32 v[78:79], v[78:79], v[248:249] op_sel_hi:[1,0]
	v_pk_add_f32 v[118:119], v[118:119], 1.0 op_sel_hi:[1,0]
	v_pk_mul_f32 v[78:79], v[14:15], v[78:79]
	v_pk_fma_f32 v[78:79], v[118:119], v[78:79], v[94:95]
	v_pk_mul_f32 v[80:81], v[80:81], v[248:249] op_sel_hi:[1,0]
	v_pk_add_f32 v[120:121], v[120:121], 1.0 op_sel_hi:[1,0]
	v_pk_mul_f32 v[80:81], v[16:17], v[80:81]
	v_pk_fma_f32 v[80:81], v[120:121], v[80:81], v[96:97]
	v_cvt_pk_bf16_f32 v94, v78, v79
	v_cvt_pk_bf16_f32 v95, v80, v81
	global_store_dwordx2 v245, v[94:95], s[10:11] offset:1536
	s_waitcnt vmcnt(4)
	v_readfirstlane_b32 s6, v114
	s_cmp_ge_u32 s6, 8
	s_cbranch_scc1 .Ldep_norm2d_ok4
	s_add_i32 s6, s37, 1024
	s_lshr_b32 s6, s6, 7
	s_lshl_b32 s6, s6, 2
	s_add_i32 s6, s6, 0x1c00
	v_mov_b32_e32 v110, s6

; DI unsigned pk_bf16(float lo, float hi) { f32x2 v = {lo, hi}; bf16v2 b = __builtin_convertvector(v, bf16v2); return __builtin_bit_cast(unsigned, b); }
; DI float red64(float x) { for (int o = 32; o > 0; o >>= 1) x += __shfl_xor(x, o); return x; }
; DI void modnorm_rows(const Params& p, int l, int which  , bool from_inputs, bool skip_ctx, int w0, int wstride, int lane) {
;     ...
;     if (i + wstride < nrows) {
;       const int rn = rowof(i + wstride); const float* src = xsrc_row(p, from_inputs, rn / TB, rn % TB);
; #pragma unroll
;       for (int q = 0; q < 4; ++q) vn[q] = *(const f32x4*)(src + q * 256 + lane * 4);
;     ...
;     float ss = 0.f;
; #pragma unroll
;     for (int q = 0; q < 4; ++q) ss += v[q][0] * v[q][0] + v[q][1] * v[q][1] + v[q][2] * v[q][2] + v[q][3] * v[q][3];
;     ss = red64(ss);
;     const float rs = rsqrtf(ss * (1.f / 1024.f) + EPSF);
;     bf16_t* dst = p.HY + (size_t)row * DM;
; #pragma unroll
;     for (int q = 0; q < 4; ++q) {
;       float o[4];
; #pragma unroll
;       for (int j = 0; j < 4; ++j) o[j] = (v[q][j] * rs * gg[q][j]) * (1.f + sc[q][j]) + sh[q][j];
;       u32x2 w = {pk_bf16(o[0], o[1]), pk_bf16(o[2], o[3])};
;       *(u32x2*)(dst + q * 256 + lane * 4) = w;
.Ldep_norm2d_ok4:
	s_add_i32 s21, s37, 1024
	s_mul_hi_u32 s7, s21, 0x38e38e39
	s_lshr_b32 s7, s7, 9
	s_mul_i32 s8, s7, 0x900
	s_sub_i32 s8, s21, s8
	s_lshl_b32 s9, s7, 11
	s_add_i32 s9, s9, s8
	s_add_i32 s9, s9, 0xffffff00
	s_lshl_b32 s10, s7, 8
	s_add_i32 s10, s10, s8
	s_cmpk_gt_i32 s8, 0xff
	s_cselect_b32 s9, s9, s10
	s_cselect_b32 s26, s12, s14
	s_cselect_b32 s27, s13, s15
	s_cselect_b32 s10, s7, 8
	s_lshl_b32 s9, s9, 12
	s_add_u32 s26, s26, s9
	s_addc_u32 s27, s27, 0
	s_add_i32 s10, s10, s82
	s_mul_i32 s10, s10, s24
	s_add_u32 s28, s58, s10
	s_addc_u32 s29, s59, 0
	s_add_u32 s28, s28, 0x3000
	s_addc_u32 s29, s29, 0
	s_add_u32 s0, s28, 0x1000
	s_addc_u32 s1, s29, 0
	global_load_dwordx4 v[66:69], v244, s[26:27]
	global_load_dwordx4 v[70:73], v244, s[26:27] offset:1024
	global_load_dwordx4 v[74:77], v244, s[26:27] offset:2048
	global_load_dwordx4 v[78:81], v244, s[26:27] offset:3072
	global_load_dwordx4 v[82:85], v244, s[28:29]
	global_load_dwordx4 v[86:89], v244, s[28:29] offset:1024
	global_load_dwordx4 v[90:93], v244, s[28:29] offset:2048
	global_load_dwordx4 v[94:97], v244, s[28:29] offset:3072
	global_load_dwordx4 v[98:101], v244, s[0:1]
	global_load_dwordx4 v[102:105], v244, s[0:1] offset:1024
	global_load_dwordx4 v[106:109], v244, s[0:1] offset:2048
	global_load_dwordx4 v[118:121], v244, s[0:1] offset:3072
	s_add_i32 s6, s37, 1280
	s_lshr_b32 s6, s6, 7
	s_lshl_b32 s6, s6, 2
	s_add_i32 s6, s6, 0x1c00
	v_mov_b32_e32 v110, s6
	global_load_dword v114, v110, s[70:71] sc1
	s_waitcnt vmcnt(35)
	v_pk_mul_f32 v[246:247], v[122:123], v[122:123]
	v_pk_fma_f32 v[246:247], v[124:125], v[124:125], v[246:247]
	v_pk_fma_f32 v[246:247], v[126:127], v[126:127], v[246:247]
	v_pk_fma_f32 v[246:247], v[128:129], v[128:129], v[246:247]
	v_pk_fma_f32 v[246:247], v[130:131], v[130:131], v[246:247]
	v_pk_fma_f32 v[246:247], v[132:133], v[132:133], v[246:247]
	v_pk_fma_f32 v[246:247], v[134:135], v[134:135], v[246:247]
	v_pk_fma_f32 v[246:247], v[136:137], v[136:137], v[246:247]
	s_nop 0
	v_add_f32_e32 v246, v246, v247
	s_nop 1
	v_add_f32_dpp v246, v246, v246 quad_perm:[1,0,3,2] row_mask:0xf bank_mask:0xf
	s_nop 1
	v_add_f32_dpp v246, v246, v246 quad_perm:[2,3,0,1] row_mask:0xf bank_mask:0xf
	s_nop 1
	v_add_f32_dpp v246, v246, v246 row_half_mirror row_mask:0xf bank_mask:0xf
	s_nop 1
	v_add_f32_dpp v246, v246, v246 row_mirror row_mask:0xf bank_mask:0xf
	s_nop 1
	v_add_f32_dpp v246, v246, v246 row_bcast:15 row_mask:0xa bank_mask:0xf
	s_nop 1
	v_add_f32_dpp v246, v246, v246 row_bcast:31 row_mask:0xc bank_mask:0xf
	s_nop 1
	v_readlane_b32 s0, v246, 63
	s_add_i32 s21, s37, 512
	s_lshl_b32 s21, s21, 11
	s_add_u32 s10, s16, s21
	s_addc_u32 s11, s17, 0
	v_mov_b32_e32 v248, s0
	v_fmamk_f32 v248, v248, 0x3a800000, v143
	v_rsq_f32_e32 v248, v248
	s_nop 0
	v_pk_mul_f32 v[122:123], v[122:123], v[248:249] op_sel_hi:[1,0]
	v_pk_add_f32 v[176:177], v[176:177], 1.0 op_sel_hi:[1,0]
	v_pk_mul_f32 v[122:123], v[2:3], v[122:123]
	v_pk_fma_f32 v[122:123], v[176:177], v[122:123], v[160:161]
	v_pk_mul_f32 v[124:125], v[124:125], v[248:249] op_sel_hi:[1,0]
	v_pk_add_f32 v[178:179], v[178:179], 1.0 op_sel_hi:[1,0]
	v_pk_mul_f32 v[124:125], v[4:5], v[124:125]
	v_pk_fma_f32 v[124:125], v[178:179], v[124:125], v[162:163]
	v_cvt_pk_bf16_f32 v160, v122, v123
	v_cvt_pk_bf16_f32 v161, v124, v125
	global_store_dwordx2 v245, v[160:161], s[10:11]
	v_pk_mul_f32 v[126:127], v[126:127], v[248:249] op_sel_hi:[1,0]
	v_pk_add_f32 v[180:181], v[180:181], 1.0 op_sel_hi:[1,0]
	v_pk_mul_f32 v[126:127], v[6:7], v[126:127]
	v_pk_fma_f32 v[126:127], v[180:181], v[126:127], v[164:165]
	v_pk_mul_f32 v[128:129], v[128:129], v[248:249] op_sel_hi:[1,0]
	v_pk_add_f32 v[182:183], v[182:183], 1.0 op_sel_hi:[1,0]
	v_pk_mul_f32 v[128:129], v[8:9], v[128:129]
	v_pk_fma_f32 v[128:129], v[182:183], v[128:129], v[166:167]
	v_cvt_pk_bf16_f32 v164, v126, v127
	v_cvt_pk_bf16_f32 v165, v128, v129
	global_store_dwordx2 v245, v[164:165], s[10:11] offset:512
	v_pk_mul_f32 v[130:131], v[130:131], v[248:249] op_sel_hi:[1,0]
	v_pk_add_f32 v[184:185], v[184:185], 1.0 op_sel_hi:[1,0]
	v_pk_mul_f32 v[130:131], v[10:11], v[130:131]
	v_pk_fma_f32 v[130:131], v[184:185], v[130:131], v[168:169]
	v_pk_mul_f32 v[132:133], v[132:133], v[248:249] op_sel_hi:[1,0]
	v_pk_add_f32 v[186:187], v[186:187], 1.0 op_sel_hi:[1,0]
	v_pk_mul_f32 v[132:133], v[12:13], v[132:133]
	v_pk_fma_f32 v[132:133], v[186:187], v[132:133], v[170:171]
	v_cvt_pk_bf16_f32 v168, v130, v131
	v_cvt_pk_bf16_f32 v169, v132, v133
	global_store_dwordx2 v245, v[168:169], s[10:11] offset:1024
	v_pk_mul_f32 v[134:135], v[134:135], v[248:249] op_sel_hi:[1,0]
	v_pk_add_f32 v[188:189], v[188:189], 1.0 op_sel_hi:[1,0]
	v_pk_mul_f32 v[134:135], v[14:15], v[134:135]
	v_pk_fma_f32 v[134:135], v[188:189], v[134:135], v[172:173]
	v_pk_mul_f32 v[136:137], v[136:137], v[248:249] op_sel_hi:[1,0]
	v_pk_add_f32 v[190:191], v[190:191], 1.0 op_sel_hi:[1,0]
	v_pk_mul_f32 v[136:137], v[16:17], v[136:137]
	v_pk_fma_f32 v[136:137], v[190:191], v[136:137], v[174:175]
	v_cvt_pk_bf16_f32 v172, v134, v135
	v_cvt_pk_bf16_f32 v173, v136, v137
	global_store_dwordx2 v245, v[172:173], s[10:11] offset:1536
	s_waitcnt vmcnt(4)
	v_readfirstlane_b32 s6, v114
	s_cmp_ge_u32 s6, 8
	s_cbranch_scc1 .Ldep_norm2d_ok5
	s_add_i32 s6, s37, 1280
	s_lshr_b32 s6, s6, 7
	s_lshl_b32 s6, s6, 2
	s_add_i32 s6, s6, 0x1c00
	v_mov_b32_e32 v110, s6

; DI unsigned pk_bf16(float lo, float hi) { f32x2 v = {lo, hi}; bf16v2 b = __builtin_convertvector(v, bf16v2); return __builtin_bit_cast(unsigned, b); }
; DI float red64(float x) { for (int o = 32; o > 0; o >>= 1) x += __shfl_xor(x, o); return x; }
; DI void modnorm_rows(const Params& p, int l, int which  , bool from_inputs, bool skip_ctx, int w0, int wstride, int lane) {
;     ...
;     if (i + wstride < nrows) {
;       const int rn = rowof(i + wstride); const float* src = xsrc_row(p, from_inputs, rn / TB, rn % TB);
; #pragma unroll
;       for (int q = 0; q < 4; ++q) vn[q] = *(const f32x4*)(src + q * 256 + lane * 4);
;     ...
;     float ss = 0.f;
; #pragma unroll
;     for (int q = 0; q < 4; ++q) ss += v[q][0] * v[q][0] + v[q][1] * v[q][1] + v[q][2] * v[q][2] + v[q][3] * v[q][3];
;     ss = red64(ss);
;     const float rs = rsqrtf(ss * (1.f / 1024.f) + EPSF);
;     bf16_t* dst = p.HY + (size_t)row * DM;
; #pragma unroll
;     for (int q = 0; q < 4; ++q) {
;       float o[4];
; #pragma unroll
;       for (int j = 0; j < 4; ++j) o[j] = (v[q][j] * rs * gg[q][j]) * (1.f + sc[q][j]) + sh[q][j];
;       u32x2 w = {pk_bf16(o[0], o[1]), pk_bf16(o[2], o[3])};
;       *(u32x2*)(dst + q * 256 + lane * 4) = w;
.Ldep_norm2d_ok5:
	s_add_i32 s21, s37, 1280
	s_mul_hi_u32 s7, s21, 0x38e38e39
	s_lshr_b32 s7, s7, 9
	s_mul_i32 s8, s7, 0x900
	s_sub_i32 s8, s21, s8
	s_lshl_b32 s9, s7, 11
	s_add_i32 s9, s9, s8
	s_add_i32 s9, s9, 0xffffff00
	s_lshl_b32 s10, s7, 8
	s_add_i32 s10, s10, s8
	s_cmpk_gt_i32 s8, 0xff
	s_cselect_b32 s9, s9, s10
	s_cselect_b32 s26, s12, s14
	s_cselect_b32 s27, s13, s15
	s_cselect_b32 s10, s7, 8
	s_lshl_b32 s9, s9, 12
	s_add_u32 s26, s26, s9
	s_addc_u32 s27, s27, 0
	s_add_i32 s10, s10, s82
	s_mul_i32 s10, s10, s24
	s_add_u32 s28, s58, s10
	s_addc_u32 s29, s59, 0
	s_add_u32 s28, s28, 0x3000
	s_addc_u32 s29, s29, 0
	s_add_u32 s0, s28, 0x1000
	s_addc_u32 s1, s29, 0
	global_load_dwordx4 v[122:125], v244, s[26:27]
	global_load_dwordx4 v[126:129], v244, s[26:27] offset:1024
	global_load_dwordx4 v[130:133], v244, s[26:27] offset:2048
	global_load_dwordx4 v[134:137], v244, s[26:27] offset:3072
	global_load_dwordx4 v[160:163], v244, s[28:29]
	global_load_dwordx4 v[164:167], v244, s[28:29] offset:1024
	global_load_dwordx4 v[168:171], v244, s[28:29] offset:2048
	global_load_dwordx4 v[172:175], v244, s[28:29] offset:3072
	global_load_dwordx4 v[176:179], v244, s[0:1]
	global_load_dwordx4 v[180:183], v244, s[0:1] offset:1024
	global_load_dwordx4 v[184:187], v244, s[0:1] offset:2048
	global_load_dwordx4 v[188:191], v244, s[0:1] offset:3072
	s_add_i32 s6, s37, 1536
	s_lshr_b32 s6, s6, 7
	s_lshl_b32 s6, s6, 2
	s_add_i32 s6, s6, 0x1c00
	v_mov_b32_e32 v110, s6
	global_load_dword v114, v110, s[70:71] sc1
	s_waitcnt vmcnt(35)
	v_pk_mul_f32 v[246:247], v[18:19], v[18:19]
	v_pk_fma_f32 v[246:247], v[20:21], v[20:21], v[246:247]
	v_pk_fma_f32 v[246:247], v[22:23], v[22:23], v[246:247]
	v_pk_fma_f32 v[246:247], v[24:25], v[24:25], v[246:247]
	v_pk_fma_f32 v[246:247], v[26:27], v[26:27], v[246:247]
	v_pk_fma_f32 v[246:247], v[28:29], v[28:29], v[246:247]
	v_pk_fma_f32 v[246:247], v[30:31], v[30:31], v[246:247]
	v_pk_fma_f32 v[246:247], v[32:33], v[32:33], v[246:247]
	s_nop 0
	v_add_f32_e32 v246, v246, v247
	s_nop 1
	v_add_f32_dpp v246, v246, v246 quad_perm:[1,0,3,2] row_mask:0xf bank_mask:0xf
	s_nop 1
	v_add_f32_dpp v246, v246, v246 quad_perm:[2,3,0,1] row_mask:0xf bank_mask:0xf
	s_nop 1
	v_add_f32_dpp v246, v246, v246 row_half_mirror row_mask:0xf bank_mask:0xf
	s_nop 1
	v_add_f32_dpp v246, v246, v246 row_mirror row_mask:0xf bank_mask:0xf
	s_nop 1
	v_add_f32_dpp v246, v246, v246 row_bcast:15 row_mask:0xa bank_mask:0xf
	s_nop 1
	v_add_f32_dpp v246, v246, v246 row_bcast:31 row_mask:0xc bank_mask:0xf
	s_nop 1
	v_readlane_b32 s0, v246, 63
	s_add_i32 s21, s37, 768
	s_lshl_b32 s21, s21, 11
	s_add_u32 s10, s16, s21
	s_addc_u32 s11, s17, 0
	v_mov_b32_e32 v248, s0
	v_fmamk_f32 v248, v248, 0x3a800000, v143
	v_rsq_f32_e32 v248, v248
	s_nop 0
	v_pk_mul_f32 v[18:19], v[18:19], v[248:249] op_sel_hi:[1,0]
	v_pk_add_f32 v[50:51], v[50:51], 1.0 op_sel_hi:[1,0]
	v_pk_mul_f32 v[18:19], v[2:3], v[18:19]
	v_pk_fma_f32 v[18:19], v[50:51], v[18:19], v[34:35]
	v_pk_mul_f32 v[20:21], v[20:21], v[248:249] op_sel_hi:[1,0]
	v_pk_add_f32 v[52:53], v[52:53], 1.0 op_sel_hi:[1,0]
	v_pk_mul_f32 v[20:21], v[4:5], v[20:21]
	v_pk_fma_f32 v[20:21], v[52:53], v[20:21], v[36:37]
	v_cvt_pk_bf16_f32 v34, v18, v19
	v_cvt_pk_bf16_f32 v35, v20, v21
	global_store_dwordx2 v245, v[34:35], s[10:11]
	v_pk_mul_f32 v[22:23], v[22:23], v[248:249] op_sel_hi:[1,0]
	v_pk_add_f32 v[54:55], v[54:55], 1.0 op_sel_hi:[1,0]
	v_pk_mul_f32 v[22:23], v[6:7], v[22:23]
	v_pk_fma_f32 v[22:23], v[54:55], v[22:23], v[38:39]
	v_pk_mul_f32 v[24:25], v[24:25], v[248:249] op_sel_hi:[1,0]
	v_pk_add_f32 v[56:57], v[56:57], 1.0 op_sel_hi:[1,0]
	v_pk_mul_f32 v[24:25], v[8:9], v[24:25]
	v_pk_fma_f32 v[24:25], v[56:57], v[24:25], v[40:41]
	v_cvt_pk_bf16_f32 v38, v22, v23
	v_cvt_pk_bf16_f32 v39, v24, v25
	global_store_dwordx2 v245, v[38:39], s[10:11] offset:512
	v_pk_mul_f32 v[26:27], v[26:27], v[248:249] op_sel_hi:[1,0]
	v_pk_add_f32 v[58:59], v[58:59], 1.0 op_sel_hi:[1,0]
	v_pk_mul_f32 v[26:27], v[10:11], v[26:27]
	v_pk_fma_f32 v[26:27], v[58:59], v[26:27], v[42:43]
	v_pk_mul_f32 v[28:29], v[28:29], v[248:249] op_sel_hi:[1,0]
	v_pk_add_f32 v[60:61], v[60:61], 1.0 op_sel_hi:[1,0]
	v_pk_mul_f32 v[28:29], v[12:13], v[28:29]
	v_pk_fma_f32 v[28:29], v[60:61], v[28:29], v[44:45]
	v_cvt_pk_bf16_f32 v42, v26, v27
	v_cvt_pk_bf16_f32 v43, v28, v29
	global_store_dwordx2 v245, v[42:43], s[10:11] offset:1024
	v_pk_mul_f32 v[30:31], v[30:31], v[248:249] op_sel_hi:[1,0]
	v_pk_add_f32 v[62:63], v[62:63], 1.0 op_sel_hi:[1,0]
	v_pk_mul_f32 v[30:31], v[14:15], v[30:31]
	v_pk_fma_f32 v[30:31], v[62:63], v[30:31], v[46:47]
	v_pk_mul_f32 v[32:33], v[32:33], v[248:249] op_sel_hi:[1,0]
	v_pk_add_f32 v[64:65], v[64:65], 1.0 op_sel_hi:[1,0]
	v_pk_mul_f32 v[32:33], v[16:17], v[32:33]
	v_pk_fma_f32 v[32:33], v[64:65], v[32:33], v[48:49]
	v_cvt_pk_bf16_f32 v46, v30, v31
	v_cvt_pk_bf16_f32 v47, v32, v33
	global_store_dwordx2 v245, v[46:47], s[10:11] offset:1536
	s_waitcnt vmcnt(4)
	v_readfirstlane_b32 s6, v114
	s_cmp_ge_u32 s6, 8
	s_cbranch_scc1 .Ldep_norm2d_ok6
	s_add_i32 s6, s37, 1536
	s_lshr_b32 s6, s6, 7
	s_lshl_b32 s6, s6, 2
	s_add_i32 s6, s6, 0x1c00
	v_mov_b32_e32 v110, s6

; DI unsigned pk_bf16(float lo, float hi) { f32x2 v = {lo, hi}; bf16v2 b = __builtin_convertvector(v, bf16v2); return __builtin_bit_cast(unsigned, b); }
; DI float red64(float x) { for (int o = 32; o > 0; o >>= 1) x += __shfl_xor(x, o); return x; }
; DI void modnorm_rows(const Params& p, int l, int which  , bool from_inputs, bool skip_ctx, int w0, int wstride, int lane) {
;     ...
;     if (i + wstride < nrows) {
;       const int rn = rowof(i + wstride); const float* src = xsrc_row(p, from_inputs, rn / TB, rn % TB);
; #pragma unroll
;       for (int q = 0; q < 4; ++q) vn[q] = *(const f32x4*)(src + q * 256 + lane * 4);
;     ...
;     float ss = 0.f;
; #pragma unroll
;     for (int q = 0; q < 4; ++q) ss += v[q][0] * v[q][0] + v[q][1] * v[q][1] + v[q][2] * v[q][2] + v[q][3] * v[q][3];
;     ss = red64(ss);
;     const float rs = rsqrtf(ss * (1.f / 1024.f) + EPSF);
;     bf16_t* dst = p.HY + (size_t)row * DM;
; #pragma unroll
;     for (int q = 0; q < 4; ++q) {
;       float o[4];
; #pragma unroll
;       for (int j = 0; j < 4; ++j) o[j] = (v[q][j] * rs * gg[q][j]) * (1.f + sc[q][j]) + sh[q][j];
;       u32x2 w = {pk_bf16(o[0], o[1]), pk_bf16(o[2], o[3])};
;       *(u32x2*)(dst + q * 256 + lane * 4) = w;
.Ldep_norm2d_ok6:
	s_add_i32 s21, s37, 1536
	s_mul_hi_u32 s7, s21, 0x38e38e39
	s_lshr_b32 s7, s7, 9
	s_mul_i32 s8, s7, 0x900
	s_sub_i32 s8, s21, s8
	s_lshl_b32 s9, s7, 11
	s_add_i32 s9, s9, s8
	s_add_i32 s9, s9, 0xffffff00
	s_lshl_b32 s10, s7, 8
	s_add_i32 s10, s10, s8
	s_cmpk_gt_i32 s8, 0xff
	s_cselect_b32 s9, s9, s10
	s_cselect_b32 s26, s12, s14
	s_cselect_b32 s27, s13, s15
	s_cselect_b32 s10, s7, 8
	s_lshl_b32 s9, s9, 12
	s_add_u32 s26, s26, s9
	s_addc_u32 s27, s27, 0
	s_add_i32 s10, s10, s82
	s_mul_i32 s10, s10, s24
	s_add_u32 s28, s58, s10
	s_addc_u32 s29, s59, 0
	s_add_u32 s28, s28, 0x3000
	s_addc_u32 s29, s29, 0
	s_add_u32 s0, s28, 0x1000
	s_addc_u32 s1, s29, 0
	global_load_dwordx4 v[18:21], v244, s[26:27]
	global_load_dwordx4 v[22:25], v244, s[26:27] offset:1024
	global_load_dwordx4 v[26:29], v244, s[26:27] offset:2048
	global_load_dwordx4 v[30:33], v244, s[26:27] offset:3072
	global_load_dwordx4 v[34:37], v244, s[28:29]
	global_load_dwordx4 v[38:41], v244, s[28:29] offset:1024
	global_load_dwordx4 v[42:45], v244, s[28:29] offset:2048
	global_load_dwordx4 v[46:49], v244, s[28:29] offset:3072
	global_load_dwordx4 v[50:53], v244, s[0:1]
	global_load_dwordx4 v[54:57], v244, s[0:1] offset:1024
	global_load_dwordx4 v[58:61], v244, s[0:1] offset:2048
	global_load_dwordx4 v[62:65], v244, s[0:1] offset:3072
	s_add_i32 s6, s37, 1792
	s_lshr_b32 s6, s6, 7
	s_lshl_b32 s6, s6, 2
	s_add_i32 s6, s6, 0x1c00
	v_mov_b32_e32 v110, s6
	global_load_dword v114, v110, s[70:71] sc1
	s_waitcnt vmcnt(35)
	v_pk_mul_f32 v[246:247], v[66:67], v[66:67]
	v_pk_fma_f32 v[246:247], v[68:69], v[68:69], v[246:247]
	v_pk_fma_f32 v[246:247], v[70:71], v[70:71], v[246:247]
	v_pk_fma_f32 v[246:247], v[72:73], v[72:73], v[246:247]
	v_pk_fma_f32 v[246:247], v[74:75], v[74:75], v[246:247]
	v_pk_fma_f32 v[246:247], v[76:77], v[76:77], v[246:247]
	v_pk_fma_f32 v[246:247], v[78:79], v[78:79], v[246:247]
	v_pk_fma_f32 v[246:247], v[80:81], v[80:81], v[246:247]
	s_nop 0
	v_add_f32_e32 v246, v246, v247
	s_nop 1
	v_add_f32_dpp v246, v246, v246 quad_perm:[1,0,3,2] row_mask:0xf bank_mask:0xf
	s_nop 1
	v_add_f32_dpp v246, v246, v246 quad_perm:[2,3,0,1] row_mask:0xf bank_mask:0xf
	s_nop 1
	v_add_f32_dpp v246, v246, v246 row_half_mirror row_mask:0xf bank_mask:0xf
	s_nop 1
	v_add_f32_dpp v246, v246, v246 row_mirror row_mask:0xf bank_mask:0xf
	s_nop 1
	v_add_f32_dpp v246, v246, v246 row_bcast:15 row_mask:0xa bank_mask:0xf
	s_nop 1
	v_add_f32_dpp v246, v246, v246 row_bcast:31 row_mask:0xc bank_mask:0xf
	s_nop 1
	v_readlane_b32 s0, v246, 63
	s_add_i32 s21, s37, 1024
	s_lshl_b32 s21, s21, 11
	s_add_u32 s10, s16, s21
	s_addc_u32 s11, s17, 0
	v_mov_b32_e32 v248, s0
	v_fmamk_f32 v248, v248, 0x3a800000, v143
	v_rsq_f32_e32 v248, v248
	s_nop 0
	v_pk_mul_f32 v[66:67], v[66:67], v[248:249] op_sel_hi:[1,0]
	v_pk_add_f32 v[98:99], v[98:99], 1.0 op_sel_hi:[1,0]
	v_pk_mul_f32 v[66:67], v[2:3], v[66:67]
	v_pk_fma_f32 v[66:67], v[98:99], v[66:67], v[82:83]
	v_pk_mul_f32 v[68:69], v[68:69], v[248:249] op_sel_hi:[1,0]
	v_pk_add_f32 v[100:101], v[100:101], 1.0 op_sel_hi:[1,0]
	v_pk_mul_f32 v[68:69], v[4:5], v[68:69]
	v_pk_fma_f32 v[68:69], v[100:101], v[68:69], v[84:85]
	v_cvt_pk_bf16_f32 v82, v66, v67
	v_cvt_pk_bf16_f32 v83, v68, v69
	global_store_dwordx2 v245, v[82:83], s[10:11]
	v_pk_mul_f32 v[70:71], v[70:71], v[248:249] op_sel_hi:[1,0]
	v_pk_add_f32 v[102:103], v[102:103], 1.0 op_sel_hi:[1,0]
	v_pk_mul_f32 v[70:71], v[6:7], v[70:71]
	v_pk_fma_f32 v[70:71], v[102:103], v[70:71], v[86:87]
	v_pk_mul_f32 v[72:73], v[72:73], v[248:249] op_sel_hi:[1,0]
	v_pk_add_f32 v[104:105], v[104:105], 1.0 op_sel_hi:[1,0]
	v_pk_mul_f32 v[72:73], v[8:9], v[72:73]
	v_pk_fma_f32 v[72:73], v[104:105], v[72:73], v[88:89]
	v_cvt_pk_bf16_f32 v86, v70, v71
	v_cvt_pk_bf16_f32 v87, v72, v73
	global_store_dwordx2 v245, v[86:87], s[10:11] offset:512
	v_pk_mul_f32 v[74:75], v[74:75], v[248:249] op_sel_hi:[1,0]
	v_pk_add_f32 v[106:107], v[106:107], 1.0 op_sel_hi:[1,0]
	v_pk_mul_f32 v[74:75], v[10:11], v[74:75]
	v_pk_fma_f32 v[74:75], v[106:107], v[74:75], v[90:91]
	v_pk_mul_f32 v[76:77], v[76:77], v[248:249] op_sel_hi:[1,0]
	v_pk_add_f32 v[108:109], v[108:109], 1.0 op_sel_hi:[1,0]
	v_pk_mul_f32 v[76:77], v[12:13], v[76:77]
	v_pk_fma_f32 v[76:77], v[108:109], v[76:77], v[92:93]
	v_cvt_pk_bf16_f32 v90, v74, v75
	v_cvt_pk_bf16_f32 v91, v76, v77
	global_store_dwordx2 v245, v[90:91], s[10:11] offset:1024
	v_pk_mul_f32 v[78:79], v[78:79], v[248:249] op_sel_hi:[1,0]
	v_pk_add_f32 v[118:119], v[118:119], 1.0 op_sel_hi:[1,0]
	v_pk_mul_f32 v[78:79], v[14:15], v[78:79]
	v_pk_fma_f32 v[78:79], v[118:119], v[78:79], v[94:95]
	v_pk_mul_f32 v[80:81], v[80:81], v[248:249] op_sel_hi:[1,0]
	v_pk_add_f32 v[120:121], v[120:121], 1.0 op_sel_hi:[1,0]
	v_pk_mul_f32 v[80:81], v[16:17], v[80:81]
	v_pk_fma_f32 v[80:81], v[120:121], v[80:81], v[96:97]
	v_cvt_pk_bf16_f32 v94, v78, v79
	v_cvt_pk_bf16_f32 v95, v80, v81
	global_store_dwordx2 v245, v[94:95], s[10:11] offset:1536
	s_waitcnt vmcnt(4)
	v_readfirstlane_b32 s6, v114
	s_cmp_ge_u32 s6, 8
	s_cbranch_scc1 .Ldep_norm2d_ok7
	s_add_i32 s6, s37, 1792
	s_lshr_b32 s6, s6, 7
	s_lshl_b32 s6, s6, 2
	s_add_i32 s6, s6, 0x1c00
	v_mov_b32_e32 v110, s6

; DI unsigned pk_bf16(float lo, float hi) { f32x2 v = {lo, hi}; bf16v2 b = __builtin_convertvector(v, bf16v2); return __builtin_bit_cast(unsigned, b); }
; DI float red64(float x) { for (int o = 32; o > 0; o >>= 1) x += __shfl_xor(x, o); return x; }
; DI void modnorm_rows(const Params& p, int l, int which  , bool from_inputs, bool skip_ctx, int w0, int wstride, int lane) {
;     ...
;     if (i + wstride < nrows) {
;       const int rn = rowof(i + wstride); const float* src = xsrc_row(p, from_inputs, rn / TB, rn % TB);
; #pragma unroll
;       for (int q = 0; q < 4; ++q) vn[q] = *(const f32x4*)(src + q * 256 + lane * 4);
;     ...
;     float ss = 0.f;
; #pragma unroll
;     for (int q = 0; q < 4; ++q) ss += v[q][0] * v[q][0] + v[q][1] * v[q][1] + v[q][2] * v[q][2] + v[q][3] * v[q][3];
;     ss = red64(ss);
;     const float rs = rsqrtf(ss * (1.f / 1024.f) + EPSF);
;     bf16_t* dst = p.HY + (size_t)row * DM;
; #pragma unroll
;     for (int q = 0; q < 4; ++q) {
;       float o[4];
; #pragma unroll
;       for (int j = 0; j < 4; ++j) o[j] = (v[q][j] * rs * gg[q][j]) * (1.f + sc[q][j]) + sh[q][j];
;       u32x2 w = {pk_bf16(o[0], o[1]), pk_bf16(o[2], o[3])};
;       *(u32x2*)(dst + q * 256 + lane * 4) = w;
.Ldep_norm2d_ok7:
	s_add_i32 s21, s37, 1792
	s_mul_hi_u32 s7, s21, 0x38e38e39
	s_lshr_b32 s7, s7, 9
	s_mul_i32 s8, s7, 0x900
	s_sub_i32 s8, s21, s8
	s_lshl_b32 s9, s7, 11
	s_add_i32 s9, s9, s8
	s_add_i32 s9, s9, 0xffffff00
	s_lshl_b32 s10, s7, 8
	s_add_i32 s10, s10, s8
	s_cmpk_gt_i32 s8, 0xff
	s_cselect_b32 s9, s9, s10
	s_cselect_b32 s26, s12, s14
	s_cselect_b32 s27, s13, s15
	s_cselect_b32 s10, s7, 8
	s_lshl_b32 s9, s9, 12
	s_add_u32 s26, s26, s9
	s_addc_u32 s27, s27, 0
	s_add_i32 s10, s10, s82
	s_mul_i32 s10, s10, s24
	s_add_u32 s28, s58, s10
	s_addc_u32 s29, s59, 0
	s_add_u32 s28, s28, 0x3000
	s_addc_u32 s29, s29, 0
	s_add_u32 s0, s28, 0x1000
	s_addc_u32 s1, s29, 0
	global_load_dwordx4 v[66:69], v244, s[26:27]
	global_load_dwordx4 v[70:73], v244, s[26:27] offset:1024
	global_load_dwordx4 v[74:77], v244, s[26:27] offset:2048
	global_load_dwordx4 v[78:81], v244, s[26:27] offset:3072
	global_load_dwordx4 v[82:85], v244, s[28:29]
	global_load_dwordx4 v[86:89], v244, s[28:29] offset:1024
	global_load_dwordx4 v[90:93], v244, s[28:29] offset:2048
	global_load_dwordx4 v[94:97], v244, s[28:29] offset:3072
	global_load_dwordx4 v[98:101], v244, s[0:1]
	global_load_dwordx4 v[102:105], v244, s[0:1] offset:1024
	global_load_dwordx4 v[106:109], v244, s[0:1] offset:2048
	global_load_dwordx4 v[118:121], v244, s[0:1] offset:3072
	s_add_i32 s6, s37, 2048
	s_lshr_b32 s6, s6, 7
	s_lshl_b32 s6, s6, 2
	s_add_i32 s6, s6, 0x1c00
	v_mov_b32_e32 v110, s6
	global_load_dword v114, v110, s[70:71] sc1
	s_waitcnt vmcnt(35)
	v_pk_mul_f32 v[246:247], v[122:123], v[122:123]
	v_pk_fma_f32 v[246:247], v[124:125], v[124:125], v[246:247]
	v_pk_fma_f32 v[246:247], v[126:127], v[126:127], v[246:247]
	v_pk_fma_f32 v[246:247], v[128:129], v[128:129], v[246:247]
	v_pk_fma_f32 v[246:247], v[130:131], v[130:131], v[246:247]
	v_pk_fma_f32 v[246:247], v[132:133], v[132:133], v[246:247]
	v_pk_fma_f32 v[246:247], v[134:135], v[134:135], v[246:247]
	v_pk_fma_f32 v[246:247], v[136:137], v[136:137], v[246:247]
	s_nop 0
	v_add_f32_e32 v246, v246, v247
	s_nop 1
	v_add_f32_dpp v246, v246, v246 quad_perm:[1,0,3,2] row_mask:0xf bank_mask:0xf
	s_nop 1
	v_add_f32_dpp v246, v246, v246 quad_perm:[2,3,0,1] row_mask:0xf bank_mask:0xf
	s_nop 1
	v_add_f32_dpp v246, v246, v246 row_half_mirror row_mask:0xf bank_mask:0xf
	s_nop 1
	v_add_f32_dpp v246, v246, v246 row_mirror row_mask:0xf bank_mask:0xf
	s_nop 1
	v_add_f32_dpp v246, v246, v246 row_bcast:15 row_mask:0xa bank_mask:0xf
	s_nop 1
	v_add_f32_dpp v246, v246, v246 row_bcast:31 row_mask:0xc bank_mask:0xf
	s_nop 1
	v_readlane_b32 s0, v246, 63
	s_add_i32 s21, s37, 1280
	s_lshl_b32 s21, s21, 11
	s_add_u32 s10, s16, s21
	s_addc_u32 s11, s17, 0
	v_mov_b32_e32 v248, s0
	v_fmamk_f32 v248, v248, 0x3a800000, v143
	v_rsq_f32_e32 v248, v248
	s_nop 0
	v_pk_mul_f32 v[122:123], v[122:123], v[248:249] op_sel_hi:[1,0]
	v_pk_add_f32 v[176:177], v[176:177], 1.0 op_sel_hi:[1,0]
	v_pk_mul_f32 v[122:123], v[2:3], v[122:123]
	v_pk_fma_f32 v[122:123], v[176:177], v[122:123], v[160:161]
	v_pk_mul_f32 v[124:125], v[124:125], v[248:249] op_sel_hi:[1,0]
	v_pk_add_f32 v[178:179], v[178:179], 1.0 op_sel_hi:[1,0]
	v_pk_mul_f32 v[124:125], v[4:5], v[124:125]
	v_pk_fma_f32 v[124:125], v[178:179], v[124:125], v[162:163]
	v_cvt_pk_bf16_f32 v160, v122, v123
	v_cvt_pk_bf16_f32 v161, v124, v125
	global_store_dwordx2 v245, v[160:161], s[10:11]
	v_pk_mul_f32 v[126:127], v[126:127], v[248:249] op_sel_hi:[1,0]
	v_pk_add_f32 v[180:181], v[180:181], 1.0 op_sel_hi:[1,0]
	v_pk_mul_f32 v[126:127], v[6:7], v[126:127]
	v_pk_fma_f32 v[126:127], v[180:181], v[126:127], v[164:165]
	v_pk_mul_f32 v[128:129], v[128:129], v[248:249] op_sel_hi:[1,0]
	v_pk_add_f32 v[182:183], v[182:183], 1.0 op_sel_hi:[1,0]
	v_pk_mul_f32 v[128:129], v[8:9], v[128:129]
	v_pk_fma_f32 v[128:129], v[182:183], v[128:129], v[166:167]
	v_cvt_pk_bf16_f32 v164, v126, v127
	v_cvt_pk_bf16_f32 v165, v128, v129
	global_store_dwordx2 v245, v[164:165], s[10:11] offset:512
	v_pk_mul_f32 v[130:131], v[130:131], v[248:249] op_sel_hi:[1,0]
	v_pk_add_f32 v[184:185], v[184:185], 1.0 op_sel_hi:[1,0]
	v_pk_mul_f32 v[130:131], v[10:11], v[130:131]
	v_pk_fma_f32 v[130:131], v[184:185], v[130:131], v[168:169]
	v_pk_mul_f32 v[132:133], v[132:133], v[248:249] op_sel_hi:[1,0]
	v_pk_add_f32 v[186:187], v[186:187], 1.0 op_sel_hi:[1,0]
	v_pk_mul_f32 v[132:133], v[12:13], v[132:133]
	v_pk_fma_f32 v[132:133], v[186:187], v[132:133], v[170:171]
	v_cvt_pk_bf16_f32 v168, v130, v131
	v_cvt_pk_bf16_f32 v169, v132, v133
	global_store_dwordx2 v245, v[168:169], s[10:11] offset:1024
	v_pk_mul_f32 v[134:135], v[134:135], v[248:249] op_sel_hi:[1,0]
	v_pk_add_f32 v[188:189], v[188:189], 1.0 op_sel_hi:[1,0]
	v_pk_mul_f32 v[134:135], v[14:15], v[134:135]
	v_pk_fma_f32 v[134:135], v[188:189], v[134:135], v[172:173]
	v_pk_mul_f32 v[136:137], v[136:137], v[248:249] op_sel_hi:[1,0]
	v_pk_add_f32 v[190:191], v[190:191], 1.0 op_sel_hi:[1,0]
	v_pk_mul_f32 v[136:137], v[16:17], v[136:137]
	v_pk_fma_f32 v[136:137], v[190:191], v[136:137], v[174:175]
	v_cvt_pk_bf16_f32 v172, v134, v135
	v_cvt_pk_bf16_f32 v173, v136, v137
	global_store_dwordx2 v245, v[172:173], s[10:11] offset:1536
	s_waitcnt vmcnt(4)
	v_readfirstlane_b32 s6, v114
	s_cmp_ge_u32 s6, 8
	s_cbranch_scc1 .Ldep_norm2d_ok8
	s_add_i32 s6, s37, 2048
	s_lshr_b32 s6, s6, 7
	s_lshl_b32 s6, s6, 2
	s_add_i32 s6, s6, 0x1c00
	v_mov_b32_e32 v110, s6

; DI unsigned pk_bf16(float lo, float hi) { f32x2 v = {lo, hi}; bf16v2 b = __builtin_convertvector(v, bf16v2); return __builtin_bit_cast(unsigned, b); }
; DI float red64(float x) { for (int o = 32; o > 0; o >>= 1) x += __shfl_xor(x, o); return x; }
; DI void modnorm_rows(const Params& p, int l, int which  , bool from_inputs, bool skip_ctx, int w0, int wstride, int lane) {
;     ...
;     if (i + wstride < nrows) {
;       const int rn = rowof(i + wstride); const float* src = xsrc_row(p, from_inputs, rn / TB, rn % TB);
; #pragma unroll
;       for (int q = 0; q < 4; ++q) vn[q] = *(const f32x4*)(src + q * 256 + lane * 4);
;     ...
;     float ss = 0.f;
; #pragma unroll
;     for (int q = 0; q < 4; ++q) ss += v[q][0] * v[q][0] + v[q][1] * v[q][1] + v[q][2] * v[q][2] + v[q][3] * v[q][3];
;     ss = red64(ss);
;     const float rs = rsqrtf(ss * (1.f / 1024.f) + EPSF);
;     bf16_t* dst = p.HY + (size_t)row * DM;
; #pragma unroll
;     for (int q = 0; q < 4; ++q) {
;       float o[4];
; #pragma unroll
;       for (int j = 0; j < 4; ++j) o[j] = (v[q][j] * rs * gg[q][j]) * (1.f + sc[q][j]) + sh[q][j];
;       u32x2 w = {pk_bf16(o[0], o[1]), pk_bf16(o[2], o[3])};
;       *(u32x2*)(dst + q * 256 + lane * 4) = w;
.Ldep_norm2d_ok8:
	s_add_i32 s21, s37, 2048
	s_mul_hi_u32 s7, s21, 0x38e38e39
	s_lshr_b32 s7, s7, 9
	s_mul_i32 s8, s7, 0x900
	s_sub_i32 s8, s21, s8
	s_lshl_b32 s9, s7, 11
	s_add_i32 s9, s9, s8
	s_add_i32 s9, s9, 0xffffff00
	s_lshl_b32 s10, s7, 8
	s_add_i32 s10, s10, s8
	s_cmpk_gt_i32 s8, 0xff
	s_cselect_b32 s9, s9, s10
	s_cselect_b32 s26, s12, s14
	s_cselect_b32 s27, s13, s15
	s_cselect_b32 s10, s7, 8
	s_lshl_b32 s9, s9, 12
	s_add_u32 s26, s26, s9
	s_addc_u32 s27, s27, 0
	s_add_i32 s10, s10, s82
	s_mul_i32 s10, s10, s24
	s_add_u32 s28, s58, s10
	s_addc_u32 s29, s59, 0
	s_add_u32 s28, s28, 0x3000
	s_addc_u32 s29, s29, 0
	s_add_u32 s0, s28, 0x1000
	s_addc_u32 s1, s29, 0
	global_load_dwordx4 v[122:125], v244, s[26:27]
	global_load_dwordx4 v[126:129], v244, s[26:27] offset:1024
	global_load_dwordx4 v[130:133], v244, s[26:27] offset:2048
	global_load_dwordx4 v[134:137], v244, s[26:27] offset:3072
	global_load_dwordx4 v[160:163], v244, s[28:29]
	global_load_dwordx4 v[164:167], v244, s[28:29] offset:1024
	global_load_dwordx4 v[168:171], v244, s[28:29] offset:2048
	global_load_dwordx4 v[172:175], v244, s[28:29] offset:3072
	global_load_dwordx4 v[176:179], v244, s[0:1]
	global_load_dwordx4 v[180:183], v244, s[0:1] offset:1024
	global_load_dwordx4 v[184:187], v244, s[0:1] offset:2048
	global_load_dwordx4 v[188:191], v244, s[0:1] offset:3072
	s_waitcnt vmcnt(34)
	v_pk_mul_f32 v[246:247], v[18:19], v[18:19]
	v_pk_fma_f32 v[246:247], v[20:21], v[20:21], v[246:247]
	v_pk_fma_f32 v[246:247], v[22:23], v[22:23], v[246:247]
	v_pk_fma_f32 v[246:247], v[24:25], v[24:25], v[246:247]
	v_pk_fma_f32 v[246:247], v[26:27], v[26:27], v[246:247]
	v_pk_fma_f32 v[246:247], v[28:29], v[28:29], v[246:247]
	v_pk_fma_f32 v[246:247], v[30:31], v[30:31], v[246:247]
	v_pk_fma_f32 v[246:247], v[32:33], v[32:33], v[246:247]
	s_nop 0
	v_add_f32_e32 v246, v246, v247
	s_nop 1
	v_add_f32_dpp v246, v246, v246 quad_perm:[1,0,3,2] row_mask:0xf bank_mask:0xf
	s_nop 1
	v_add_f32_dpp v246, v246, v246 quad_perm:[2,3,0,1] row_mask:0xf bank_mask:0xf
	s_nop 1
	v_add_f32_dpp v246, v246, v246 row_half_mirror row_mask:0xf bank_mask:0xf
	s_nop 1
	v_add_f32_dpp v246, v246, v246 row_mirror row_mask:0xf bank_mask:0xf
	s_nop 1
	v_add_f32_dpp v246, v246, v246 row_bcast:15 row_mask:0xa bank_mask:0xf
	s_nop 1
	v_add_f32_dpp v246, v246, v246 row_bcast:31 row_mask:0xc bank_mask:0xf
	s_nop 1
	v_readlane_b32 s0, v246, 63
	s_add_i32 s21, s37, 1536
	s_lshl_b32 s21, s21, 11
	s_add_u32 s10, s16, s21
	s_addc_u32 s11, s17, 0
	v_mov_b32_e32 v248, s0
	v_fmamk_f32 v248, v248, 0x3a800000, v143
	v_rsq_f32_e32 v248, v248
	s_nop 0
	v_pk_mul_f32 v[18:19], v[18:19], v[248:249] op_sel_hi:[1,0]
	v_pk_add_f32 v[50:51], v[50:51], 1.0 op_sel_hi:[1,0]
	v_pk_mul_f32 v[18:19], v[2:3], v[18:19]
	v_pk_fma_f32 v[18:19], v[50:51], v[18:19], v[34:35]
	v_pk_mul_f32 v[20:21], v[20:21], v[248:249] op_sel_hi:[1,0]
	v_pk_add_f32 v[52:53], v[52:53], 1.0 op_sel_hi:[1,0]
	v_pk_mul_f32 v[20:21], v[4:5], v[20:21]
	v_pk_fma_f32 v[20:21], v[52:53], v[20:21], v[36:37]
	v_cvt_pk_bf16_f32 v34, v18, v19
	v_cvt_pk_bf16_f32 v35, v20, v21
	global_store_dwordx2 v245, v[34:35], s[10:11]
	v_pk_mul_f32 v[22:23], v[22:23], v[248:249] op_sel_hi:[1,0]
	v_pk_add_f32 v[54:55], v[54:55], 1.0 op_sel_hi:[1,0]
	v_pk_mul_f32 v[22:23], v[6:7], v[22:23]
	v_pk_fma_f32 v[22:23], v[54:55], v[22:23], v[38:39]
	v_pk_mul_f32 v[24:25], v[24:25], v[248:249] op_sel_hi:[1,0]
	v_pk_add_f32 v[56:57], v[56:57], 1.0 op_sel_hi:[1,0]
	v_pk_mul_f32 v[24:25], v[8:9], v[24:25]
	v_pk_fma_f32 v[24:25], v[56:57], v[24:25], v[40:41]
	v_cvt_pk_bf16_f32 v38, v22, v23
	v_cvt_pk_bf16_f32 v39, v24, v25
	global_store_dwordx2 v245, v[38:39], s[10:11] offset:512
	v_pk_mul_f32 v[26:27], v[26:27], v[248:249] op_sel_hi:[1,0]
	v_pk_add_f32 v[58:59], v[58:59], 1.0 op_sel_hi:[1,0]
	v_pk_mul_f32 v[26:27], v[10:11], v[26:27]
	v_pk_fma_f32 v[26:27], v[58:59], v[26:27], v[42:43]
	v_pk_mul_f32 v[28:29], v[28:29], v[248:249] op_sel_hi:[1,0]
	v_pk_add_f32 v[60:61], v[60:61], 1.0 op_sel_hi:[1,0]
	v_pk_mul_f32 v[28:29], v[12:13], v[28:29]
	v_pk_fma_f32 v[28:29], v[60:61], v[28:29], v[44:45]
	v_cvt_pk_bf16_f32 v42, v26, v27
	v_cvt_pk_bf16_f32 v43, v28, v29
	global_store_dwordx2 v245, v[42:43], s[10:11] offset:1024
	v_pk_mul_f32 v[30:31], v[30:31], v[248:249] op_sel_hi:[1,0]
	v_pk_add_f32 v[62:63], v[62:63], 1.0 op_sel_hi:[1,0]
	v_pk_mul_f32 v[30:31], v[14:15], v[30:31]
	v_pk_fma_f32 v[30:31], v[62:63], v[30:31], v[46:47]
	v_pk_mul_f32 v[32:33], v[32:33], v[248:249] op_sel_hi:[1,0]
	v_pk_add_f32 v[64:65], v[64:65], 1.0 op_sel_hi:[1,0]
	v_pk_mul_f32 v[32:33], v[16:17], v[32:33]
	v_pk_fma_f32 v[32:33], v[64:65], v[32:33], v[48:49]
	v_cvt_pk_bf16_f32 v46, v30, v31
	v_cvt_pk_bf16_f32 v47, v32, v33
	global_store_dwordx2 v245, v[46:47], s[10:11] offset:1536
	s_waitcnt vmcnt(21)
; DI unsigned pk_bf16(float lo, float hi) { f32x2 v = {lo, hi}; bf16v2 b = __builtin_convertvector(v, bf16v2); return __builtin_bit_cast(unsigned, b); }
; DI float red64(float x) { for (int o = 32; o > 0; o >>= 1) x += __shfl_xor(x, o); return x; }
; DI void modnorm_rows(const Params& p, int l, int which  , bool from_inputs, bool skip_ctx, int w0, int wstride, int lane) {
;     ...
;     float ss = 0.f;
; #pragma unroll
;     for (int q = 0; q < 4; ++q) ss += v[q][0] * v[q][0] + v[q][1] * v[q][1] + v[q][2] * v[q][2] + v[q][3] * v[q][3];
;     ss = red64(ss);
;     const float rs = rsqrtf(ss * (1.f / 1024.f) + EPSF);
;     bf16_t* dst = p.HY + (size_t)row * DM;
; #pragma unroll
;     for (int q = 0; q < 4; ++q) {
;       float o[4];
; #pragma unroll
;       for (int j = 0; j < 4; ++j) o[j] = (v[q][j] * rs * gg[q][j]) * (1.f + sc[q][j]) + sh[q][j];
;       u32x2 w = {pk_bf16(o[0], o[1]), pk_bf16(o[2], o[3])};
;       *(u32x2*)(dst + q * 256 + lane * 4) = w;
	v_pk_mul_f32 v[246:247], v[66:67], v[66:67]
	v_pk_fma_f32 v[246:247], v[68:69], v[68:69], v[246:247]
	v_pk_fma_f32 v[246:247], v[70:71], v[70:71], v[246:247]
	v_pk_fma_f32 v[246:247], v[72:73], v[72:73], v[246:247]
	v_pk_fma_f32 v[246:247], v[74:75], v[74:75], v[246:247]
	v_pk_fma_f32 v[246:247], v[76:77], v[76:77], v[246:247]
	v_pk_fma_f32 v[246:247], v[78:79], v[78:79], v[246:247]
	v_pk_fma_f32 v[246:247], v[80:81], v[80:81], v[246:247]
	s_nop 0
	v_add_f32_e32 v246, v246, v247
	s_nop 1
	v_add_f32_dpp v246, v246, v246 quad_perm:[1,0,3,2] row_mask:0xf bank_mask:0xf
	s_nop 1
	v_add_f32_dpp v246, v246, v246 quad_perm:[2,3,0,1] row_mask:0xf bank_mask:0xf
	s_nop 1
	v_add_f32_dpp v246, v246, v246 row_half_mirror row_mask:0xf bank_mask:0xf
	s_nop 1
	v_add_f32_dpp v246, v246, v246 row_mirror row_mask:0xf bank_mask:0xf
	s_nop 1
	v_add_f32_dpp v246, v246, v246 row_bcast:15 row_mask:0xa bank_mask:0xf
	s_nop 1
	v_add_f32_dpp v246, v246, v246 row_bcast:31 row_mask:0xc bank_mask:0xf
	s_nop 1
	v_readlane_b32 s0, v246, 63
	s_add_i32 s21, s37, 1792
	s_lshl_b32 s21, s21, 11
	s_add_u32 s10, s16, s21
	s_addc_u32 s11, s17, 0
	v_mov_b32_e32 v248, s0
	v_fmamk_f32 v248, v248, 0x3a800000, v143
	v_rsq_f32_e32 v248, v248
	s_nop 0
	v_pk_mul_f32 v[66:67], v[66:67], v[248:249] op_sel_hi:[1,0]
	v_pk_add_f32 v[98:99], v[98:99], 1.0 op_sel_hi:[1,0]
	v_pk_mul_f32 v[66:67], v[2:3], v[66:67]
	v_pk_fma_f32 v[66:67], v[98:99], v[66:67], v[82:83]
	v_pk_mul_f32 v[68:69], v[68:69], v[248:249] op_sel_hi:[1,0]
	v_pk_add_f32 v[100:101], v[100:101], 1.0 op_sel_hi:[1,0]
	v_pk_mul_f32 v[68:69], v[4:5], v[68:69]
	v_pk_fma_f32 v[68:69], v[100:101], v[68:69], v[84:85]
	v_cvt_pk_bf16_f32 v82, v66, v67
	v_cvt_pk_bf16_f32 v83, v68, v69
	global_store_dwordx2 v245, v[82:83], s[10:11]
	v_pk_mul_f32 v[70:71], v[70:71], v[248:249] op_sel_hi:[1,0]
	v_pk_add_f32 v[102:103], v[102:103], 1.0 op_sel_hi:[1,0]
	v_pk_mul_f32 v[70:71], v[6:7], v[70:71]
	v_pk_fma_f32 v[70:71], v[102:103], v[70:71], v[86:87]
	v_pk_mul_f32 v[72:73], v[72:73], v[248:249] op_sel_hi:[1,0]
	v_pk_add_f32 v[104:105], v[104:105], 1.0 op_sel_hi:[1,0]
	v_pk_mul_f32 v[72:73], v[8:9], v[72:73]
	v_pk_fma_f32 v[72:73], v[104:105], v[72:73], v[88:89]
	v_cvt_pk_bf16_f32 v86, v70, v71
	v_cvt_pk_bf16_f32 v87, v72, v73
	global_store_dwordx2 v245, v[86:87], s[10:11] offset:512
	v_pk_mul_f32 v[74:75], v[74:75], v[248:249] op_sel_hi:[1,0]
	v_pk_add_f32 v[106:107], v[106:107], 1.0 op_sel_hi:[1,0]
	v_pk_mul_f32 v[74:75], v[10:11], v[74:75]
	v_pk_fma_f32 v[74:75], v[106:107], v[74:75], v[90:91]
	v_pk_mul_f32 v[76:77], v[76:77], v[248:249] op_sel_hi:[1,0]
	v_pk_add_f32 v[108:109], v[108:109], 1.0 op_sel_hi:[1,0]
	v_pk_mul_f32 v[76:77], v[12:13], v[76:77]
	v_pk_fma_f32 v[76:77], v[108:109], v[76:77], v[92:93]
	v_cvt_pk_bf16_f32 v90, v74, v75
	v_cvt_pk_bf16_f32 v91, v76, v77
	global_store_dwordx2 v245, v[90:91], s[10:11] offset:1024
	v_pk_mul_f32 v[78:79], v[78:79], v[248:249] op_sel_hi:[1,0]
	v_pk_add_f32 v[118:119], v[118:119], 1.0 op_sel_hi:[1,0]
	v_pk_mul_f32 v[78:79], v[14:15], v[78:79]
	v_pk_fma_f32 v[78:79], v[118:119], v[78:79], v[94:95]
	v_pk_mul_f32 v[80:81], v[80:81], v[248:249] op_sel_hi:[1,0]
	v_pk_add_f32 v[120:121], v[120:121], 1.0 op_sel_hi:[1,0]
	v_pk_mul_f32 v[80:81], v[16:17], v[80:81]
	v_pk_fma_f32 v[80:81], v[120:121], v[80:81], v[96:97]
	v_cvt_pk_bf16_f32 v94, v78, v79
	v_cvt_pk_bf16_f32 v95, v80, v81
	global_store_dwordx2 v245, v[94:95], s[10:11] offset:1536
	s_waitcnt vmcnt(8)
; DI unsigned pk_bf16(float lo, float hi) { f32x2 v = {lo, hi}; bf16v2 b = __builtin_convertvector(v, bf16v2); return __builtin_bit_cast(unsigned, b); }
; DI float red64(float x) { for (int o = 32; o > 0; o >>= 1) x += __shfl_xor(x, o); return x; }
; DI void modnorm_rows(const Params& p, int l, int which  , bool from_inputs, bool skip_ctx, int w0, int wstride, int lane) {
;     ...
;     float ss = 0.f;
; #pragma unroll
;     for (int q = 0; q < 4; ++q) ss += v[q][0] * v[q][0] + v[q][1] * v[q][1] + v[q][2] * v[q][2] + v[q][3] * v[q][3];
;     ss = red64(ss);
;     const float rs = rsqrtf(ss * (1.f / 1024.f) + EPSF);
;     bf16_t* dst = p.HY + (size_t)row * DM;
; #pragma unroll
;     for (int q = 0; q < 4; ++q) {
;       float o[4];
; #pragma unroll
;       for (int j = 0; j < 4; ++j) o[j] = (v[q][j] * rs * gg[q][j]) * (1.f + sc[q][j]) + sh[q][j];
;       u32x2 w = {pk_bf16(o[0], o[1]), pk_bf16(o[2], o[3])};
;       *(u32x2*)(dst + q * 256 + lane * 4) = w;
	v_pk_mul_f32 v[246:247], v[122:123], v[122:123]
	v_pk_fma_f32 v[246:247], v[124:125], v[124:125], v[246:247]
	v_pk_fma_f32 v[246:247], v[126:127], v[126:127], v[246:247]
	v_pk_fma_f32 v[246:247], v[128:129], v[128:129], v[246:247]
	v_pk_fma_f32 v[246:247], v[130:131], v[130:131], v[246:247]
	v_pk_fma_f32 v[246:247], v[132:133], v[132:133], v[246:247]
	v_pk_fma_f32 v[246:247], v[134:135], v[134:135], v[246:247]
	v_pk_fma_f32 v[246:247], v[136:137], v[136:137], v[246:247]
	s_nop 0
	v_add_f32_e32 v246, v246, v247
	s_nop 1
	v_add_f32_dpp v246, v246, v246 quad_perm:[1,0,3,2] row_mask:0xf bank_mask:0xf
	s_nop 1
	v_add_f32_dpp v246, v246, v246 quad_perm:[2,3,0,1] row_mask:0xf bank_mask:0xf
	s_nop 1
	v_add_f32_dpp v246, v246, v246 row_half_mirror row_mask:0xf bank_mask:0xf
	s_nop 1
	v_add_f32_dpp v246, v246, v246 row_mirror row_mask:0xf bank_mask:0xf
	s_nop 1
	v_add_f32_dpp v246, v246, v246 row_bcast:15 row_mask:0xa bank_mask:0xf
	s_nop 1
	v_add_f32_dpp v246, v246, v246 row_bcast:31 row_mask:0xc bank_mask:0xf
	s_nop 1
	v_readlane_b32 s0, v246, 63
	s_add_i32 s21, s37, 2048
	s_lshl_b32 s21, s21, 11
	s_add_u32 s10, s16, s21
	s_addc_u32 s11, s17, 0
	v_mov_b32_e32 v248, s0
	v_fmamk_f32 v248, v248, 0x3a800000, v143
	v_rsq_f32_e32 v248, v248
	s_nop 0
	v_pk_mul_f32 v[122:123], v[122:123], v[248:249] op_sel_hi:[1,0]
	v_pk_add_f32 v[176:177], v[176:177], 1.0 op_sel_hi:[1,0]
	v_pk_mul_f32 v[122:123], v[2:3], v[122:123]
	v_pk_fma_f32 v[122:123], v[176:177], v[122:123], v[160:161]
	v_pk_mul_f32 v[124:125], v[124:125], v[248:249] op_sel_hi:[1,0]
	v_pk_add_f32 v[178:179], v[178:179], 1.0 op_sel_hi:[1,0]
	v_pk_mul_f32 v[124:125], v[4:5], v[124:125]
	v_pk_fma_f32 v[124:125], v[178:179], v[124:125], v[162:163]
	v_cvt_pk_bf16_f32 v160, v122, v123
	v_cvt_pk_bf16_f32 v161, v124, v125
	global_store_dwordx2 v245, v[160:161], s[10:11]
	v_pk_mul_f32 v[126:127], v[126:127], v[248:249] op_sel_hi:[1,0]
	v_pk_add_f32 v[180:181], v[180:181], 1.0 op_sel_hi:[1,0]
	v_pk_mul_f32 v[126:127], v[6:7], v[126:127]
	v_pk_fma_f32 v[126:127], v[180:181], v[126:127], v[164:165]
	v_pk_mul_f32 v[128:129], v[128:129], v[248:249] op_sel_hi:[1,0]
	v_pk_add_f32 v[182:183], v[182:183], 1.0 op_sel_hi:[1,0]
	v_pk_mul_f32 v[128:129], v[8:9], v[128:129]
	v_pk_fma_f32 v[128:129], v[182:183], v[128:129], v[166:167]
	v_cvt_pk_bf16_f32 v164, v126, v127
	v_cvt_pk_bf16_f32 v165, v128, v129
	global_store_dwordx2 v245, v[164:165], s[10:11] offset:512
	v_pk_mul_f32 v[130:131], v[130:131], v[248:249] op_sel_hi:[1,0]
	v_pk_add_f32 v[184:185], v[184:185], 1.0 op_sel_hi:[1,0]
	v_pk_mul_f32 v[130:131], v[10:11], v[130:131]
	v_pk_fma_f32 v[130:131], v[184:185], v[130:131], v[168:169]
	v_pk_mul_f32 v[132:133], v[132:133], v[248:249] op_sel_hi:[1,0]
	v_pk_add_f32 v[186:187], v[186:187], 1.0 op_sel_hi:[1,0]
	v_pk_mul_f32 v[132:133], v[12:13], v[132:133]
	v_pk_fma_f32 v[132:133], v[186:187], v[132:133], v[170:171]
	v_cvt_pk_bf16_f32 v168, v130, v131
	v_cvt_pk_bf16_f32 v169, v132, v133
	global_store_dwordx2 v245, v[168:169], s[10:11] offset:1024
	v_pk_mul_f32 v[134:135], v[134:135], v[248:249] op_sel_hi:[1,0]
	v_pk_add_f32 v[188:189], v[188:189], 1.0 op_sel_hi:[1,0]
	v_pk_mul_f32 v[134:135], v[14:15], v[134:135]
	v_pk_fma_f32 v[134:135], v[188:189], v[134:135], v[172:173]
	v_pk_mul_f32 v[136:137], v[136:137], v[248:249] op_sel_hi:[1,0]
	v_pk_add_f32 v[190:191], v[190:191], 1.0 op_sel_hi:[1,0]
	v_pk_mul_f32 v[136:137], v[16:17], v[136:137]
	v_pk_fma_f32 v[136:137], v[190:191], v[136:137], v[174:175]
	v_cvt_pk_bf16_f32 v172, v134, v135
	v_cvt_pk_bf16_f32 v173, v136, v137
	global_store_dwordx2 v245, v[172:173], s[10:11] offset:1536
	s_branch .Lnorm2_done

; template <class Epi>
; DI void gemm_tile(const bf16_t* __restrict__ A, int lda, const bf16_t* __restrict__ Bt, int ldb, int K, int row0, int col0, char* lds, const Epi& epi) {
;     ...
;   for (int kt = 0; kt < KT; ++kt) {
;     asm volatile("s_waitcnt vmcnt(0)" ::: "memory");
;     __syncthreads();
;     const char* sa = lds + (kt & 1) * 32768 + (wr * 64 + fr) * 128;
;     const char* sb = lds + (kt & 1) * 32768 + 16384 + (wc * 64 + fr) * 128;
; #pragma unroll
;     for (int kk = 0; kk < 2; ++kk) {
;       if (kt + 1 < KT) { if (kk == 0) stage_a(kt + 1, (kt + 1) & 1); else stage_b(kt + 1, (kt + 1) & 1); }
;       bf16x8 a[4], b[4];
;       const int co = ((kk * 4 + fq) ^ swz) * 16;
; #pragma unroll
;       for (int m = 0; m < 4; ++m) a[m] = *(const bf16x8*)(sa + m * 2048 + co);
; #pragma unroll
;       for (int n = 0; n < 4; ++n) b[n] = *(const bf16x8*)(sb + n * 2048 + co);
; #pragma unroll
;       for (int m = 0; m < 4; ++m)
; #pragma unroll
;         for (int n = 0; n < 4; ++n) acc[m][n] = __builtin_amdgcn_mfma_f32_16x16x32_bf16(b[n], a[m], acc[m][n], 0, 0, 0);
;     }
;   }
.LBB0_267:
	s_add_i32 s20, s3, 0xffff8000
	s_and_b32 s29, s3, 0x8000
	s_and_b32 s20, s20, 0x8000
	v_add_u32_e32 v102, s29, v90
	v_add_u32_e32 v110, s20, v91
	v_or_b32_e32 v136, s20, v93
	v_add_u32_e32 v103, 0x1000, v102
	v_readfirstlane_b32 s20, v102
	v_lshl_add_u64 v[94:95], v[74:75], 0, s[0:1]
	v_add_u32_e32 v104, 0x2000, v102
	s_mov_b32 m0, s20
	v_readfirstlane_b32 s20, v103
	s_waitcnt vmcnt(0)
	s_waitcnt vmcnt(0) lgkmcnt(0)
	s_barrier
	v_lshl_add_u64 v[96:97], v[76:77], 0, s[0:1]
	v_add_u32_e32 v105, 0x3000, v102
	global_load_lds_dwordx4 v[94:95], off
	s_mov_b32 m0, s20
	v_readfirstlane_b32 s20, v104
	v_add_u32_e32 v137, 0x4000, v102
	v_lshl_add_u64 v[98:99], v[78:79], 0, s[0:1]
	global_load_lds_dwordx4 v[96:97], off
	s_mov_b32 m0, s20
	v_readfirstlane_b32 s20, v105
	v_add_u32_e32 v159, 0x5000, v102
	v_lshl_add_u64 v[100:101], v[80:81], 0, s[0:1]
	global_load_lds_dwordx4 v[98:99], off
	s_mov_b32 m0, s20
	v_readfirstlane_b32 s20, v137
	v_lshl_add_u64 v[132:133], v[66:67], 0, s[0:1]
	v_add_u32_e32 v160, 0x6000, v102
	global_load_lds_dwordx4 v[100:101], off
	v_add_u32_e32 v106, v110, v92
	v_add_u32_e32 v128, v136, v92
	s_mov_b32 m0, s20
	v_readfirstlane_b32 s20, v159
	v_lshl_add_u64 v[134:135], v[68:69], 0, s[0:1]
	v_add_u32_e32 v161, 0x7000, v102
	ds_read_b128 v[94:97], v106
	ds_read_b128 v[98:101], v106 offset:2048
	ds_read_b128 v[102:105], v106 offset:4096
	ds_read_b128 v[106:109], v106 offset:6144
	ds_read_b128 v[116:119], v128 offset:16384
	ds_read_b128 v[120:123], v128 offset:18432
	ds_read_b128 v[124:127], v128 offset:20480
	ds_read_b128 v[128:131], v128 offset:22528
	global_load_lds_dwordx4 v[132:133], off
	s_mov_b32 m0, s20
	v_readfirstlane_b32 s20, v160
	v_lshl_add_u64 v[84:85], v[70:71], 0, s[0:1]
	global_load_lds_dwordx4 v[134:135], off
	s_mov_b32 m0, s20
	v_readfirstlane_b32 s20, v161
	v_lshl_add_u64 v[82:83], v[72:73], 0, s[0:1]
	global_load_lds_dwordx4 v[84:85], off
	s_mov_b32 m0, s20
	s_waitcnt lgkmcnt(0)
	v_mfma_f32_16x16x32_bf16 v[30:33], v[116:119], v[102:105], v[30:33]
	global_load_lds_dwordx4 v[82:83], off
	s_add_u32 s0, s0, 0x80
	v_mfma_f32_16x16x32_bf16 v[26:29], v[120:123], v[102:105], v[26:29]
	s_addc_u32 s1, s1, 0
	s_add_i32 s3, s3, 0x8000
	s_cmpk_eq_i32 s0, 0x780
	v_mfma_f32_16x16x32_bf16 v[22:25], v[124:127], v[102:105], v[22:25]
	v_mfma_f32_16x16x32_bf16 v[18:21], v[128:131], v[102:105], v[18:21]
	v_add_u32_e32 v102, v110, v89
	v_add_u32_e32 v110, v136, v89
	v_mfma_f32_16x16x32_bf16 v[62:65], v[116:119], v[94:97], v[62:65]
	v_mfma_f32_16x16x32_bf16 v[58:61], v[120:123], v[94:97], v[58:61]
	v_mfma_f32_16x16x32_bf16 v[54:57], v[124:127], v[94:97], v[54:57]
	v_mfma_f32_16x16x32_bf16 v[50:53], v[128:131], v[94:97], v[50:53]
	v_mfma_f32_16x16x32_bf16 v[46:49], v[116:119], v[98:101], v[46:49]
	v_mfma_f32_16x16x32_bf16 v[42:45], v[120:123], v[98:101], v[42:45]
	v_mfma_f32_16x16x32_bf16 v[38:41], v[124:127], v[98:101], v[38:41]
	v_mfma_f32_16x16x32_bf16 v[34:37], v[128:131], v[98:101], v[34:37]
	ds_read_b128 v[82:85], v102
	ds_read_b128 v[94:97], v102 offset:2048
	ds_read_b128 v[98:101], v102 offset:4096
	ds_read_b128 v[102:105], v102 offset:6144
	v_mfma_f32_16x16x32_bf16 v[14:17], v[116:119], v[106:109], v[14:17]
	v_mfma_f32_16x16x32_bf16 v[10:13], v[120:123], v[106:109], v[10:13]
	v_mfma_f32_16x16x32_bf16 v[6:9], v[124:127], v[106:109], v[6:9]
	v_mfma_f32_16x16x32_bf16 v[2:5], v[128:131], v[106:109], v[2:5]
	ds_read_b128 v[106:109], v110 offset:16384
	ds_read_b128 v[116:119], v110 offset:18432
	ds_read_b128 v[120:123], v110 offset:20480
	ds_read_b128 v[124:127], v110 offset:22528
	s_waitcnt lgkmcnt(0)
	v_mfma_f32_16x16x32_bf16 v[62:65], v[106:109], v[82:85], v[62:65]
	v_mfma_f32_16x16x32_bf16 v[58:61], v[116:119], v[82:85], v[58:61]
	v_mfma_f32_16x16x32_bf16 v[54:57], v[120:123], v[82:85], v[54:57]
	v_mfma_f32_16x16x32_bf16 v[50:53], v[124:127], v[82:85], v[50:53]
	v_mfma_f32_16x16x32_bf16 v[46:49], v[106:109], v[94:97], v[46:49]
	v_mfma_f32_16x16x32_bf16 v[42:45], v[116:119], v[94:97], v[42:45]
	v_mfma_f32_16x16x32_bf16 v[38:41], v[120:123], v[94:97], v[38:41]
	v_mfma_f32_16x16x32_bf16 v[34:37], v[124:127], v[94:97], v[34:37]
	v_mfma_f32_16x16x32_bf16 v[30:33], v[106:109], v[98:101], v[30:33]
	v_mfma_f32_16x16x32_bf16 v[26:29], v[116:119], v[98:101], v[26:29]
	v_mfma_f32_16x16x32_bf16 v[22:25], v[120:123], v[98:101], v[22:25]
	v_mfma_f32_16x16x32_bf16 v[18:21], v[124:127], v[98:101], v[18:21]
	v_mfma_f32_16x16x32_bf16 v[14:17], v[106:109], v[102:105], v[14:17]
	v_mfma_f32_16x16x32_bf16 v[10:13], v[116:119], v[102:105], v[10:13]
	v_mfma_f32_16x16x32_bf16 v[6:9], v[120:123], v[102:105], v[6:9]
	v_mfma_f32_16x16x32_bf16 v[2:5], v[124:127], v[102:105], v[2:5]
	s_cbranch_scc0 .LBB0_267
	v_add_u32_e32 v90, s29, v93
	v_add_u32_e32 v91, s29, v91
	v_add_u32_e32 v82, v90, v92
	v_add_u32_e32 v92, v91, v92
	s_waitcnt vmcnt(0)
	s_waitcnt vmcnt(0)
	s_barrier
; template <class Epi>
; DI void gemm_tile(const bf16_t* __restrict__ A, int lda, const bf16_t* __restrict__ Bt, int ldb, int K, int row0, int col0, char* lds, const Epi& epi) {
;     ...
;       for (int m = 0; m < 4; ++m) a[m] = *(const bf16x8*)(sa + m * 2048 + co);
; #pragma unroll
;       for (int n = 0; n < 4; ++n) b[n] = *(const bf16x8*)(sb + n * 2048 + co);
; #pragma unroll
;       for (int m = 0; m < 4; ++m)
; #pragma unroll
;         for (int n = 0; n < 4; ++n) acc[m][n] = __builtin_amdgcn_mfma_f32_16x16x32_bf16(b[n], a[m], acc[m][n], 0, 0, 0);
;   DI void operator()(const f32x4 (&acc)[4][4], int r0, int c0, int fr, int fq) const {
;     ...
;       const int row = r0 + m * 16 + fr; const int b = row / TB, s = row % TB;
;       const float* src = xsrc_row(*p, from_inputs, b, s);
;       float* dst = xdst_row(*p, b, s);
;       const float* gate = p->MOD + (size_t)(l * 9 + (s < NCTX ? 8 : b)) * 6144 + gate_off;
; #pragma unroll
;       for (int n = 0; n < 4; ++n) {
;         const int col = c0 + n * 16 + fq * 4;
;         f32x4 g = *(const f32x4*)(gate + col), xv = *(const f32x4*)(src + col);
	ds_read_b128 v[66:69], v82 offset:16384
	ds_read_b128 v[74:77], v82 offset:18432
	ds_read_b128 v[70:73], v92
	ds_read_b128 v[78:81], v82 offset:20480
	ds_read_b128 v[82:85], v82 offset:22528
	s_waitcnt lgkmcnt(2)
	v_mfma_f32_16x16x32_bf16 v[62:65], v[66:69], v[70:73], v[62:65]
	s_and_b64 vcc, exec, s[38:39]
	v_mfma_f32_16x16x32_bf16 v[58:61], v[74:77], v[70:73], v[58:61]
	s_waitcnt lgkmcnt(1)
	v_mfma_f32_16x16x32_bf16 v[54:57], v[78:81], v[70:73], v[54:57]
	s_waitcnt lgkmcnt(0)
	v_mfma_f32_16x16x32_bf16 v[50:53], v[82:85], v[70:73], v[50:53]
	ds_read_b128 v[70:73], v92 offset:2048
	s_waitcnt lgkmcnt(0)
	v_mfma_f32_16x16x32_bf16 v[46:49], v[66:69], v[70:73], v[46:49]
	v_mfma_f32_16x16x32_bf16 v[42:45], v[74:77], v[70:73], v[42:45]
	v_mfma_f32_16x16x32_bf16 v[38:41], v[78:81], v[70:73], v[38:41]
	v_mfma_f32_16x16x32_bf16 v[34:37], v[82:85], v[70:73], v[34:37]
	ds_read_b128 v[70:73], v92 offset:4096
	s_waitcnt lgkmcnt(0)
	v_mfma_f32_16x16x32_bf16 v[30:33], v[66:69], v[70:73], v[30:33]
	v_mfma_f32_16x16x32_bf16 v[26:29], v[74:77], v[70:73], v[26:29]
	v_mfma_f32_16x16x32_bf16 v[22:25], v[78:81], v[70:73], v[22:25]
	v_mfma_f32_16x16x32_bf16 v[18:21], v[82:85], v[70:73], v[18:21]
	ds_read_b128 v[70:73], v92 offset:6144
	s_waitcnt lgkmcnt(0)
	v_mfma_f32_16x16x32_bf16 v[10:13], v[74:77], v[70:73], v[10:13]
	v_add_u32_e32 v74, v90, v89
	v_add_u32_e32 v75, v91, v89
	ds_read_b128 v[90:93], v74 offset:22528
	v_mfma_f32_16x16x32_bf16 v[14:17], v[66:69], v[70:73], v[14:17]
	ds_read_b128 v[66:69], v74 offset:16384
	v_mfma_f32_16x16x32_bf16 v[6:9], v[78:81], v[70:73], v[6:9]
	ds_read_b128 v[76:79], v74 offset:18432
	v_mfma_f32_16x16x32_bf16 v[2:5], v[82:85], v[70:73], v[2:5]
	ds_read_b128 v[80:83], v74 offset:20480
	ds_read_b128 v[70:73], v75
	v_or_b32_e32 v74, s2, v87
	s_waitcnt lgkmcnt(0)
	v_mfma_f32_16x16x32_bf16 v[62:65], v[66:69], v[70:73], v[62:65]
	v_lshl_add_u32 v74, v88, 6, v74
	s_mov_b64 s[2:3], -1
	v_mfma_f32_16x16x32_bf16 v[58:61], v[76:79], v[70:73], v[58:61]
	v_mfma_f32_16x16x32_bf16 v[54:57], v[80:83], v[70:73], v[54:57]
	v_mfma_f32_16x16x32_bf16 v[50:53], v[90:93], v[70:73], v[50:53]
	ds_read_b128 v[70:73], v75 offset:2048
	s_waitcnt lgkmcnt(0)
	v_mfma_f32_16x16x32_bf16 v[46:49], v[66:69], v[70:73], v[46:49]
	v_mfma_f32_16x16x32_bf16 v[42:45], v[76:79], v[70:73], v[42:45]
	v_mfma_f32_16x16x32_bf16 v[38:41], v[80:83], v[70:73], v[38:41]
	v_mfma_f32_16x16x32_bf16 v[34:37], v[90:93], v[70:73], v[34:37]
	ds_read_b128 v[70:73], v75 offset:4096
	s_waitcnt lgkmcnt(0)
	v_mfma_f32_16x16x32_bf16 v[30:33], v[66:69], v[70:73], v[30:33]
	v_mfma_f32_16x16x32_bf16 v[26:29], v[76:79], v[70:73], v[26:29]
	v_mfma_f32_16x16x32_bf16 v[22:25], v[80:83], v[70:73], v[22:25]
	v_mfma_f32_16x16x32_bf16 v[18:21], v[90:93], v[70:73], v[18:21]
	ds_read_b128 v[70:73], v75 offset:6144
	s_waitcnt lgkmcnt(0)
	v_mfma_f32_16x16x32_bf16 v[14:17], v[66:69], v[70:73], v[14:17]
	v_mul_hi_i32 v66, v74, s47
	v_lshrrev_b32_e32 v67, 31, v66
	v_ashrrev_i32_e32 v66, 9, v66
	v_mfma_f32_16x16x32_bf16 v[10:13], v[76:79], v[70:73], v[10:13]
	v_add_u32_e32 v75, v66, v67
	v_mul_i32_i24_e32 v66, 0x900, v75
	v_sub_u32_e32 v67, v74, v66
	v_mfma_f32_16x16x32_bf16 v[6:9], v[80:83], v[70:73], v[6:9]
	v_cmp_lt_i32_e64 s[0:1], s33, v67
	v_mfma_f32_16x16x32_bf16 v[2:5], v[90:93], v[70:73], v[2:5]
	v_readlane_b32 s4, v254, 28
	v_readlane_b32 s5, v254, 29
	v_readlane_b32 s8, v254, 32
	v_readlane_b32 s9, v254, 33
	s_nop 3
	s_cmp_lg_u64 s[38:39], 0
	s_cselect_b32 s4, s56, s4
	s_cselect_b32 s5, s57, s5
	s_cselect_b32 s8, s64, s8
	s_cselect_b32 s9, s65, s9
	v_lshlrev_b32_e32 v1, 6, v1
	v_lshlrev_b32_e32 v67, 2, v86
	v_or3_b32 v80, v1, v67, s28
	v_lshlrev_b32_e32 v66, 2, v80
	v_mov_b32_e32 v67, 0
	v_mov_b32_e32 v100, s8
	v_mov_b32_e32 v101, s9
	v_mov_b32_e32 v102, s4
	v_mov_b32_e32 v103, s5
	v_mov_b32_e32 v104, s64
	v_mov_b32_e32 v105, s65
	v_mov_b32_e32 v106, s56
	v_mov_b32_e32 v107, s57
	s_add_u32 s0, s58, 0x2000
	s_addc_u32 s1, s59, 0
	v_mov_b32_e32 v108, s0
	v_mov_b32_e32 v109, s1
	v_mov_b32_e32 v110, 8
	v_mov_b32_e32 v88, v74
	v_mul_hi_i32 v89, v88, s47
	v_lshrrev_b32_e32 v90, 31, v89
	v_ashrrev_i32_e32 v89, 9, v89
	v_add_u32_e32 v91, v89, v90
	v_mul_i32_i24_e32 v89, 0x900, v91
	v_sub_u32_e32 v92, v88, v89
	v_cmp_lt_i32_e32 vcc, s33, v92
	v_lshlrev_b32_e32 v89, 11, v91
	v_add3_u32 v89, v92, v89, s75
	v_lshl_add_u32 v90, v91, 8, v92
	v_cndmask_b32_e32 v94, v90, v89, vcc
	v_ashrrev_i32_e32 v95, 31, v94
	v_lshlrev_b64 v[96:97], 12, v[94:95]
	v_lshl_add_u64 v[96:97], v[96:97], 0, v[66:67]
	v_cndmask_b32_e32 v98, v100, v102, vcc
	v_cndmask_b32_e32 v99, v101, v103, vcc
	v_lshl_add_u64 v[224:225], v[98:99], 0, v[96:97]
	v_cndmask_b32_e32 v98, v104, v106, vcc
	v_cndmask_b32_e32 v99, v105, v107, vcc
	v_lshl_add_u64 v[232:233], v[98:99], 0, v[96:97]
	v_cndmask_b32_e32 v93, v110, v91, vcc
	v_add_u32_e32 v93, s82, v93
	v_mad_i64_i32 v[240:241], s[0:1], v93, s24, v[108:109]
	s_nop 0
	v_lshl_add_u64 v[240:241], v[240:241], 0, v[66:67]
	global_load_dwordx4 v[116:119], v[240:241], off
	global_load_dwordx4 v[120:123], v[240:241], off offset:64
	global_load_dwordx4 v[124:127], v[240:241], off offset:128
	global_load_dwordx4 v[128:131], v[240:241], off offset:192
	global_load_dwordx4 v[160:163], v[224:225], off
	global_load_dwordx4 v[164:167], v[224:225], off offset:64
	global_load_dwordx4 v[168:171], v[224:225], off offset:128
	global_load_dwordx4 v[172:175], v[224:225], off offset:192
	v_or_b32_e32 v88, 16, v74
	v_mul_hi_i32 v89, v88, s47
	v_lshrrev_b32_e32 v90, 31, v89
	v_ashrrev_i32_e32 v89, 9, v89
	v_add_u32_e32 v91, v89, v90
	v_mul_i32_i24_e32 v89, 0x900, v91
	v_sub_u32_e32 v92, v88, v89
	v_cmp_lt_i32_e32 vcc, s33, v92
;   DI void operator()(const f32x4 (&acc)[4][4], int r0, int c0, int fr, int fq) const {
;     ...
;       for (int n = 0; n < 4; ++n) {
;         const int col = c0 + n * 16 + fq * 4;
;         f32x4 g = *(const f32x4*)(gate + col), xv = *(const f32x4*)(src + col);
;         *(f32x4*)(dst + col) = xv + g * acc[m][n];
;       }
	v_lshlrev_b32_e32 v89, 11, v91
	v_add3_u32 v89, v92, v89, s75
	v_lshl_add_u32 v90, v91, 8, v92
	v_cndmask_b32_e32 v94, v90, v89, vcc
	v_ashrrev_i32_e32 v95, 31, v94
	v_lshlrev_b64 v[96:97], 12, v[94:95]
	v_lshl_add_u64 v[96:97], v[96:97], 0, v[66:67]
	v_cndmask_b32_e32 v98, v100, v102, vcc
	v_cndmask_b32_e32 v99, v101, v103, vcc
	v_lshl_add_u64 v[226:227], v[98:99], 0, v[96:97]
	v_cndmask_b32_e32 v98, v104, v106, vcc
	v_cndmask_b32_e32 v99, v105, v107, vcc
	v_lshl_add_u64 v[234:235], v[98:99], 0, v[96:97]
	global_load_dwordx4 v[176:179], v[226:227], off
	global_load_dwordx4 v[180:183], v[226:227], off offset:64
	global_load_dwordx4 v[184:187], v[226:227], off offset:128
	global_load_dwordx4 v[188:191], v[226:227], off offset:192
	v_or_b32_e32 v88, 32, v74
	v_mul_hi_i32 v89, v88, s47
	v_lshrrev_b32_e32 v90, 31, v89
	v_ashrrev_i32_e32 v89, 9, v89
	v_add_u32_e32 v91, v89, v90
	v_mul_i32_i24_e32 v89, 0x900, v91
	v_sub_u32_e32 v92, v88, v89
	v_cmp_lt_i32_e32 vcc, s33, v92
	v_lshlrev_b32_e32 v89, 11, v91
	v_add3_u32 v89, v92, v89, s75
	v_lshl_add_u32 v90, v91, 8, v92
	v_cndmask_b32_e32 v94, v90, v89, vcc
	v_ashrrev_i32_e32 v95, 31, v94
	v_lshlrev_b64 v[96:97], 12, v[94:95]
	v_lshl_add_u64 v[96:97], v[96:97], 0, v[66:67]
	v_cndmask_b32_e32 v98, v100, v102, vcc
	v_cndmask_b32_e32 v99, v101, v103, vcc
	v_lshl_add_u64 v[228:229], v[98:99], 0, v[96:97]
	v_cndmask_b32_e32 v98, v104, v106, vcc
	v_cndmask_b32_e32 v99, v105, v107, vcc
	v_lshl_add_u64 v[236:237], v[98:99], 0, v[96:97]
	global_load_dwordx4 v[192:195], v[228:229], off
	global_load_dwordx4 v[196:199], v[228:229], off offset:64
	global_load_dwordx4 v[200:203], v[228:229], off offset:128
	global_load_dwordx4 v[204:207], v[228:229], off offset:192
	v_or_b32_e32 v88, 48, v74
	v_mul_hi_i32 v89, v88, s47
	v_lshrrev_b32_e32 v90, 31, v89
	v_ashrrev_i32_e32 v89, 9, v89
	v_add_u32_e32 v91, v89, v90
	v_mul_i32_i24_e32 v89, 0x900, v91
	v_sub_u32_e32 v92, v88, v89
	v_cmp_lt_i32_e32 vcc, s33, v92
	v_lshlrev_b32_e32 v89, 11, v91
	v_add3_u32 v89, v92, v89, s75
	v_lshl_add_u32 v90, v91, 8, v92
	v_cndmask_b32_e32 v94, v90, v89, vcc
	v_ashrrev_i32_e32 v95, 31, v94
	v_lshlrev_b64 v[96:97], 12, v[94:95]
	v_lshl_add_u64 v[96:97], v[96:97], 0, v[66:67]
	v_cndmask_b32_e32 v98, v100, v102, vcc
	v_cndmask_b32_e32 v99, v101, v103, vcc
	v_lshl_add_u64 v[230:231], v[98:99], 0, v[96:97]
	v_cndmask_b32_e32 v98, v104, v106, vcc
	v_cndmask_b32_e32 v99, v105, v107, vcc
	v_lshl_add_u64 v[238:239], v[98:99], 0, v[96:97]
	global_load_dwordx4 v[208:211], v[230:231], off
	global_load_dwordx4 v[212:215], v[230:231], off offset:64
	global_load_dwordx4 v[216:219], v[230:231], off offset:128
	global_load_dwordx4 v[220:223], v[230:231], off offset:192
	s_waitcnt vmcnt(15)
	v_pk_fma_f32 v[64:65], v[64:65], v[118:119], v[162:163]
	v_pk_fma_f32 v[62:63], v[62:63], v[116:117], v[160:161]
	global_store_dwordx4 v[232:233], v[62:65], off
	s_waitcnt vmcnt(15)
	v_pk_fma_f32 v[60:61], v[60:61], v[122:123], v[166:167]
	v_pk_fma_f32 v[58:59], v[58:59], v[120:121], v[164:165]
	global_store_dwordx4 v[232:233], v[58:61], off offset:64
	s_waitcnt vmcnt(15)
	v_pk_fma_f32 v[56:57], v[56:57], v[126:127], v[170:171]
	v_pk_fma_f32 v[54:55], v[54:55], v[124:125], v[168:169]
	global_store_dwordx4 v[232:233], v[54:57], off offset:128
	s_waitcnt vmcnt(15)
	v_pk_fma_f32 v[52:53], v[52:53], v[130:131], v[174:175]
	v_pk_fma_f32 v[50:51], v[50:51], v[128:129], v[172:173]
	global_store_dwordx4 v[232:233], v[50:53], off offset:192
	s_waitcnt vmcnt(15)
	v_pk_fma_f32 v[48:49], v[48:49], v[118:119], v[178:179]
	v_pk_fma_f32 v[46:47], v[46:47], v[116:117], v[176:177]
	global_store_dwordx4 v[234:235], v[46:49], off
	s_waitcnt vmcnt(15)
	v_pk_fma_f32 v[44:45], v[44:45], v[122:123], v[182:183]
	v_pk_fma_f32 v[42:43], v[42:43], v[120:121], v[180:181]
	global_store_dwordx4 v[234:235], v[42:45], off offset:64
	s_waitcnt vmcnt(15)
	v_pk_fma_f32 v[40:41], v[40:41], v[126:127], v[186:187]
	v_pk_fma_f32 v[38:39], v[38:39], v[124:125], v[184:185]
	global_store_dwordx4 v[234:235], v[38:41], off offset:128
	s_waitcnt vmcnt(15)
	v_pk_fma_f32 v[36:37], v[36:37], v[130:131], v[190:191]
	v_pk_fma_f32 v[34:35], v[34:35], v[128:129], v[188:189]
	global_store_dwordx4 v[234:235], v[34:37], off offset:192
	s_waitcnt vmcnt(15)
	v_pk_fma_f32 v[32:33], v[32:33], v[118:119], v[194:195]
	v_pk_fma_f32 v[30:31], v[30:31], v[116:117], v[192:193]
	global_store_dwordx4 v[236:237], v[30:33], off
	s_waitcnt vmcnt(15)
	v_pk_fma_f32 v[28:29], v[28:29], v[122:123], v[198:199]
	v_pk_fma_f32 v[26:27], v[26:27], v[120:121], v[196:197]
	global_store_dwordx4 v[236:237], v[26:29], off offset:64
	s_waitcnt vmcnt(15)
	v_pk_fma_f32 v[24:25], v[24:25], v[126:127], v[202:203]
	v_pk_fma_f32 v[22:23], v[22:23], v[124:125], v[200:201]
	global_store_dwordx4 v[236:237], v[22:25], off offset:128
	s_waitcnt vmcnt(15)
	v_pk_fma_f32 v[20:21], v[20:21], v[130:131], v[206:207]
	v_pk_fma_f32 v[18:19], v[18:19], v[128:129], v[204:205]
	global_store_dwordx4 v[236:237], v[18:21], off offset:192
	s_waitcnt vmcnt(15)
	v_pk_fma_f32 v[16:17], v[16:17], v[118:119], v[210:211]
	v_pk_fma_f32 v[14:15], v[14:15], v[116:117], v[208:209]
	global_store_dwordx4 v[238:239], v[14:17], off
	s_waitcnt vmcnt(15)
	v_pk_fma_f32 v[12:13], v[12:13], v[122:123], v[214:215]
	v_pk_fma_f32 v[10:11], v[10:11], v[120:121], v[212:213]
	global_store_dwordx4 v[238:239], v[10:13], off offset:64
	s_waitcnt vmcnt(15)
	v_pk_fma_f32 v[8:9], v[8:9], v[126:127], v[218:219]
	v_pk_fma_f32 v[6:7], v[6:7], v[124:125], v[216:217]
	global_store_dwordx4 v[238:239], v[6:9], off offset:128
	s_waitcnt vmcnt(15)
	v_pk_fma_f32 v[4:5], v[4:5], v[130:131], v[222:223]
	v_pk_fma_f32 v[2:3], v[2:3], v[128:129], v[220:221]
	global_store_dwordx4 v[238:239], v[2:5], off offset:192
	s_cmp_lg_u32 s77, 6
	s_cbranch_scc1 .Ldep_nosig_k6
	s_waitcnt vmcnt(0)
	s_barrier
	v_readfirstlane_b32 s0, v74
	s_lshr_b32 s0, s0, 7
	s_lshl_b32 s0, s0, 2
	s_add_i32 s0, s0, 0x1c00
	v_mov_b32_e32 v88, s0
	v_mov_b32_e32 v89, 1
	v_cmp_eq_u32_e32 vcc, 0, v138
	s_and_saveexec_b64 s[0:1], vcc
	global_atomic_add v88, v89, s[70:71]
	s_or_b64 exec, exec, s[0:1]

; DI void modnorm_rows(const Params& p, int l, int which  , bool from_inputs, bool skip_ctx, int w0, int wstride, int lane) {
;   const float* g = (which ? p.norm2_g : p.norm1_g) + l * DM;
;   f32x4 gg[4];
; #pragma unroll
;   for (int i = 0; i < 4; ++i) gg[i] = *(const f32x4*)(g + i * 256 + lane * 4);
;   const int nrows = skip_ctx ? 8 * NLAT : T_TOK;
;   auto rowof = [&](int i) -> int { return skip_ctx ? (i / NLAT) * TB + NCTX + (i % NLAT) : i; };
;   int i = w0;
;   if (i >= nrows) return;
;   f32x4 vn[4];
;   {
;     const int row = rowof(i); const float* src = xsrc_row(p, from_inputs, row / TB, row % TB);
; #pragma unroll
;     for (int q = 0; q < 4; ++q) vn[q] = *(const f32x4*)(src + q * 256 + lane * 4);
;   }
;   for (; i < nrows; i += wstride) {
;     const int row = rowof(i); const int b = row / TB, s = row % TB;
;     f32x4 v[4];
; #pragma unroll
;     for (int q = 0; q < 4; ++q) v[q] = vn[q];
;     if (i + wstride < nrows) {
;       const int rn = rowof(i + wstride); const float* src = xsrc_row(p, from_inputs, rn / TB, rn % TB);
; #pragma unroll
;       for (int q = 0; q < 4; ++q) vn[q] = *(const f32x4*)(src + q * 256 + lane * 4);
.LBB0_823:
	s_or_b64 exec, exec, s[0:1]
	v_readlane_b32 s0, v252, 9
	s_nop 1
	v_add_u32_e32 v50, s0, v158
	s_movk_i32 s0, 0x4800
	v_cmp_gt_i32_e32 vcc, s0, v50
	s_and_saveexec_b64 s[2:3], vcc
	s_cbranch_execz .LBB0_852
	v_readlane_b32 s0, v252, 9
	v_lshlrev_b32_e32 v244, 4, v115
	v_lshlrev_b32_e32 v245, 3, v115
	v_add_u32_e32 v1, s0, v158
	s_nop 1
	v_readfirstlane_b32 s20, v1
	v_readlane_b32 s4, v254, 40
	v_readlane_b32 s5, v254, 41
	v_readlane_b32 s12, v254, 28
	v_readlane_b32 s13, v254, 29
	v_readlane_b32 s14, v254, 32
	v_readlane_b32 s15, v254, 33
	v_readlane_b32 s16, v253, 40
	v_readlane_b32 s17, v253, 41
	v_readlane_b32 s18, v250, 4
	v_readlane_b32 s19, v250, 5
	s_nop 3
	s_lshl_b32 s0, s49, 12
	s_add_u32 s4, s4, s0
	s_addc_u32 s5, s5, 0
	global_load_dwordx4 v[2:5], v244, s[4:5]
	global_load_dwordx4 v[6:9], v244, s[4:5] offset:1024
	global_load_dwordx4 v[10:13], v244, s[4:5] offset:2048
	global_load_dwordx4 v[14:17], v244, s[4:5] offset:3072
	s_add_i32 s0, s77, 7
	s_cmp_gt_u32 s0, 16
	s_cselect_b32 s12, s56, s12
	s_cselect_b32 s13, s57, s13
	s_cselect_b32 s14, s64, s14
	s_cselect_b32 s15, s65, s15
	s_cmp_gt_u32 s77, 9
	s_cbranch_scc0 .Lnorm1_nodep
	v_readlane_b32 s6, v250, 43
	s_nop 1
	s_cmp_eq_u32 s6, 1
	s_cbranch_scc1 .Lnorm1_l1
.Lnorm1_nodep:
	s_add_i32 s21, s20, 0
	s_mul_hi_u32 s7, s21, 0x38e38e39
	s_lshr_b32 s7, s7, 9
	s_mul_i32 s8, s7, 0x900
	s_sub_i32 s8, s21, s8
	s_lshl_b32 s9, s7, 11
	s_add_i32 s9, s9, s8
	s_add_i32 s9, s9, 0xffffff00
	s_lshl_b32 s10, s7, 8
	s_add_i32 s10, s10, s8
	s_cmpk_gt_i32 s8, 0xff
	s_cselect_b32 s9, s9, s10
	s_cselect_b32 s26, s12, s14
	s_cselect_b32 s27, s13, s15
	s_cselect_b32 s10, s7, 8
	s_lshl_b32 s9, s9, 12
	s_add_u32 s26, s26, s9
	s_addc_u32 s27, s27, 0
	s_add_i32 s10, s10, s82
	s_mul_i32 s10, s10, s24
	s_add_u32 s28, s58, s10
	s_addc_u32 s29, s59, 0
	s_add_u32 s28, s28, 0x0
	s_addc_u32 s29, s29, 0
	s_add_u32 s0, s28, 0x1000
	s_addc_u32 s1, s29, 0
	global_load_dwordx4 v[18:21], v244, s[26:27]
	global_load_dwordx4 v[22:25], v244, s[26:27] offset:1024
	global_load_dwordx4 v[26:29], v244, s[26:27] offset:2048
	global_load_dwordx4 v[30:33], v244, s[26:27] offset:3072
	global_load_dwordx4 v[34:37], v244, s[28:29]
	global_load_dwordx4 v[38:41], v244, s[28:29] offset:1024
	global_load_dwordx4 v[42:45], v244, s[28:29] offset:2048
	global_load_dwordx4 v[46:49], v244, s[28:29] offset:3072
	global_load_dwordx4 v[50:53], v244, s[0:1]
	global_load_dwordx4 v[54:57], v244, s[0:1] offset:1024
	global_load_dwordx4 v[58:61], v244, s[0:1] offset:2048
	global_load_dwordx4 v[62:65], v244, s[0:1] offset:3072
	s_add_i32 s21, s20, 2048
	s_mul_hi_u32 s7, s21, 0x38e38e39
	s_lshr_b32 s7, s7, 9
	s_mul_i32 s8, s7, 0x900
	s_sub_i32 s8, s21, s8
	s_lshl_b32 s9, s7, 11
	s_add_i32 s9, s9, s8
	s_add_i32 s9, s9, 0xffffff00
	s_lshl_b32 s10, s7, 8
	s_add_i32 s10, s10, s8
	s_cmpk_gt_i32 s8, 0xff
	s_cselect_b32 s9, s9, s10
	s_cselect_b32 s26, s12, s14
	s_cselect_b32 s27, s13, s15
	s_cselect_b32 s10, s7, 8
	s_lshl_b32 s9, s9, 12
	s_add_u32 s26, s26, s9
	s_addc_u32 s27, s27, 0
	s_add_i32 s10, s10, s82
	s_mul_i32 s10, s10, s24
	s_add_u32 s28, s58, s10
	s_addc_u32 s29, s59, 0
	s_add_u32 s28, s28, 0x0
	s_addc_u32 s29, s29, 0
	s_add_u32 s0, s28, 0x1000
	s_addc_u32 s1, s29, 0
	global_load_dwordx4 v[66:69], v244, s[26:27]
	global_load_dwordx4 v[70:73], v244, s[26:27] offset:1024
	global_load_dwordx4 v[74:77], v244, s[26:27] offset:2048
	global_load_dwordx4 v[78:81], v244, s[26:27] offset:3072
	global_load_dwordx4 v[82:85], v244, s[28:29]
	global_load_dwordx4 v[86:89], v244, s[28:29] offset:1024
	global_load_dwordx4 v[90:93], v244, s[28:29] offset:2048
	global_load_dwordx4 v[94:97], v244, s[28:29] offset:3072
	global_load_dwordx4 v[98:101], v244, s[0:1]
	global_load_dwordx4 v[102:105], v244, s[0:1] offset:1024
	global_load_dwordx4 v[106:109], v244, s[0:1] offset:2048
	global_load_dwordx4 v[118:121], v244, s[0:1] offset:3072
	s_add_i32 s21, s20, 4096
	s_mul_hi_u32 s7, s21, 0x38e38e39
	s_lshr_b32 s7, s7, 9
	s_mul_i32 s8, s7, 0x900
	s_sub_i32 s8, s21, s8
	s_lshl_b32 s9, s7, 11
	s_add_i32 s9, s9, s8
	s_add_i32 s9, s9, 0xffffff00
	s_lshl_b32 s10, s7, 8
	s_add_i32 s10, s10, s8
	s_cmpk_gt_i32 s8, 0xff
	s_cselect_b32 s9, s9, s10
	s_cselect_b32 s26, s12, s14
	s_cselect_b32 s27, s13, s15
	s_cselect_b32 s10, s7, 8
	s_lshl_b32 s9, s9, 12
	s_add_u32 s26, s26, s9
	s_addc_u32 s27, s27, 0
	s_add_i32 s10, s10, s82
	s_mul_i32 s10, s10, s24
	s_add_u32 s28, s58, s10
	s_addc_u32 s29, s59, 0
	s_add_u32 s28, s28, 0x0
	s_addc_u32 s29, s29, 0
	s_add_u32 s0, s28, 0x1000
	s_addc_u32 s1, s29, 0
	global_load_dwordx4 v[122:125], v244, s[26:27]
	global_load_dwordx4 v[126:129], v244, s[26:27] offset:1024
	global_load_dwordx4 v[130:133], v244, s[26:27] offset:2048
	global_load_dwordx4 v[134:137], v244, s[26:27] offset:3072
	global_load_dwordx4 v[160:163], v244, s[28:29]
	global_load_dwordx4 v[164:167], v244, s[28:29] offset:1024
	global_load_dwordx4 v[168:171], v244, s[28:29] offset:2048
	global_load_dwordx4 v[172:175], v244, s[28:29] offset:3072
	global_load_dwordx4 v[176:179], v244, s[0:1]
	global_load_dwordx4 v[180:183], v244, s[0:1] offset:1024
	global_load_dwordx4 v[184:187], v244, s[0:1] offset:2048
	global_load_dwordx4 v[188:191], v244, s[0:1] offset:3072
	s_waitcnt vmcnt(24)
; DI unsigned pk_bf16(float lo, float hi) { f32x2 v = {lo, hi}; bf16v2 b = __builtin_convertvector(v, bf16v2); return __builtin_bit_cast(unsigned, b); }
; DI float red64(float x) { for (int o = 32; o > 0; o >>= 1) x += __shfl_xor(x, o); return x; }
; DI void modnorm_rows(const Params& p, int l, int which  , bool from_inputs, bool skip_ctx, int w0, int wstride, int lane) {
;     ...
;     if (i + wstride < nrows) {
;       const int rn = rowof(i + wstride); const float* src = xsrc_row(p, from_inputs, rn / TB, rn % TB);
; #pragma unroll
;       for (int q = 0; q < 4; ++q) vn[q] = *(const f32x4*)(src + q * 256 + lane * 4);
;     ...
;     float ss = 0.f;
; #pragma unroll
;     for (int q = 0; q < 4; ++q) ss += v[q][0] * v[q][0] + v[q][1] * v[q][1] + v[q][2] * v[q][2] + v[q][3] * v[q][3];
;     ss = red64(ss);
;     const float rs = rsqrtf(ss * (1.f / 1024.f) + EPSF);
;     bf16_t* dst = p.HY + (size_t)row * DM;
; #pragma unroll
;     for (int q = 0; q < 4; ++q) {
;       float o[4];
; #pragma unroll
;       for (int j = 0; j < 4; ++j) o[j] = (v[q][j] * rs * gg[q][j]) * (1.f + sc[q][j]) + sh[q][j];
;       u32x2 w = {pk_bf16(o[0], o[1]), pk_bf16(o[2], o[3])};
;       *(u32x2*)(dst + q * 256 + lane * 4) = w;
	v_pk_mul_f32 v[246:247], v[18:19], v[18:19]
	v_pk_fma_f32 v[246:247], v[20:21], v[20:21], v[246:247]
	v_pk_fma_f32 v[246:247], v[22:23], v[22:23], v[246:247]
	v_pk_fma_f32 v[246:247], v[24:25], v[24:25], v[246:247]
	v_pk_fma_f32 v[246:247], v[26:27], v[26:27], v[246:247]
	v_pk_fma_f32 v[246:247], v[28:29], v[28:29], v[246:247]
	v_pk_fma_f32 v[246:247], v[30:31], v[30:31], v[246:247]
	v_pk_fma_f32 v[246:247], v[32:33], v[32:33], v[246:247]
	s_nop 0
	v_add_f32_e32 v246, v246, v247
	s_nop 1
	v_add_f32_dpp v246, v246, v246 quad_perm:[1,0,3,2] row_mask:0xf bank_mask:0xf
	s_nop 1
	v_add_f32_dpp v246, v246, v246 quad_perm:[2,3,0,1] row_mask:0xf bank_mask:0xf
	s_nop 1
	v_add_f32_dpp v246, v246, v246 row_half_mirror row_mask:0xf bank_mask:0xf
	s_nop 1
	v_add_f32_dpp v246, v246, v246 row_mirror row_mask:0xf bank_mask:0xf
	s_nop 1
	v_add_f32_dpp v246, v246, v246 row_bcast:15 row_mask:0xa bank_mask:0xf
	s_nop 1
	v_add_f32_dpp v246, v246, v246 row_bcast:31 row_mask:0xc bank_mask:0xf
	s_nop 1
	v_readlane_b32 s0, v246, 63
	s_add_i32 s21, s20, 0
	s_lshl_b32 s21, s21, 11
	s_add_u32 s10, s16, s21
	s_addc_u32 s11, s17, 0
	v_mov_b32_e32 v248, s0
	v_fmamk_f32 v248, v248, 0x3a800000, v143
	v_rsq_f32_e32 v248, v248
	s_nop 0
	v_pk_mul_f32 v[18:19], v[18:19], v[248:249] op_sel_hi:[1,0]
	v_pk_add_f32 v[50:51], v[50:51], 1.0 op_sel_hi:[1,0]
	v_pk_mul_f32 v[18:19], v[2:3], v[18:19]
	v_pk_fma_f32 v[18:19], v[50:51], v[18:19], v[34:35]
	v_pk_mul_f32 v[20:21], v[20:21], v[248:249] op_sel_hi:[1,0]
	v_pk_add_f32 v[52:53], v[52:53], 1.0 op_sel_hi:[1,0]
	v_pk_mul_f32 v[20:21], v[4:5], v[20:21]
	v_pk_fma_f32 v[20:21], v[52:53], v[20:21], v[36:37]
	v_cvt_pk_bf16_f32 v34, v18, v19
	v_cvt_pk_bf16_f32 v35, v20, v21
	global_store_dwordx2 v245, v[34:35], s[10:11]
	v_pk_mul_f32 v[22:23], v[22:23], v[248:249] op_sel_hi:[1,0]
	v_pk_add_f32 v[54:55], v[54:55], 1.0 op_sel_hi:[1,0]
	v_pk_mul_f32 v[22:23], v[6:7], v[22:23]
	v_pk_fma_f32 v[22:23], v[54:55], v[22:23], v[38:39]
	v_pk_mul_f32 v[24:25], v[24:25], v[248:249] op_sel_hi:[1,0]
	v_pk_add_f32 v[56:57], v[56:57], 1.0 op_sel_hi:[1,0]
	v_pk_mul_f32 v[24:25], v[8:9], v[24:25]
	v_pk_fma_f32 v[24:25], v[56:57], v[24:25], v[40:41]
	v_cvt_pk_bf16_f32 v38, v22, v23
	v_cvt_pk_bf16_f32 v39, v24, v25
	global_store_dwordx2 v245, v[38:39], s[10:11] offset:512
	v_pk_mul_f32 v[26:27], v[26:27], v[248:249] op_sel_hi:[1,0]
	v_pk_add_f32 v[58:59], v[58:59], 1.0 op_sel_hi:[1,0]
	v_pk_mul_f32 v[26:27], v[10:11], v[26:27]
	v_pk_fma_f32 v[26:27], v[58:59], v[26:27], v[42:43]
	v_pk_mul_f32 v[28:29], v[28:29], v[248:249] op_sel_hi:[1,0]
	v_pk_add_f32 v[60:61], v[60:61], 1.0 op_sel_hi:[1,0]
	v_pk_mul_f32 v[28:29], v[12:13], v[28:29]
	v_pk_fma_f32 v[28:29], v[60:61], v[28:29], v[44:45]
	v_cvt_pk_bf16_f32 v42, v26, v27
	v_cvt_pk_bf16_f32 v43, v28, v29
	global_store_dwordx2 v245, v[42:43], s[10:11] offset:1024
	v_pk_mul_f32 v[30:31], v[30:31], v[248:249] op_sel_hi:[1,0]
	v_pk_add_f32 v[62:63], v[62:63], 1.0 op_sel_hi:[1,0]
	v_pk_mul_f32 v[30:31], v[14:15], v[30:31]
	v_pk_fma_f32 v[30:31], v[62:63], v[30:31], v[46:47]
	v_pk_mul_f32 v[32:33], v[32:33], v[248:249] op_sel_hi:[1,0]
	v_pk_add_f32 v[64:65], v[64:65], 1.0 op_sel_hi:[1,0]
	v_pk_mul_f32 v[32:33], v[16:17], v[32:33]
	v_pk_fma_f32 v[32:33], v[64:65], v[32:33], v[48:49]
	v_cvt_pk_bf16_f32 v46, v30, v31
	v_cvt_pk_bf16_f32 v47, v32, v33
	global_store_dwordx2 v245, v[46:47], s[10:11] offset:1536
	s_add_i32 s21, s20, 6144
	s_mul_hi_u32 s7, s21, 0x38e38e39
	s_lshr_b32 s7, s7, 9
	s_mul_i32 s8, s7, 0x900
	s_sub_i32 s8, s21, s8
	s_lshl_b32 s9, s7, 11
	s_add_i32 s9, s9, s8
	s_add_i32 s9, s9, 0xffffff00
	s_lshl_b32 s10, s7, 8
	s_add_i32 s10, s10, s8
	s_cmpk_gt_i32 s8, 0xff
	s_cselect_b32 s9, s9, s10
	s_cselect_b32 s26, s12, s14
	s_cselect_b32 s27, s13, s15
	s_cselect_b32 s10, s7, 8
	s_lshl_b32 s9, s9, 12
	s_add_u32 s26, s26, s9
	s_addc_u32 s27, s27, 0
	s_add_i32 s10, s10, s82
	s_mul_i32 s10, s10, s24
	s_add_u32 s28, s58, s10
	s_addc_u32 s29, s59, 0
	s_add_u32 s28, s28, 0x0
	s_addc_u32 s29, s29, 0
	s_add_u32 s0, s28, 0x1000
	s_addc_u32 s1, s29, 0
	global_load_dwordx4 v[18:21], v244, s[26:27]
	global_load_dwordx4 v[22:25], v244, s[26:27] offset:1024
	global_load_dwordx4 v[26:29], v244, s[26:27] offset:2048
	global_load_dwordx4 v[30:33], v244, s[26:27] offset:3072
	global_load_dwordx4 v[34:37], v244, s[28:29]
	global_load_dwordx4 v[38:41], v244, s[28:29] offset:1024
	global_load_dwordx4 v[42:45], v244, s[28:29] offset:2048
	global_load_dwordx4 v[46:49], v244, s[28:29] offset:3072
	global_load_dwordx4 v[50:53], v244, s[0:1]
	global_load_dwordx4 v[54:57], v244, s[0:1] offset:1024
	global_load_dwordx4 v[58:61], v244, s[0:1] offset:2048
	global_load_dwordx4 v[62:65], v244, s[0:1] offset:3072
	s_waitcnt vmcnt(28)
; DI unsigned pk_bf16(float lo, float hi) { f32x2 v = {lo, hi}; bf16v2 b = __builtin_convertvector(v, bf16v2); return __builtin_bit_cast(unsigned, b); }
; DI float red64(float x) { for (int o = 32; o > 0; o >>= 1) x += __shfl_xor(x, o); return x; }
; DI void modnorm_rows(const Params& p, int l, int which  , bool from_inputs, bool skip_ctx, int w0, int wstride, int lane) {
;     ...
;   for (; i < nrows; i += wstride) {
;     const int row = rowof(i); const int b = row / TB, s = row % TB;
;     f32x4 v[4];
; #pragma unroll
;     for (int q = 0; q < 4; ++q) v[q] = vn[q];
;     if (i + wstride < nrows) {
;       const int rn = rowof(i + wstride); const float* src = xsrc_row(p, from_inputs, rn / TB, rn % TB);
; #pragma unroll
;       for (int q = 0; q < 4; ++q) vn[q] = *(const f32x4*)(src + q * 256 + lane * 4);
;     }
;     const float* mod = p.MOD + (size_t)(l * 9 + (s < NCTX ? 8 : b)) * 6144 + (which ? 3 * 1024 : 0);
;     f32x4 sh[4], sc[4];
; #pragma unroll
;     for (int q = 0; q < 4; ++q) { sh[q] = *(const f32x4*)(mod + q * 256 + lane * 4); sc[q] = *(const f32x4*)(mod + 1024 + q * 256 + lane * 4); }
;     float ss = 0.f;
; #pragma unroll
;     for (int q = 0; q < 4; ++q) ss += v[q][0] * v[q][0] + v[q][1] * v[q][1] + v[q][2] * v[q][2] + v[q][3] * v[q][3];
;     ss = red64(ss);
;     const float rs = rsqrtf(ss * (1.f / 1024.f) + EPSF);
;     bf16_t* dst = p.HY + (size_t)row * DM;
; #pragma unroll
;     for (int q = 0; q < 4; ++q) {
;       float o[4];
; #pragma unroll
;       for (int j = 0; j < 4; ++j) o[j] = (v[q][j] * rs * gg[q][j]) * (1.f + sc[q][j]) + sh[q][j];
;       u32x2 w = {pk_bf16(o[0], o[1]), pk_bf16(o[2], o[3])};
;       *(u32x2*)(dst + q * 256 + lane * 4) = w;
;     }
	v_pk_mul_f32 v[246:247], v[66:67], v[66:67]
	v_pk_fma_f32 v[246:247], v[68:69], v[68:69], v[246:247]
	v_pk_fma_f32 v[246:247], v[70:71], v[70:71], v[246:247]
	v_pk_fma_f32 v[246:247], v[72:73], v[72:73], v[246:247]
	v_pk_fma_f32 v[246:247], v[74:75], v[74:75], v[246:247]
	v_pk_fma_f32 v[246:247], v[76:77], v[76:77], v[246:247]
	v_pk_fma_f32 v[246:247], v[78:79], v[78:79], v[246:247]
	v_pk_fma_f32 v[246:247], v[80:81], v[80:81], v[246:247]
	s_nop 0
	v_add_f32_e32 v246, v246, v247
	s_nop 1
	v_add_f32_dpp v246, v246, v246 quad_perm:[1,0,3,2] row_mask:0xf bank_mask:0xf
	s_nop 1
	v_add_f32_dpp v246, v246, v246 quad_perm:[2,3,0,1] row_mask:0xf bank_mask:0xf
	s_nop 1
	v_add_f32_dpp v246, v246, v246 row_half_mirror row_mask:0xf bank_mask:0xf
	s_nop 1
	v_add_f32_dpp v246, v246, v246 row_mirror row_mask:0xf bank_mask:0xf
	s_nop 1
	v_add_f32_dpp v246, v246, v246 row_bcast:15 row_mask:0xa bank_mask:0xf
	s_nop 1
	v_add_f32_dpp v246, v246, v246 row_bcast:31 row_mask:0xc bank_mask:0xf
	s_nop 1
	v_readlane_b32 s0, v246, 63
	s_add_i32 s21, s20, 2048
	s_lshl_b32 s21, s21, 11
	s_add_u32 s10, s16, s21
	s_addc_u32 s11, s17, 0
	v_mov_b32_e32 v248, s0
	v_fmamk_f32 v248, v248, 0x3a800000, v143
	v_rsq_f32_e32 v248, v248
	s_nop 0
	v_pk_mul_f32 v[66:67], v[66:67], v[248:249] op_sel_hi:[1,0]
	v_pk_add_f32 v[98:99], v[98:99], 1.0 op_sel_hi:[1,0]
	v_pk_mul_f32 v[66:67], v[2:3], v[66:67]
	v_pk_fma_f32 v[66:67], v[98:99], v[66:67], v[82:83]
	v_pk_mul_f32 v[68:69], v[68:69], v[248:249] op_sel_hi:[1,0]
	v_pk_add_f32 v[100:101], v[100:101], 1.0 op_sel_hi:[1,0]
	v_pk_mul_f32 v[68:69], v[4:5], v[68:69]
	v_pk_fma_f32 v[68:69], v[100:101], v[68:69], v[84:85]
	v_cvt_pk_bf16_f32 v82, v66, v67
	v_cvt_pk_bf16_f32 v83, v68, v69
	global_store_dwordx2 v245, v[82:83], s[10:11]
	v_pk_mul_f32 v[70:71], v[70:71], v[248:249] op_sel_hi:[1,0]
	v_pk_add_f32 v[102:103], v[102:103], 1.0 op_sel_hi:[1,0]
	v_pk_mul_f32 v[70:71], v[6:7], v[70:71]
	v_pk_fma_f32 v[70:71], v[102:103], v[70:71], v[86:87]
	v_pk_mul_f32 v[72:73], v[72:73], v[248:249] op_sel_hi:[1,0]
	v_pk_add_f32 v[104:105], v[104:105], 1.0 op_sel_hi:[1,0]
	v_pk_mul_f32 v[72:73], v[8:9], v[72:73]
	v_pk_fma_f32 v[72:73], v[104:105], v[72:73], v[88:89]
	v_cvt_pk_bf16_f32 v86, v70, v71
	v_cvt_pk_bf16_f32 v87, v72, v73
	global_store_dwordx2 v245, v[86:87], s[10:11] offset:512
	v_pk_mul_f32 v[74:75], v[74:75], v[248:249] op_sel_hi:[1,0]
	v_pk_add_f32 v[106:107], v[106:107], 1.0 op_sel_hi:[1,0]
	v_pk_mul_f32 v[74:75], v[10:11], v[74:75]
	v_pk_fma_f32 v[74:75], v[106:107], v[74:75], v[90:91]
	v_pk_mul_f32 v[76:77], v[76:77], v[248:249] op_sel_hi:[1,0]
	v_pk_add_f32 v[108:109], v[108:109], 1.0 op_sel_hi:[1,0]
	v_pk_mul_f32 v[76:77], v[12:13], v[76:77]
	v_pk_fma_f32 v[76:77], v[108:109], v[76:77], v[92:93]
	v_cvt_pk_bf16_f32 v90, v74, v75
	v_cvt_pk_bf16_f32 v91, v76, v77
	global_store_dwordx2 v245, v[90:91], s[10:11] offset:1024
	v_pk_mul_f32 v[78:79], v[78:79], v[248:249] op_sel_hi:[1,0]
	v_pk_add_f32 v[118:119], v[118:119], 1.0 op_sel_hi:[1,0]
	v_pk_mul_f32 v[78:79], v[14:15], v[78:79]
	v_pk_fma_f32 v[78:79], v[118:119], v[78:79], v[94:95]
	v_pk_mul_f32 v[80:81], v[80:81], v[248:249] op_sel_hi:[1,0]
	v_pk_add_f32 v[120:121], v[120:121], 1.0 op_sel_hi:[1,0]
	v_pk_mul_f32 v[80:81], v[16:17], v[80:81]
	v_pk_fma_f32 v[80:81], v[120:121], v[80:81], v[96:97]
	v_cvt_pk_bf16_f32 v94, v78, v79
	v_cvt_pk_bf16_f32 v95, v80, v81
	global_store_dwordx2 v245, v[94:95], s[10:11] offset:1536
	s_add_i32 s21, s20, 8192
	s_mul_hi_u32 s7, s21, 0x38e38e39
	s_lshr_b32 s7, s7, 9
	s_mul_i32 s8, s7, 0x900
	s_sub_i32 s8, s21, s8
	s_lshl_b32 s9, s7, 11
	s_add_i32 s9, s9, s8
	s_add_i32 s9, s9, 0xffffff00
	s_lshl_b32 s10, s7, 8
	s_add_i32 s10, s10, s8
	s_cmpk_gt_i32 s8, 0xff
	s_cselect_b32 s9, s9, s10
	s_cselect_b32 s26, s12, s14
	s_cselect_b32 s27, s13, s15
	s_cselect_b32 s10, s7, 8
	s_lshl_b32 s9, s9, 12
	s_add_u32 s26, s26, s9
	s_addc_u32 s27, s27, 0
	s_add_i32 s10, s10, s82
	s_mul_i32 s10, s10, s24
	s_add_u32 s28, s58, s10
	s_addc_u32 s29, s59, 0
	s_add_u32 s28, s28, 0x0
	s_addc_u32 s29, s29, 0
	s_add_u32 s0, s28, 0x1000
	s_addc_u32 s1, s29, 0
	global_load_dwordx4 v[66:69], v244, s[26:27]
	global_load_dwordx4 v[70:73], v244, s[26:27] offset:1024
	global_load_dwordx4 v[74:77], v244, s[26:27] offset:2048
	global_load_dwordx4 v[78:81], v244, s[26:27] offset:3072
	global_load_dwordx4 v[82:85], v244, s[28:29]
	global_load_dwordx4 v[86:89], v244, s[28:29] offset:1024
	global_load_dwordx4 v[90:93], v244, s[28:29] offset:2048
	global_load_dwordx4 v[94:97], v244, s[28:29] offset:3072
	global_load_dwordx4 v[98:101], v244, s[0:1]
	global_load_dwordx4 v[102:105], v244, s[0:1] offset:1024
	global_load_dwordx4 v[106:109], v244, s[0:1] offset:2048
	global_load_dwordx4 v[118:121], v244, s[0:1] offset:3072
	s_waitcnt vmcnt(32)
; DI unsigned pk_bf16(float lo, float hi) { f32x2 v = {lo, hi}; bf16v2 b = __builtin_convertvector(v, bf16v2); return __builtin_bit_cast(unsigned, b); }
; DI float red64(float x) { for (int o = 32; o > 0; o >>= 1) x += __shfl_xor(x, o); return x; }
; DI void modnorm_rows(const Params& p, int l, int which  , bool from_inputs, bool skip_ctx, int w0, int wstride, int lane) {
;     ...
;   for (; i < nrows; i += wstride) {
;     const int row = rowof(i); const int b = row / TB, s = row % TB;
;     f32x4 v[4];
; #pragma unroll
;     for (int q = 0; q < 4; ++q) v[q] = vn[q];
;     if (i + wstride < nrows) {
;       const int rn = rowof(i + wstride); const float* src = xsrc_row(p, from_inputs, rn / TB, rn % TB);
; #pragma unroll
;       for (int q = 0; q < 4; ++q) vn[q] = *(const f32x4*)(src + q * 256 + lane * 4);
;     }
;     const float* mod = p.MOD + (size_t)(l * 9 + (s < NCTX ? 8 : b)) * 6144 + (which ? 3 * 1024 : 0);
;     f32x4 sh[4], sc[4];
; #pragma unroll
;     for (int q = 0; q < 4; ++q) { sh[q] = *(const f32x4*)(mod + q * 256 + lane * 4); sc[q] = *(const f32x4*)(mod + 1024 + q * 256 + lane * 4); }
;     float ss = 0.f;
; #pragma unroll
;     for (int q = 0; q < 4; ++q) ss += v[q][0] * v[q][0] + v[q][1] * v[q][1] + v[q][2] * v[q][2] + v[q][3] * v[q][3];
;     ss = red64(ss);
;     const float rs = rsqrtf(ss * (1.f / 1024.f) + EPSF);
;     bf16_t* dst = p.HY + (size_t)row * DM;
; #pragma unroll
;     for (int q = 0; q < 4; ++q) {
;       float o[4];
; #pragma unroll
;       for (int j = 0; j < 4; ++j) o[j] = (v[q][j] * rs * gg[q][j]) * (1.f + sc[q][j]) + sh[q][j];
;       u32x2 w = {pk_bf16(o[0], o[1]), pk_bf16(o[2], o[3])};
;       *(u32x2*)(dst + q * 256 + lane * 4) = w;
;     }
	v_pk_mul_f32 v[246:247], v[122:123], v[122:123]
	v_pk_fma_f32 v[246:247], v[124:125], v[124:125], v[246:247]
	v_pk_fma_f32 v[246:247], v[126:127], v[126:127], v[246:247]
	v_pk_fma_f32 v[246:247], v[128:129], v[128:129], v[246:247]
	v_pk_fma_f32 v[246:247], v[130:131], v[130:131], v[246:247]
	v_pk_fma_f32 v[246:247], v[132:133], v[132:133], v[246:247]
	v_pk_fma_f32 v[246:247], v[134:135], v[134:135], v[246:247]
	v_pk_fma_f32 v[246:247], v[136:137], v[136:137], v[246:247]
	s_nop 0
	v_add_f32_e32 v246, v246, v247
	s_nop 1
	v_add_f32_dpp v246, v246, v246 quad_perm:[1,0,3,2] row_mask:0xf bank_mask:0xf
	s_nop 1
	v_add_f32_dpp v246, v246, v246 quad_perm:[2,3,0,1] row_mask:0xf bank_mask:0xf
	s_nop 1
	v_add_f32_dpp v246, v246, v246 row_half_mirror row_mask:0xf bank_mask:0xf
	s_nop 1
	v_add_f32_dpp v246, v246, v246 row_mirror row_mask:0xf bank_mask:0xf
	s_nop 1
	v_add_f32_dpp v246, v246, v246 row_bcast:15 row_mask:0xa bank_mask:0xf
	s_nop 1
	v_add_f32_dpp v246, v246, v246 row_bcast:31 row_mask:0xc bank_mask:0xf
	s_nop 1
	v_readlane_b32 s0, v246, 63
	s_add_i32 s21, s20, 4096
	s_lshl_b32 s21, s21, 11
	s_add_u32 s10, s16, s21
	s_addc_u32 s11, s17, 0
	v_mov_b32_e32 v248, s0
	v_fmamk_f32 v248, v248, 0x3a800000, v143
	v_rsq_f32_e32 v248, v248
	s_nop 0
	v_pk_mul_f32 v[122:123], v[122:123], v[248:249] op_sel_hi:[1,0]
	v_pk_add_f32 v[176:177], v[176:177], 1.0 op_sel_hi:[1,0]
	v_pk_mul_f32 v[122:123], v[2:3], v[122:123]
	v_pk_fma_f32 v[122:123], v[176:177], v[122:123], v[160:161]
	v_pk_mul_f32 v[124:125], v[124:125], v[248:249] op_sel_hi:[1,0]
	v_pk_add_f32 v[178:179], v[178:179], 1.0 op_sel_hi:[1,0]
	v_pk_mul_f32 v[124:125], v[4:5], v[124:125]
	v_pk_fma_f32 v[124:125], v[178:179], v[124:125], v[162:163]
	v_cvt_pk_bf16_f32 v160, v122, v123
	v_cvt_pk_bf16_f32 v161, v124, v125
	global_store_dwordx2 v245, v[160:161], s[10:11]
	v_pk_mul_f32 v[126:127], v[126:127], v[248:249] op_sel_hi:[1,0]
	v_pk_add_f32 v[180:181], v[180:181], 1.0 op_sel_hi:[1,0]
	v_pk_mul_f32 v[126:127], v[6:7], v[126:127]
	v_pk_fma_f32 v[126:127], v[180:181], v[126:127], v[164:165]
	v_pk_mul_f32 v[128:129], v[128:129], v[248:249] op_sel_hi:[1,0]
	v_pk_add_f32 v[182:183], v[182:183], 1.0 op_sel_hi:[1,0]
	v_pk_mul_f32 v[128:129], v[8:9], v[128:129]
	v_pk_fma_f32 v[128:129], v[182:183], v[128:129], v[166:167]
	v_cvt_pk_bf16_f32 v164, v126, v127
	v_cvt_pk_bf16_f32 v165, v128, v129
	global_store_dwordx2 v245, v[164:165], s[10:11] offset:512
	v_pk_mul_f32 v[130:131], v[130:131], v[248:249] op_sel_hi:[1,0]
	v_pk_add_f32 v[184:185], v[184:185], 1.0 op_sel_hi:[1,0]
	v_pk_mul_f32 v[130:131], v[10:11], v[130:131]
	v_pk_fma_f32 v[130:131], v[184:185], v[130:131], v[168:169]
	v_pk_mul_f32 v[132:133], v[132:133], v[248:249] op_sel_hi:[1,0]
	v_pk_add_f32 v[186:187], v[186:187], 1.0 op_sel_hi:[1,0]
	v_pk_mul_f32 v[132:133], v[12:13], v[132:133]
	v_pk_fma_f32 v[132:133], v[186:187], v[132:133], v[170:171]
	v_cvt_pk_bf16_f32 v168, v130, v131
	v_cvt_pk_bf16_f32 v169, v132, v133
	global_store_dwordx2 v245, v[168:169], s[10:11] offset:1024
	v_pk_mul_f32 v[134:135], v[134:135], v[248:249] op_sel_hi:[1,0]
	v_pk_add_f32 v[188:189], v[188:189], 1.0 op_sel_hi:[1,0]
	v_pk_mul_f32 v[134:135], v[14:15], v[134:135]
	v_pk_fma_f32 v[134:135], v[188:189], v[134:135], v[172:173]
	v_pk_mul_f32 v[136:137], v[136:137], v[248:249] op_sel_hi:[1,0]
	v_pk_add_f32 v[190:191], v[190:191], 1.0 op_sel_hi:[1,0]
	v_pk_mul_f32 v[136:137], v[16:17], v[136:137]
	v_pk_fma_f32 v[136:137], v[190:191], v[136:137], v[174:175]
	v_cvt_pk_bf16_f32 v172, v134, v135
	v_cvt_pk_bf16_f32 v173, v136, v137
	global_store_dwordx2 v245, v[172:173], s[10:11] offset:1536
	s_add_i32 s21, s20, 10240
	s_mul_hi_u32 s7, s21, 0x38e38e39
	s_lshr_b32 s7, s7, 9
	s_mul_i32 s8, s7, 0x900
	s_sub_i32 s8, s21, s8
	s_lshl_b32 s9, s7, 11
	s_add_i32 s9, s9, s8
	s_add_i32 s9, s9, 0xffffff00
	s_lshl_b32 s10, s7, 8
	s_add_i32 s10, s10, s8
	s_cmpk_gt_i32 s8, 0xff
	s_cselect_b32 s9, s9, s10
	s_cselect_b32 s26, s12, s14
	s_cselect_b32 s27, s13, s15
	s_cselect_b32 s10, s7, 8
	s_lshl_b32 s9, s9, 12
	s_add_u32 s26, s26, s9
	s_addc_u32 s27, s27, 0
	s_add_i32 s10, s10, s82
	s_mul_i32 s10, s10, s24
	s_add_u32 s28, s58, s10
	s_addc_u32 s29, s59, 0
	s_add_u32 s28, s28, 0x0
	s_addc_u32 s29, s29, 0
	s_add_u32 s0, s28, 0x1000
	s_addc_u32 s1, s29, 0
	global_load_dwordx4 v[122:125], v244, s[26:27]
	global_load_dwordx4 v[126:129], v244, s[26:27] offset:1024
	global_load_dwordx4 v[130:133], v244, s[26:27] offset:2048
	global_load_dwordx4 v[134:137], v244, s[26:27] offset:3072
	global_load_dwordx4 v[160:163], v244, s[28:29]
	global_load_dwordx4 v[164:167], v244, s[28:29] offset:1024
	global_load_dwordx4 v[168:171], v244, s[28:29] offset:2048
	global_load_dwordx4 v[172:175], v244, s[28:29] offset:3072
	global_load_dwordx4 v[176:179], v244, s[0:1]
	global_load_dwordx4 v[180:183], v244, s[0:1] offset:1024
	global_load_dwordx4 v[184:187], v244, s[0:1] offset:2048
	global_load_dwordx4 v[188:191], v244, s[0:1] offset:3072
	s_waitcnt vmcnt(32)
; DI unsigned pk_bf16(float lo, float hi) { f32x2 v = {lo, hi}; bf16v2 b = __builtin_convertvector(v, bf16v2); return __builtin_bit_cast(unsigned, b); }
; DI float red64(float x) { for (int o = 32; o > 0; o >>= 1) x += __shfl_xor(x, o); return x; }
; DI void modnorm_rows(const Params& p, int l, int which  , bool from_inputs, bool skip_ctx, int w0, int wstride, int lane) {
;     ...
;   for (; i < nrows; i += wstride) {
;     const int row = rowof(i); const int b = row / TB, s = row % TB;
;     f32x4 v[4];
; #pragma unroll
;     for (int q = 0; q < 4; ++q) v[q] = vn[q];
;     if (i + wstride < nrows) {
;       const int rn = rowof(i + wstride); const float* src = xsrc_row(p, from_inputs, rn / TB, rn % TB);
; #pragma unroll
;       for (int q = 0; q < 4; ++q) vn[q] = *(const f32x4*)(src + q * 256 + lane * 4);
;     }
;     const float* mod = p.MOD + (size_t)(l * 9 + (s < NCTX ? 8 : b)) * 6144 + (which ? 3 * 1024 : 0);
;     f32x4 sh[4], sc[4];
; #pragma unroll
;     for (int q = 0; q < 4; ++q) { sh[q] = *(const f32x4*)(mod + q * 256 + lane * 4); sc[q] = *(const f32x4*)(mod + 1024 + q * 256 + lane * 4); }
;     float ss = 0.f;
; #pragma unroll
;     for (int q = 0; q < 4; ++q) ss += v[q][0] * v[q][0] + v[q][1] * v[q][1] + v[q][2] * v[q][2] + v[q][3] * v[q][3];
;     ss = red64(ss);
;     const float rs = rsqrtf(ss * (1.f / 1024.f) + EPSF);
;     bf16_t* dst = p.HY + (size_t)row * DM;
; #pragma unroll
;     for (int q = 0; q < 4; ++q) {
;       float o[4];
; #pragma unroll
;       for (int j = 0; j < 4; ++j) o[j] = (v[q][j] * rs * gg[q][j]) * (1.f + sc[q][j]) + sh[q][j];
;       u32x2 w = {pk_bf16(o[0], o[1]), pk_bf16(o[2], o[3])};
;       *(u32x2*)(dst + q * 256 + lane * 4) = w;
;     }
	v_pk_mul_f32 v[246:247], v[18:19], v[18:19]
	v_pk_fma_f32 v[246:247], v[20:21], v[20:21], v[246:247]
	v_pk_fma_f32 v[246:247], v[22:23], v[22:23], v[246:247]
	v_pk_fma_f32 v[246:247], v[24:25], v[24:25], v[246:247]
	v_pk_fma_f32 v[246:247], v[26:27], v[26:27], v[246:247]
	v_pk_fma_f32 v[246:247], v[28:29], v[28:29], v[246:247]
	v_pk_fma_f32 v[246:247], v[30:31], v[30:31], v[246:247]
	v_pk_fma_f32 v[246:247], v[32:33], v[32:33], v[246:247]
	s_nop 0
	v_add_f32_e32 v246, v246, v247
	s_nop 1
	v_add_f32_dpp v246, v246, v246 quad_perm:[1,0,3,2] row_mask:0xf bank_mask:0xf
	s_nop 1
	v_add_f32_dpp v246, v246, v246 quad_perm:[2,3,0,1] row_mask:0xf bank_mask:0xf
	s_nop 1
	v_add_f32_dpp v246, v246, v246 row_half_mirror row_mask:0xf bank_mask:0xf
	s_nop 1
	v_add_f32_dpp v246, v246, v246 row_mirror row_mask:0xf bank_mask:0xf
	s_nop 1
	v_add_f32_dpp v246, v246, v246 row_bcast:15 row_mask:0xa bank_mask:0xf
	s_nop 1
	v_add_f32_dpp v246, v246, v246 row_bcast:31 row_mask:0xc bank_mask:0xf
	s_nop 1
	v_readlane_b32 s0, v246, 63
	s_add_i32 s21, s20, 6144
	s_lshl_b32 s21, s21, 11
	s_add_u32 s10, s16, s21
	s_addc_u32 s11, s17, 0
	v_mov_b32_e32 v248, s0
	v_fmamk_f32 v248, v248, 0x3a800000, v143
	v_rsq_f32_e32 v248, v248
	s_nop 0
	v_pk_mul_f32 v[18:19], v[18:19], v[248:249] op_sel_hi:[1,0]
	v_pk_add_f32 v[50:51], v[50:51], 1.0 op_sel_hi:[1,0]
	v_pk_mul_f32 v[18:19], v[2:3], v[18:19]
	v_pk_fma_f32 v[18:19], v[50:51], v[18:19], v[34:35]
	v_pk_mul_f32 v[20:21], v[20:21], v[248:249] op_sel_hi:[1,0]
	v_pk_add_f32 v[52:53], v[52:53], 1.0 op_sel_hi:[1,0]
	v_pk_mul_f32 v[20:21], v[4:5], v[20:21]
	v_pk_fma_f32 v[20:21], v[52:53], v[20:21], v[36:37]
	v_cvt_pk_bf16_f32 v34, v18, v19
	v_cvt_pk_bf16_f32 v35, v20, v21
	global_store_dwordx2 v245, v[34:35], s[10:11]
	v_pk_mul_f32 v[22:23], v[22:23], v[248:249] op_sel_hi:[1,0]
	v_pk_add_f32 v[54:55], v[54:55], 1.0 op_sel_hi:[1,0]
	v_pk_mul_f32 v[22:23], v[6:7], v[22:23]
	v_pk_fma_f32 v[22:23], v[54:55], v[22:23], v[38:39]
	v_pk_mul_f32 v[24:25], v[24:25], v[248:249] op_sel_hi:[1,0]
	v_pk_add_f32 v[56:57], v[56:57], 1.0 op_sel_hi:[1,0]
	v_pk_mul_f32 v[24:25], v[8:9], v[24:25]
	v_pk_fma_f32 v[24:25], v[56:57], v[24:25], v[40:41]
	v_cvt_pk_bf16_f32 v38, v22, v23
	v_cvt_pk_bf16_f32 v39, v24, v25
	global_store_dwordx2 v245, v[38:39], s[10:11] offset:512
	v_pk_mul_f32 v[26:27], v[26:27], v[248:249] op_sel_hi:[1,0]
	v_pk_add_f32 v[58:59], v[58:59], 1.0 op_sel_hi:[1,0]
	v_pk_mul_f32 v[26:27], v[10:11], v[26:27]
	v_pk_fma_f32 v[26:27], v[58:59], v[26:27], v[42:43]
	v_pk_mul_f32 v[28:29], v[28:29], v[248:249] op_sel_hi:[1,0]
	v_pk_add_f32 v[60:61], v[60:61], 1.0 op_sel_hi:[1,0]
	v_pk_mul_f32 v[28:29], v[12:13], v[28:29]
	v_pk_fma_f32 v[28:29], v[60:61], v[28:29], v[44:45]
	v_cvt_pk_bf16_f32 v42, v26, v27
	v_cvt_pk_bf16_f32 v43, v28, v29
	global_store_dwordx2 v245, v[42:43], s[10:11] offset:1024
	v_pk_mul_f32 v[30:31], v[30:31], v[248:249] op_sel_hi:[1,0]
	v_pk_add_f32 v[62:63], v[62:63], 1.0 op_sel_hi:[1,0]
	v_pk_mul_f32 v[30:31], v[14:15], v[30:31]
	v_pk_fma_f32 v[30:31], v[62:63], v[30:31], v[46:47]
	v_pk_mul_f32 v[32:33], v[32:33], v[248:249] op_sel_hi:[1,0]
	v_pk_add_f32 v[64:65], v[64:65], 1.0 op_sel_hi:[1,0]
	v_pk_mul_f32 v[32:33], v[16:17], v[32:33]
	v_pk_fma_f32 v[32:33], v[64:65], v[32:33], v[48:49]
	v_cvt_pk_bf16_f32 v46, v30, v31
	v_cvt_pk_bf16_f32 v47, v32, v33
	global_store_dwordx2 v245, v[46:47], s[10:11] offset:1536
	s_add_i32 s21, s20, 12288
	s_mul_hi_u32 s7, s21, 0x38e38e39
	s_lshr_b32 s7, s7, 9
	s_mul_i32 s8, s7, 0x900
	s_sub_i32 s8, s21, s8
	s_lshl_b32 s9, s7, 11
	s_add_i32 s9, s9, s8
	s_add_i32 s9, s9, 0xffffff00
	s_lshl_b32 s10, s7, 8
	s_add_i32 s10, s10, s8
	s_cmpk_gt_i32 s8, 0xff
	s_cselect_b32 s9, s9, s10
	s_cselect_b32 s26, s12, s14
	s_cselect_b32 s27, s13, s15
	s_cselect_b32 s10, s7, 8
	s_lshl_b32 s9, s9, 12
	s_add_u32 s26, s26, s9
	s_addc_u32 s27, s27, 0
	s_add_i32 s10, s10, s82
	s_mul_i32 s10, s10, s24
	s_add_u32 s28, s58, s10
	s_addc_u32 s29, s59, 0
	s_add_u32 s28, s28, 0x0
	s_addc_u32 s29, s29, 0
	s_add_u32 s0, s28, 0x1000
	s_addc_u32 s1, s29, 0
	global_load_dwordx4 v[18:21], v244, s[26:27]
	global_load_dwordx4 v[22:25], v244, s[26:27] offset:1024
	global_load_dwordx4 v[26:29], v244, s[26:27] offset:2048
	global_load_dwordx4 v[30:33], v244, s[26:27] offset:3072
	global_load_dwordx4 v[34:37], v244, s[28:29]
	global_load_dwordx4 v[38:41], v244, s[28:29] offset:1024
	global_load_dwordx4 v[42:45], v244, s[28:29] offset:2048
	global_load_dwordx4 v[46:49], v244, s[28:29] offset:3072
	global_load_dwordx4 v[50:53], v244, s[0:1]
	global_load_dwordx4 v[54:57], v244, s[0:1] offset:1024
	global_load_dwordx4 v[58:61], v244, s[0:1] offset:2048
	global_load_dwordx4 v[62:65], v244, s[0:1] offset:3072
	s_waitcnt vmcnt(32)
; DI unsigned pk_bf16(float lo, float hi) { f32x2 v = {lo, hi}; bf16v2 b = __builtin_convertvector(v, bf16v2); return __builtin_bit_cast(unsigned, b); }
; DI float red64(float x) { for (int o = 32; o > 0; o >>= 1) x += __shfl_xor(x, o); return x; }
; DI void modnorm_rows(const Params& p, int l, int which  , bool from_inputs, bool skip_ctx, int w0, int wstride, int lane) {
;     ...
;   for (; i < nrows; i += wstride) {
;     const int row = rowof(i); const int b = row / TB, s = row % TB;
;     f32x4 v[4];
; #pragma unroll
;     for (int q = 0; q < 4; ++q) v[q] = vn[q];
;     if (i + wstride < nrows) {
;       const int rn = rowof(i + wstride); const float* src = xsrc_row(p, from_inputs, rn / TB, rn % TB);
; #pragma unroll
;       for (int q = 0; q < 4; ++q) vn[q] = *(const f32x4*)(src + q * 256 + lane * 4);
;     }
;     const float* mod = p.MOD + (size_t)(l * 9 + (s < NCTX ? 8 : b)) * 6144 + (which ? 3 * 1024 : 0);
;     f32x4 sh[4], sc[4];
; #pragma unroll
;     for (int q = 0; q < 4; ++q) { sh[q] = *(const f32x4*)(mod + q * 256 + lane * 4); sc[q] = *(const f32x4*)(mod + 1024 + q * 256 + lane * 4); }
;     float ss = 0.f;
; #pragma unroll
;     for (int q = 0; q < 4; ++q) ss += v[q][0] * v[q][0] + v[q][1] * v[q][1] + v[q][2] * v[q][2] + v[q][3] * v[q][3];
;     ss = red64(ss);
;     const float rs = rsqrtf(ss * (1.f / 1024.f) + EPSF);
;     bf16_t* dst = p.HY + (size_t)row * DM;
; #pragma unroll
;     for (int q = 0; q < 4; ++q) {
;       float o[4];
; #pragma unroll
;       for (int j = 0; j < 4; ++j) o[j] = (v[q][j] * rs * gg[q][j]) * (1.f + sc[q][j]) + sh[q][j];
;       u32x2 w = {pk_bf16(o[0], o[1]), pk_bf16(o[2], o[3])};
;       *(u32x2*)(dst + q * 256 + lane * 4) = w;
;     }
	v_pk_mul_f32 v[246:247], v[66:67], v[66:67]
	v_pk_fma_f32 v[246:247], v[68:69], v[68:69], v[246:247]
	v_pk_fma_f32 v[246:247], v[70:71], v[70:71], v[246:247]
	v_pk_fma_f32 v[246:247], v[72:73], v[72:73], v[246:247]
	v_pk_fma_f32 v[246:247], v[74:75], v[74:75], v[246:247]
	v_pk_fma_f32 v[246:247], v[76:77], v[76:77], v[246:247]
	v_pk_fma_f32 v[246:247], v[78:79], v[78:79], v[246:247]
	v_pk_fma_f32 v[246:247], v[80:81], v[80:81], v[246:247]
	s_nop 0
	v_add_f32_e32 v246, v246, v247
	s_nop 1
	v_add_f32_dpp v246, v246, v246 quad_perm:[1,0,3,2] row_mask:0xf bank_mask:0xf
	s_nop 1
	v_add_f32_dpp v246, v246, v246 quad_perm:[2,3,0,1] row_mask:0xf bank_mask:0xf
	s_nop 1
	v_add_f32_dpp v246, v246, v246 row_half_mirror row_mask:0xf bank_mask:0xf
	s_nop 1
	v_add_f32_dpp v246, v246, v246 row_mirror row_mask:0xf bank_mask:0xf
	s_nop 1
	v_add_f32_dpp v246, v246, v246 row_bcast:15 row_mask:0xa bank_mask:0xf
	s_nop 1
	v_add_f32_dpp v246, v246, v246 row_bcast:31 row_mask:0xc bank_mask:0xf
	s_nop 1
	v_readlane_b32 s0, v246, 63
	s_add_i32 s21, s20, 8192
	s_lshl_b32 s21, s21, 11
	s_add_u32 s10, s16, s21
	s_addc_u32 s11, s17, 0
	v_mov_b32_e32 v248, s0
	v_fmamk_f32 v248, v248, 0x3a800000, v143
	v_rsq_f32_e32 v248, v248
	s_nop 0
	v_pk_mul_f32 v[66:67], v[66:67], v[248:249] op_sel_hi:[1,0]
	v_pk_add_f32 v[98:99], v[98:99], 1.0 op_sel_hi:[1,0]
	v_pk_mul_f32 v[66:67], v[2:3], v[66:67]
	v_pk_fma_f32 v[66:67], v[98:99], v[66:67], v[82:83]
	v_pk_mul_f32 v[68:69], v[68:69], v[248:249] op_sel_hi:[1,0]
	v_pk_add_f32 v[100:101], v[100:101], 1.0 op_sel_hi:[1,0]
	v_pk_mul_f32 v[68:69], v[4:5], v[68:69]
	v_pk_fma_f32 v[68:69], v[100:101], v[68:69], v[84:85]
	v_cvt_pk_bf16_f32 v82, v66, v67
	v_cvt_pk_bf16_f32 v83, v68, v69
	global_store_dwordx2 v245, v[82:83], s[10:11]
	v_pk_mul_f32 v[70:71], v[70:71], v[248:249] op_sel_hi:[1,0]
	v_pk_add_f32 v[102:103], v[102:103], 1.0 op_sel_hi:[1,0]
	v_pk_mul_f32 v[70:71], v[6:7], v[70:71]
	v_pk_fma_f32 v[70:71], v[102:103], v[70:71], v[86:87]
	v_pk_mul_f32 v[72:73], v[72:73], v[248:249] op_sel_hi:[1,0]
	v_pk_add_f32 v[104:105], v[104:105], 1.0 op_sel_hi:[1,0]
	v_pk_mul_f32 v[72:73], v[8:9], v[72:73]
	v_pk_fma_f32 v[72:73], v[104:105], v[72:73], v[88:89]
	v_cvt_pk_bf16_f32 v86, v70, v71
	v_cvt_pk_bf16_f32 v87, v72, v73
	global_store_dwordx2 v245, v[86:87], s[10:11] offset:512
	v_pk_mul_f32 v[74:75], v[74:75], v[248:249] op_sel_hi:[1,0]
	v_pk_add_f32 v[106:107], v[106:107], 1.0 op_sel_hi:[1,0]
	v_pk_mul_f32 v[74:75], v[10:11], v[74:75]
	v_pk_fma_f32 v[74:75], v[106:107], v[74:75], v[90:91]
	v_pk_mul_f32 v[76:77], v[76:77], v[248:249] op_sel_hi:[1,0]
	v_pk_add_f32 v[108:109], v[108:109], 1.0 op_sel_hi:[1,0]
	v_pk_mul_f32 v[76:77], v[12:13], v[76:77]
	v_pk_fma_f32 v[76:77], v[108:109], v[76:77], v[92:93]
	v_cvt_pk_bf16_f32 v90, v74, v75
	v_cvt_pk_bf16_f32 v91, v76, v77
	global_store_dwordx2 v245, v[90:91], s[10:11] offset:1024
	v_pk_mul_f32 v[78:79], v[78:79], v[248:249] op_sel_hi:[1,0]
	v_pk_add_f32 v[118:119], v[118:119], 1.0 op_sel_hi:[1,0]
	v_pk_mul_f32 v[78:79], v[14:15], v[78:79]
	v_pk_fma_f32 v[78:79], v[118:119], v[78:79], v[94:95]
	v_pk_mul_f32 v[80:81], v[80:81], v[248:249] op_sel_hi:[1,0]
	v_pk_add_f32 v[120:121], v[120:121], 1.0 op_sel_hi:[1,0]
	v_pk_mul_f32 v[80:81], v[16:17], v[80:81]
	v_pk_fma_f32 v[80:81], v[120:121], v[80:81], v[96:97]
	v_cvt_pk_bf16_f32 v94, v78, v79
	v_cvt_pk_bf16_f32 v95, v80, v81
	global_store_dwordx2 v245, v[94:95], s[10:11] offset:1536
	s_add_i32 s21, s20, 14336
	s_mul_hi_u32 s7, s21, 0x38e38e39
	s_lshr_b32 s7, s7, 9
	s_mul_i32 s8, s7, 0x900
	s_sub_i32 s8, s21, s8
	s_lshl_b32 s9, s7, 11
	s_add_i32 s9, s9, s8
	s_add_i32 s9, s9, 0xffffff00
	s_lshl_b32 s10, s7, 8
	s_add_i32 s10, s10, s8
	s_cmpk_gt_i32 s8, 0xff
	s_cselect_b32 s9, s9, s10
	s_cselect_b32 s26, s12, s14
	s_cselect_b32 s27, s13, s15
	s_cselect_b32 s10, s7, 8
	s_lshl_b32 s9, s9, 12
	s_add_u32 s26, s26, s9
	s_addc_u32 s27, s27, 0
	s_add_i32 s10, s10, s82
	s_mul_i32 s10, s10, s24
	s_add_u32 s28, s58, s10
	s_addc_u32 s29, s59, 0
	s_add_u32 s28, s28, 0x0
	s_addc_u32 s29, s29, 0
	s_add_u32 s0, s28, 0x1000
	s_addc_u32 s1, s29, 0
	global_load_dwordx4 v[66:69], v244, s[26:27]
	global_load_dwordx4 v[70:73], v244, s[26:27] offset:1024
	global_load_dwordx4 v[74:77], v244, s[26:27] offset:2048
	global_load_dwordx4 v[78:81], v244, s[26:27] offset:3072
	global_load_dwordx4 v[82:85], v244, s[28:29]
	global_load_dwordx4 v[86:89], v244, s[28:29] offset:1024
	global_load_dwordx4 v[90:93], v244, s[28:29] offset:2048
	global_load_dwordx4 v[94:97], v244, s[28:29] offset:3072
	global_load_dwordx4 v[98:101], v244, s[0:1]
	global_load_dwordx4 v[102:105], v244, s[0:1] offset:1024
	global_load_dwordx4 v[106:109], v244, s[0:1] offset:2048
	global_load_dwordx4 v[118:121], v244, s[0:1] offset:3072
	s_waitcnt vmcnt(32)
; DI unsigned pk_bf16(float lo, float hi) { f32x2 v = {lo, hi}; bf16v2 b = __builtin_convertvector(v, bf16v2); return __builtin_bit_cast(unsigned, b); }
; DI float red64(float x) { for (int o = 32; o > 0; o >>= 1) x += __shfl_xor(x, o); return x; }
; DI void modnorm_rows(const Params& p, int l, int which  , bool from_inputs, bool skip_ctx, int w0, int wstride, int lane) {
;     ...
;   for (; i < nrows; i += wstride) {
;     const int row = rowof(i); const int b = row / TB, s = row % TB;
;     f32x4 v[4];
; #pragma unroll
;     for (int q = 0; q < 4; ++q) v[q] = vn[q];
;     if (i + wstride < nrows) {
;       const int rn = rowof(i + wstride); const float* src = xsrc_row(p, from_inputs, rn / TB, rn % TB);
; #pragma unroll
;       for (int q = 0; q < 4; ++q) vn[q] = *(const f32x4*)(src + q * 256 + lane * 4);
;     }
;     const float* mod = p.MOD + (size_t)(l * 9 + (s < NCTX ? 8 : b)) * 6144 + (which ? 3 * 1024 : 0);
;     f32x4 sh[4], sc[4];
; #pragma unroll
;     for (int q = 0; q < 4; ++q) { sh[q] = *(const f32x4*)(mod + q * 256 + lane * 4); sc[q] = *(const f32x4*)(mod + 1024 + q * 256 + lane * 4); }
;     float ss = 0.f;
; #pragma unroll
;     for (int q = 0; q < 4; ++q) ss += v[q][0] * v[q][0] + v[q][1] * v[q][1] + v[q][2] * v[q][2] + v[q][3] * v[q][3];
;     ss = red64(ss);
;     const float rs = rsqrtf(ss * (1.f / 1024.f) + EPSF);
;     bf16_t* dst = p.HY + (size_t)row * DM;
; #pragma unroll
;     for (int q = 0; q < 4; ++q) {
;       float o[4];
; #pragma unroll
;       for (int j = 0; j < 4; ++j) o[j] = (v[q][j] * rs * gg[q][j]) * (1.f + sc[q][j]) + sh[q][j];
;       u32x2 w = {pk_bf16(o[0], o[1]), pk_bf16(o[2], o[3])};
;       *(u32x2*)(dst + q * 256 + lane * 4) = w;
;     }
	v_pk_mul_f32 v[246:247], v[122:123], v[122:123]
	v_pk_fma_f32 v[246:247], v[124:125], v[124:125], v[246:247]
	v_pk_fma_f32 v[246:247], v[126:127], v[126:127], v[246:247]
	v_pk_fma_f32 v[246:247], v[128:129], v[128:129], v[246:247]
	v_pk_fma_f32 v[246:247], v[130:131], v[130:131], v[246:247]
	v_pk_fma_f32 v[246:247], v[132:133], v[132:133], v[246:247]
	v_pk_fma_f32 v[246:247], v[134:135], v[134:135], v[246:247]
	v_pk_fma_f32 v[246:247], v[136:137], v[136:137], v[246:247]
	s_nop 0
	v_add_f32_e32 v246, v246, v247
	s_nop 1
	v_add_f32_dpp v246, v246, v246 quad_perm:[1,0,3,2] row_mask:0xf bank_mask:0xf
	s_nop 1
	v_add_f32_dpp v246, v246, v246 quad_perm:[2,3,0,1] row_mask:0xf bank_mask:0xf
	s_nop 1
	v_add_f32_dpp v246, v246, v246 row_half_mirror row_mask:0xf bank_mask:0xf
	s_nop 1
	v_add_f32_dpp v246, v246, v246 row_mirror row_mask:0xf bank_mask:0xf
	s_nop 1
	v_add_f32_dpp v246, v246, v246 row_bcast:15 row_mask:0xa bank_mask:0xf
	s_nop 1
	v_add_f32_dpp v246, v246, v246 row_bcast:31 row_mask:0xc bank_mask:0xf
	s_nop 1
	v_readlane_b32 s0, v246, 63
	s_add_i32 s21, s20, 10240
	s_lshl_b32 s21, s21, 11
	s_add_u32 s10, s16, s21
	s_addc_u32 s11, s17, 0
	v_mov_b32_e32 v248, s0
	v_fmamk_f32 v248, v248, 0x3a800000, v143
	v_rsq_f32_e32 v248, v248
	s_nop 0
	v_pk_mul_f32 v[122:123], v[122:123], v[248:249] op_sel_hi:[1,0]
	v_pk_add_f32 v[176:177], v[176:177], 1.0 op_sel_hi:[1,0]
	v_pk_mul_f32 v[122:123], v[2:3], v[122:123]
	v_pk_fma_f32 v[122:123], v[176:177], v[122:123], v[160:161]
	v_pk_mul_f32 v[124:125], v[124:125], v[248:249] op_sel_hi:[1,0]
	v_pk_add_f32 v[178:179], v[178:179], 1.0 op_sel_hi:[1,0]
	v_pk_mul_f32 v[124:125], v[4:5], v[124:125]
	v_pk_fma_f32 v[124:125], v[178:179], v[124:125], v[162:163]
	v_cvt_pk_bf16_f32 v160, v122, v123
	v_cvt_pk_bf16_f32 v161, v124, v125
	global_store_dwordx2 v245, v[160:161], s[10:11]
	v_pk_mul_f32 v[126:127], v[126:127], v[248:249] op_sel_hi:[1,0]
	v_pk_add_f32 v[180:181], v[180:181], 1.0 op_sel_hi:[1,0]
	v_pk_mul_f32 v[126:127], v[6:7], v[126:127]
	v_pk_fma_f32 v[126:127], v[180:181], v[126:127], v[164:165]
	v_pk_mul_f32 v[128:129], v[128:129], v[248:249] op_sel_hi:[1,0]
	v_pk_add_f32 v[182:183], v[182:183], 1.0 op_sel_hi:[1,0]
	v_pk_mul_f32 v[128:129], v[8:9], v[128:129]
	v_pk_fma_f32 v[128:129], v[182:183], v[128:129], v[166:167]
	v_cvt_pk_bf16_f32 v164, v126, v127
	v_cvt_pk_bf16_f32 v165, v128, v129
	global_store_dwordx2 v245, v[164:165], s[10:11] offset:512
	v_pk_mul_f32 v[130:131], v[130:131], v[248:249] op_sel_hi:[1,0]
	v_pk_add_f32 v[184:185], v[184:185], 1.0 op_sel_hi:[1,0]
	v_pk_mul_f32 v[130:131], v[10:11], v[130:131]
	v_pk_fma_f32 v[130:131], v[184:185], v[130:131], v[168:169]
	v_pk_mul_f32 v[132:133], v[132:133], v[248:249] op_sel_hi:[1,0]
	v_pk_add_f32 v[186:187], v[186:187], 1.0 op_sel_hi:[1,0]
	v_pk_mul_f32 v[132:133], v[12:13], v[132:133]
	v_pk_fma_f32 v[132:133], v[186:187], v[132:133], v[170:171]
	v_cvt_pk_bf16_f32 v168, v130, v131
	v_cvt_pk_bf16_f32 v169, v132, v133
	global_store_dwordx2 v245, v[168:169], s[10:11] offset:1024
	v_pk_mul_f32 v[134:135], v[134:135], v[248:249] op_sel_hi:[1,0]
	v_pk_add_f32 v[188:189], v[188:189], 1.0 op_sel_hi:[1,0]
	v_pk_mul_f32 v[134:135], v[14:15], v[134:135]
	v_pk_fma_f32 v[134:135], v[188:189], v[134:135], v[172:173]
	v_pk_mul_f32 v[136:137], v[136:137], v[248:249] op_sel_hi:[1,0]
	v_pk_add_f32 v[190:191], v[190:191], 1.0 op_sel_hi:[1,0]
	v_pk_mul_f32 v[136:137], v[16:17], v[136:137]
	v_pk_fma_f32 v[136:137], v[190:191], v[136:137], v[174:175]
	v_cvt_pk_bf16_f32 v172, v134, v135
	v_cvt_pk_bf16_f32 v173, v136, v137
	global_store_dwordx2 v245, v[172:173], s[10:11] offset:1536
	s_add_i32 s21, s20, 16384
	s_mul_hi_u32 s7, s21, 0x38e38e39
	s_lshr_b32 s7, s7, 9
	s_mul_i32 s8, s7, 0x900
	s_sub_i32 s8, s21, s8
	s_lshl_b32 s9, s7, 11
	s_add_i32 s9, s9, s8
	s_add_i32 s9, s9, 0xffffff00
	s_lshl_b32 s10, s7, 8
	s_add_i32 s10, s10, s8
	s_cmpk_gt_i32 s8, 0xff
	s_cselect_b32 s9, s9, s10
	s_cselect_b32 s26, s12, s14
	s_cselect_b32 s27, s13, s15
	s_cselect_b32 s10, s7, 8
	s_lshl_b32 s9, s9, 12
	s_add_u32 s26, s26, s9
	s_addc_u32 s27, s27, 0
	s_add_i32 s10, s10, s82
	s_mul_i32 s10, s10, s24
	s_add_u32 s28, s58, s10
	s_addc_u32 s29, s59, 0
	s_add_u32 s28, s28, 0x0
	s_addc_u32 s29, s29, 0
	s_add_u32 s0, s28, 0x1000
	s_addc_u32 s1, s29, 0
	global_load_dwordx4 v[122:125], v244, s[26:27]
	global_load_dwordx4 v[126:129], v244, s[26:27] offset:1024
	global_load_dwordx4 v[130:133], v244, s[26:27] offset:2048
	global_load_dwordx4 v[134:137], v244, s[26:27] offset:3072
	global_load_dwordx4 v[160:163], v244, s[28:29]
	global_load_dwordx4 v[164:167], v244, s[28:29] offset:1024
	global_load_dwordx4 v[168:171], v244, s[28:29] offset:2048
	global_load_dwordx4 v[172:175], v244, s[28:29] offset:3072
	global_load_dwordx4 v[176:179], v244, s[0:1]
	global_load_dwordx4 v[180:183], v244, s[0:1] offset:1024
	global_load_dwordx4 v[184:187], v244, s[0:1] offset:2048
	global_load_dwordx4 v[188:191], v244, s[0:1] offset:3072
	s_waitcnt vmcnt(32)
; DI unsigned pk_bf16(float lo, float hi) { f32x2 v = {lo, hi}; bf16v2 b = __builtin_convertvector(v, bf16v2); return __builtin_bit_cast(unsigned, b); }
; DI float red64(float x) { for (int o = 32; o > 0; o >>= 1) x += __shfl_xor(x, o); return x; }
; DI void modnorm_rows(const Params& p, int l, int which  , bool from_inputs, bool skip_ctx, int w0, int wstride, int lane) {
;     ...
;   for (; i < nrows; i += wstride) {
;     const int row = rowof(i); const int b = row / TB, s = row % TB;
;     f32x4 v[4];
; #pragma unroll
;     for (int q = 0; q < 4; ++q) v[q] = vn[q];
;     if (i + wstride < nrows) {
;       const int rn = rowof(i + wstride); const float* src = xsrc_row(p, from_inputs, rn / TB, rn % TB);
; #pragma unroll
;       for (int q = 0; q < 4; ++q) vn[q] = *(const f32x4*)(src + q * 256 + lane * 4);
;     }
;     const float* mod = p.MOD + (size_t)(l * 9 + (s < NCTX ? 8 : b)) * 6144 + (which ? 3 * 1024 : 0);
;     f32x4 sh[4], sc[4];
; #pragma unroll
;     for (int q = 0; q < 4; ++q) { sh[q] = *(const f32x4*)(mod + q * 256 + lane * 4); sc[q] = *(const f32x4*)(mod + 1024 + q * 256 + lane * 4); }
;     float ss = 0.f;
; #pragma unroll
;     for (int q = 0; q < 4; ++q) ss += v[q][0] * v[q][0] + v[q][1] * v[q][1] + v[q][2] * v[q][2] + v[q][3] * v[q][3];
;     ss = red64(ss);
;     const float rs = rsqrtf(ss * (1.f / 1024.f) + EPSF);
;     bf16_t* dst = p.HY + (size_t)row * DM;
; #pragma unroll
;     for (int q = 0; q < 4; ++q) {
;       float o[4];
; #pragma unroll
;       for (int j = 0; j < 4; ++j) o[j] = (v[q][j] * rs * gg[q][j]) * (1.f + sc[q][j]) + sh[q][j];
;       u32x2 w = {pk_bf16(o[0], o[1]), pk_bf16(o[2], o[3])};
;       *(u32x2*)(dst + q * 256 + lane * 4) = w;
;     }
	v_pk_mul_f32 v[246:247], v[18:19], v[18:19]
	v_pk_fma_f32 v[246:247], v[20:21], v[20:21], v[246:247]
	v_pk_fma_f32 v[246:247], v[22:23], v[22:23], v[246:247]
	v_pk_fma_f32 v[246:247], v[24:25], v[24:25], v[246:247]
	v_pk_fma_f32 v[246:247], v[26:27], v[26:27], v[246:247]
	v_pk_fma_f32 v[246:247], v[28:29], v[28:29], v[246:247]
	v_pk_fma_f32 v[246:247], v[30:31], v[30:31], v[246:247]
	v_pk_fma_f32 v[246:247], v[32:33], v[32:33], v[246:247]
	s_nop 0
	v_add_f32_e32 v246, v246, v247
	s_nop 1
	v_add_f32_dpp v246, v246, v246 quad_perm:[1,0,3,2] row_mask:0xf bank_mask:0xf
	s_nop 1
	v_add_f32_dpp v246, v246, v246 quad_perm:[2,3,0,1] row_mask:0xf bank_mask:0xf
	s_nop 1
	v_add_f32_dpp v246, v246, v246 row_half_mirror row_mask:0xf bank_mask:0xf
	s_nop 1
	v_add_f32_dpp v246, v246, v246 row_mirror row_mask:0xf bank_mask:0xf
	s_nop 1
	v_add_f32_dpp v246, v246, v246 row_bcast:15 row_mask:0xa bank_mask:0xf
	s_nop 1
	v_add_f32_dpp v246, v246, v246 row_bcast:31 row_mask:0xc bank_mask:0xf
	s_nop 1
	v_readlane_b32 s0, v246, 63
	s_add_i32 s21, s20, 12288
	s_lshl_b32 s21, s21, 11
	s_add_u32 s10, s16, s21
	s_addc_u32 s11, s17, 0
	v_mov_b32_e32 v248, s0
	v_fmamk_f32 v248, v248, 0x3a800000, v143
	v_rsq_f32_e32 v248, v248
	s_nop 0
	v_pk_mul_f32 v[18:19], v[18:19], v[248:249] op_sel_hi:[1,0]
	v_pk_add_f32 v[50:51], v[50:51], 1.0 op_sel_hi:[1,0]
	v_pk_mul_f32 v[18:19], v[2:3], v[18:19]
	v_pk_fma_f32 v[18:19], v[50:51], v[18:19], v[34:35]
	v_pk_mul_f32 v[20:21], v[20:21], v[248:249] op_sel_hi:[1,0]
	v_pk_add_f32 v[52:53], v[52:53], 1.0 op_sel_hi:[1,0]
	v_pk_mul_f32 v[20:21], v[4:5], v[20:21]
	v_pk_fma_f32 v[20:21], v[52:53], v[20:21], v[36:37]
	v_cvt_pk_bf16_f32 v34, v18, v19
	v_cvt_pk_bf16_f32 v35, v20, v21
	global_store_dwordx2 v245, v[34:35], s[10:11]
	v_pk_mul_f32 v[22:23], v[22:23], v[248:249] op_sel_hi:[1,0]
	v_pk_add_f32 v[54:55], v[54:55], 1.0 op_sel_hi:[1,0]
	v_pk_mul_f32 v[22:23], v[6:7], v[22:23]
	v_pk_fma_f32 v[22:23], v[54:55], v[22:23], v[38:39]
	v_pk_mul_f32 v[24:25], v[24:25], v[248:249] op_sel_hi:[1,0]
	v_pk_add_f32 v[56:57], v[56:57], 1.0 op_sel_hi:[1,0]
	v_pk_mul_f32 v[24:25], v[8:9], v[24:25]
	v_pk_fma_f32 v[24:25], v[56:57], v[24:25], v[40:41]
	v_cvt_pk_bf16_f32 v38, v22, v23
	v_cvt_pk_bf16_f32 v39, v24, v25
	global_store_dwordx2 v245, v[38:39], s[10:11] offset:512
	v_pk_mul_f32 v[26:27], v[26:27], v[248:249] op_sel_hi:[1,0]
	v_pk_add_f32 v[58:59], v[58:59], 1.0 op_sel_hi:[1,0]
	v_pk_mul_f32 v[26:27], v[10:11], v[26:27]
	v_pk_fma_f32 v[26:27], v[58:59], v[26:27], v[42:43]
	v_pk_mul_f32 v[28:29], v[28:29], v[248:249] op_sel_hi:[1,0]
	v_pk_add_f32 v[60:61], v[60:61], 1.0 op_sel_hi:[1,0]
	v_pk_mul_f32 v[28:29], v[12:13], v[28:29]
	v_pk_fma_f32 v[28:29], v[60:61], v[28:29], v[44:45]
	v_cvt_pk_bf16_f32 v42, v26, v27
	v_cvt_pk_bf16_f32 v43, v28, v29
	global_store_dwordx2 v245, v[42:43], s[10:11] offset:1024
	v_pk_mul_f32 v[30:31], v[30:31], v[248:249] op_sel_hi:[1,0]
	v_pk_add_f32 v[62:63], v[62:63], 1.0 op_sel_hi:[1,0]
	v_pk_mul_f32 v[30:31], v[14:15], v[30:31]
	v_pk_fma_f32 v[30:31], v[62:63], v[30:31], v[46:47]
	v_pk_mul_f32 v[32:33], v[32:33], v[248:249] op_sel_hi:[1,0]
	v_pk_add_f32 v[64:65], v[64:65], 1.0 op_sel_hi:[1,0]
	v_pk_mul_f32 v[32:33], v[16:17], v[32:33]
	v_pk_fma_f32 v[32:33], v[64:65], v[32:33], v[48:49]
	v_cvt_pk_bf16_f32 v46, v30, v31
	v_cvt_pk_bf16_f32 v47, v32, v33
	global_store_dwordx2 v245, v[46:47], s[10:11] offset:1536
	s_waitcnt vmcnt(20)
	v_pk_mul_f32 v[246:247], v[66:67], v[66:67]
	v_pk_fma_f32 v[246:247], v[68:69], v[68:69], v[246:247]
	v_pk_fma_f32 v[246:247], v[70:71], v[70:71], v[246:247]
	v_pk_fma_f32 v[246:247], v[72:73], v[72:73], v[246:247]
	v_pk_fma_f32 v[246:247], v[74:75], v[74:75], v[246:247]
	v_pk_fma_f32 v[246:247], v[76:77], v[76:77], v[246:247]
	v_pk_fma_f32 v[246:247], v[78:79], v[78:79], v[246:247]
	v_pk_fma_f32 v[246:247], v[80:81], v[80:81], v[246:247]
	s_nop 0
	v_add_f32_e32 v246, v246, v247
	s_nop 1
	v_add_f32_dpp v246, v246, v246 quad_perm:[1,0,3,2] row_mask:0xf bank_mask:0xf
	s_nop 1
	v_add_f32_dpp v246, v246, v246 quad_perm:[2,3,0,1] row_mask:0xf bank_mask:0xf
	s_nop 1
	v_add_f32_dpp v246, v246, v246 row_half_mirror row_mask:0xf bank_mask:0xf
	s_nop 1
	v_add_f32_dpp v246, v246, v246 row_mirror row_mask:0xf bank_mask:0xf
	s_nop 1
	v_add_f32_dpp v246, v246, v246 row_bcast:15 row_mask:0xa bank_mask:0xf
	s_nop 1
	v_add_f32_dpp v246, v246, v246 row_bcast:31 row_mask:0xc bank_mask:0xf
	s_nop 1
	v_readlane_b32 s0, v246, 63
	s_add_i32 s21, s20, 14336
	s_lshl_b32 s21, s21, 11
	s_add_u32 s10, s16, s21
	s_addc_u32 s11, s17, 0
	v_mov_b32_e32 v248, s0
	v_fmamk_f32 v248, v248, 0x3a800000, v143
	v_rsq_f32_e32 v248, v248
	s_nop 0
	v_pk_mul_f32 v[66:67], v[66:67], v[248:249] op_sel_hi:[1,0]
	v_pk_add_f32 v[98:99], v[98:99], 1.0 op_sel_hi:[1,0]
	v_pk_mul_f32 v[66:67], v[2:3], v[66:67]
	v_pk_fma_f32 v[66:67], v[98:99], v[66:67], v[82:83]
	v_pk_mul_f32 v[68:69], v[68:69], v[248:249] op_sel_hi:[1,0]
	v_pk_add_f32 v[100:101], v[100:101], 1.0 op_sel_hi:[1,0]
	v_pk_mul_f32 v[68:69], v[4:5], v[68:69]
	v_pk_fma_f32 v[68:69], v[100:101], v[68:69], v[84:85]
	v_cvt_pk_bf16_f32 v82, v66, v67
	v_cvt_pk_bf16_f32 v83, v68, v69
	global_store_dwordx2 v245, v[82:83], s[10:11]
	v_pk_mul_f32 v[70:71], v[70:71], v[248:249] op_sel_hi:[1,0]
	v_pk_add_f32 v[102:103], v[102:103], 1.0 op_sel_hi:[1,0]
	v_pk_mul_f32 v[70:71], v[6:7], v[70:71]
	v_pk_fma_f32 v[70:71], v[102:103], v[70:71], v[86:87]
	v_pk_mul_f32 v[72:73], v[72:73], v[248:249] op_sel_hi:[1,0]
	v_pk_add_f32 v[104:105], v[104:105], 1.0 op_sel_hi:[1,0]
	v_pk_mul_f32 v[72:73], v[8:9], v[72:73]
	v_pk_fma_f32 v[72:73], v[104:105], v[72:73], v[88:89]
	v_cvt_pk_bf16_f32 v86, v70, v71
	v_cvt_pk_bf16_f32 v87, v72, v73
	global_store_dwordx2 v245, v[86:87], s[10:11] offset:512
	v_pk_mul_f32 v[74:75], v[74:75], v[248:249] op_sel_hi:[1,0]
	v_pk_add_f32 v[106:107], v[106:107], 1.0 op_sel_hi:[1,0]
	v_pk_mul_f32 v[74:75], v[10:11], v[74:75]
	v_pk_fma_f32 v[74:75], v[106:107], v[74:75], v[90:91]
	v_pk_mul_f32 v[76:77], v[76:77], v[248:249] op_sel_hi:[1,0]
	v_pk_add_f32 v[108:109], v[108:109], 1.0 op_sel_hi:[1,0]
	v_pk_mul_f32 v[76:77], v[12:13], v[76:77]
	v_pk_fma_f32 v[76:77], v[108:109], v[76:77], v[92:93]
	v_cvt_pk_bf16_f32 v90, v74, v75
	v_cvt_pk_bf16_f32 v91, v76, v77
	global_store_dwordx2 v245, v[90:91], s[10:11] offset:1024
	v_pk_mul_f32 v[78:79], v[78:79], v[248:249] op_sel_hi:[1,0]
	v_pk_add_f32 v[118:119], v[118:119], 1.0 op_sel_hi:[1,0]
	v_pk_mul_f32 v[78:79], v[14:15], v[78:79]
	v_pk_fma_f32 v[78:79], v[118:119], v[78:79], v[94:95]
	v_pk_mul_f32 v[80:81], v[80:81], v[248:249] op_sel_hi:[1,0]
	v_pk_add_f32 v[120:121], v[120:121], 1.0 op_sel_hi:[1,0]
	v_pk_mul_f32 v[80:81], v[16:17], v[80:81]
	v_pk_fma_f32 v[80:81], v[120:121], v[80:81], v[96:97]
	v_cvt_pk_bf16_f32 v94, v78, v79
	v_cvt_pk_bf16_f32 v95, v80, v81
	global_store_dwordx2 v245, v[94:95], s[10:11] offset:1536
	s_waitcnt vmcnt(8)
; DI unsigned pk_bf16(float lo, float hi) { f32x2 v = {lo, hi}; bf16v2 b = __builtin_convertvector(v, bf16v2); return __builtin_bit_cast(unsigned, b); }
; DI float red64(float x) { for (int o = 32; o > 0; o >>= 1) x += __shfl_xor(x, o); return x; }
; DI void modnorm_rows(const Params& p, int l, int which  , bool from_inputs, bool skip_ctx, int w0, int wstride, int lane) {
;     ...
;   int i = w0;
;   if (i >= nrows) return;
;   f32x4 vn[4];
;   {
;     const int row = rowof(i); const float* src = xsrc_row(p, from_inputs, row / TB, row % TB);
; #pragma unroll
;     for (int q = 0; q < 4; ++q) vn[q] = *(const f32x4*)(src + q * 256 + lane * 4);
;     ...
;   for (; i < nrows; i += wstride) {
;     const int row = rowof(i); const int b = row / TB, s = row % TB;
;     f32x4 v[4];
; #pragma unroll
;     for (int q = 0; q < 4; ++q) v[q] = vn[q];
;     if (i + wstride < nrows) {
;       const int rn = rowof(i + wstride); const float* src = xsrc_row(p, from_inputs, rn / TB, rn % TB);
; #pragma unroll
;       for (int q = 0; q < 4; ++q) vn[q] = *(const f32x4*)(src + q * 256 + lane * 4);
;     }
;     const float* mod = p.MOD + (size_t)(l * 9 + (s < NCTX ? 8 : b)) * 6144 + (which ? 3 * 1024 : 0);
;     f32x4 sh[4], sc[4];
; #pragma unroll
;     for (int q = 0; q < 4; ++q) { sh[q] = *(const f32x4*)(mod + q * 256 + lane * 4); sc[q] = *(const f32x4*)(mod + 1024 + q * 256 + lane * 4); }
;     float ss = 0.f;
; #pragma unroll
;     for (int q = 0; q < 4; ++q) ss += v[q][0] * v[q][0] + v[q][1] * v[q][1] + v[q][2] * v[q][2] + v[q][3] * v[q][3];
;     ss = red64(ss);
;     const float rs = rsqrtf(ss * (1.f / 1024.f) + EPSF);
;     bf16_t* dst = p.HY + (size_t)row * DM;
; #pragma unroll
;     for (int q = 0; q < 4; ++q) {
;       float o[4];
; #pragma unroll
;       for (int j = 0; j < 4; ++j) o[j] = (v[q][j] * rs * gg[q][j]) * (1.f + sc[q][j]) + sh[q][j];
;       u32x2 w = {pk_bf16(o[0], o[1]), pk_bf16(o[2], o[3])};
;       *(u32x2*)(dst + q * 256 + lane * 4) = w;
;     }
	v_pk_mul_f32 v[246:247], v[122:123], v[122:123]
	v_pk_fma_f32 v[246:247], v[124:125], v[124:125], v[246:247]
	v_pk_fma_f32 v[246:247], v[126:127], v[126:127], v[246:247]
	v_pk_fma_f32 v[246:247], v[128:129], v[128:129], v[246:247]
	v_pk_fma_f32 v[246:247], v[130:131], v[130:131], v[246:247]
	v_pk_fma_f32 v[246:247], v[132:133], v[132:133], v[246:247]
	v_pk_fma_f32 v[246:247], v[134:135], v[134:135], v[246:247]
	v_pk_fma_f32 v[246:247], v[136:137], v[136:137], v[246:247]
	s_nop 0
	v_add_f32_e32 v246, v246, v247
	s_nop 1
	v_add_f32_dpp v246, v246, v246 quad_perm:[1,0,3,2] row_mask:0xf bank_mask:0xf
	s_nop 1
	v_add_f32_dpp v246, v246, v246 quad_perm:[2,3,0,1] row_mask:0xf bank_mask:0xf
	s_nop 1
	v_add_f32_dpp v246, v246, v246 row_half_mirror row_mask:0xf bank_mask:0xf
	s_nop 1
	v_add_f32_dpp v246, v246, v246 row_mirror row_mask:0xf bank_mask:0xf
	s_nop 1
	v_add_f32_dpp v246, v246, v246 row_bcast:15 row_mask:0xa bank_mask:0xf
	s_nop 1
	v_add_f32_dpp v246, v246, v246 row_bcast:31 row_mask:0xc bank_mask:0xf
	s_nop 1
	v_readlane_b32 s0, v246, 63
	s_add_i32 s21, s20, 16384
	s_lshl_b32 s21, s21, 11
	s_add_u32 s10, s16, s21
	s_addc_u32 s11, s17, 0
	v_mov_b32_e32 v248, s0
	v_fmamk_f32 v248, v248, 0x3a800000, v143
	v_rsq_f32_e32 v248, v248
	s_nop 0
	v_pk_mul_f32 v[122:123], v[122:123], v[248:249] op_sel_hi:[1,0]
	v_pk_add_f32 v[176:177], v[176:177], 1.0 op_sel_hi:[1,0]
	v_pk_mul_f32 v[122:123], v[2:3], v[122:123]
	v_pk_fma_f32 v[122:123], v[176:177], v[122:123], v[160:161]
	v_pk_mul_f32 v[124:125], v[124:125], v[248:249] op_sel_hi:[1,0]
	v_pk_add_f32 v[178:179], v[178:179], 1.0 op_sel_hi:[1,0]
	v_pk_mul_f32 v[124:125], v[4:5], v[124:125]
	v_pk_fma_f32 v[124:125], v[178:179], v[124:125], v[162:163]
	v_cvt_pk_bf16_f32 v160, v122, v123
	v_cvt_pk_bf16_f32 v161, v124, v125
	global_store_dwordx2 v245, v[160:161], s[10:11]
	v_pk_mul_f32 v[126:127], v[126:127], v[248:249] op_sel_hi:[1,0]
	v_pk_add_f32 v[180:181], v[180:181], 1.0 op_sel_hi:[1,0]
	v_pk_mul_f32 v[126:127], v[6:7], v[126:127]
	v_pk_fma_f32 v[126:127], v[180:181], v[126:127], v[164:165]
	v_pk_mul_f32 v[128:129], v[128:129], v[248:249] op_sel_hi:[1,0]
	v_pk_add_f32 v[182:183], v[182:183], 1.0 op_sel_hi:[1,0]
	v_pk_mul_f32 v[128:129], v[8:9], v[128:129]
	v_pk_fma_f32 v[128:129], v[182:183], v[128:129], v[166:167]
	v_cvt_pk_bf16_f32 v164, v126, v127
	v_cvt_pk_bf16_f32 v165, v128, v129
	global_store_dwordx2 v245, v[164:165], s[10:11] offset:512
	v_pk_mul_f32 v[130:131], v[130:131], v[248:249] op_sel_hi:[1,0]
	v_pk_add_f32 v[184:185], v[184:185], 1.0 op_sel_hi:[1,0]
	v_pk_mul_f32 v[130:131], v[10:11], v[130:131]
	v_pk_fma_f32 v[130:131], v[184:185], v[130:131], v[168:169]
	v_pk_mul_f32 v[132:133], v[132:133], v[248:249] op_sel_hi:[1,0]
	v_pk_add_f32 v[186:187], v[186:187], 1.0 op_sel_hi:[1,0]
	v_pk_mul_f32 v[132:133], v[12:13], v[132:133]
	v_pk_fma_f32 v[132:133], v[186:187], v[132:133], v[170:171]
	v_cvt_pk_bf16_f32 v168, v130, v131
	v_cvt_pk_bf16_f32 v169, v132, v133
	global_store_dwordx2 v245, v[168:169], s[10:11] offset:1024
	v_pk_mul_f32 v[134:135], v[134:135], v[248:249] op_sel_hi:[1,0]
	v_pk_add_f32 v[188:189], v[188:189], 1.0 op_sel_hi:[1,0]
	v_pk_mul_f32 v[134:135], v[14:15], v[134:135]
	v_pk_fma_f32 v[134:135], v[188:189], v[134:135], v[172:173]
	v_pk_mul_f32 v[136:137], v[136:137], v[248:249] op_sel_hi:[1,0]
	v_pk_add_f32 v[190:191], v[190:191], 1.0 op_sel_hi:[1,0]
	v_pk_mul_f32 v[136:137], v[16:17], v[136:137]
	v_pk_fma_f32 v[136:137], v[190:191], v[136:137], v[174:175]
	v_cvt_pk_bf16_f32 v172, v134, v135
	v_cvt_pk_bf16_f32 v173, v136, v137
	global_store_dwordx2 v245, v[172:173], s[10:11] offset:1536
	s_branch .Lnorm1_done
.Lnorm1_l1:
	buffer_inv sc1
	s_mov_b32 s36, 0
	s_lshr_b32 s37, s20, 5
	s_lshl_b32 s37, s37, 2
	s_and_b32 s38, s20, 3
	s_or_b32 s37, s37, s38
	s_lshr_b32 s38, s20, 2
	s_and_b32 s38, s38, 7
	s_mulk_i32 s38, 0x900
	s_add_i32 s37, s37, s38
	s_add_i32 s6, s37, 0
	s_lshr_b32 s6, s6, 7
	s_lshl_b32 s6, s6, 2
	s_add_i32 s6, s6, 0x1e40
	v_mov_b32_e32 v110, s6
	global_load_dword v114, v110, s[70:71] sc1
	s_add_i32 s6, s37, 256
	s_lshr_b32 s6, s6, 7
	s_lshl_b32 s6, s6, 2
	s_add_i32 s6, s6, 0x1e40
	v_mov_b32_e32 v110, s6
	global_load_dword v116, v110, s[70:71] sc1
	s_add_i32 s6, s37, 512
	s_lshr_b32 s6, s6, 7
	s_lshl_b32 s6, s6, 2
	s_add_i32 s6, s6, 0x1e40
	v_mov_b32_e32 v110, s6
	global_load_dword v117, v110, s[70:71] sc1
	s_waitcnt vmcnt(2)
	v_readfirstlane_b32 s6, v114
	s_cmp_ge_u32 s6, 8
	s_cbranch_scc1 .Ldep_norm1d_ok0
	s_add_i32 s6, s37, 0
	s_lshr_b32 s6, s6, 7
	s_lshl_b32 s6, s6, 2
	s_add_i32 s6, s6, 0x1e40
	v_mov_b32_e32 v110, s6

; DI void modnorm_rows(const Params& p, int l, int which  , bool from_inputs, bool skip_ctx, int w0, int wstride, int lane) {
;     ...
;   for (; i < nrows; i += wstride) {
;     const int row = rowof(i); const int b = row / TB, s = row % TB;
;     f32x4 v[4];
; #pragma unroll
;     for (int q = 0; q < 4; ++q) v[q] = vn[q];
;     if (i + wstride < nrows) {
;       const int rn = rowof(i + wstride); const float* src = xsrc_row(p, from_inputs, rn / TB, rn % TB);
; #pragma unroll
;       for (int q = 0; q < 4; ++q) vn[q] = *(const f32x4*)(src + q * 256 + lane * 4);
.Ldep_norm1d_ok0:
	s_waitcnt vmcnt(1)
	v_readfirstlane_b32 s6, v116
	s_cmp_ge_u32 s6, 8
	s_cbranch_scc1 .Ldep_norm1d_ok1
	s_add_i32 s6, s37, 256
	s_lshr_b32 s6, s6, 7
	s_lshl_b32 s6, s6, 2
	s_add_i32 s6, s6, 0x1e40
	v_mov_b32_e32 v110, s6

; DI void modnorm_rows(const Params& p, int l, int which  , bool from_inputs, bool skip_ctx, int w0, int wstride, int lane) {
;     ...
;   for (; i < nrows; i += wstride) {
;     const int row = rowof(i); const int b = row / TB, s = row % TB;
;     f32x4 v[4];
; #pragma unroll
;     for (int q = 0; q < 4; ++q) v[q] = vn[q];
;     if (i + wstride < nrows) {
;       const int rn = rowof(i + wstride); const float* src = xsrc_row(p, from_inputs, rn / TB, rn % TB);
; #pragma unroll
;       for (int q = 0; q < 4; ++q) vn[q] = *(const f32x4*)(src + q * 256 + lane * 4);
.Ldep_norm1d_ok1:
	s_waitcnt vmcnt(0)
	v_readfirstlane_b32 s6, v117
	s_cmp_ge_u32 s6, 8
	s_cbranch_scc1 .Ldep_norm1d_ok2
	s_add_i32 s6, s37, 512
	s_lshr_b32 s6, s6, 7
	s_lshl_b32 s6, s6, 2
	s_add_i32 s6, s6, 0x1e40
	v_mov_b32_e32 v110, s6

; DI void modnorm_rows(const Params& p, int l, int which  , bool from_inputs, bool skip_ctx, int w0, int wstride, int lane) {
;     ...
;   int i = w0;
;   if (i >= nrows) return;
;   f32x4 vn[4];
;   {
;     const int row = rowof(i); const float* src = xsrc_row(p, from_inputs, row / TB, row % TB);
; #pragma unroll
;     for (int q = 0; q < 4; ++q) vn[q] = *(const f32x4*)(src + q * 256 + lane * 4);
;   }
;   for (; i < nrows; i += wstride) {
;     const int row = rowof(i); const int b = row / TB, s = row % TB;
;     f32x4 v[4];
; #pragma unroll
;     for (int q = 0; q < 4; ++q) v[q] = vn[q];
;     if (i + wstride < nrows) {
;       const int rn = rowof(i + wstride); const float* src = xsrc_row(p, from_inputs, rn / TB, rn % TB);
; #pragma unroll
;       for (int q = 0; q < 4; ++q) vn[q] = *(const f32x4*)(src + q * 256 + lane * 4);
.Ldep_norm1d_ok2:
	s_add_i32 s21, s37, 0
	s_mul_hi_u32 s7, s21, 0x38e38e39
	s_lshr_b32 s7, s7, 9
	s_mul_i32 s8, s7, 0x900
	s_sub_i32 s8, s21, s8
	s_lshl_b32 s9, s7, 11
	s_add_i32 s9, s9, s8
	s_add_i32 s9, s9, 0xffffff00
	s_lshl_b32 s10, s7, 8
	s_add_i32 s10, s10, s8
	s_cmpk_gt_i32 s8, 0xff
	s_cselect_b32 s9, s9, s10
	s_cselect_b32 s26, s12, s14
	s_cselect_b32 s27, s13, s15
	s_cselect_b32 s10, s7, 8
	s_lshl_b32 s9, s9, 12
	s_add_u32 s26, s26, s9
	s_addc_u32 s27, s27, 0
	s_add_i32 s10, s10, s82
	s_mul_i32 s10, s10, s24
	s_add_u32 s28, s58, s10
	s_addc_u32 s29, s59, 0
	s_add_u32 s28, s28, 0x0
	s_addc_u32 s29, s29, 0
	s_add_u32 s0, s28, 0x1000
	s_addc_u32 s1, s29, 0
	global_load_dwordx4 v[18:21], v244, s[26:27]
	global_load_dwordx4 v[22:25], v244, s[26:27] offset:1024
	global_load_dwordx4 v[26:29], v244, s[26:27] offset:2048
	global_load_dwordx4 v[30:33], v244, s[26:27] offset:3072
	global_load_dwordx4 v[34:37], v244, s[28:29]
	global_load_dwordx4 v[38:41], v244, s[28:29] offset:1024
	global_load_dwordx4 v[42:45], v244, s[28:29] offset:2048
	global_load_dwordx4 v[46:49], v244, s[28:29] offset:3072
	global_load_dwordx4 v[50:53], v244, s[0:1]
	global_load_dwordx4 v[54:57], v244, s[0:1] offset:1024
	global_load_dwordx4 v[58:61], v244, s[0:1] offset:2048
	global_load_dwordx4 v[62:65], v244, s[0:1] offset:3072
	s_add_i32 s21, s37, 256
	s_mul_hi_u32 s7, s21, 0x38e38e39
	s_lshr_b32 s7, s7, 9
	s_mul_i32 s8, s7, 0x900
	s_sub_i32 s8, s21, s8
	s_lshl_b32 s9, s7, 11
	s_add_i32 s9, s9, s8
	s_add_i32 s9, s9, 0xffffff00
	s_lshl_b32 s10, s7, 8
	s_add_i32 s10, s10, s8
	s_cmpk_gt_i32 s8, 0xff
	s_cselect_b32 s9, s9, s10
	s_cselect_b32 s26, s12, s14
	s_cselect_b32 s27, s13, s15
	s_cselect_b32 s10, s7, 8
	s_lshl_b32 s9, s9, 12
	s_add_u32 s26, s26, s9
	s_addc_u32 s27, s27, 0
	s_add_i32 s10, s10, s82
	s_mul_i32 s10, s10, s24
	s_add_u32 s28, s58, s10
	s_addc_u32 s29, s59, 0
	s_add_u32 s28, s28, 0x0
	s_addc_u32 s29, s29, 0
	s_add_u32 s0, s28, 0x1000
	s_addc_u32 s1, s29, 0
	global_load_dwordx4 v[66:69], v244, s[26:27]
	global_load_dwordx4 v[70:73], v244, s[26:27] offset:1024
	global_load_dwordx4 v[74:77], v244, s[26:27] offset:2048
	global_load_dwordx4 v[78:81], v244, s[26:27] offset:3072
	global_load_dwordx4 v[82:85], v244, s[28:29]
	global_load_dwordx4 v[86:89], v244, s[28:29] offset:1024
	global_load_dwordx4 v[90:93], v244, s[28:29] offset:2048
	global_load_dwordx4 v[94:97], v244, s[28:29] offset:3072
	global_load_dwordx4 v[98:101], v244, s[0:1]
	global_load_dwordx4 v[102:105], v244, s[0:1] offset:1024
	global_load_dwordx4 v[106:109], v244, s[0:1] offset:2048
	global_load_dwordx4 v[118:121], v244, s[0:1] offset:3072
	s_add_i32 s21, s37, 512
	s_mul_hi_u32 s7, s21, 0x38e38e39
	s_lshr_b32 s7, s7, 9
	s_mul_i32 s8, s7, 0x900
	s_sub_i32 s8, s21, s8
	s_lshl_b32 s9, s7, 11
	s_add_i32 s9, s9, s8
	s_add_i32 s9, s9, 0xffffff00
	s_lshl_b32 s10, s7, 8
	s_add_i32 s10, s10, s8
	s_cmpk_gt_i32 s8, 0xff
	s_cselect_b32 s9, s9, s10
	s_cselect_b32 s26, s12, s14
	s_cselect_b32 s27, s13, s15
	s_cselect_b32 s10, s7, 8
	s_lshl_b32 s9, s9, 12
	s_add_u32 s26, s26, s9
	s_addc_u32 s27, s27, 0
	s_add_i32 s10, s10, s82
	s_mul_i32 s10, s10, s24
	s_add_u32 s28, s58, s10
	s_addc_u32 s29, s59, 0
	s_add_u32 s28, s28, 0x0
	s_addc_u32 s29, s29, 0
	s_add_u32 s0, s28, 0x1000
	s_addc_u32 s1, s29, 0
	global_load_dwordx4 v[122:125], v244, s[26:27]
	global_load_dwordx4 v[126:129], v244, s[26:27] offset:1024
	global_load_dwordx4 v[130:133], v244, s[26:27] offset:2048
	global_load_dwordx4 v[134:137], v244, s[26:27] offset:3072
	global_load_dwordx4 v[160:163], v244, s[28:29]
	global_load_dwordx4 v[164:167], v244, s[28:29] offset:1024
	global_load_dwordx4 v[168:171], v244, s[28:29] offset:2048
	global_load_dwordx4 v[172:175], v244, s[28:29] offset:3072
	global_load_dwordx4 v[176:179], v244, s[0:1]
	global_load_dwordx4 v[180:183], v244, s[0:1] offset:1024
	global_load_dwordx4 v[184:187], v244, s[0:1] offset:2048
	global_load_dwordx4 v[188:191], v244, s[0:1] offset:3072
	s_add_i32 s6, s37, 768
	s_lshr_b32 s6, s6, 7
	s_lshl_b32 s6, s6, 2
	s_add_i32 s6, s6, 0x1e40
	v_mov_b32_e32 v110, s6
	global_load_dword v114, v110, s[70:71] sc1
	s_waitcnt vmcnt(25)
; DI unsigned pk_bf16(float lo, float hi) { f32x2 v = {lo, hi}; bf16v2 b = __builtin_convertvector(v, bf16v2); return __builtin_bit_cast(unsigned, b); }
; DI float red64(float x) { for (int o = 32; o > 0; o >>= 1) x += __shfl_xor(x, o); return x; }
; DI void modnorm_rows(const Params& p, int l, int which  , bool from_inputs, bool skip_ctx, int w0, int wstride, int lane) {
;     ...
;     const float* mod = p.MOD + (size_t)(l * 9 + (s < NCTX ? 8 : b)) * 6144 + (which ? 3 * 1024 : 0);
;     f32x4 sh[4], sc[4];
; #pragma unroll
;     for (int q = 0; q < 4; ++q) { sh[q] = *(const f32x4*)(mod + q * 256 + lane * 4); sc[q] = *(const f32x4*)(mod + 1024 + q * 256 + lane * 4); }
;     float ss = 0.f;
; #pragma unroll
;     for (int q = 0; q < 4; ++q) ss += v[q][0] * v[q][0] + v[q][1] * v[q][1] + v[q][2] * v[q][2] + v[q][3] * v[q][3];
;     ss = red64(ss);
;     const float rs = rsqrtf(ss * (1.f / 1024.f) + EPSF);
;     bf16_t* dst = p.HY + (size_t)row * DM;
; #pragma unroll
;     for (int q = 0; q < 4; ++q) {
;       float o[4];
; #pragma unroll
;       for (int j = 0; j < 4; ++j) o[j] = (v[q][j] * rs * gg[q][j]) * (1.f + sc[q][j]) + sh[q][j];
;       u32x2 w = {pk_bf16(o[0], o[1]), pk_bf16(o[2], o[3])};
;       *(u32x2*)(dst + q * 256 + lane * 4) = w;
;     }
	v_pk_mul_f32 v[246:247], v[18:19], v[18:19]
	v_pk_fma_f32 v[246:247], v[20:21], v[20:21], v[246:247]
	v_pk_fma_f32 v[246:247], v[22:23], v[22:23], v[246:247]
	v_pk_fma_f32 v[246:247], v[24:25], v[24:25], v[246:247]
	v_pk_fma_f32 v[246:247], v[26:27], v[26:27], v[246:247]
	v_pk_fma_f32 v[246:247], v[28:29], v[28:29], v[246:247]
	v_pk_fma_f32 v[246:247], v[30:31], v[30:31], v[246:247]
	v_pk_fma_f32 v[246:247], v[32:33], v[32:33], v[246:247]
	s_nop 0
	v_add_f32_e32 v246, v246, v247
	s_nop 1
	v_add_f32_dpp v246, v246, v246 quad_perm:[1,0,3,2] row_mask:0xf bank_mask:0xf
	s_nop 1
	v_add_f32_dpp v246, v246, v246 quad_perm:[2,3,0,1] row_mask:0xf bank_mask:0xf
	s_nop 1
	v_add_f32_dpp v246, v246, v246 row_half_mirror row_mask:0xf bank_mask:0xf
	s_nop 1
	v_add_f32_dpp v246, v246, v246 row_mirror row_mask:0xf bank_mask:0xf
	s_nop 1
	v_add_f32_dpp v246, v246, v246 row_bcast:15 row_mask:0xa bank_mask:0xf
	s_nop 1
	v_add_f32_dpp v246, v246, v246 row_bcast:31 row_mask:0xc bank_mask:0xf
	s_nop 1
	v_readlane_b32 s0, v246, 63
	s_add_i32 s21, s37, 0
	s_lshl_b32 s21, s21, 11
	s_add_u32 s10, s16, s21
	s_addc_u32 s11, s17, 0
	v_mov_b32_e32 v248, s0
	v_fmamk_f32 v248, v248, 0x3a800000, v143
	v_rsq_f32_e32 v248, v248
	s_nop 0
	v_pk_mul_f32 v[18:19], v[18:19], v[248:249] op_sel_hi:[1,0]
	v_pk_add_f32 v[50:51], v[50:51], 1.0 op_sel_hi:[1,0]
	v_pk_mul_f32 v[18:19], v[2:3], v[18:19]
	v_pk_fma_f32 v[18:19], v[50:51], v[18:19], v[34:35]
	v_pk_mul_f32 v[20:21], v[20:21], v[248:249] op_sel_hi:[1,0]
	v_pk_add_f32 v[52:53], v[52:53], 1.0 op_sel_hi:[1,0]
	v_pk_mul_f32 v[20:21], v[4:5], v[20:21]
	v_pk_fma_f32 v[20:21], v[52:53], v[20:21], v[36:37]
	v_cvt_pk_bf16_f32 v34, v18, v19
	v_cvt_pk_bf16_f32 v35, v20, v21
	global_store_dwordx2 v245, v[34:35], s[10:11]
	v_pk_mul_f32 v[22:23], v[22:23], v[248:249] op_sel_hi:[1,0]
	v_pk_add_f32 v[54:55], v[54:55], 1.0 op_sel_hi:[1,0]
	v_pk_mul_f32 v[22:23], v[6:7], v[22:23]
	v_pk_fma_f32 v[22:23], v[54:55], v[22:23], v[38:39]
	v_pk_mul_f32 v[24:25], v[24:25], v[248:249] op_sel_hi:[1,0]
	v_pk_add_f32 v[56:57], v[56:57], 1.0 op_sel_hi:[1,0]
	v_pk_mul_f32 v[24:25], v[8:9], v[24:25]
	v_pk_fma_f32 v[24:25], v[56:57], v[24:25], v[40:41]
	v_cvt_pk_bf16_f32 v38, v22, v23
	v_cvt_pk_bf16_f32 v39, v24, v25
	global_store_dwordx2 v245, v[38:39], s[10:11] offset:512
	v_pk_mul_f32 v[26:27], v[26:27], v[248:249] op_sel_hi:[1,0]
	v_pk_add_f32 v[58:59], v[58:59], 1.0 op_sel_hi:[1,0]
	v_pk_mul_f32 v[26:27], v[10:11], v[26:27]
	v_pk_fma_f32 v[26:27], v[58:59], v[26:27], v[42:43]
	v_pk_mul_f32 v[28:29], v[28:29], v[248:249] op_sel_hi:[1,0]
	v_pk_add_f32 v[60:61], v[60:61], 1.0 op_sel_hi:[1,0]
	v_pk_mul_f32 v[28:29], v[12:13], v[28:29]
	v_pk_fma_f32 v[28:29], v[60:61], v[28:29], v[44:45]
	v_cvt_pk_bf16_f32 v42, v26, v27
	v_cvt_pk_bf16_f32 v43, v28, v29
	global_store_dwordx2 v245, v[42:43], s[10:11] offset:1024
	v_pk_mul_f32 v[30:31], v[30:31], v[248:249] op_sel_hi:[1,0]
	v_pk_add_f32 v[62:63], v[62:63], 1.0 op_sel_hi:[1,0]
	v_pk_mul_f32 v[30:31], v[14:15], v[30:31]
	v_pk_fma_f32 v[30:31], v[62:63], v[30:31], v[46:47]
	v_pk_mul_f32 v[32:33], v[32:33], v[248:249] op_sel_hi:[1,0]
	v_pk_add_f32 v[64:65], v[64:65], 1.0 op_sel_hi:[1,0]
	v_pk_mul_f32 v[32:33], v[16:17], v[32:33]
	v_pk_fma_f32 v[32:33], v[64:65], v[32:33], v[48:49]
	v_cvt_pk_bf16_f32 v46, v30, v31
	v_cvt_pk_bf16_f32 v47, v32, v33
	global_store_dwordx2 v245, v[46:47], s[10:11] offset:1536
	s_waitcnt vmcnt(4)
	v_readfirstlane_b32 s6, v114
	s_cmp_ge_u32 s6, 8
	s_cbranch_scc1 .Ldep_norm1d_ok3
	s_add_i32 s6, s37, 768
	s_lshr_b32 s6, s6, 7
	s_lshl_b32 s6, s6, 2
	s_add_i32 s6, s6, 0x1e40
	v_mov_b32_e32 v110, s6

; DI unsigned pk_bf16(float lo, float hi) { f32x2 v = {lo, hi}; bf16v2 b = __builtin_convertvector(v, bf16v2); return __builtin_bit_cast(unsigned, b); }
; DI float red64(float x) { for (int o = 32; o > 0; o >>= 1) x += __shfl_xor(x, o); return x; }
; DI void modnorm_rows(const Params& p, int l, int which  , bool from_inputs, bool skip_ctx, int w0, int wstride, int lane) {
;     ...
;   for (; i < nrows; i += wstride) {
;     const int row = rowof(i); const int b = row / TB, s = row % TB;
;     f32x4 v[4];
; #pragma unroll
;     for (int q = 0; q < 4; ++q) v[q] = vn[q];
;     if (i + wstride < nrows) {
;       const int rn = rowof(i + wstride); const float* src = xsrc_row(p, from_inputs, rn / TB, rn % TB);
; #pragma unroll
;       for (int q = 0; q < 4; ++q) vn[q] = *(const f32x4*)(src + q * 256 + lane * 4);
;     }
;     const float* mod = p.MOD + (size_t)(l * 9 + (s < NCTX ? 8 : b)) * 6144 + (which ? 3 * 1024 : 0);
;     f32x4 sh[4], sc[4];
; #pragma unroll
;     for (int q = 0; q < 4; ++q) { sh[q] = *(const f32x4*)(mod + q * 256 + lane * 4); sc[q] = *(const f32x4*)(mod + 1024 + q * 256 + lane * 4); }
;     float ss = 0.f;
; #pragma unroll
;     for (int q = 0; q < 4; ++q) ss += v[q][0] * v[q][0] + v[q][1] * v[q][1] + v[q][2] * v[q][2] + v[q][3] * v[q][3];
;     ss = red64(ss);
;     const float rs = rsqrtf(ss * (1.f / 1024.f) + EPSF);
;     bf16_t* dst = p.HY + (size_t)row * DM;
; #pragma unroll
;     for (int q = 0; q < 4; ++q) {
;       float o[4];
; #pragma unroll
;       for (int j = 0; j < 4; ++j) o[j] = (v[q][j] * rs * gg[q][j]) * (1.f + sc[q][j]) + sh[q][j];
;       u32x2 w = {pk_bf16(o[0], o[1]), pk_bf16(o[2], o[3])};
;       *(u32x2*)(dst + q * 256 + lane * 4) = w;
;     }
.Ldep_norm1d_ok3:
	s_add_i32 s21, s37, 768
	s_mul_hi_u32 s7, s21, 0x38e38e39
	s_lshr_b32 s7, s7, 9
	s_mul_i32 s8, s7, 0x900
	s_sub_i32 s8, s21, s8
	s_lshl_b32 s9, s7, 11
	s_add_i32 s9, s9, s8
	s_add_i32 s9, s9, 0xffffff00
	s_lshl_b32 s10, s7, 8
	s_add_i32 s10, s10, s8
	s_cmpk_gt_i32 s8, 0xff
	s_cselect_b32 s9, s9, s10
	s_cselect_b32 s26, s12, s14
	s_cselect_b32 s27, s13, s15
	s_cselect_b32 s10, s7, 8
	s_lshl_b32 s9, s9, 12
	s_add_u32 s26, s26, s9
	s_addc_u32 s27, s27, 0
	s_add_i32 s10, s10, s82
	s_mul_i32 s10, s10, s24
	s_add_u32 s28, s58, s10
	s_addc_u32 s29, s59, 0
	s_add_u32 s28, s28, 0x0
	s_addc_u32 s29, s29, 0
	s_add_u32 s0, s28, 0x1000
	s_addc_u32 s1, s29, 0
	global_load_dwordx4 v[18:21], v244, s[26:27]
	global_load_dwordx4 v[22:25], v244, s[26:27] offset:1024
	global_load_dwordx4 v[26:29], v244, s[26:27] offset:2048
	global_load_dwordx4 v[30:33], v244, s[26:27] offset:3072
	global_load_dwordx4 v[34:37], v244, s[28:29]
	global_load_dwordx4 v[38:41], v244, s[28:29] offset:1024
	global_load_dwordx4 v[42:45], v244, s[28:29] offset:2048
	global_load_dwordx4 v[46:49], v244, s[28:29] offset:3072
	global_load_dwordx4 v[50:53], v244, s[0:1]
	global_load_dwordx4 v[54:57], v244, s[0:1] offset:1024
	global_load_dwordx4 v[58:61], v244, s[0:1] offset:2048
	global_load_dwordx4 v[62:65], v244, s[0:1] offset:3072
	s_add_i32 s6, s37, 1024
	s_lshr_b32 s6, s6, 7
	s_lshl_b32 s6, s6, 2
	s_add_i32 s6, s6, 0x1e40
	v_mov_b32_e32 v110, s6
	global_load_dword v114, v110, s[70:71] sc1
	s_waitcnt vmcnt(30)
	v_pk_mul_f32 v[246:247], v[66:67], v[66:67]
	v_pk_fma_f32 v[246:247], v[68:69], v[68:69], v[246:247]
	v_pk_fma_f32 v[246:247], v[70:71], v[70:71], v[246:247]
	v_pk_fma_f32 v[246:247], v[72:73], v[72:73], v[246:247]
	v_pk_fma_f32 v[246:247], v[74:75], v[74:75], v[246:247]
	v_pk_fma_f32 v[246:247], v[76:77], v[76:77], v[246:247]
	v_pk_fma_f32 v[246:247], v[78:79], v[78:79], v[246:247]
	v_pk_fma_f32 v[246:247], v[80:81], v[80:81], v[246:247]
	s_nop 0
	v_add_f32_e32 v246, v246, v247
	s_nop 1
	v_add_f32_dpp v246, v246, v246 quad_perm:[1,0,3,2] row_mask:0xf bank_mask:0xf
	s_nop 1
	v_add_f32_dpp v246, v246, v246 quad_perm:[2,3,0,1] row_mask:0xf bank_mask:0xf
	s_nop 1
	v_add_f32_dpp v246, v246, v246 row_half_mirror row_mask:0xf bank_mask:0xf
	s_nop 1
	v_add_f32_dpp v246, v246, v246 row_mirror row_mask:0xf bank_mask:0xf
	s_nop 1
	v_add_f32_dpp v246, v246, v246 row_bcast:15 row_mask:0xa bank_mask:0xf
	s_nop 1
	v_add_f32_dpp v246, v246, v246 row_bcast:31 row_mask:0xc bank_mask:0xf
	s_nop 1
	v_readlane_b32 s0, v246, 63
	s_add_i32 s21, s37, 256
	s_lshl_b32 s21, s21, 11
	s_add_u32 s10, s16, s21
	s_addc_u32 s11, s17, 0
	v_mov_b32_e32 v248, s0
	v_fmamk_f32 v248, v248, 0x3a800000, v143
	v_rsq_f32_e32 v248, v248
	s_nop 0
	v_pk_mul_f32 v[66:67], v[66:67], v[248:249] op_sel_hi:[1,0]
	v_pk_add_f32 v[98:99], v[98:99], 1.0 op_sel_hi:[1,0]
	v_pk_mul_f32 v[66:67], v[2:3], v[66:67]
	v_pk_fma_f32 v[66:67], v[98:99], v[66:67], v[82:83]
	v_pk_mul_f32 v[68:69], v[68:69], v[248:249] op_sel_hi:[1,0]
	v_pk_add_f32 v[100:101], v[100:101], 1.0 op_sel_hi:[1,0]
	v_pk_mul_f32 v[68:69], v[4:5], v[68:69]
	v_pk_fma_f32 v[68:69], v[100:101], v[68:69], v[84:85]
	v_cvt_pk_bf16_f32 v82, v66, v67
	v_cvt_pk_bf16_f32 v83, v68, v69
	global_store_dwordx2 v245, v[82:83], s[10:11]
	v_pk_mul_f32 v[70:71], v[70:71], v[248:249] op_sel_hi:[1,0]
	v_pk_add_f32 v[102:103], v[102:103], 1.0 op_sel_hi:[1,0]
	v_pk_mul_f32 v[70:71], v[6:7], v[70:71]
	v_pk_fma_f32 v[70:71], v[102:103], v[70:71], v[86:87]
	v_pk_mul_f32 v[72:73], v[72:73], v[248:249] op_sel_hi:[1,0]
	v_pk_add_f32 v[104:105], v[104:105], 1.0 op_sel_hi:[1,0]
	v_pk_mul_f32 v[72:73], v[8:9], v[72:73]
	v_pk_fma_f32 v[72:73], v[104:105], v[72:73], v[88:89]
	v_cvt_pk_bf16_f32 v86, v70, v71
	v_cvt_pk_bf16_f32 v87, v72, v73
	global_store_dwordx2 v245, v[86:87], s[10:11] offset:512
	v_pk_mul_f32 v[74:75], v[74:75], v[248:249] op_sel_hi:[1,0]
	v_pk_add_f32 v[106:107], v[106:107], 1.0 op_sel_hi:[1,0]
	v_pk_mul_f32 v[74:75], v[10:11], v[74:75]
	v_pk_fma_f32 v[74:75], v[106:107], v[74:75], v[90:91]
	v_pk_mul_f32 v[76:77], v[76:77], v[248:249] op_sel_hi:[1,0]
	v_pk_add_f32 v[108:109], v[108:109], 1.0 op_sel_hi:[1,0]
	v_pk_mul_f32 v[76:77], v[12:13], v[76:77]
	v_pk_fma_f32 v[76:77], v[108:109], v[76:77], v[92:93]
	v_cvt_pk_bf16_f32 v90, v74, v75
	v_cvt_pk_bf16_f32 v91, v76, v77
	global_store_dwordx2 v245, v[90:91], s[10:11] offset:1024
	v_pk_mul_f32 v[78:79], v[78:79], v[248:249] op_sel_hi:[1,0]
	v_pk_add_f32 v[118:119], v[118:119], 1.0 op_sel_hi:[1,0]
	v_pk_mul_f32 v[78:79], v[14:15], v[78:79]
	v_pk_fma_f32 v[78:79], v[118:119], v[78:79], v[94:95]
	v_pk_mul_f32 v[80:81], v[80:81], v[248:249] op_sel_hi:[1,0]
	v_pk_add_f32 v[120:121], v[120:121], 1.0 op_sel_hi:[1,0]
	v_pk_mul_f32 v[80:81], v[16:17], v[80:81]
	v_pk_fma_f32 v[80:81], v[120:121], v[80:81], v[96:97]
	v_cvt_pk_bf16_f32 v94, v78, v79
	v_cvt_pk_bf16_f32 v95, v80, v81
	global_store_dwordx2 v245, v[94:95], s[10:11] offset:1536
	s_waitcnt vmcnt(4)
	v_readfirstlane_b32 s6, v114
	s_cmp_ge_u32 s6, 8
	s_cbranch_scc1 .Ldep_norm1d_ok4
	s_add_i32 s6, s37, 1024
	s_lshr_b32 s6, s6, 7
	s_lshl_b32 s6, s6, 2
	s_add_i32 s6, s6, 0x1e40
	v_mov_b32_e32 v110, s6

; DI unsigned pk_bf16(float lo, float hi) { f32x2 v = {lo, hi}; bf16v2 b = __builtin_convertvector(v, bf16v2); return __builtin_bit_cast(unsigned, b); }
; DI float red64(float x) { for (int o = 32; o > 0; o >>= 1) x += __shfl_xor(x, o); return x; }
; DI void modnorm_rows(const Params& p, int l, int which  , bool from_inputs, bool skip_ctx, int w0, int wstride, int lane) {
;     ...
;   for (; i < nrows; i += wstride) {
;     const int row = rowof(i); const int b = row / TB, s = row % TB;
;     f32x4 v[4];
; #pragma unroll
;     for (int q = 0; q < 4; ++q) v[q] = vn[q];
;     if (i + wstride < nrows) {
;       const int rn = rowof(i + wstride); const float* src = xsrc_row(p, from_inputs, rn / TB, rn % TB);
; #pragma unroll
;       for (int q = 0; q < 4; ++q) vn[q] = *(const f32x4*)(src + q * 256 + lane * 4);
;     }
;     const float* mod = p.MOD + (size_t)(l * 9 + (s < NCTX ? 8 : b)) * 6144 + (which ? 3 * 1024 : 0);
;     f32x4 sh[4], sc[4];
; #pragma unroll
;     for (int q = 0; q < 4; ++q) { sh[q] = *(const f32x4*)(mod + q * 256 + lane * 4); sc[q] = *(const f32x4*)(mod + 1024 + q * 256 + lane * 4); }
;     float ss = 0.f;
; #pragma unroll
;     for (int q = 0; q < 4; ++q) ss += v[q][0] * v[q][0] + v[q][1] * v[q][1] + v[q][2] * v[q][2] + v[q][3] * v[q][3];
;     ss = red64(ss);
;     const float rs = rsqrtf(ss * (1.f / 1024.f) + EPSF);
;     bf16_t* dst = p.HY + (size_t)row * DM;
; #pragma unroll
;     for (int q = 0; q < 4; ++q) {
;       float o[4];
; #pragma unroll
;       for (int j = 0; j < 4; ++j) o[j] = (v[q][j] * rs * gg[q][j]) * (1.f + sc[q][j]) + sh[q][j];
;       u32x2 w = {pk_bf16(o[0], o[1]), pk_bf16(o[2], o[3])};
;       *(u32x2*)(dst + q * 256 + lane * 4) = w;
;     }
.Ldep_norm1d_ok4:
	s_add_i32 s21, s37, 1024
	s_mul_hi_u32 s7, s21, 0x38e38e39
	s_lshr_b32 s7, s7, 9
	s_mul_i32 s8, s7, 0x900
	s_sub_i32 s8, s21, s8
	s_lshl_b32 s9, s7, 11
	s_add_i32 s9, s9, s8
	s_add_i32 s9, s9, 0xffffff00
	s_lshl_b32 s10, s7, 8
	s_add_i32 s10, s10, s8
	s_cmpk_gt_i32 s8, 0xff
	s_cselect_b32 s9, s9, s10
	s_cselect_b32 s26, s12, s14
	s_cselect_b32 s27, s13, s15
	s_cselect_b32 s10, s7, 8
	s_lshl_b32 s9, s9, 12
	s_add_u32 s26, s26, s9
	s_addc_u32 s27, s27, 0
	s_add_i32 s10, s10, s82
	s_mul_i32 s10, s10, s24
	s_add_u32 s28, s58, s10
	s_addc_u32 s29, s59, 0
	s_add_u32 s28, s28, 0x0
	s_addc_u32 s29, s29, 0
	s_add_u32 s0, s28, 0x1000
	s_addc_u32 s1, s29, 0
	global_load_dwordx4 v[66:69], v244, s[26:27]
	global_load_dwordx4 v[70:73], v244, s[26:27] offset:1024
	global_load_dwordx4 v[74:77], v244, s[26:27] offset:2048
	global_load_dwordx4 v[78:81], v244, s[26:27] offset:3072
	global_load_dwordx4 v[82:85], v244, s[28:29]
	global_load_dwordx4 v[86:89], v244, s[28:29] offset:1024
	global_load_dwordx4 v[90:93], v244, s[28:29] offset:2048
	global_load_dwordx4 v[94:97], v244, s[28:29] offset:3072
	global_load_dwordx4 v[98:101], v244, s[0:1]
	global_load_dwordx4 v[102:105], v244, s[0:1] offset:1024
	global_load_dwordx4 v[106:109], v244, s[0:1] offset:2048
	global_load_dwordx4 v[118:121], v244, s[0:1] offset:3072
	s_add_i32 s6, s37, 1280
	s_lshr_b32 s6, s6, 7
	s_lshl_b32 s6, s6, 2
	s_add_i32 s6, s6, 0x1e40
	v_mov_b32_e32 v110, s6
	global_load_dword v114, v110, s[70:71] sc1
	s_waitcnt vmcnt(35)
	v_pk_mul_f32 v[246:247], v[122:123], v[122:123]
	v_pk_fma_f32 v[246:247], v[124:125], v[124:125], v[246:247]
	v_pk_fma_f32 v[246:247], v[126:127], v[126:127], v[246:247]
	v_pk_fma_f32 v[246:247], v[128:129], v[128:129], v[246:247]
	v_pk_fma_f32 v[246:247], v[130:131], v[130:131], v[246:247]
	v_pk_fma_f32 v[246:247], v[132:133], v[132:133], v[246:247]
	v_pk_fma_f32 v[246:247], v[134:135], v[134:135], v[246:247]
	v_pk_fma_f32 v[246:247], v[136:137], v[136:137], v[246:247]
	s_nop 0
	v_add_f32_e32 v246, v246, v247
	s_nop 1
	v_add_f32_dpp v246, v246, v246 quad_perm:[1,0,3,2] row_mask:0xf bank_mask:0xf
	s_nop 1
	v_add_f32_dpp v246, v246, v246 quad_perm:[2,3,0,1] row_mask:0xf bank_mask:0xf
	s_nop 1
	v_add_f32_dpp v246, v246, v246 row_half_mirror row_mask:0xf bank_mask:0xf
	s_nop 1
	v_add_f32_dpp v246, v246, v246 row_mirror row_mask:0xf bank_mask:0xf
	s_nop 1
	v_add_f32_dpp v246, v246, v246 row_bcast:15 row_mask:0xa bank_mask:0xf
	s_nop 1
	v_add_f32_dpp v246, v246, v246 row_bcast:31 row_mask:0xc bank_mask:0xf
	s_nop 1
	v_readlane_b32 s0, v246, 63
	s_add_i32 s21, s37, 512
	s_lshl_b32 s21, s21, 11
	s_add_u32 s10, s16, s21
	s_addc_u32 s11, s17, 0
	v_mov_b32_e32 v248, s0
	v_fmamk_f32 v248, v248, 0x3a800000, v143
	v_rsq_f32_e32 v248, v248
	s_nop 0
	v_pk_mul_f32 v[122:123], v[122:123], v[248:249] op_sel_hi:[1,0]
	v_pk_add_f32 v[176:177], v[176:177], 1.0 op_sel_hi:[1,0]
	v_pk_mul_f32 v[122:123], v[2:3], v[122:123]
	v_pk_fma_f32 v[122:123], v[176:177], v[122:123], v[160:161]
	v_pk_mul_f32 v[124:125], v[124:125], v[248:249] op_sel_hi:[1,0]
	v_pk_add_f32 v[178:179], v[178:179], 1.0 op_sel_hi:[1,0]
	v_pk_mul_f32 v[124:125], v[4:5], v[124:125]
	v_pk_fma_f32 v[124:125], v[178:179], v[124:125], v[162:163]
	v_cvt_pk_bf16_f32 v160, v122, v123
	v_cvt_pk_bf16_f32 v161, v124, v125
	global_store_dwordx2 v245, v[160:161], s[10:11]
	v_pk_mul_f32 v[126:127], v[126:127], v[248:249] op_sel_hi:[1,0]
	v_pk_add_f32 v[180:181], v[180:181], 1.0 op_sel_hi:[1,0]
	v_pk_mul_f32 v[126:127], v[6:7], v[126:127]
	v_pk_fma_f32 v[126:127], v[180:181], v[126:127], v[164:165]
	v_pk_mul_f32 v[128:129], v[128:129], v[248:249] op_sel_hi:[1,0]
	v_pk_add_f32 v[182:183], v[182:183], 1.0 op_sel_hi:[1,0]
	v_pk_mul_f32 v[128:129], v[8:9], v[128:129]
	v_pk_fma_f32 v[128:129], v[182:183], v[128:129], v[166:167]
	v_cvt_pk_bf16_f32 v164, v126, v127
	v_cvt_pk_bf16_f32 v165, v128, v129
	global_store_dwordx2 v245, v[164:165], s[10:11] offset:512
	v_pk_mul_f32 v[130:131], v[130:131], v[248:249] op_sel_hi:[1,0]
	v_pk_add_f32 v[184:185], v[184:185], 1.0 op_sel_hi:[1,0]
	v_pk_mul_f32 v[130:131], v[10:11], v[130:131]
	v_pk_fma_f32 v[130:131], v[184:185], v[130:131], v[168:169]
	v_pk_mul_f32 v[132:133], v[132:133], v[248:249] op_sel_hi:[1,0]
	v_pk_add_f32 v[186:187], v[186:187], 1.0 op_sel_hi:[1,0]
	v_pk_mul_f32 v[132:133], v[12:13], v[132:133]
	v_pk_fma_f32 v[132:133], v[186:187], v[132:133], v[170:171]
	v_cvt_pk_bf16_f32 v168, v130, v131
	v_cvt_pk_bf16_f32 v169, v132, v133
	global_store_dwordx2 v245, v[168:169], s[10:11] offset:1024
	v_pk_mul_f32 v[134:135], v[134:135], v[248:249] op_sel_hi:[1,0]
	v_pk_add_f32 v[188:189], v[188:189], 1.0 op_sel_hi:[1,0]
	v_pk_mul_f32 v[134:135], v[14:15], v[134:135]
	v_pk_fma_f32 v[134:135], v[188:189], v[134:135], v[172:173]
	v_pk_mul_f32 v[136:137], v[136:137], v[248:249] op_sel_hi:[1,0]
	v_pk_add_f32 v[190:191], v[190:191], 1.0 op_sel_hi:[1,0]
	v_pk_mul_f32 v[136:137], v[16:17], v[136:137]
	v_pk_fma_f32 v[136:137], v[190:191], v[136:137], v[174:175]
	v_cvt_pk_bf16_f32 v172, v134, v135
	v_cvt_pk_bf16_f32 v173, v136, v137
	global_store_dwordx2 v245, v[172:173], s[10:11] offset:1536
	s_waitcnt vmcnt(4)
	v_readfirstlane_b32 s6, v114
	s_cmp_ge_u32 s6, 8
	s_cbranch_scc1 .Ldep_norm1d_ok5
	s_add_i32 s6, s37, 1280
	s_lshr_b32 s6, s6, 7
	s_lshl_b32 s6, s6, 2
	s_add_i32 s6, s6, 0x1e40
	v_mov_b32_e32 v110, s6

; DI unsigned pk_bf16(float lo, float hi) { f32x2 v = {lo, hi}; bf16v2 b = __builtin_convertvector(v, bf16v2); return __builtin_bit_cast(unsigned, b); }
; DI float red64(float x) { for (int o = 32; o > 0; o >>= 1) x += __shfl_xor(x, o); return x; }
; DI void modnorm_rows(const Params& p, int l, int which  , bool from_inputs, bool skip_ctx, int w0, int wstride, int lane) {
;     ...
;   for (; i < nrows; i += wstride) {
;     const int row = rowof(i); const int b = row / TB, s = row % TB;
;     f32x4 v[4];
; #pragma unroll
;     for (int q = 0; q < 4; ++q) v[q] = vn[q];
;     if (i + wstride < nrows) {
;       const int rn = rowof(i + wstride); const float* src = xsrc_row(p, from_inputs, rn / TB, rn % TB);
; #pragma unroll
;       for (int q = 0; q < 4; ++q) vn[q] = *(const f32x4*)(src + q * 256 + lane * 4);
;     }
;     const float* mod = p.MOD + (size_t)(l * 9 + (s < NCTX ? 8 : b)) * 6144 + (which ? 3 * 1024 : 0);
;     f32x4 sh[4], sc[4];
; #pragma unroll
;     for (int q = 0; q < 4; ++q) { sh[q] = *(const f32x4*)(mod + q * 256 + lane * 4); sc[q] = *(const f32x4*)(mod + 1024 + q * 256 + lane * 4); }
;     float ss = 0.f;
; #pragma unroll
;     for (int q = 0; q < 4; ++q) ss += v[q][0] * v[q][0] + v[q][1] * v[q][1] + v[q][2] * v[q][2] + v[q][3] * v[q][3];
;     ss = red64(ss);
;     const float rs = rsqrtf(ss * (1.f / 1024.f) + EPSF);
;     bf16_t* dst = p.HY + (size_t)row * DM;
; #pragma unroll
;     for (int q = 0; q < 4; ++q) {
;       float o[4];
; #pragma unroll
;       for (int j = 0; j < 4; ++j) o[j] = (v[q][j] * rs * gg[q][j]) * (1.f + sc[q][j]) + sh[q][j];
;       u32x2 w = {pk_bf16(o[0], o[1]), pk_bf16(o[2], o[3])};
;       *(u32x2*)(dst + q * 256 + lane * 4) = w;
;     }
.Ldep_norm1d_ok5:
	s_add_i32 s21, s37, 1280
	s_mul_hi_u32 s7, s21, 0x38e38e39
	s_lshr_b32 s7, s7, 9
	s_mul_i32 s8, s7, 0x900
	s_sub_i32 s8, s21, s8
	s_lshl_b32 s9, s7, 11
	s_add_i32 s9, s9, s8
	s_add_i32 s9, s9, 0xffffff00
	s_lshl_b32 s10, s7, 8
	s_add_i32 s10, s10, s8
	s_cmpk_gt_i32 s8, 0xff
	s_cselect_b32 s9, s9, s10
	s_cselect_b32 s26, s12, s14
	s_cselect_b32 s27, s13, s15
	s_cselect_b32 s10, s7, 8
	s_lshl_b32 s9, s9, 12
	s_add_u32 s26, s26, s9
	s_addc_u32 s27, s27, 0
	s_add_i32 s10, s10, s82
	s_mul_i32 s10, s10, s24
	s_add_u32 s28, s58, s10
	s_addc_u32 s29, s59, 0
	s_add_u32 s28, s28, 0x0
	s_addc_u32 s29, s29, 0
	s_add_u32 s0, s28, 0x1000
	s_addc_u32 s1, s29, 0
	global_load_dwordx4 v[122:125], v244, s[26:27]
	global_load_dwordx4 v[126:129], v244, s[26:27] offset:1024
	global_load_dwordx4 v[130:133], v244, s[26:27] offset:2048
	global_load_dwordx4 v[134:137], v244, s[26:27] offset:3072
	global_load_dwordx4 v[160:163], v244, s[28:29]
	global_load_dwordx4 v[164:167], v244, s[28:29] offset:1024
	global_load_dwordx4 v[168:171], v244, s[28:29] offset:2048
	global_load_dwordx4 v[172:175], v244, s[28:29] offset:3072
	global_load_dwordx4 v[176:179], v244, s[0:1]
	global_load_dwordx4 v[180:183], v244, s[0:1] offset:1024
	global_load_dwordx4 v[184:187], v244, s[0:1] offset:2048
	global_load_dwordx4 v[188:191], v244, s[0:1] offset:3072
	s_add_i32 s6, s37, 1536
	s_lshr_b32 s6, s6, 7
	s_lshl_b32 s6, s6, 2
	s_add_i32 s6, s6, 0x1e40
	v_mov_b32_e32 v110, s6
	global_load_dword v114, v110, s[70:71] sc1
	s_waitcnt vmcnt(35)
	v_pk_mul_f32 v[246:247], v[18:19], v[18:19]
	v_pk_fma_f32 v[246:247], v[20:21], v[20:21], v[246:247]
	v_pk_fma_f32 v[246:247], v[22:23], v[22:23], v[246:247]
	v_pk_fma_f32 v[246:247], v[24:25], v[24:25], v[246:247]
	v_pk_fma_f32 v[246:247], v[26:27], v[26:27], v[246:247]
	v_pk_fma_f32 v[246:247], v[28:29], v[28:29], v[246:247]
	v_pk_fma_f32 v[246:247], v[30:31], v[30:31], v[246:247]
	v_pk_fma_f32 v[246:247], v[32:33], v[32:33], v[246:247]
	s_nop 0
	v_add_f32_e32 v246, v246, v247
	s_nop 1
	v_add_f32_dpp v246, v246, v246 quad_perm:[1,0,3,2] row_mask:0xf bank_mask:0xf
	s_nop 1
	v_add_f32_dpp v246, v246, v246 quad_perm:[2,3,0,1] row_mask:0xf bank_mask:0xf
	s_nop 1
	v_add_f32_dpp v246, v246, v246 row_half_mirror row_mask:0xf bank_mask:0xf
	s_nop 1
	v_add_f32_dpp v246, v246, v246 row_mirror row_mask:0xf bank_mask:0xf
	s_nop 1
	v_add_f32_dpp v246, v246, v246 row_bcast:15 row_mask:0xa bank_mask:0xf
	s_nop 1
	v_add_f32_dpp v246, v246, v246 row_bcast:31 row_mask:0xc bank_mask:0xf
	s_nop 1
	v_readlane_b32 s0, v246, 63
	s_add_i32 s21, s37, 768
	s_lshl_b32 s21, s21, 11
	s_add_u32 s10, s16, s21
	s_addc_u32 s11, s17, 0
	v_mov_b32_e32 v248, s0
	v_fmamk_f32 v248, v248, 0x3a800000, v143
	v_rsq_f32_e32 v248, v248
	s_nop 0
	v_pk_mul_f32 v[18:19], v[18:19], v[248:249] op_sel_hi:[1,0]
	v_pk_add_f32 v[50:51], v[50:51], 1.0 op_sel_hi:[1,0]
	v_pk_mul_f32 v[18:19], v[2:3], v[18:19]
	v_pk_fma_f32 v[18:19], v[50:51], v[18:19], v[34:35]
	v_pk_mul_f32 v[20:21], v[20:21], v[248:249] op_sel_hi:[1,0]
	v_pk_add_f32 v[52:53], v[52:53], 1.0 op_sel_hi:[1,0]
	v_pk_mul_f32 v[20:21], v[4:5], v[20:21]
	v_pk_fma_f32 v[20:21], v[52:53], v[20:21], v[36:37]
	v_cvt_pk_bf16_f32 v34, v18, v19
	v_cvt_pk_bf16_f32 v35, v20, v21
	global_store_dwordx2 v245, v[34:35], s[10:11]
	v_pk_mul_f32 v[22:23], v[22:23], v[248:249] op_sel_hi:[1,0]
	v_pk_add_f32 v[54:55], v[54:55], 1.0 op_sel_hi:[1,0]
	v_pk_mul_f32 v[22:23], v[6:7], v[22:23]
	v_pk_fma_f32 v[22:23], v[54:55], v[22:23], v[38:39]
	v_pk_mul_f32 v[24:25], v[24:25], v[248:249] op_sel_hi:[1,0]
	v_pk_add_f32 v[56:57], v[56:57], 1.0 op_sel_hi:[1,0]
	v_pk_mul_f32 v[24:25], v[8:9], v[24:25]
	v_pk_fma_f32 v[24:25], v[56:57], v[24:25], v[40:41]
	v_cvt_pk_bf16_f32 v38, v22, v23
	v_cvt_pk_bf16_f32 v39, v24, v25
	global_store_dwordx2 v245, v[38:39], s[10:11] offset:512
	v_pk_mul_f32 v[26:27], v[26:27], v[248:249] op_sel_hi:[1,0]
	v_pk_add_f32 v[58:59], v[58:59], 1.0 op_sel_hi:[1,0]
	v_pk_mul_f32 v[26:27], v[10:11], v[26:27]
	v_pk_fma_f32 v[26:27], v[58:59], v[26:27], v[42:43]
	v_pk_mul_f32 v[28:29], v[28:29], v[248:249] op_sel_hi:[1,0]
	v_pk_add_f32 v[60:61], v[60:61], 1.0 op_sel_hi:[1,0]
	v_pk_mul_f32 v[28:29], v[12:13], v[28:29]
	v_pk_fma_f32 v[28:29], v[60:61], v[28:29], v[44:45]
	v_cvt_pk_bf16_f32 v42, v26, v27
	v_cvt_pk_bf16_f32 v43, v28, v29
	global_store_dwordx2 v245, v[42:43], s[10:11] offset:1024
	v_pk_mul_f32 v[30:31], v[30:31], v[248:249] op_sel_hi:[1,0]
	v_pk_add_f32 v[62:63], v[62:63], 1.0 op_sel_hi:[1,0]
	v_pk_mul_f32 v[30:31], v[14:15], v[30:31]
	v_pk_fma_f32 v[30:31], v[62:63], v[30:31], v[46:47]
	v_pk_mul_f32 v[32:33], v[32:33], v[248:249] op_sel_hi:[1,0]
	v_pk_add_f32 v[64:65], v[64:65], 1.0 op_sel_hi:[1,0]
	v_pk_mul_f32 v[32:33], v[16:17], v[32:33]
	v_pk_fma_f32 v[32:33], v[64:65], v[32:33], v[48:49]
	v_cvt_pk_bf16_f32 v46, v30, v31
	v_cvt_pk_bf16_f32 v47, v32, v33
	global_store_dwordx2 v245, v[46:47], s[10:11] offset:1536
	s_waitcnt vmcnt(4)
	v_readfirstlane_b32 s6, v114
	s_cmp_ge_u32 s6, 8
	s_cbranch_scc1 .Ldep_norm1d_ok6
	s_add_i32 s6, s37, 1536
	s_lshr_b32 s6, s6, 7
	s_lshl_b32 s6, s6, 2
	s_add_i32 s6, s6, 0x1e40
	v_mov_b32_e32 v110, s6

; DI unsigned pk_bf16(float lo, float hi) { f32x2 v = {lo, hi}; bf16v2 b = __builtin_convertvector(v, bf16v2); return __builtin_bit_cast(unsigned, b); }
; DI float red64(float x) { for (int o = 32; o > 0; o >>= 1) x += __shfl_xor(x, o); return x; }
; DI void modnorm_rows(const Params& p, int l, int which  , bool from_inputs, bool skip_ctx, int w0, int wstride, int lane) {
;     ...
;   for (; i < nrows; i += wstride) {
;     const int row = rowof(i); const int b = row / TB, s = row % TB;
;     f32x4 v[4];
; #pragma unroll
;     for (int q = 0; q < 4; ++q) v[q] = vn[q];
;     if (i + wstride < nrows) {
;       const int rn = rowof(i + wstride); const float* src = xsrc_row(p, from_inputs, rn / TB, rn % TB);
; #pragma unroll
;       for (int q = 0; q < 4; ++q) vn[q] = *(const f32x4*)(src + q * 256 + lane * 4);
;     }
;     const float* mod = p.MOD + (size_t)(l * 9 + (s < NCTX ? 8 : b)) * 6144 + (which ? 3 * 1024 : 0);
;     f32x4 sh[4], sc[4];
; #pragma unroll
;     for (int q = 0; q < 4; ++q) { sh[q] = *(const f32x4*)(mod + q * 256 + lane * 4); sc[q] = *(const f32x4*)(mod + 1024 + q * 256 + lane * 4); }
;     float ss = 0.f;
; #pragma unroll
;     for (int q = 0; q < 4; ++q) ss += v[q][0] * v[q][0] + v[q][1] * v[q][1] + v[q][2] * v[q][2] + v[q][3] * v[q][3];
;     ss = red64(ss);
;     const float rs = rsqrtf(ss * (1.f / 1024.f) + EPSF);
;     bf16_t* dst = p.HY + (size_t)row * DM;
; #pragma unroll
;     for (int q = 0; q < 4; ++q) {
;       float o[4];
; #pragma unroll
;       for (int j = 0; j < 4; ++j) o[j] = (v[q][j] * rs * gg[q][j]) * (1.f + sc[q][j]) + sh[q][j];
;       u32x2 w = {pk_bf16(o[0], o[1]), pk_bf16(o[2], o[3])};
;       *(u32x2*)(dst + q * 256 + lane * 4) = w;
;     }
.Ldep_norm1d_ok6:
	s_add_i32 s21, s37, 1536
	s_mul_hi_u32 s7, s21, 0x38e38e39
	s_lshr_b32 s7, s7, 9
	s_mul_i32 s8, s7, 0x900
	s_sub_i32 s8, s21, s8
	s_lshl_b32 s9, s7, 11
	s_add_i32 s9, s9, s8
	s_add_i32 s9, s9, 0xffffff00
	s_lshl_b32 s10, s7, 8
	s_add_i32 s10, s10, s8
	s_cmpk_gt_i32 s8, 0xff
	s_cselect_b32 s9, s9, s10
	s_cselect_b32 s26, s12, s14
	s_cselect_b32 s27, s13, s15
	s_cselect_b32 s10, s7, 8
	s_lshl_b32 s9, s9, 12
	s_add_u32 s26, s26, s9
	s_addc_u32 s27, s27, 0
	s_add_i32 s10, s10, s82
	s_mul_i32 s10, s10, s24
	s_add_u32 s28, s58, s10
	s_addc_u32 s29, s59, 0
	s_add_u32 s28, s28, 0x0
	s_addc_u32 s29, s29, 0
	s_add_u32 s0, s28, 0x1000
	s_addc_u32 s1, s29, 0
	global_load_dwordx4 v[18:21], v244, s[26:27]
	global_load_dwordx4 v[22:25], v244, s[26:27] offset:1024
	global_load_dwordx4 v[26:29], v244, s[26:27] offset:2048
	global_load_dwordx4 v[30:33], v244, s[26:27] offset:3072
	global_load_dwordx4 v[34:37], v244, s[28:29]
	global_load_dwordx4 v[38:41], v244, s[28:29] offset:1024
	global_load_dwordx4 v[42:45], v244, s[28:29] offset:2048
	global_load_dwordx4 v[46:49], v244, s[28:29] offset:3072
	global_load_dwordx4 v[50:53], v244, s[0:1]
	global_load_dwordx4 v[54:57], v244, s[0:1] offset:1024
	global_load_dwordx4 v[58:61], v244, s[0:1] offset:2048
	global_load_dwordx4 v[62:65], v244, s[0:1] offset:3072
	s_add_i32 s6, s37, 1792
	s_lshr_b32 s6, s6, 7
	s_lshl_b32 s6, s6, 2
	s_add_i32 s6, s6, 0x1e40
	v_mov_b32_e32 v110, s6
	global_load_dword v114, v110, s[70:71] sc1
	s_waitcnt vmcnt(35)
	v_pk_mul_f32 v[246:247], v[66:67], v[66:67]
	v_pk_fma_f32 v[246:247], v[68:69], v[68:69], v[246:247]
	v_pk_fma_f32 v[246:247], v[70:71], v[70:71], v[246:247]
	v_pk_fma_f32 v[246:247], v[72:73], v[72:73], v[246:247]
	v_pk_fma_f32 v[246:247], v[74:75], v[74:75], v[246:247]
	v_pk_fma_f32 v[246:247], v[76:77], v[76:77], v[246:247]
	v_pk_fma_f32 v[246:247], v[78:79], v[78:79], v[246:247]
	v_pk_fma_f32 v[246:247], v[80:81], v[80:81], v[246:247]
	s_nop 0
	v_add_f32_e32 v246, v246, v247
	s_nop 1
	v_add_f32_dpp v246, v246, v246 quad_perm:[1,0,3,2] row_mask:0xf bank_mask:0xf
	s_nop 1
	v_add_f32_dpp v246, v246, v246 quad_perm:[2,3,0,1] row_mask:0xf bank_mask:0xf
	s_nop 1
	v_add_f32_dpp v246, v246, v246 row_half_mirror row_mask:0xf bank_mask:0xf
	s_nop 1
	v_add_f32_dpp v246, v246, v246 row_mirror row_mask:0xf bank_mask:0xf
	s_nop 1
	v_add_f32_dpp v246, v246, v246 row_bcast:15 row_mask:0xa bank_mask:0xf
	s_nop 1
	v_add_f32_dpp v246, v246, v246 row_bcast:31 row_mask:0xc bank_mask:0xf
	s_nop 1
	v_readlane_b32 s0, v246, 63
	s_add_i32 s21, s37, 1024
	s_lshl_b32 s21, s21, 11
	s_add_u32 s10, s16, s21
	s_addc_u32 s11, s17, 0
	v_mov_b32_e32 v248, s0
	v_fmamk_f32 v248, v248, 0x3a800000, v143
	v_rsq_f32_e32 v248, v248
	s_nop 0
	v_pk_mul_f32 v[66:67], v[66:67], v[248:249] op_sel_hi:[1,0]
	v_pk_add_f32 v[98:99], v[98:99], 1.0 op_sel_hi:[1,0]
	v_pk_mul_f32 v[66:67], v[2:3], v[66:67]
	v_pk_fma_f32 v[66:67], v[98:99], v[66:67], v[82:83]
	v_pk_mul_f32 v[68:69], v[68:69], v[248:249] op_sel_hi:[1,0]
	v_pk_add_f32 v[100:101], v[100:101], 1.0 op_sel_hi:[1,0]
	v_pk_mul_f32 v[68:69], v[4:5], v[68:69]
	v_pk_fma_f32 v[68:69], v[100:101], v[68:69], v[84:85]
	v_cvt_pk_bf16_f32 v82, v66, v67
	v_cvt_pk_bf16_f32 v83, v68, v69
	global_store_dwordx2 v245, v[82:83], s[10:11]
	v_pk_mul_f32 v[70:71], v[70:71], v[248:249] op_sel_hi:[1,0]
	v_pk_add_f32 v[102:103], v[102:103], 1.0 op_sel_hi:[1,0]
	v_pk_mul_f32 v[70:71], v[6:7], v[70:71]
	v_pk_fma_f32 v[70:71], v[102:103], v[70:71], v[86:87]
	v_pk_mul_f32 v[72:73], v[72:73], v[248:249] op_sel_hi:[1,0]
	v_pk_add_f32 v[104:105], v[104:105], 1.0 op_sel_hi:[1,0]
	v_pk_mul_f32 v[72:73], v[8:9], v[72:73]
	v_pk_fma_f32 v[72:73], v[104:105], v[72:73], v[88:89]
	v_cvt_pk_bf16_f32 v86, v70, v71
	v_cvt_pk_bf16_f32 v87, v72, v73
	global_store_dwordx2 v245, v[86:87], s[10:11] offset:512
	v_pk_mul_f32 v[74:75], v[74:75], v[248:249] op_sel_hi:[1,0]
	v_pk_add_f32 v[106:107], v[106:107], 1.0 op_sel_hi:[1,0]
	v_pk_mul_f32 v[74:75], v[10:11], v[74:75]
	v_pk_fma_f32 v[74:75], v[106:107], v[74:75], v[90:91]
	v_pk_mul_f32 v[76:77], v[76:77], v[248:249] op_sel_hi:[1,0]
	v_pk_add_f32 v[108:109], v[108:109], 1.0 op_sel_hi:[1,0]
	v_pk_mul_f32 v[76:77], v[12:13], v[76:77]
	v_pk_fma_f32 v[76:77], v[108:109], v[76:77], v[92:93]
	v_cvt_pk_bf16_f32 v90, v74, v75
	v_cvt_pk_bf16_f32 v91, v76, v77
	global_store_dwordx2 v245, v[90:91], s[10:11] offset:1024
	v_pk_mul_f32 v[78:79], v[78:79], v[248:249] op_sel_hi:[1,0]
	v_pk_add_f32 v[118:119], v[118:119], 1.0 op_sel_hi:[1,0]
	v_pk_mul_f32 v[78:79], v[14:15], v[78:79]
	v_pk_fma_f32 v[78:79], v[118:119], v[78:79], v[94:95]
	v_pk_mul_f32 v[80:81], v[80:81], v[248:249] op_sel_hi:[1,0]
	v_pk_add_f32 v[120:121], v[120:121], 1.0 op_sel_hi:[1,0]
	v_pk_mul_f32 v[80:81], v[16:17], v[80:81]
	v_pk_fma_f32 v[80:81], v[120:121], v[80:81], v[96:97]
	v_cvt_pk_bf16_f32 v94, v78, v79
	v_cvt_pk_bf16_f32 v95, v80, v81
	global_store_dwordx2 v245, v[94:95], s[10:11] offset:1536
	s_waitcnt vmcnt(4)
	v_readfirstlane_b32 s6, v114
	s_cmp_ge_u32 s6, 8
	s_cbranch_scc1 .Ldep_norm1d_ok7
	s_add_i32 s6, s37, 1792
	s_lshr_b32 s6, s6, 7
	s_lshl_b32 s6, s6, 2
	s_add_i32 s6, s6, 0x1e40
	v_mov_b32_e32 v110, s6

; DI unsigned pk_bf16(float lo, float hi) { f32x2 v = {lo, hi}; bf16v2 b = __builtin_convertvector(v, bf16v2); return __builtin_bit_cast(unsigned, b); }
; DI float red64(float x) { for (int o = 32; o > 0; o >>= 1) x += __shfl_xor(x, o); return x; }
; DI void modnorm_rows(const Params& p, int l, int which  , bool from_inputs, bool skip_ctx, int w0, int wstride, int lane) {
;     ...
;   for (; i < nrows; i += wstride) {
;     const int row = rowof(i); const int b = row / TB, s = row % TB;
;     f32x4 v[4];
; #pragma unroll
;     for (int q = 0; q < 4; ++q) v[q] = vn[q];
;     if (i + wstride < nrows) {
;       const int rn = rowof(i + wstride); const float* src = xsrc_row(p, from_inputs, rn / TB, rn % TB);
; #pragma unroll
;       for (int q = 0; q < 4; ++q) vn[q] = *(const f32x4*)(src + q * 256 + lane * 4);
;     }
;     const float* mod = p.MOD + (size_t)(l * 9 + (s < NCTX ? 8 : b)) * 6144 + (which ? 3 * 1024 : 0);
;     f32x4 sh[4], sc[4];
; #pragma unroll
;     for (int q = 0; q < 4; ++q) { sh[q] = *(const f32x4*)(mod + q * 256 + lane * 4); sc[q] = *(const f32x4*)(mod + 1024 + q * 256 + lane * 4); }
;     float ss = 0.f;
; #pragma unroll
;     for (int q = 0; q < 4; ++q) ss += v[q][0] * v[q][0] + v[q][1] * v[q][1] + v[q][2] * v[q][2] + v[q][3] * v[q][3];
;     ss = red64(ss);
;     const float rs = rsqrtf(ss * (1.f / 1024.f) + EPSF);
;     bf16_t* dst = p.HY + (size_t)row * DM;
; #pragma unroll
;     for (int q = 0; q < 4; ++q) {
;       float o[4];
; #pragma unroll
;       for (int j = 0; j < 4; ++j) o[j] = (v[q][j] * rs * gg[q][j]) * (1.f + sc[q][j]) + sh[q][j];
;       u32x2 w = {pk_bf16(o[0], o[1]), pk_bf16(o[2], o[3])};
;       *(u32x2*)(dst + q * 256 + lane * 4) = w;
;     }
.Ldep_norm1d_ok7:
	s_add_i32 s21, s37, 1792
	s_mul_hi_u32 s7, s21, 0x38e38e39
	s_lshr_b32 s7, s7, 9
	s_mul_i32 s8, s7, 0x900
	s_sub_i32 s8, s21, s8
	s_lshl_b32 s9, s7, 11
	s_add_i32 s9, s9, s8
	s_add_i32 s9, s9, 0xffffff00
	s_lshl_b32 s10, s7, 8
	s_add_i32 s10, s10, s8
	s_cmpk_gt_i32 s8, 0xff
	s_cselect_b32 s9, s9, s10
	s_cselect_b32 s26, s12, s14
	s_cselect_b32 s27, s13, s15
	s_cselect_b32 s10, s7, 8
	s_lshl_b32 s9, s9, 12
	s_add_u32 s26, s26, s9
	s_addc_u32 s27, s27, 0
	s_add_i32 s10, s10, s82
	s_mul_i32 s10, s10, s24
	s_add_u32 s28, s58, s10
	s_addc_u32 s29, s59, 0
	s_add_u32 s28, s28, 0x0
	s_addc_u32 s29, s29, 0
	s_add_u32 s0, s28, 0x1000
	s_addc_u32 s1, s29, 0
	global_load_dwordx4 v[66:69], v244, s[26:27]
	global_load_dwordx4 v[70:73], v244, s[26:27] offset:1024
	global_load_dwordx4 v[74:77], v244, s[26:27] offset:2048
	global_load_dwordx4 v[78:81], v244, s[26:27] offset:3072
	global_load_dwordx4 v[82:85], v244, s[28:29]
	global_load_dwordx4 v[86:89], v244, s[28:29] offset:1024
	global_load_dwordx4 v[90:93], v244, s[28:29] offset:2048
	global_load_dwordx4 v[94:97], v244, s[28:29] offset:3072
	global_load_dwordx4 v[98:101], v244, s[0:1]
	global_load_dwordx4 v[102:105], v244, s[0:1] offset:1024
	global_load_dwordx4 v[106:109], v244, s[0:1] offset:2048
	global_load_dwordx4 v[118:121], v244, s[0:1] offset:3072
	s_add_i32 s6, s37, 2048
	s_lshr_b32 s6, s6, 7
	s_lshl_b32 s6, s6, 2
	s_add_i32 s6, s6, 0x1e40
	v_mov_b32_e32 v110, s6
	global_load_dword v114, v110, s[70:71] sc1
	s_waitcnt vmcnt(35)
	v_pk_mul_f32 v[246:247], v[122:123], v[122:123]
	v_pk_fma_f32 v[246:247], v[124:125], v[124:125], v[246:247]
	v_pk_fma_f32 v[246:247], v[126:127], v[126:127], v[246:247]
	v_pk_fma_f32 v[246:247], v[128:129], v[128:129], v[246:247]
	v_pk_fma_f32 v[246:247], v[130:131], v[130:131], v[246:247]
	v_pk_fma_f32 v[246:247], v[132:133], v[132:133], v[246:247]
	v_pk_fma_f32 v[246:247], v[134:135], v[134:135], v[246:247]
	v_pk_fma_f32 v[246:247], v[136:137], v[136:137], v[246:247]
	s_nop 0
	v_add_f32_e32 v246, v246, v247
	s_nop 1
	v_add_f32_dpp v246, v246, v246 quad_perm:[1,0,3,2] row_mask:0xf bank_mask:0xf
	s_nop 1
	v_add_f32_dpp v246, v246, v246 quad_perm:[2,3,0,1] row_mask:0xf bank_mask:0xf
	s_nop 1
	v_add_f32_dpp v246, v246, v246 row_half_mirror row_mask:0xf bank_mask:0xf
	s_nop 1
	v_add_f32_dpp v246, v246, v246 row_mirror row_mask:0xf bank_mask:0xf
	s_nop 1
	v_add_f32_dpp v246, v246, v246 row_bcast:15 row_mask:0xa bank_mask:0xf
	s_nop 1
	v_add_f32_dpp v246, v246, v246 row_bcast:31 row_mask:0xc bank_mask:0xf
	s_nop 1
	v_readlane_b32 s0, v246, 63
	s_add_i32 s21, s37, 1280
	s_lshl_b32 s21, s21, 11
	s_add_u32 s10, s16, s21
	s_addc_u32 s11, s17, 0
	v_mov_b32_e32 v248, s0
	v_fmamk_f32 v248, v248, 0x3a800000, v143
	v_rsq_f32_e32 v248, v248
	s_nop 0
	v_pk_mul_f32 v[122:123], v[122:123], v[248:249] op_sel_hi:[1,0]
	v_pk_add_f32 v[176:177], v[176:177], 1.0 op_sel_hi:[1,0]
	v_pk_mul_f32 v[122:123], v[2:3], v[122:123]
	v_pk_fma_f32 v[122:123], v[176:177], v[122:123], v[160:161]
	v_pk_mul_f32 v[124:125], v[124:125], v[248:249] op_sel_hi:[1,0]
	v_pk_add_f32 v[178:179], v[178:179], 1.0 op_sel_hi:[1,0]
	v_pk_mul_f32 v[124:125], v[4:5], v[124:125]
	v_pk_fma_f32 v[124:125], v[178:179], v[124:125], v[162:163]
	v_cvt_pk_bf16_f32 v160, v122, v123
	v_cvt_pk_bf16_f32 v161, v124, v125
	global_store_dwordx2 v245, v[160:161], s[10:11]
	v_pk_mul_f32 v[126:127], v[126:127], v[248:249] op_sel_hi:[1,0]
	v_pk_add_f32 v[180:181], v[180:181], 1.0 op_sel_hi:[1,0]
	v_pk_mul_f32 v[126:127], v[6:7], v[126:127]
	v_pk_fma_f32 v[126:127], v[180:181], v[126:127], v[164:165]
	v_pk_mul_f32 v[128:129], v[128:129], v[248:249] op_sel_hi:[1,0]
	v_pk_add_f32 v[182:183], v[182:183], 1.0 op_sel_hi:[1,0]
	v_pk_mul_f32 v[128:129], v[8:9], v[128:129]
	v_pk_fma_f32 v[128:129], v[182:183], v[128:129], v[166:167]
	v_cvt_pk_bf16_f32 v164, v126, v127
	v_cvt_pk_bf16_f32 v165, v128, v129
	global_store_dwordx2 v245, v[164:165], s[10:11] offset:512
	v_pk_mul_f32 v[130:131], v[130:131], v[248:249] op_sel_hi:[1,0]
	v_pk_add_f32 v[184:185], v[184:185], 1.0 op_sel_hi:[1,0]
	v_pk_mul_f32 v[130:131], v[10:11], v[130:131]
	v_pk_fma_f32 v[130:131], v[184:185], v[130:131], v[168:169]
	v_pk_mul_f32 v[132:133], v[132:133], v[248:249] op_sel_hi:[1,0]
	v_pk_add_f32 v[186:187], v[186:187], 1.0 op_sel_hi:[1,0]
	v_pk_mul_f32 v[132:133], v[12:13], v[132:133]
	v_pk_fma_f32 v[132:133], v[186:187], v[132:133], v[170:171]
	v_cvt_pk_bf16_f32 v168, v130, v131
	v_cvt_pk_bf16_f32 v169, v132, v133
	global_store_dwordx2 v245, v[168:169], s[10:11] offset:1024
	v_pk_mul_f32 v[134:135], v[134:135], v[248:249] op_sel_hi:[1,0]
	v_pk_add_f32 v[188:189], v[188:189], 1.0 op_sel_hi:[1,0]
	v_pk_mul_f32 v[134:135], v[14:15], v[134:135]
	v_pk_fma_f32 v[134:135], v[188:189], v[134:135], v[172:173]
	v_pk_mul_f32 v[136:137], v[136:137], v[248:249] op_sel_hi:[1,0]
	v_pk_add_f32 v[190:191], v[190:191], 1.0 op_sel_hi:[1,0]
	v_pk_mul_f32 v[136:137], v[16:17], v[136:137]
	v_pk_fma_f32 v[136:137], v[190:191], v[136:137], v[174:175]
	v_cvt_pk_bf16_f32 v172, v134, v135
	v_cvt_pk_bf16_f32 v173, v136, v137
	global_store_dwordx2 v245, v[172:173], s[10:11] offset:1536
	s_waitcnt vmcnt(4)
	v_readfirstlane_b32 s6, v114
	s_cmp_ge_u32 s6, 8
	s_cbranch_scc1 .Ldep_norm1d_ok8
	s_add_i32 s6, s37, 2048
	s_lshr_b32 s6, s6, 7
	s_lshl_b32 s6, s6, 2
	s_add_i32 s6, s6, 0x1e40
	v_mov_b32_e32 v110, s6

; DI unsigned pk_bf16(float lo, float hi) { f32x2 v = {lo, hi}; bf16v2 b = __builtin_convertvector(v, bf16v2); return __builtin_bit_cast(unsigned, b); }
; DI float red64(float x) { for (int o = 32; o > 0; o >>= 1) x += __shfl_xor(x, o); return x; }
; DI void modnorm_rows(const Params& p, int l, int which  , bool from_inputs, bool skip_ctx, int w0, int wstride, int lane) {
;     ...
;   for (; i < nrows; i += wstride) {
;     const int row = rowof(i); const int b = row / TB, s = row % TB;
;     f32x4 v[4];
; #pragma unroll
;     for (int q = 0; q < 4; ++q) v[q] = vn[q];
;     if (i + wstride < nrows) {
;       const int rn = rowof(i + wstride); const float* src = xsrc_row(p, from_inputs, rn / TB, rn % TB);
; #pragma unroll
;       for (int q = 0; q < 4; ++q) vn[q] = *(const f32x4*)(src + q * 256 + lane * 4);
;     }
;     const float* mod = p.MOD + (size_t)(l * 9 + (s < NCTX ? 8 : b)) * 6144 + (which ? 3 * 1024 : 0);
;     f32x4 sh[4], sc[4];
; #pragma unroll
;     for (int q = 0; q < 4; ++q) { sh[q] = *(const f32x4*)(mod + q * 256 + lane * 4); sc[q] = *(const f32x4*)(mod + 1024 + q * 256 + lane * 4); }
;     float ss = 0.f;
; #pragma unroll
;     for (int q = 0; q < 4; ++q) ss += v[q][0] * v[q][0] + v[q][1] * v[q][1] + v[q][2] * v[q][2] + v[q][3] * v[q][3];
;     ss = red64(ss);
;     const float rs = rsqrtf(ss * (1.f / 1024.f) + EPSF);
;     bf16_t* dst = p.HY + (size_t)row * DM;
; #pragma unroll
;     for (int q = 0; q < 4; ++q) {
;       float o[4];
; #pragma unroll
;       for (int j = 0; j < 4; ++j) o[j] = (v[q][j] * rs * gg[q][j]) * (1.f + sc[q][j]) + sh[q][j];
;       u32x2 w = {pk_bf16(o[0], o[1]), pk_bf16(o[2], o[3])};
;       *(u32x2*)(dst + q * 256 + lane * 4) = w;
;     }
.Ldep_norm1d_ok8:
	s_add_i32 s21, s37, 2048
	s_mul_hi_u32 s7, s21, 0x38e38e39
	s_lshr_b32 s7, s7, 9
	s_mul_i32 s8, s7, 0x900
	s_sub_i32 s8, s21, s8
	s_lshl_b32 s9, s7, 11
	s_add_i32 s9, s9, s8
	s_add_i32 s9, s9, 0xffffff00
	s_lshl_b32 s10, s7, 8
	s_add_i32 s10, s10, s8
	s_cmpk_gt_i32 s8, 0xff
	s_cselect_b32 s9, s9, s10
	s_cselect_b32 s26, s12, s14
	s_cselect_b32 s27, s13, s15
	s_cselect_b32 s10, s7, 8
	s_lshl_b32 s9, s9, 12
	s_add_u32 s26, s26, s9
	s_addc_u32 s27, s27, 0
	s_add_i32 s10, s10, s82
	s_mul_i32 s10, s10, s24
	s_add_u32 s28, s58, s10
	s_addc_u32 s29, s59, 0
	s_add_u32 s28, s28, 0x0
	s_addc_u32 s29, s29, 0
	s_add_u32 s0, s28, 0x1000
	s_addc_u32 s1, s29, 0
	global_load_dwordx4 v[122:125], v244, s[26:27]
	global_load_dwordx4 v[126:129], v244, s[26:27] offset:1024
	global_load_dwordx4 v[130:133], v244, s[26:27] offset:2048
	global_load_dwordx4 v[134:137], v244, s[26:27] offset:3072
	global_load_dwordx4 v[160:163], v244, s[28:29]
	global_load_dwordx4 v[164:167], v244, s[28:29] offset:1024
	global_load_dwordx4 v[168:171], v244, s[28:29] offset:2048
	global_load_dwordx4 v[172:175], v244, s[28:29] offset:3072
	global_load_dwordx4 v[176:179], v244, s[0:1]
	global_load_dwordx4 v[180:183], v244, s[0:1] offset:1024
	global_load_dwordx4 v[184:187], v244, s[0:1] offset:2048
	global_load_dwordx4 v[188:191], v244, s[0:1] offset:3072
	s_waitcnt vmcnt(34)
	v_pk_mul_f32 v[246:247], v[18:19], v[18:19]
	v_pk_fma_f32 v[246:247], v[20:21], v[20:21], v[246:247]
	v_pk_fma_f32 v[246:247], v[22:23], v[22:23], v[246:247]
	v_pk_fma_f32 v[246:247], v[24:25], v[24:25], v[246:247]
	v_pk_fma_f32 v[246:247], v[26:27], v[26:27], v[246:247]
	v_pk_fma_f32 v[246:247], v[28:29], v[28:29], v[246:247]
	v_pk_fma_f32 v[246:247], v[30:31], v[30:31], v[246:247]
	v_pk_fma_f32 v[246:247], v[32:33], v[32:33], v[246:247]
	s_nop 0
	v_add_f32_e32 v246, v246, v247
	s_nop 1
	v_add_f32_dpp v246, v246, v246 quad_perm:[1,0,3,2] row_mask:0xf bank_mask:0xf
	s_nop 1
	v_add_f32_dpp v246, v246, v246 quad_perm:[2,3,0,1] row_mask:0xf bank_mask:0xf
	s_nop 1
	v_add_f32_dpp v246, v246, v246 row_half_mirror row_mask:0xf bank_mask:0xf
	s_nop 1
	v_add_f32_dpp v246, v246, v246 row_mirror row_mask:0xf bank_mask:0xf
	s_nop 1
	v_add_f32_dpp v246, v246, v246 row_bcast:15 row_mask:0xa bank_mask:0xf
	s_nop 1
	v_add_f32_dpp v246, v246, v246 row_bcast:31 row_mask:0xc bank_mask:0xf
	s_nop 1
	v_readlane_b32 s0, v246, 63
	s_add_i32 s21, s37, 1536
	s_lshl_b32 s21, s21, 11
	s_add_u32 s10, s16, s21
	s_addc_u32 s11, s17, 0
	v_mov_b32_e32 v248, s0
	v_fmamk_f32 v248, v248, 0x3a800000, v143
	v_rsq_f32_e32 v248, v248
	s_nop 0
	v_pk_mul_f32 v[18:19], v[18:19], v[248:249] op_sel_hi:[1,0]
	v_pk_add_f32 v[50:51], v[50:51], 1.0 op_sel_hi:[1,0]
	v_pk_mul_f32 v[18:19], v[2:3], v[18:19]
	v_pk_fma_f32 v[18:19], v[50:51], v[18:19], v[34:35]
	v_pk_mul_f32 v[20:21], v[20:21], v[248:249] op_sel_hi:[1,0]
	v_pk_add_f32 v[52:53], v[52:53], 1.0 op_sel_hi:[1,0]
	v_pk_mul_f32 v[20:21], v[4:5], v[20:21]
	v_pk_fma_f32 v[20:21], v[52:53], v[20:21], v[36:37]
	v_cvt_pk_bf16_f32 v34, v18, v19
	v_cvt_pk_bf16_f32 v35, v20, v21
	global_store_dwordx2 v245, v[34:35], s[10:11]
	v_pk_mul_f32 v[22:23], v[22:23], v[248:249] op_sel_hi:[1,0]
	v_pk_add_f32 v[54:55], v[54:55], 1.0 op_sel_hi:[1,0]
	v_pk_mul_f32 v[22:23], v[6:7], v[22:23]
	v_pk_fma_f32 v[22:23], v[54:55], v[22:23], v[38:39]
	v_pk_mul_f32 v[24:25], v[24:25], v[248:249] op_sel_hi:[1,0]
	v_pk_add_f32 v[56:57], v[56:57], 1.0 op_sel_hi:[1,0]
	v_pk_mul_f32 v[24:25], v[8:9], v[24:25]
	v_pk_fma_f32 v[24:25], v[56:57], v[24:25], v[40:41]
	v_cvt_pk_bf16_f32 v38, v22, v23
	v_cvt_pk_bf16_f32 v39, v24, v25
	global_store_dwordx2 v245, v[38:39], s[10:11] offset:512
	v_pk_mul_f32 v[26:27], v[26:27], v[248:249] op_sel_hi:[1,0]
	v_pk_add_f32 v[58:59], v[58:59], 1.0 op_sel_hi:[1,0]
	v_pk_mul_f32 v[26:27], v[10:11], v[26:27]
	v_pk_fma_f32 v[26:27], v[58:59], v[26:27], v[42:43]
	v_pk_mul_f32 v[28:29], v[28:29], v[248:249] op_sel_hi:[1,0]
	v_pk_add_f32 v[60:61], v[60:61], 1.0 op_sel_hi:[1,0]
	v_pk_mul_f32 v[28:29], v[12:13], v[28:29]
	v_pk_fma_f32 v[28:29], v[60:61], v[28:29], v[44:45]
	v_cvt_pk_bf16_f32 v42, v26, v27
	v_cvt_pk_bf16_f32 v43, v28, v29
	global_store_dwordx2 v245, v[42:43], s[10:11] offset:1024
	v_pk_mul_f32 v[30:31], v[30:31], v[248:249] op_sel_hi:[1,0]
	v_pk_add_f32 v[62:63], v[62:63], 1.0 op_sel_hi:[1,0]
	v_pk_mul_f32 v[30:31], v[14:15], v[30:31]
	v_pk_fma_f32 v[30:31], v[62:63], v[30:31], v[46:47]
	v_pk_mul_f32 v[32:33], v[32:33], v[248:249] op_sel_hi:[1,0]
	v_pk_add_f32 v[64:65], v[64:65], 1.0 op_sel_hi:[1,0]
	v_pk_mul_f32 v[32:33], v[16:17], v[32:33]
	v_pk_fma_f32 v[32:33], v[64:65], v[32:33], v[48:49]
	v_cvt_pk_bf16_f32 v46, v30, v31
	v_cvt_pk_bf16_f32 v47, v32, v33
	global_store_dwordx2 v245, v[46:47], s[10:11] offset:1536
	s_waitcnt vmcnt(21)
; DI unsigned pk_bf16(float lo, float hi) { f32x2 v = {lo, hi}; bf16v2 b = __builtin_convertvector(v, bf16v2); return __builtin_bit_cast(unsigned, b); }
; DI float red64(float x) { for (int o = 32; o > 0; o >>= 1) x += __shfl_xor(x, o); return x; }
; DI void modnorm_rows(const Params& p, int l, int which  , bool from_inputs, bool skip_ctx, int w0, int wstride, int lane) {
;     ...
;     const float* mod = p.MOD + (size_t)(l * 9 + (s < NCTX ? 8 : b)) * 6144 + (which ? 3 * 1024 : 0);
;     f32x4 sh[4], sc[4];
; #pragma unroll
;     for (int q = 0; q < 4; ++q) { sh[q] = *(const f32x4*)(mod + q * 256 + lane * 4); sc[q] = *(const f32x4*)(mod + 1024 + q * 256 + lane * 4); }
;     float ss = 0.f;
; #pragma unroll
;     for (int q = 0; q < 4; ++q) ss += v[q][0] * v[q][0] + v[q][1] * v[q][1] + v[q][2] * v[q][2] + v[q][3] * v[q][3];
;     ss = red64(ss);
;     const float rs = rsqrtf(ss * (1.f / 1024.f) + EPSF);
;     bf16_t* dst = p.HY + (size_t)row * DM;
; #pragma unroll
;     for (int q = 0; q < 4; ++q) {
;       float o[4];
; #pragma unroll
;       for (int j = 0; j < 4; ++j) o[j] = (v[q][j] * rs * gg[q][j]) * (1.f + sc[q][j]) + sh[q][j];
;       u32x2 w = {pk_bf16(o[0], o[1]), pk_bf16(o[2], o[3])};
;       *(u32x2*)(dst + q * 256 + lane * 4) = w;
;     }
	v_pk_mul_f32 v[246:247], v[66:67], v[66:67]
	v_pk_fma_f32 v[246:247], v[68:69], v[68:69], v[246:247]
	v_pk_fma_f32 v[246:247], v[70:71], v[70:71], v[246:247]
	v_pk_fma_f32 v[246:247], v[72:73], v[72:73], v[246:247]
	v_pk_fma_f32 v[246:247], v[74:75], v[74:75], v[246:247]
	v_pk_fma_f32 v[246:247], v[76:77], v[76:77], v[246:247]
	v_pk_fma_f32 v[246:247], v[78:79], v[78:79], v[246:247]
	v_pk_fma_f32 v[246:247], v[80:81], v[80:81], v[246:247]
	s_nop 0
	v_add_f32_e32 v246, v246, v247
	s_nop 1
	v_add_f32_dpp v246, v246, v246 quad_perm:[1,0,3,2] row_mask:0xf bank_mask:0xf
	s_nop 1
	v_add_f32_dpp v246, v246, v246 quad_perm:[2,3,0,1] row_mask:0xf bank_mask:0xf
	s_nop 1
	v_add_f32_dpp v246, v246, v246 row_half_mirror row_mask:0xf bank_mask:0xf
	s_nop 1
	v_add_f32_dpp v246, v246, v246 row_mirror row_mask:0xf bank_mask:0xf
	s_nop 1
	v_add_f32_dpp v246, v246, v246 row_bcast:15 row_mask:0xa bank_mask:0xf
	s_nop 1
	v_add_f32_dpp v246, v246, v246 row_bcast:31 row_mask:0xc bank_mask:0xf
	s_nop 1
	v_readlane_b32 s0, v246, 63
	s_add_i32 s21, s37, 1792
	s_lshl_b32 s21, s21, 11
	s_add_u32 s10, s16, s21
	s_addc_u32 s11, s17, 0
	v_mov_b32_e32 v248, s0
	v_fmamk_f32 v248, v248, 0x3a800000, v143
	v_rsq_f32_e32 v248, v248
	s_nop 0
	v_pk_mul_f32 v[66:67], v[66:67], v[248:249] op_sel_hi:[1,0]
	v_pk_add_f32 v[98:99], v[98:99], 1.0 op_sel_hi:[1,0]
	v_pk_mul_f32 v[66:67], v[2:3], v[66:67]
	v_pk_fma_f32 v[66:67], v[98:99], v[66:67], v[82:83]
	v_pk_mul_f32 v[68:69], v[68:69], v[248:249] op_sel_hi:[1,0]
	v_pk_add_f32 v[100:101], v[100:101], 1.0 op_sel_hi:[1,0]
	v_pk_mul_f32 v[68:69], v[4:5], v[68:69]
	v_pk_fma_f32 v[68:69], v[100:101], v[68:69], v[84:85]
	v_cvt_pk_bf16_f32 v82, v66, v67
	v_cvt_pk_bf16_f32 v83, v68, v69
	global_store_dwordx2 v245, v[82:83], s[10:11]
	v_pk_mul_f32 v[70:71], v[70:71], v[248:249] op_sel_hi:[1,0]
	v_pk_add_f32 v[102:103], v[102:103], 1.0 op_sel_hi:[1,0]
	v_pk_mul_f32 v[70:71], v[6:7], v[70:71]
	v_pk_fma_f32 v[70:71], v[102:103], v[70:71], v[86:87]
	v_pk_mul_f32 v[72:73], v[72:73], v[248:249] op_sel_hi:[1,0]
	v_pk_add_f32 v[104:105], v[104:105], 1.0 op_sel_hi:[1,0]
	v_pk_mul_f32 v[72:73], v[8:9], v[72:73]
	v_pk_fma_f32 v[72:73], v[104:105], v[72:73], v[88:89]
	v_cvt_pk_bf16_f32 v86, v70, v71
	v_cvt_pk_bf16_f32 v87, v72, v73
	global_store_dwordx2 v245, v[86:87], s[10:11] offset:512
	v_pk_mul_f32 v[74:75], v[74:75], v[248:249] op_sel_hi:[1,0]
	v_pk_add_f32 v[106:107], v[106:107], 1.0 op_sel_hi:[1,0]
	v_pk_mul_f32 v[74:75], v[10:11], v[74:75]
	v_pk_fma_f32 v[74:75], v[106:107], v[74:75], v[90:91]
	v_pk_mul_f32 v[76:77], v[76:77], v[248:249] op_sel_hi:[1,0]
	v_pk_add_f32 v[108:109], v[108:109], 1.0 op_sel_hi:[1,0]
	v_pk_mul_f32 v[76:77], v[12:13], v[76:77]
	v_pk_fma_f32 v[76:77], v[108:109], v[76:77], v[92:93]
	v_cvt_pk_bf16_f32 v90, v74, v75
	v_cvt_pk_bf16_f32 v91, v76, v77
	global_store_dwordx2 v245, v[90:91], s[10:11] offset:1024
	v_pk_mul_f32 v[78:79], v[78:79], v[248:249] op_sel_hi:[1,0]
	v_pk_add_f32 v[118:119], v[118:119], 1.0 op_sel_hi:[1,0]
	v_pk_mul_f32 v[78:79], v[14:15], v[78:79]
	v_pk_fma_f32 v[78:79], v[118:119], v[78:79], v[94:95]
	v_pk_mul_f32 v[80:81], v[80:81], v[248:249] op_sel_hi:[1,0]
	v_pk_add_f32 v[120:121], v[120:121], 1.0 op_sel_hi:[1,0]
	v_pk_mul_f32 v[80:81], v[16:17], v[80:81]
	v_pk_fma_f32 v[80:81], v[120:121], v[80:81], v[96:97]
	v_cvt_pk_bf16_f32 v94, v78, v79
	v_cvt_pk_bf16_f32 v95, v80, v81
	global_store_dwordx2 v245, v[94:95], s[10:11] offset:1536
	s_waitcnt vmcnt(8)
; DI unsigned pk_bf16(float lo, float hi) { f32x2 v = {lo, hi}; bf16v2 b = __builtin_convertvector(v, bf16v2); return __builtin_bit_cast(unsigned, b); }
; DI float red64(float x) { for (int o = 32; o > 0; o >>= 1) x += __shfl_xor(x, o); return x; }
; DI void modnorm_rows(const Params& p, int l, int which  , bool from_inputs, bool skip_ctx, int w0, int wstride, int lane) {
;     ...
;     const float* mod = p.MOD + (size_t)(l * 9 + (s < NCTX ? 8 : b)) * 6144 + (which ? 3 * 1024 : 0);
;     f32x4 sh[4], sc[4];
; #pragma unroll
;     for (int q = 0; q < 4; ++q) { sh[q] = *(const f32x4*)(mod + q * 256 + lane * 4); sc[q] = *(const f32x4*)(mod + 1024 + q * 256 + lane * 4); }
;     float ss = 0.f;
; #pragma unroll
;     for (int q = 0; q < 4; ++q) ss += v[q][0] * v[q][0] + v[q][1] * v[q][1] + v[q][2] * v[q][2] + v[q][3] * v[q][3];
;     ss = red64(ss);
;     const float rs = rsqrtf(ss * (1.f / 1024.f) + EPSF);
;     bf16_t* dst = p.HY + (size_t)row * DM;
; #pragma unroll
;     for (int q = 0; q < 4; ++q) {
;       float o[4];
; #pragma unroll
;       for (int j = 0; j < 4; ++j) o[j] = (v[q][j] * rs * gg[q][j]) * (1.f + sc[q][j]) + sh[q][j];
;       u32x2 w = {pk_bf16(o[0], o[1]), pk_bf16(o[2], o[3])};
;       *(u32x2*)(dst + q * 256 + lane * 4) = w;
;     }
	v_pk_mul_f32 v[246:247], v[122:123], v[122:123]
	v_pk_fma_f32 v[246:247], v[124:125], v[124:125], v[246:247]
	v_pk_fma_f32 v[246:247], v[126:127], v[126:127], v[246:247]
	v_pk_fma_f32 v[246:247], v[128:129], v[128:129], v[246:247]
	v_pk_fma_f32 v[246:247], v[130:131], v[130:131], v[246:247]
	v_pk_fma_f32 v[246:247], v[132:133], v[132:133], v[246:247]
	v_pk_fma_f32 v[246:247], v[134:135], v[134:135], v[246:247]
	v_pk_fma_f32 v[246:247], v[136:137], v[136:137], v[246:247]
	s_nop 0
	v_add_f32_e32 v246, v246, v247
	s_nop 1
	v_add_f32_dpp v246, v246, v246 quad_perm:[1,0,3,2] row_mask:0xf bank_mask:0xf
	s_nop 1
	v_add_f32_dpp v246, v246, v246 quad_perm:[2,3,0,1] row_mask:0xf bank_mask:0xf
	s_nop 1
	v_add_f32_dpp v246, v246, v246 row_half_mirror row_mask:0xf bank_mask:0xf
	s_nop 1
	v_add_f32_dpp v246, v246, v246 row_mirror row_mask:0xf bank_mask:0xf
	s_nop 1
	v_add_f32_dpp v246, v246, v246 row_bcast:15 row_mask:0xa bank_mask:0xf
	s_nop 1
	v_add_f32_dpp v246, v246, v246 row_bcast:31 row_mask:0xc bank_mask:0xf
	s_nop 1
	v_readlane_b32 s0, v246, 63
	s_add_i32 s21, s37, 2048
	s_lshl_b32 s21, s21, 11
	s_add_u32 s10, s16, s21
	s_addc_u32 s11, s17, 0
	v_mov_b32_e32 v248, s0
	v_fmamk_f32 v248, v248, 0x3a800000, v143
	v_rsq_f32_e32 v248, v248
	s_nop 0
	v_pk_mul_f32 v[122:123], v[122:123], v[248:249] op_sel_hi:[1,0]
	v_pk_add_f32 v[176:177], v[176:177], 1.0 op_sel_hi:[1,0]
	v_pk_mul_f32 v[122:123], v[2:3], v[122:123]
	v_pk_fma_f32 v[122:123], v[176:177], v[122:123], v[160:161]
	v_pk_mul_f32 v[124:125], v[124:125], v[248:249] op_sel_hi:[1,0]
	v_pk_add_f32 v[178:179], v[178:179], 1.0 op_sel_hi:[1,0]
	v_pk_mul_f32 v[124:125], v[4:5], v[124:125]
	v_pk_fma_f32 v[124:125], v[178:179], v[124:125], v[162:163]
	v_cvt_pk_bf16_f32 v160, v122, v123
	v_cvt_pk_bf16_f32 v161, v124, v125
	global_store_dwordx2 v245, v[160:161], s[10:11]
	v_pk_mul_f32 v[126:127], v[126:127], v[248:249] op_sel_hi:[1,0]
	v_pk_add_f32 v[180:181], v[180:181], 1.0 op_sel_hi:[1,0]
	v_pk_mul_f32 v[126:127], v[6:7], v[126:127]
	v_pk_fma_f32 v[126:127], v[180:181], v[126:127], v[164:165]
	v_pk_mul_f32 v[128:129], v[128:129], v[248:249] op_sel_hi:[1,0]
	v_pk_add_f32 v[182:183], v[182:183], 1.0 op_sel_hi:[1,0]
	v_pk_mul_f32 v[128:129], v[8:9], v[128:129]
	v_pk_fma_f32 v[128:129], v[182:183], v[128:129], v[166:167]
	v_cvt_pk_bf16_f32 v164, v126, v127
	v_cvt_pk_bf16_f32 v165, v128, v129
	global_store_dwordx2 v245, v[164:165], s[10:11] offset:512
	v_pk_mul_f32 v[130:131], v[130:131], v[248:249] op_sel_hi:[1,0]
	v_pk_add_f32 v[184:185], v[184:185], 1.0 op_sel_hi:[1,0]
	v_pk_mul_f32 v[130:131], v[10:11], v[130:131]
	v_pk_fma_f32 v[130:131], v[184:185], v[130:131], v[168:169]
	v_pk_mul_f32 v[132:133], v[132:133], v[248:249] op_sel_hi:[1,0]
	v_pk_add_f32 v[186:187], v[186:187], 1.0 op_sel_hi:[1,0]
	v_pk_mul_f32 v[132:133], v[12:13], v[132:133]
	v_pk_fma_f32 v[132:133], v[186:187], v[132:133], v[170:171]
	v_cvt_pk_bf16_f32 v168, v130, v131
	v_cvt_pk_bf16_f32 v169, v132, v133
	global_store_dwordx2 v245, v[168:169], s[10:11] offset:1024
	v_pk_mul_f32 v[134:135], v[134:135], v[248:249] op_sel_hi:[1,0]
	v_pk_add_f32 v[188:189], v[188:189], 1.0 op_sel_hi:[1,0]
	v_pk_mul_f32 v[134:135], v[14:15], v[134:135]
	v_pk_fma_f32 v[134:135], v[188:189], v[134:135], v[172:173]
	v_pk_mul_f32 v[136:137], v[136:137], v[248:249] op_sel_hi:[1,0]
	v_pk_add_f32 v[190:191], v[190:191], 1.0 op_sel_hi:[1,0]
	v_pk_mul_f32 v[136:137], v[16:17], v[136:137]
	v_pk_fma_f32 v[136:137], v[190:191], v[136:137], v[174:175]
	v_cvt_pk_bf16_f32 v172, v134, v135
	v_cvt_pk_bf16_f32 v173, v136, v137
	global_store_dwordx2 v245, v[172:173], s[10:11] offset:1536
	s_branch .Lnorm1_done
